# P5/P8 residual epilogues: row-group order rotated by (pn>>2)&3 (4 code variants) so CUs of a panel work on different 16-row groups at the same time
# baseline (speedup 1.0000x reference)
.LBB0_1016:
	s_bfe_u32 s94, s0, 0x20002
	s_cmp_eq_u32 s94, 1
	s_cbranch_scc1 .Lrot_p5_1
	s_cmp_eq_u32 s94, 2
	s_cbranch_scc1 .Lrot_p5_2
	s_cmp_eq_u32 s94, 3
	s_cbranch_scc1 .Lrot_p5_3
	v_and_b32_e32 v181, 8, v219
	v_cmp_ne_u32_e64 s[90:91], 0, v181
	v_sub_u32_e32 v191, v1, v181
	v_lshlrev_b32_e32 v181, 1, v181
	s_lshl_b32 s94, s0, 8
	v_add3_u32 v192, v179, v181, s94
	v_sub_u32_e32 v193, v179, v181
	v_add3_u32 v193, v193, 16, s94
	v_lshlrev_b32_e32 v182, 14, v191
	v_lshl_add_u32 v183, v193, 2, v182
	v_add_u32_e32 v183, 0x20000, v183
	v_lshl_add_u32 v182, v192, 2, v182
	v_lshlrev_b32_e32 v184, 13, v191
	v_lshl_add_u32 v185, v193, 1, v184
	v_add_u32_e32 v185, 0x10000, v185
	v_lshl_add_u32 v184, v192, 1, v184
	v_lshlrev_b32_e32 v186, 2, v192
	v_lshlrev_b32_e32 v187, 2, v193
	global_load_dwordx4 v[148:151], v186, s[44:45]
	global_load_dwordx4 v[156:159], v187, s[44:45]
	global_load_dwordx4 v[152:155], v186, s[44:45] offset:512
	global_load_dwordx4 v[160:163], v187, s[44:45] offset:512
	s_lshl_b32 s94, s0, 4
	s_lshl_b32 s95, s64, 2
	s_add_i32 s94, s94, s95
	v_lshlrev_b32_e32 v188, 8, v1
	v_add_u32_e32 v188, s94, v188
	v_xor_b32_e32 v189, 16, v219
	v_lshlrev_b32_e32 v189, 2, v189
	v_xor_b32_e32 v190, 32, v219
	v_lshlrev_b32_e32 v190, 2, v190
	s_lshl_b32 s94, s1, 8
	s_lshl_b32 s94, s94, 14
	s_add_u32 s84, s16, s94
	s_addc_u32 s85, s17, 0
	global_load_dwordx4 v[48:51], v182, s[84:85]
	global_load_dwordx4 v[56:59], v183, s[84:85]
	global_load_dwordx4 v[60:63], v182, s[84:85] offset:512
	global_load_dwordx4 v[64:67], v183, s[84:85] offset:512
	s_lshl_b32 s94, s1, 8
	s_add_i32 s94, s94, 16
	s_lshl_b32 s94, s94, 14
	s_add_u32 s84, s16, s94
	s_addc_u32 s85, s17, 0
	global_load_dwordx4 v[170:173], v182, s[84:85]
	global_load_dwordx4 v[174:177], v183, s[84:85]
	global_load_dwordx4 v[206:209], v182, s[84:85] offset:512
	global_load_dwordx4 v[232:235], v183, s[84:85] offset:512
	v_mov_b32_dpp v224, v140 row_ror:8 row_mask:0xf bank_mask:0xf
	v_mov_b32_dpp v225, v141 row_ror:8 row_mask:0xf bank_mask:0xf
	v_mov_b32_dpp v226, v142 row_ror:8 row_mask:0xf bank_mask:0xf
	v_mov_b32_dpp v227, v143 row_ror:8 row_mask:0xf bank_mask:0xf
	v_cndmask_b32_e64 v140, v224, v144, s[90:91]
	v_cndmask_b32_e64 v141, v225, v145, s[90:91]
	v_cndmask_b32_e64 v142, v226, v146, s[90:91]
	v_cndmask_b32_e64 v143, v227, v147, s[90:91]
	v_cndmask_b32_e64 v144, v144, v224, s[90:91]
	v_cndmask_b32_e64 v145, v145, v225, s[90:91]
	v_cndmask_b32_e64 v146, v146, v226, s[90:91]
	v_cndmask_b32_e64 v147, v147, v227, s[90:91]
	v_mov_b32_dpp v224, v132 row_ror:8 row_mask:0xf bank_mask:0xf
	v_mov_b32_dpp v225, v133 row_ror:8 row_mask:0xf bank_mask:0xf
	v_mov_b32_dpp v226, v134 row_ror:8 row_mask:0xf bank_mask:0xf
	v_mov_b32_dpp v227, v135 row_ror:8 row_mask:0xf bank_mask:0xf
	v_cndmask_b32_e64 v132, v224, v136, s[90:91]
	v_cndmask_b32_e64 v133, v225, v137, s[90:91]
	v_cndmask_b32_e64 v134, v226, v138, s[90:91]
	v_cndmask_b32_e64 v135, v227, v139, s[90:91]
	v_cndmask_b32_e64 v136, v136, v224, s[90:91]
	v_cndmask_b32_e64 v137, v137, v225, s[90:91]
	v_cndmask_b32_e64 v138, v138, v226, s[90:91]
	v_cndmask_b32_e64 v139, v139, v227, s[90:91]
	s_lshl_b32 s94, s1, 8
	s_lshl_b32 s94, s94, 14
	s_add_u32 s86, s48, s94
	s_addc_u32 s87, s49, 0
	s_lshl_b32 s94, s1, 8
	s_lshl_b32 s94, s94, 13
	s_add_u32 s88, s12, s94
	s_addc_u32 s89, s13, 0
	s_lshl_b32 s94, s1, 8
	s_lshl_b32 s94, s94, 8
	s_add_u32 s92, s46, s94
	s_addc_u32 s93, s47, 0
	s_waitcnt vmcnt(4)
	v_pk_add_f32 v[144:145], v[144:145], v[48:49]
	v_pk_add_f32 v[146:147], v[146:147], v[50:51]
	v_pk_add_f32 v[140:141], v[140:141], v[56:57]
	v_pk_add_f32 v[142:143], v[142:143], v[58:59]
	global_store_dwordx4 v182, v[144:147], s[86:87]
	global_store_dwordx4 v183, v[140:143], s[86:87]
	v_mul_f32_e32 v191, v144, v144
	v_fmac_f32_e32 v191, v145, v145
	v_fmac_f32_e32 v191, v146, v146
	v_fmac_f32_e32 v191, v147, v147
	v_mul_f32_e32 v192, v140, v140
	v_fmac_f32_e32 v192, v141, v141
	v_fmac_f32_e32 v192, v142, v142
	v_fmac_f32_e32 v192, v143, v143
	v_pk_mul_f32 v[224:225], v[144:145], v[148:149]
	v_pk_mul_f32 v[226:227], v[146:147], v[150:151]
	v_cvt_pk_bf16_f32 v210, v224, v225
	v_cvt_pk_bf16_f32 v211, v226, v227
	global_store_dwordx2 v184, v[210:211], s[88:89]
	v_pk_mul_f32 v[224:225], v[140:141], v[156:157]
	v_pk_mul_f32 v[226:227], v[142:143], v[158:159]
	v_cvt_pk_bf16_f32 v212, v224, v225
	v_cvt_pk_bf16_f32 v213, v226, v227
	global_store_dwordx2 v185, v[212:213], s[88:89]
	v_pk_add_f32 v[136:137], v[136:137], v[60:61]
	v_pk_add_f32 v[138:139], v[138:139], v[62:63]
	v_pk_add_f32 v[132:133], v[132:133], v[64:65]
	v_pk_add_f32 v[134:135], v[134:135], v[66:67]
	global_store_dwordx4 v182, v[136:139], s[86:87] offset:512
	global_store_dwordx4 v183, v[132:135], s[86:87] offset:512
	v_fmac_f32_e32 v191, v136, v136
	v_fmac_f32_e32 v191, v137, v137
	v_fmac_f32_e32 v191, v138, v138
	v_fmac_f32_e32 v191, v139, v139
	v_fmac_f32_e32 v192, v132, v132
	v_fmac_f32_e32 v192, v133, v133
	v_fmac_f32_e32 v192, v134, v134
	v_fmac_f32_e32 v192, v135, v135
	v_pk_mul_f32 v[224:225], v[136:137], v[152:153]
	v_pk_mul_f32 v[226:227], v[138:139], v[154:155]
	v_cvt_pk_bf16_f32 v210, v224, v225
	v_cvt_pk_bf16_f32 v211, v226, v227
	global_store_dwordx2 v184, v[210:211], s[88:89] offset:256
	v_pk_mul_f32 v[224:225], v[132:133], v[160:161]
	v_pk_mul_f32 v[226:227], v[134:135], v[162:163]
	v_cvt_pk_bf16_f32 v212, v224, v225
	v_cvt_pk_bf16_f32 v213, v226, v227
	global_store_dwordx2 v185, v[212:213], s[88:89] offset:256
	s_nop 1
	v_add_f32_dpp v193, v191, v191 row_ror:8 row_mask:0xf bank_mask:0xf
	v_add_f32_dpp v181, v192, v192 row_ror:8 row_mask:0xf bank_mask:0xf
	v_cndmask_b32_e64 v191, v193, v181, s[90:91]
	v_mov_b32_e32 v192, v191
	s_nop 1
	v_permlane16_swap_b32_e32 v191, v192
	v_add_f32_e32 v191, v191, v192
	v_mov_b32_e32 v192, v191
	s_nop 1
	v_permlane32_swap_b32_e32 v191, v192
	v_add_f32_e32 v191, v191, v192
	s_and_saveexec_b64 s[14:15], s[40:41]
	global_store_dword v188, v191, s[92:93]
	s_or_b64 exec, exec, s[14:15]
	s_lshl_b32 s94, s1, 8
	s_add_i32 s94, s94, 32
	s_lshl_b32 s94, s94, 14
	s_add_u32 s84, s16, s94
	s_addc_u32 s85, s17, 0
	global_load_dwordx4 v[144:147], v182, s[84:85]
	global_load_dwordx4 v[140:143], v183, s[84:85]
	global_load_dwordx4 v[136:139], v182, s[84:85] offset:512
	global_load_dwordx4 v[132:135], v183, s[84:85] offset:512
	v_mov_b32_dpp v224, v124 row_ror:8 row_mask:0xf bank_mask:0xf
	v_mov_b32_dpp v225, v125 row_ror:8 row_mask:0xf bank_mask:0xf
	v_mov_b32_dpp v226, v126 row_ror:8 row_mask:0xf bank_mask:0xf
	v_mov_b32_dpp v227, v127 row_ror:8 row_mask:0xf bank_mask:0xf
	v_cndmask_b32_e64 v124, v224, v128, s[90:91]
	v_cndmask_b32_e64 v125, v225, v129, s[90:91]
	v_cndmask_b32_e64 v126, v226, v130, s[90:91]
	v_cndmask_b32_e64 v127, v227, v131, s[90:91]
	v_cndmask_b32_e64 v128, v128, v224, s[90:91]
	v_cndmask_b32_e64 v129, v129, v225, s[90:91]
	v_cndmask_b32_e64 v130, v130, v226, s[90:91]
	v_cndmask_b32_e64 v131, v131, v227, s[90:91]
	v_mov_b32_dpp v224, v116 row_ror:8 row_mask:0xf bank_mask:0xf
	v_mov_b32_dpp v225, v117 row_ror:8 row_mask:0xf bank_mask:0xf
	v_mov_b32_dpp v226, v118 row_ror:8 row_mask:0xf bank_mask:0xf
	v_mov_b32_dpp v227, v119 row_ror:8 row_mask:0xf bank_mask:0xf
	v_cndmask_b32_e64 v116, v224, v120, s[90:91]
	v_cndmask_b32_e64 v117, v225, v121, s[90:91]
	v_cndmask_b32_e64 v118, v226, v122, s[90:91]
	v_cndmask_b32_e64 v119, v227, v123, s[90:91]
	v_cndmask_b32_e64 v120, v120, v224, s[90:91]
	v_cndmask_b32_e64 v121, v121, v225, s[90:91]
	v_cndmask_b32_e64 v122, v122, v226, s[90:91]
	v_cndmask_b32_e64 v123, v123, v227, s[90:91]
	s_lshl_b32 s94, s1, 8
	s_add_i32 s94, s94, 16
	s_lshl_b32 s94, s94, 14
	s_add_u32 s86, s48, s94
	s_addc_u32 s87, s49, 0
	s_lshl_b32 s94, s1, 8
	s_add_i32 s94, s94, 16
	s_lshl_b32 s94, s94, 13
	s_add_u32 s88, s12, s94
	s_addc_u32 s89, s13, 0
	s_lshl_b32 s94, s1, 8
	s_add_i32 s94, s94, 16
	s_lshl_b32 s94, s94, 8
	s_add_u32 s92, s46, s94
	s_addc_u32 s93, s47, 0
	s_waitcnt vmcnt(13)
	v_pk_add_f32 v[128:129], v[128:129], v[170:171]
	v_pk_add_f32 v[130:131], v[130:131], v[172:173]
	v_pk_add_f32 v[124:125], v[124:125], v[174:175]
	v_pk_add_f32 v[126:127], v[126:127], v[176:177]
	global_store_dwordx4 v182, v[128:131], s[86:87]
	global_store_dwordx4 v183, v[124:127], s[86:87]
	v_mul_f32_e32 v191, v128, v128
	v_fmac_f32_e32 v191, v129, v129
	v_fmac_f32_e32 v191, v130, v130
	v_fmac_f32_e32 v191, v131, v131
	v_mul_f32_e32 v192, v124, v124
	v_fmac_f32_e32 v192, v125, v125
	v_fmac_f32_e32 v192, v126, v126
	v_fmac_f32_e32 v192, v127, v127
	v_pk_mul_f32 v[224:225], v[128:129], v[148:149]
	v_pk_mul_f32 v[226:227], v[130:131], v[150:151]
	v_cvt_pk_bf16_f32 v210, v224, v225
	v_cvt_pk_bf16_f32 v211, v226, v227
	global_store_dwordx2 v184, v[210:211], s[88:89]
	v_pk_mul_f32 v[224:225], v[124:125], v[156:157]
	v_pk_mul_f32 v[226:227], v[126:127], v[158:159]
	v_cvt_pk_bf16_f32 v212, v224, v225
	v_cvt_pk_bf16_f32 v213, v226, v227
	global_store_dwordx2 v185, v[212:213], s[88:89]
	v_pk_add_f32 v[120:121], v[120:121], v[206:207]
	v_pk_add_f32 v[122:123], v[122:123], v[208:209]
	v_pk_add_f32 v[116:117], v[116:117], v[232:233]
	v_pk_add_f32 v[118:119], v[118:119], v[234:235]
	global_store_dwordx4 v182, v[120:123], s[86:87] offset:512
	global_store_dwordx4 v183, v[116:119], s[86:87] offset:512
	v_fmac_f32_e32 v191, v120, v120
	v_fmac_f32_e32 v191, v121, v121
	v_fmac_f32_e32 v191, v122, v122
	v_fmac_f32_e32 v191, v123, v123
	v_fmac_f32_e32 v192, v116, v116
	v_fmac_f32_e32 v192, v117, v117
	v_fmac_f32_e32 v192, v118, v118
	v_fmac_f32_e32 v192, v119, v119
	v_pk_mul_f32 v[224:225], v[120:121], v[152:153]
	v_pk_mul_f32 v[226:227], v[122:123], v[154:155]
	v_cvt_pk_bf16_f32 v210, v224, v225
	v_cvt_pk_bf16_f32 v211, v226, v227
	global_store_dwordx2 v184, v[210:211], s[88:89] offset:256
	v_pk_mul_f32 v[224:225], v[116:117], v[160:161]
	v_pk_mul_f32 v[226:227], v[118:119], v[162:163]
	v_cvt_pk_bf16_f32 v212, v224, v225
	v_cvt_pk_bf16_f32 v213, v226, v227
	global_store_dwordx2 v185, v[212:213], s[88:89] offset:256
	s_nop 1
	v_add_f32_dpp v193, v191, v191 row_ror:8 row_mask:0xf bank_mask:0xf
	v_add_f32_dpp v181, v192, v192 row_ror:8 row_mask:0xf bank_mask:0xf
	v_cndmask_b32_e64 v191, v193, v181, s[90:91]
	v_mov_b32_e32 v192, v191
	s_nop 1
	v_permlane16_swap_b32_e32 v191, v192
	v_add_f32_e32 v191, v191, v192
	v_mov_b32_e32 v192, v191
	s_nop 1
	v_permlane32_swap_b32_e32 v191, v192
	v_add_f32_e32 v191, v191, v192
	s_and_saveexec_b64 s[14:15], s[40:41]
	global_store_dword v188, v191, s[92:93]
	s_or_b64 exec, exec, s[14:15]
	s_lshl_b32 s94, s1, 8
	s_add_i32 s94, s94, 48
	s_lshl_b32 s94, s94, 14
	s_add_u32 s84, s16, s94
	s_addc_u32 s85, s17, 0
	global_load_dwordx4 v[128:131], v182, s[84:85]
	global_load_dwordx4 v[124:127], v183, s[84:85]
	global_load_dwordx4 v[120:123], v182, s[84:85] offset:512
	global_load_dwordx4 v[116:119], v183, s[84:85] offset:512
	v_mov_b32_dpp v224, v108 row_ror:8 row_mask:0xf bank_mask:0xf
	v_mov_b32_dpp v225, v109 row_ror:8 row_mask:0xf bank_mask:0xf
	v_mov_b32_dpp v226, v110 row_ror:8 row_mask:0xf bank_mask:0xf
	v_mov_b32_dpp v227, v111 row_ror:8 row_mask:0xf bank_mask:0xf
	v_cndmask_b32_e64 v108, v224, v112, s[90:91]
	v_cndmask_b32_e64 v109, v225, v113, s[90:91]
	v_cndmask_b32_e64 v110, v226, v114, s[90:91]
	v_cndmask_b32_e64 v111, v227, v115, s[90:91]
	v_cndmask_b32_e64 v112, v112, v224, s[90:91]
	v_cndmask_b32_e64 v113, v113, v225, s[90:91]
	v_cndmask_b32_e64 v114, v114, v226, s[90:91]
	v_cndmask_b32_e64 v115, v115, v227, s[90:91]
	v_mov_b32_dpp v224, v100 row_ror:8 row_mask:0xf bank_mask:0xf
	v_mov_b32_dpp v225, v101 row_ror:8 row_mask:0xf bank_mask:0xf
	v_mov_b32_dpp v226, v102 row_ror:8 row_mask:0xf bank_mask:0xf
	v_mov_b32_dpp v227, v103 row_ror:8 row_mask:0xf bank_mask:0xf
	v_cndmask_b32_e64 v100, v224, v104, s[90:91]
	v_cndmask_b32_e64 v101, v225, v105, s[90:91]
	v_cndmask_b32_e64 v102, v226, v106, s[90:91]
	v_cndmask_b32_e64 v103, v227, v107, s[90:91]
	v_cndmask_b32_e64 v104, v104, v224, s[90:91]
	v_cndmask_b32_e64 v105, v105, v225, s[90:91]
	v_cndmask_b32_e64 v106, v106, v226, s[90:91]
	v_cndmask_b32_e64 v107, v107, v227, s[90:91]
	s_lshl_b32 s94, s1, 8
	s_add_i32 s94, s94, 32
	s_lshl_b32 s94, s94, 14
	s_add_u32 s86, s48, s94
	s_addc_u32 s87, s49, 0
	s_lshl_b32 s94, s1, 8
	s_add_i32 s94, s94, 32
	s_lshl_b32 s94, s94, 13
	s_add_u32 s88, s12, s94
	s_addc_u32 s89, s13, 0
	s_lshl_b32 s94, s1, 8
	s_add_i32 s94, s94, 32
	s_lshl_b32 s94, s94, 8
	s_add_u32 s92, s46, s94
	s_addc_u32 s93, s47, 0
	s_waitcnt vmcnt(13)
	v_pk_add_f32 v[112:113], v[112:113], v[144:145]
	v_pk_add_f32 v[114:115], v[114:115], v[146:147]
	v_pk_add_f32 v[108:109], v[108:109], v[140:141]
	v_pk_add_f32 v[110:111], v[110:111], v[142:143]
	global_store_dwordx4 v182, v[112:115], s[86:87]
	global_store_dwordx4 v183, v[108:111], s[86:87]
	v_mul_f32_e32 v191, v112, v112
	v_fmac_f32_e32 v191, v113, v113
	v_fmac_f32_e32 v191, v114, v114
	v_fmac_f32_e32 v191, v115, v115
	v_mul_f32_e32 v192, v108, v108
	v_fmac_f32_e32 v192, v109, v109
	v_fmac_f32_e32 v192, v110, v110
	v_fmac_f32_e32 v192, v111, v111
	v_pk_mul_f32 v[224:225], v[112:113], v[148:149]
	v_pk_mul_f32 v[226:227], v[114:115], v[150:151]
	v_cvt_pk_bf16_f32 v210, v224, v225
	v_cvt_pk_bf16_f32 v211, v226, v227
	global_store_dwordx2 v184, v[210:211], s[88:89]
	v_pk_mul_f32 v[224:225], v[108:109], v[156:157]
	v_pk_mul_f32 v[226:227], v[110:111], v[158:159]
	v_cvt_pk_bf16_f32 v212, v224, v225
	v_cvt_pk_bf16_f32 v213, v226, v227
	global_store_dwordx2 v185, v[212:213], s[88:89]
	v_pk_add_f32 v[104:105], v[104:105], v[136:137]
	v_pk_add_f32 v[106:107], v[106:107], v[138:139]
	v_pk_add_f32 v[100:101], v[100:101], v[132:133]
	v_pk_add_f32 v[102:103], v[102:103], v[134:135]
	global_store_dwordx4 v182, v[104:107], s[86:87] offset:512
	global_store_dwordx4 v183, v[100:103], s[86:87] offset:512
	v_fmac_f32_e32 v191, v104, v104
	v_fmac_f32_e32 v191, v105, v105
	v_fmac_f32_e32 v191, v106, v106
	v_fmac_f32_e32 v191, v107, v107
	v_fmac_f32_e32 v192, v100, v100
	v_fmac_f32_e32 v192, v101, v101
	v_fmac_f32_e32 v192, v102, v102
	v_fmac_f32_e32 v192, v103, v103
	v_pk_mul_f32 v[224:225], v[104:105], v[152:153]
	v_pk_mul_f32 v[226:227], v[106:107], v[154:155]
	v_cvt_pk_bf16_f32 v210, v224, v225
	v_cvt_pk_bf16_f32 v211, v226, v227
	global_store_dwordx2 v184, v[210:211], s[88:89] offset:256
	v_pk_mul_f32 v[224:225], v[100:101], v[160:161]
	v_pk_mul_f32 v[226:227], v[102:103], v[162:163]
	v_cvt_pk_bf16_f32 v212, v224, v225
	v_cvt_pk_bf16_f32 v213, v226, v227
	global_store_dwordx2 v185, v[212:213], s[88:89] offset:256
	s_nop 1
	v_add_f32_dpp v193, v191, v191 row_ror:8 row_mask:0xf bank_mask:0xf
	v_add_f32_dpp v181, v192, v192 row_ror:8 row_mask:0xf bank_mask:0xf
	v_cndmask_b32_e64 v191, v193, v181, s[90:91]
	v_mov_b32_e32 v192, v191
	s_nop 1
	v_permlane16_swap_b32_e32 v191, v192
	v_add_f32_e32 v191, v191, v192
	v_mov_b32_e32 v192, v191
	s_nop 1
	v_permlane32_swap_b32_e32 v191, v192
	v_add_f32_e32 v191, v191, v192
	s_and_saveexec_b64 s[14:15], s[40:41]
	global_store_dword v188, v191, s[92:93]
	s_or_b64 exec, exec, s[14:15]
	s_lshl_b32 s94, s1, 8
	s_add_i32 s94, s94, 128
	s_lshl_b32 s94, s94, 14
	s_add_u32 s84, s16, s94
	s_addc_u32 s85, s17, 0
	global_load_dwordx4 v[112:115], v182, s[84:85]
	global_load_dwordx4 v[108:111], v183, s[84:85]
	global_load_dwordx4 v[104:107], v182, s[84:85] offset:512
	global_load_dwordx4 v[100:103], v183, s[84:85] offset:512
	v_mov_b32_dpp v224, v92 row_ror:8 row_mask:0xf bank_mask:0xf
	v_mov_b32_dpp v225, v93 row_ror:8 row_mask:0xf bank_mask:0xf
	v_mov_b32_dpp v226, v94 row_ror:8 row_mask:0xf bank_mask:0xf
	v_mov_b32_dpp v227, v95 row_ror:8 row_mask:0xf bank_mask:0xf
	v_cndmask_b32_e64 v92, v224, v96, s[90:91]
	v_cndmask_b32_e64 v93, v225, v97, s[90:91]
	v_cndmask_b32_e64 v94, v226, v98, s[90:91]
	v_cndmask_b32_e64 v95, v227, v99, s[90:91]
	v_cndmask_b32_e64 v96, v96, v224, s[90:91]
	v_cndmask_b32_e64 v97, v97, v225, s[90:91]
	v_cndmask_b32_e64 v98, v98, v226, s[90:91]
	v_cndmask_b32_e64 v99, v99, v227, s[90:91]
	v_mov_b32_dpp v224, v84 row_ror:8 row_mask:0xf bank_mask:0xf
	v_mov_b32_dpp v225, v85 row_ror:8 row_mask:0xf bank_mask:0xf
	v_mov_b32_dpp v226, v86 row_ror:8 row_mask:0xf bank_mask:0xf
	v_mov_b32_dpp v227, v87 row_ror:8 row_mask:0xf bank_mask:0xf
	v_cndmask_b32_e64 v84, v224, v88, s[90:91]
	v_cndmask_b32_e64 v85, v225, v89, s[90:91]
	v_cndmask_b32_e64 v86, v226, v90, s[90:91]
	v_cndmask_b32_e64 v87, v227, v91, s[90:91]
	v_cndmask_b32_e64 v88, v88, v224, s[90:91]
	v_cndmask_b32_e64 v89, v89, v225, s[90:91]
	v_cndmask_b32_e64 v90, v90, v226, s[90:91]
	v_cndmask_b32_e64 v91, v91, v227, s[90:91]
	s_lshl_b32 s94, s1, 8
	s_add_i32 s94, s94, 48
	s_lshl_b32 s94, s94, 14
	s_add_u32 s86, s48, s94
	s_addc_u32 s87, s49, 0
	s_lshl_b32 s94, s1, 8
	s_add_i32 s94, s94, 48
	s_lshl_b32 s94, s94, 13
	s_add_u32 s88, s12, s94
	s_addc_u32 s89, s13, 0
	s_lshl_b32 s94, s1, 8
	s_add_i32 s94, s94, 48
	s_lshl_b32 s94, s94, 8
	s_add_u32 s92, s46, s94
	s_addc_u32 s93, s47, 0
	s_waitcnt vmcnt(13)
	v_pk_add_f32 v[96:97], v[96:97], v[128:129]
	v_pk_add_f32 v[98:99], v[98:99], v[130:131]
	v_pk_add_f32 v[92:93], v[92:93], v[124:125]
	v_pk_add_f32 v[94:95], v[94:95], v[126:127]
	global_store_dwordx4 v182, v[96:99], s[86:87]
	global_store_dwordx4 v183, v[92:95], s[86:87]
	v_mul_f32_e32 v191, v96, v96
	v_fmac_f32_e32 v191, v97, v97
	v_fmac_f32_e32 v191, v98, v98
	v_fmac_f32_e32 v191, v99, v99
	v_mul_f32_e32 v192, v92, v92
	v_fmac_f32_e32 v192, v93, v93
	v_fmac_f32_e32 v192, v94, v94
	v_fmac_f32_e32 v192, v95, v95
	v_pk_mul_f32 v[224:225], v[96:97], v[148:149]
	v_pk_mul_f32 v[226:227], v[98:99], v[150:151]
	v_cvt_pk_bf16_f32 v210, v224, v225
	v_cvt_pk_bf16_f32 v211, v226, v227
	global_store_dwordx2 v184, v[210:211], s[88:89]
	v_pk_mul_f32 v[224:225], v[92:93], v[156:157]
	v_pk_mul_f32 v[226:227], v[94:95], v[158:159]
	v_cvt_pk_bf16_f32 v212, v224, v225
	v_cvt_pk_bf16_f32 v213, v226, v227
	global_store_dwordx2 v185, v[212:213], s[88:89]
	v_pk_add_f32 v[88:89], v[88:89], v[120:121]
	v_pk_add_f32 v[90:91], v[90:91], v[122:123]
	v_pk_add_f32 v[84:85], v[84:85], v[116:117]
	v_pk_add_f32 v[86:87], v[86:87], v[118:119]
	global_store_dwordx4 v182, v[88:91], s[86:87] offset:512
	global_store_dwordx4 v183, v[84:87], s[86:87] offset:512
	v_fmac_f32_e32 v191, v88, v88
	v_fmac_f32_e32 v191, v89, v89
	v_fmac_f32_e32 v191, v90, v90
	v_fmac_f32_e32 v191, v91, v91
	v_fmac_f32_e32 v192, v84, v84
	v_fmac_f32_e32 v192, v85, v85
	v_fmac_f32_e32 v192, v86, v86
	v_fmac_f32_e32 v192, v87, v87
	v_pk_mul_f32 v[224:225], v[88:89], v[152:153]
	v_pk_mul_f32 v[226:227], v[90:91], v[154:155]
	v_cvt_pk_bf16_f32 v210, v224, v225
	v_cvt_pk_bf16_f32 v211, v226, v227
	global_store_dwordx2 v184, v[210:211], s[88:89] offset:256
	v_pk_mul_f32 v[224:225], v[84:85], v[160:161]
	v_pk_mul_f32 v[226:227], v[86:87], v[162:163]
	v_cvt_pk_bf16_f32 v212, v224, v225
	v_cvt_pk_bf16_f32 v213, v226, v227
	global_store_dwordx2 v185, v[212:213], s[88:89] offset:256
	s_nop 1
	v_add_f32_dpp v193, v191, v191 row_ror:8 row_mask:0xf bank_mask:0xf
	v_add_f32_dpp v181, v192, v192 row_ror:8 row_mask:0xf bank_mask:0xf
	v_cndmask_b32_e64 v191, v193, v181, s[90:91]
	v_mov_b32_e32 v192, v191
	s_nop 1
	v_permlane16_swap_b32_e32 v191, v192
	v_add_f32_e32 v191, v191, v192
	v_mov_b32_e32 v192, v191
	s_nop 1
	v_permlane32_swap_b32_e32 v191, v192
	v_add_f32_e32 v191, v191, v192
	s_and_saveexec_b64 s[14:15], s[40:41]
	global_store_dword v188, v191, s[92:93]
	s_or_b64 exec, exec, s[14:15]
	s_lshl_b32 s94, s1, 8
	s_add_i32 s94, s94, 144
	s_lshl_b32 s94, s94, 14
	s_add_u32 s84, s16, s94
	s_addc_u32 s85, s17, 0
	global_load_dwordx4 v[96:99], v182, s[84:85]
	global_load_dwordx4 v[92:95], v183, s[84:85]
	global_load_dwordx4 v[88:91], v182, s[84:85] offset:512
	global_load_dwordx4 v[84:87], v183, s[84:85] offset:512
	v_mov_b32_dpp v224, v76 row_ror:8 row_mask:0xf bank_mask:0xf
	v_mov_b32_dpp v225, v77 row_ror:8 row_mask:0xf bank_mask:0xf
	v_mov_b32_dpp v226, v78 row_ror:8 row_mask:0xf bank_mask:0xf
	v_mov_b32_dpp v227, v79 row_ror:8 row_mask:0xf bank_mask:0xf
	v_cndmask_b32_e64 v76, v224, v80, s[90:91]
	v_cndmask_b32_e64 v77, v225, v81, s[90:91]
	v_cndmask_b32_e64 v78, v226, v82, s[90:91]
	v_cndmask_b32_e64 v79, v227, v83, s[90:91]
	v_cndmask_b32_e64 v80, v80, v224, s[90:91]
	v_cndmask_b32_e64 v81, v81, v225, s[90:91]
	v_cndmask_b32_e64 v82, v82, v226, s[90:91]
	v_cndmask_b32_e64 v83, v83, v227, s[90:91]
	v_mov_b32_dpp v224, v68 row_ror:8 row_mask:0xf bank_mask:0xf
	v_mov_b32_dpp v225, v69 row_ror:8 row_mask:0xf bank_mask:0xf
	v_mov_b32_dpp v226, v70 row_ror:8 row_mask:0xf bank_mask:0xf
	v_mov_b32_dpp v227, v71 row_ror:8 row_mask:0xf bank_mask:0xf
	v_cndmask_b32_e64 v68, v224, v72, s[90:91]
	v_cndmask_b32_e64 v69, v225, v73, s[90:91]
	v_cndmask_b32_e64 v70, v226, v74, s[90:91]
	v_cndmask_b32_e64 v71, v227, v75, s[90:91]
	v_cndmask_b32_e64 v72, v72, v224, s[90:91]
	v_cndmask_b32_e64 v73, v73, v225, s[90:91]
	v_cndmask_b32_e64 v74, v74, v226, s[90:91]
	v_cndmask_b32_e64 v75, v75, v227, s[90:91]
	s_lshl_b32 s94, s1, 8
	s_add_i32 s94, s94, 128
	s_lshl_b32 s94, s94, 14
	s_add_u32 s86, s48, s94
	s_addc_u32 s87, s49, 0
	s_lshl_b32 s94, s1, 8
	s_add_i32 s94, s94, 128
	s_lshl_b32 s94, s94, 13
	s_add_u32 s88, s12, s94
	s_addc_u32 s89, s13, 0
	s_lshl_b32 s94, s1, 8
	s_add_i32 s94, s94, 128
	s_lshl_b32 s94, s94, 8
	s_add_u32 s92, s46, s94
	s_addc_u32 s93, s47, 0
	s_waitcnt vmcnt(13)
	v_pk_add_f32 v[80:81], v[80:81], v[112:113]
	v_pk_add_f32 v[82:83], v[82:83], v[114:115]
	v_pk_add_f32 v[76:77], v[76:77], v[108:109]
	v_pk_add_f32 v[78:79], v[78:79], v[110:111]
	global_store_dwordx4 v182, v[80:83], s[86:87]
	global_store_dwordx4 v183, v[76:79], s[86:87]
	v_mul_f32_e32 v191, v80, v80
	v_fmac_f32_e32 v191, v81, v81
	v_fmac_f32_e32 v191, v82, v82
	v_fmac_f32_e32 v191, v83, v83
	v_mul_f32_e32 v192, v76, v76
	v_fmac_f32_e32 v192, v77, v77
	v_fmac_f32_e32 v192, v78, v78
	v_fmac_f32_e32 v192, v79, v79
	v_pk_mul_f32 v[224:225], v[80:81], v[148:149]
	v_pk_mul_f32 v[226:227], v[82:83], v[150:151]
	v_cvt_pk_bf16_f32 v210, v224, v225
	v_cvt_pk_bf16_f32 v211, v226, v227
	global_store_dwordx2 v184, v[210:211], s[88:89]
	v_pk_mul_f32 v[224:225], v[76:77], v[156:157]
	v_pk_mul_f32 v[226:227], v[78:79], v[158:159]
	v_cvt_pk_bf16_f32 v212, v224, v225
	v_cvt_pk_bf16_f32 v213, v226, v227
	global_store_dwordx2 v185, v[212:213], s[88:89]
	v_pk_add_f32 v[72:73], v[72:73], v[104:105]
	v_pk_add_f32 v[74:75], v[74:75], v[106:107]
	v_pk_add_f32 v[68:69], v[68:69], v[100:101]
	v_pk_add_f32 v[70:71], v[70:71], v[102:103]
	global_store_dwordx4 v182, v[72:75], s[86:87] offset:512
	global_store_dwordx4 v183, v[68:71], s[86:87] offset:512
	v_fmac_f32_e32 v191, v72, v72
	v_fmac_f32_e32 v191, v73, v73
	v_fmac_f32_e32 v191, v74, v74
	v_fmac_f32_e32 v191, v75, v75
	v_fmac_f32_e32 v192, v68, v68
	v_fmac_f32_e32 v192, v69, v69
	v_fmac_f32_e32 v192, v70, v70
	v_fmac_f32_e32 v192, v71, v71
	v_pk_mul_f32 v[224:225], v[72:73], v[152:153]
	v_pk_mul_f32 v[226:227], v[74:75], v[154:155]
	v_cvt_pk_bf16_f32 v210, v224, v225
	v_cvt_pk_bf16_f32 v211, v226, v227
	global_store_dwordx2 v184, v[210:211], s[88:89] offset:256
	v_pk_mul_f32 v[224:225], v[68:69], v[160:161]
	v_pk_mul_f32 v[226:227], v[70:71], v[162:163]
	v_cvt_pk_bf16_f32 v212, v224, v225
	v_cvt_pk_bf16_f32 v213, v226, v227
	global_store_dwordx2 v185, v[212:213], s[88:89] offset:256
	s_nop 1
	v_add_f32_dpp v193, v191, v191 row_ror:8 row_mask:0xf bank_mask:0xf
	v_add_f32_dpp v181, v192, v192 row_ror:8 row_mask:0xf bank_mask:0xf
	v_cndmask_b32_e64 v191, v193, v181, s[90:91]
	v_mov_b32_e32 v192, v191
	s_nop 1
	v_permlane16_swap_b32_e32 v191, v192
	v_add_f32_e32 v191, v191, v192
	v_mov_b32_e32 v192, v191
	s_nop 1
	v_permlane32_swap_b32_e32 v191, v192
	v_add_f32_e32 v191, v191, v192
	s_and_saveexec_b64 s[14:15], s[40:41]
	global_store_dword v188, v191, s[92:93]
	s_or_b64 exec, exec, s[14:15]
	s_lshl_b32 s94, s1, 8
	s_add_i32 s94, s94, 160
	s_lshl_b32 s94, s94, 14
	s_add_u32 s84, s16, s94
	s_addc_u32 s85, s17, 0
	global_load_dwordx4 v[80:83], v182, s[84:85]
	global_load_dwordx4 v[76:79], v183, s[84:85]
	global_load_dwordx4 v[72:75], v182, s[84:85] offset:512
	global_load_dwordx4 v[68:71], v183, s[84:85] offset:512
	v_mov_b32_dpp v224, v44 row_ror:8 row_mask:0xf bank_mask:0xf
	v_mov_b32_dpp v225, v45 row_ror:8 row_mask:0xf bank_mask:0xf
	v_mov_b32_dpp v226, v46 row_ror:8 row_mask:0xf bank_mask:0xf
	v_mov_b32_dpp v227, v47 row_ror:8 row_mask:0xf bank_mask:0xf
	v_cndmask_b32_e64 v44, v224, v52, s[90:91]
	v_cndmask_b32_e64 v45, v225, v53, s[90:91]
	v_cndmask_b32_e64 v46, v226, v54, s[90:91]
	v_cndmask_b32_e64 v47, v227, v55, s[90:91]
	v_cndmask_b32_e64 v52, v52, v224, s[90:91]
	v_cndmask_b32_e64 v53, v53, v225, s[90:91]
	v_cndmask_b32_e64 v54, v54, v226, s[90:91]
	v_cndmask_b32_e64 v55, v55, v227, s[90:91]
	v_mov_b32_dpp v224, v36 row_ror:8 row_mask:0xf bank_mask:0xf
	v_mov_b32_dpp v225, v37 row_ror:8 row_mask:0xf bank_mask:0xf
	v_mov_b32_dpp v226, v38 row_ror:8 row_mask:0xf bank_mask:0xf
	v_mov_b32_dpp v227, v39 row_ror:8 row_mask:0xf bank_mask:0xf
	v_cndmask_b32_e64 v36, v224, v40, s[90:91]
	v_cndmask_b32_e64 v37, v225, v41, s[90:91]
	v_cndmask_b32_e64 v38, v226, v42, s[90:91]
	v_cndmask_b32_e64 v39, v227, v43, s[90:91]
	v_cndmask_b32_e64 v40, v40, v224, s[90:91]
	v_cndmask_b32_e64 v41, v41, v225, s[90:91]
	v_cndmask_b32_e64 v42, v42, v226, s[90:91]
	v_cndmask_b32_e64 v43, v43, v227, s[90:91]
	s_lshl_b32 s94, s1, 8
	s_add_i32 s94, s94, 144
	s_lshl_b32 s94, s94, 14
	s_add_u32 s86, s48, s94
	s_addc_u32 s87, s49, 0
	s_lshl_b32 s94, s1, 8
	s_add_i32 s94, s94, 144
	s_lshl_b32 s94, s94, 13
	s_add_u32 s88, s12, s94
	s_addc_u32 s89, s13, 0
	s_lshl_b32 s94, s1, 8
	s_add_i32 s94, s94, 144
	s_lshl_b32 s94, s94, 8
	s_add_u32 s92, s46, s94
	s_addc_u32 s93, s47, 0
	s_waitcnt vmcnt(13)
	v_pk_add_f32 v[52:53], v[52:53], v[96:97]
	v_pk_add_f32 v[54:55], v[54:55], v[98:99]
	v_pk_add_f32 v[44:45], v[44:45], v[92:93]
	v_pk_add_f32 v[46:47], v[46:47], v[94:95]
	global_store_dwordx4 v182, v[52:55], s[86:87]
	global_store_dwordx4 v183, v[44:47], s[86:87]
	v_mul_f32_e32 v191, v52, v52
	v_fmac_f32_e32 v191, v53, v53
	v_fmac_f32_e32 v191, v54, v54
	v_fmac_f32_e32 v191, v55, v55
	v_mul_f32_e32 v192, v44, v44
	v_fmac_f32_e32 v192, v45, v45
	v_fmac_f32_e32 v192, v46, v46
	v_fmac_f32_e32 v192, v47, v47
	v_pk_mul_f32 v[224:225], v[52:53], v[148:149]
	v_pk_mul_f32 v[226:227], v[54:55], v[150:151]
	v_cvt_pk_bf16_f32 v210, v224, v225
	v_cvt_pk_bf16_f32 v211, v226, v227
	global_store_dwordx2 v184, v[210:211], s[88:89]
	v_pk_mul_f32 v[224:225], v[44:45], v[156:157]
	v_pk_mul_f32 v[226:227], v[46:47], v[158:159]
	v_cvt_pk_bf16_f32 v212, v224, v225
	v_cvt_pk_bf16_f32 v213, v226, v227
	global_store_dwordx2 v185, v[212:213], s[88:89]
	v_pk_add_f32 v[40:41], v[40:41], v[88:89]
	v_pk_add_f32 v[42:43], v[42:43], v[90:91]
	v_pk_add_f32 v[36:37], v[36:37], v[84:85]
	v_pk_add_f32 v[38:39], v[38:39], v[86:87]
	global_store_dwordx4 v182, v[40:43], s[86:87] offset:512
	global_store_dwordx4 v183, v[36:39], s[86:87] offset:512
	v_fmac_f32_e32 v191, v40, v40
	v_fmac_f32_e32 v191, v41, v41
	v_fmac_f32_e32 v191, v42, v42
	v_fmac_f32_e32 v191, v43, v43
	v_fmac_f32_e32 v192, v36, v36
	v_fmac_f32_e32 v192, v37, v37
	v_fmac_f32_e32 v192, v38, v38
	v_fmac_f32_e32 v192, v39, v39
	v_pk_mul_f32 v[224:225], v[40:41], v[152:153]
	v_pk_mul_f32 v[226:227], v[42:43], v[154:155]
	v_cvt_pk_bf16_f32 v210, v224, v225
	v_cvt_pk_bf16_f32 v211, v226, v227
	global_store_dwordx2 v184, v[210:211], s[88:89] offset:256
	v_pk_mul_f32 v[224:225], v[36:37], v[160:161]
	v_pk_mul_f32 v[226:227], v[38:39], v[162:163]
	v_cvt_pk_bf16_f32 v212, v224, v225
	v_cvt_pk_bf16_f32 v213, v226, v227
	global_store_dwordx2 v185, v[212:213], s[88:89] offset:256
	s_nop 1
	v_add_f32_dpp v193, v191, v191 row_ror:8 row_mask:0xf bank_mask:0xf
	v_add_f32_dpp v181, v192, v192 row_ror:8 row_mask:0xf bank_mask:0xf
	v_cndmask_b32_e64 v191, v193, v181, s[90:91]
	v_mov_b32_e32 v192, v191
	s_nop 1
	v_permlane16_swap_b32_e32 v191, v192
	v_add_f32_e32 v191, v191, v192
	v_mov_b32_e32 v192, v191
	s_nop 1
	v_permlane32_swap_b32_e32 v191, v192
	v_add_f32_e32 v191, v191, v192
	s_and_saveexec_b64 s[14:15], s[40:41]
	global_store_dword v188, v191, s[92:93]
	s_or_b64 exec, exec, s[14:15]
	s_lshl_b32 s94, s1, 8
	s_add_i32 s94, s94, 176
	s_lshl_b32 s94, s94, 14
	s_add_u32 s84, s16, s94
	s_addc_u32 s85, s17, 0
	global_load_dwordx4 v[52:55], v182, s[84:85]
	global_load_dwordx4 v[44:47], v183, s[84:85]
	global_load_dwordx4 v[40:43], v182, s[84:85] offset:512
	global_load_dwordx4 v[36:39], v183, s[84:85] offset:512
	v_mov_b32_dpp v224, v28 row_ror:8 row_mask:0xf bank_mask:0xf
	v_mov_b32_dpp v225, v29 row_ror:8 row_mask:0xf bank_mask:0xf
	v_mov_b32_dpp v226, v30 row_ror:8 row_mask:0xf bank_mask:0xf
	v_mov_b32_dpp v227, v31 row_ror:8 row_mask:0xf bank_mask:0xf
	v_cndmask_b32_e64 v28, v224, v32, s[90:91]
	v_cndmask_b32_e64 v29, v225, v33, s[90:91]
	v_cndmask_b32_e64 v30, v226, v34, s[90:91]
	v_cndmask_b32_e64 v31, v227, v35, s[90:91]
	v_cndmask_b32_e64 v32, v32, v224, s[90:91]
	v_cndmask_b32_e64 v33, v33, v225, s[90:91]
	v_cndmask_b32_e64 v34, v34, v226, s[90:91]
	v_cndmask_b32_e64 v35, v35, v227, s[90:91]
	v_mov_b32_dpp v224, v20 row_ror:8 row_mask:0xf bank_mask:0xf
	v_mov_b32_dpp v225, v21 row_ror:8 row_mask:0xf bank_mask:0xf
	v_mov_b32_dpp v226, v22 row_ror:8 row_mask:0xf bank_mask:0xf
	v_mov_b32_dpp v227, v23 row_ror:8 row_mask:0xf bank_mask:0xf
	v_cndmask_b32_e64 v20, v224, v24, s[90:91]
	v_cndmask_b32_e64 v21, v225, v25, s[90:91]
	v_cndmask_b32_e64 v22, v226, v26, s[90:91]
	v_cndmask_b32_e64 v23, v227, v27, s[90:91]
	v_cndmask_b32_e64 v24, v24, v224, s[90:91]
	v_cndmask_b32_e64 v25, v25, v225, s[90:91]
	v_cndmask_b32_e64 v26, v26, v226, s[90:91]
	v_cndmask_b32_e64 v27, v27, v227, s[90:91]
	s_lshl_b32 s94, s1, 8
	s_add_i32 s94, s94, 160
	s_lshl_b32 s94, s94, 14
	s_add_u32 s86, s48, s94
	s_addc_u32 s87, s49, 0
	s_lshl_b32 s94, s1, 8
	s_add_i32 s94, s94, 160
	s_lshl_b32 s94, s94, 13
	s_add_u32 s88, s12, s94
	s_addc_u32 s89, s13, 0
	s_lshl_b32 s94, s1, 8
	s_add_i32 s94, s94, 160
	s_lshl_b32 s94, s94, 8
	s_add_u32 s92, s46, s94
	s_addc_u32 s93, s47, 0
	s_waitcnt vmcnt(13)
	v_pk_add_f32 v[32:33], v[32:33], v[80:81]
	v_pk_add_f32 v[34:35], v[34:35], v[82:83]
	v_pk_add_f32 v[28:29], v[28:29], v[76:77]
	v_pk_add_f32 v[30:31], v[30:31], v[78:79]
	global_store_dwordx4 v182, v[32:35], s[86:87]
	global_store_dwordx4 v183, v[28:31], s[86:87]
	v_mul_f32_e32 v191, v32, v32
	v_fmac_f32_e32 v191, v33, v33
	v_fmac_f32_e32 v191, v34, v34
	v_fmac_f32_e32 v191, v35, v35
	v_mul_f32_e32 v192, v28, v28
	v_fmac_f32_e32 v192, v29, v29
	v_fmac_f32_e32 v192, v30, v30
	v_fmac_f32_e32 v192, v31, v31
	v_pk_mul_f32 v[224:225], v[32:33], v[148:149]
	v_pk_mul_f32 v[226:227], v[34:35], v[150:151]
	v_cvt_pk_bf16_f32 v210, v224, v225
	v_cvt_pk_bf16_f32 v211, v226, v227
	global_store_dwordx2 v184, v[210:211], s[88:89]
	v_pk_mul_f32 v[224:225], v[28:29], v[156:157]
	v_pk_mul_f32 v[226:227], v[30:31], v[158:159]
	v_cvt_pk_bf16_f32 v212, v224, v225
	v_cvt_pk_bf16_f32 v213, v226, v227
	global_store_dwordx2 v185, v[212:213], s[88:89]
	v_pk_add_f32 v[24:25], v[24:25], v[72:73]
	v_pk_add_f32 v[26:27], v[26:27], v[74:75]
	v_pk_add_f32 v[20:21], v[20:21], v[68:69]
	v_pk_add_f32 v[22:23], v[22:23], v[70:71]
	global_store_dwordx4 v182, v[24:27], s[86:87] offset:512
	global_store_dwordx4 v183, v[20:23], s[86:87] offset:512
	v_fmac_f32_e32 v191, v24, v24
	v_fmac_f32_e32 v191, v25, v25
	v_fmac_f32_e32 v191, v26, v26
	v_fmac_f32_e32 v191, v27, v27
	v_fmac_f32_e32 v192, v20, v20
	v_fmac_f32_e32 v192, v21, v21
	v_fmac_f32_e32 v192, v22, v22
	v_fmac_f32_e32 v192, v23, v23
	v_pk_mul_f32 v[224:225], v[24:25], v[152:153]
	v_pk_mul_f32 v[226:227], v[26:27], v[154:155]
	v_cvt_pk_bf16_f32 v210, v224, v225
	v_cvt_pk_bf16_f32 v211, v226, v227
	global_store_dwordx2 v184, v[210:211], s[88:89] offset:256
	v_pk_mul_f32 v[224:225], v[20:21], v[160:161]
	v_pk_mul_f32 v[226:227], v[22:23], v[162:163]
	v_cvt_pk_bf16_f32 v212, v224, v225
	v_cvt_pk_bf16_f32 v213, v226, v227
	global_store_dwordx2 v185, v[212:213], s[88:89] offset:256
	s_nop 1
	v_add_f32_dpp v193, v191, v191 row_ror:8 row_mask:0xf bank_mask:0xf
	v_add_f32_dpp v181, v192, v192 row_ror:8 row_mask:0xf bank_mask:0xf
	v_cndmask_b32_e64 v191, v193, v181, s[90:91]
	v_mov_b32_e32 v192, v191
	s_nop 1
	v_permlane16_swap_b32_e32 v191, v192
	v_add_f32_e32 v191, v191, v192
	v_mov_b32_e32 v192, v191
	s_nop 1
	v_permlane32_swap_b32_e32 v191, v192
	v_add_f32_e32 v191, v191, v192
	s_and_saveexec_b64 s[14:15], s[40:41]
	global_store_dword v188, v191, s[92:93]
	s_or_b64 exec, exec, s[14:15]
	v_mov_b32_dpp v224, v12 row_ror:8 row_mask:0xf bank_mask:0xf
	v_mov_b32_dpp v225, v13 row_ror:8 row_mask:0xf bank_mask:0xf
	v_mov_b32_dpp v226, v14 row_ror:8 row_mask:0xf bank_mask:0xf
	v_mov_b32_dpp v227, v15 row_ror:8 row_mask:0xf bank_mask:0xf
	v_cndmask_b32_e64 v12, v224, v16, s[90:91]
	v_cndmask_b32_e64 v13, v225, v17, s[90:91]
	v_cndmask_b32_e64 v14, v226, v18, s[90:91]
	v_cndmask_b32_e64 v15, v227, v19, s[90:91]
	v_cndmask_b32_e64 v16, v16, v224, s[90:91]
	v_cndmask_b32_e64 v17, v17, v225, s[90:91]
	v_cndmask_b32_e64 v18, v18, v226, s[90:91]
	v_cndmask_b32_e64 v19, v19, v227, s[90:91]
	v_mov_b32_dpp v224, v4 row_ror:8 row_mask:0xf bank_mask:0xf
	v_mov_b32_dpp v225, v5 row_ror:8 row_mask:0xf bank_mask:0xf
	v_mov_b32_dpp v226, v6 row_ror:8 row_mask:0xf bank_mask:0xf
	v_mov_b32_dpp v227, v7 row_ror:8 row_mask:0xf bank_mask:0xf
	v_cndmask_b32_e64 v4, v224, v8, s[90:91]
	v_cndmask_b32_e64 v5, v225, v9, s[90:91]
	v_cndmask_b32_e64 v6, v226, v10, s[90:91]
	v_cndmask_b32_e64 v7, v227, v11, s[90:91]
	v_cndmask_b32_e64 v8, v8, v224, s[90:91]
	v_cndmask_b32_e64 v9, v9, v225, s[90:91]
	v_cndmask_b32_e64 v10, v10, v226, s[90:91]
	v_cndmask_b32_e64 v11, v11, v227, s[90:91]
	s_lshl_b32 s94, s1, 8
	s_add_i32 s94, s94, 176
	s_lshl_b32 s94, s94, 14
	s_add_u32 s86, s48, s94
	s_addc_u32 s87, s49, 0
	s_lshl_b32 s94, s1, 8
	s_add_i32 s94, s94, 176
	s_lshl_b32 s94, s94, 13
	s_add_u32 s88, s12, s94
	s_addc_u32 s89, s13, 0
	s_lshl_b32 s94, s1, 8
	s_add_i32 s94, s94, 176
	s_lshl_b32 s94, s94, 8
	s_add_u32 s92, s46, s94
	s_addc_u32 s93, s47, 0
	s_waitcnt vmcnt(9)
	v_pk_add_f32 v[16:17], v[16:17], v[52:53]
	v_pk_add_f32 v[18:19], v[18:19], v[54:55]
	v_pk_add_f32 v[12:13], v[12:13], v[44:45]
	v_pk_add_f32 v[14:15], v[14:15], v[46:47]
	global_store_dwordx4 v182, v[16:19], s[86:87]
	global_store_dwordx4 v183, v[12:15], s[86:87]
	v_mul_f32_e32 v191, v16, v16
	v_fmac_f32_e32 v191, v17, v17
	v_fmac_f32_e32 v191, v18, v18
	v_fmac_f32_e32 v191, v19, v19
	v_mul_f32_e32 v192, v12, v12
	v_fmac_f32_e32 v192, v13, v13
	v_fmac_f32_e32 v192, v14, v14
	v_fmac_f32_e32 v192, v15, v15
	v_pk_mul_f32 v[224:225], v[16:17], v[148:149]
	v_pk_mul_f32 v[226:227], v[18:19], v[150:151]
	v_cvt_pk_bf16_f32 v210, v224, v225
	v_cvt_pk_bf16_f32 v211, v226, v227
	global_store_dwordx2 v184, v[210:211], s[88:89]
	v_pk_mul_f32 v[224:225], v[12:13], v[156:157]
	v_pk_mul_f32 v[226:227], v[14:15], v[158:159]
	v_cvt_pk_bf16_f32 v212, v224, v225
	v_cvt_pk_bf16_f32 v213, v226, v227
	global_store_dwordx2 v185, v[212:213], s[88:89]
	v_pk_add_f32 v[8:9], v[8:9], v[40:41]
	v_pk_add_f32 v[10:11], v[10:11], v[42:43]
	v_pk_add_f32 v[4:5], v[4:5], v[36:37]
	v_pk_add_f32 v[6:7], v[6:7], v[38:39]
	global_store_dwordx4 v182, v[8:11], s[86:87] offset:512
	global_store_dwordx4 v183, v[4:7], s[86:87] offset:512
	v_fmac_f32_e32 v191, v8, v8
	v_fmac_f32_e32 v191, v9, v9
	v_fmac_f32_e32 v191, v10, v10
	v_fmac_f32_e32 v191, v11, v11
	v_fmac_f32_e32 v192, v4, v4
	v_fmac_f32_e32 v192, v5, v5
	v_fmac_f32_e32 v192, v6, v6
	v_fmac_f32_e32 v192, v7, v7
	v_pk_mul_f32 v[224:225], v[8:9], v[152:153]
	v_pk_mul_f32 v[226:227], v[10:11], v[154:155]
	v_cvt_pk_bf16_f32 v210, v224, v225
	v_cvt_pk_bf16_f32 v211, v226, v227
	global_store_dwordx2 v184, v[210:211], s[88:89] offset:256
	v_pk_mul_f32 v[224:225], v[4:5], v[160:161]
	v_pk_mul_f32 v[226:227], v[6:7], v[162:163]
	v_cvt_pk_bf16_f32 v212, v224, v225
	v_cvt_pk_bf16_f32 v213, v226, v227
	global_store_dwordx2 v185, v[212:213], s[88:89] offset:256
	s_nop 1
	v_add_f32_dpp v193, v191, v191 row_ror:8 row_mask:0xf bank_mask:0xf
	v_add_f32_dpp v181, v192, v192 row_ror:8 row_mask:0xf bank_mask:0xf
	v_cndmask_b32_e64 v191, v193, v181, s[90:91]
	v_mov_b32_e32 v192, v191
	s_nop 1
	v_permlane16_swap_b32_e32 v191, v192
	v_add_f32_e32 v191, v191, v192
	v_mov_b32_e32 v192, v191
	s_nop 1
	v_permlane32_swap_b32_e32 v191, v192
	v_add_f32_e32 v191, v191, v192
	s_and_saveexec_b64 s[14:15], s[40:41]
	global_store_dword v188, v191, s[92:93]
	s_or_b64 exec, exec, s[14:15]
	s_branch .Lrot_p5_end
.Lrot_p5_1:
	v_and_b32_e32 v181, 8, v219
	v_cmp_ne_u32_e64 s[90:91], 0, v181
	v_sub_u32_e32 v191, v1, v181
	v_lshlrev_b32_e32 v181, 1, v181
	s_lshl_b32 s94, s0, 8
	v_add3_u32 v192, v179, v181, s94
	v_sub_u32_e32 v193, v179, v181
	v_add3_u32 v193, v193, 16, s94
	v_lshlrev_b32_e32 v182, 14, v191
	v_lshl_add_u32 v183, v193, 2, v182
	v_add_u32_e32 v183, 0x20000, v183
	v_lshl_add_u32 v182, v192, 2, v182
	v_lshlrev_b32_e32 v184, 13, v191
	v_lshl_add_u32 v185, v193, 1, v184
	v_add_u32_e32 v185, 0x10000, v185
	v_lshl_add_u32 v184, v192, 1, v184
	v_lshlrev_b32_e32 v186, 2, v192
	v_lshlrev_b32_e32 v187, 2, v193
	global_load_dwordx4 v[148:151], v186, s[44:45]
	global_load_dwordx4 v[156:159], v187, s[44:45]
	global_load_dwordx4 v[152:155], v186, s[44:45] offset:512
	global_load_dwordx4 v[160:163], v187, s[44:45] offset:512
	s_lshl_b32 s94, s0, 4
	s_lshl_b32 s95, s64, 2
	s_add_i32 s94, s94, s95
	v_lshlrev_b32_e32 v188, 8, v1
	v_add_u32_e32 v188, s94, v188
	v_xor_b32_e32 v189, 16, v219
	v_lshlrev_b32_e32 v189, 2, v189
	v_xor_b32_e32 v190, 32, v219
	v_lshlrev_b32_e32 v190, 2, v190
	s_lshl_b32 s94, s1, 8
	s_add_i32 s94, s94, 16
	s_lshl_b32 s94, s94, 14
	s_add_u32 s84, s16, s94
	s_addc_u32 s85, s17, 0
	global_load_dwordx4 v[48:51], v182, s[84:85]
	global_load_dwordx4 v[56:59], v183, s[84:85]
	global_load_dwordx4 v[60:63], v182, s[84:85] offset:512
	global_load_dwordx4 v[64:67], v183, s[84:85] offset:512
	s_lshl_b32 s94, s1, 8
	s_add_i32 s94, s94, 32
	s_lshl_b32 s94, s94, 14
	s_add_u32 s84, s16, s94
	s_addc_u32 s85, s17, 0
	global_load_dwordx4 v[170:173], v182, s[84:85]
	global_load_dwordx4 v[174:177], v183, s[84:85]
	global_load_dwordx4 v[206:209], v182, s[84:85] offset:512
	global_load_dwordx4 v[232:235], v183, s[84:85] offset:512
	v_mov_b32_dpp v224, v124 row_ror:8 row_mask:0xf bank_mask:0xf
	v_mov_b32_dpp v225, v125 row_ror:8 row_mask:0xf bank_mask:0xf
	v_mov_b32_dpp v226, v126 row_ror:8 row_mask:0xf bank_mask:0xf
	v_mov_b32_dpp v227, v127 row_ror:8 row_mask:0xf bank_mask:0xf
	v_cndmask_b32_e64 v124, v224, v128, s[90:91]
	v_cndmask_b32_e64 v125, v225, v129, s[90:91]
	v_cndmask_b32_e64 v126, v226, v130, s[90:91]
	v_cndmask_b32_e64 v127, v227, v131, s[90:91]
	v_cndmask_b32_e64 v128, v128, v224, s[90:91]
	v_cndmask_b32_e64 v129, v129, v225, s[90:91]
	v_cndmask_b32_e64 v130, v130, v226, s[90:91]
	v_cndmask_b32_e64 v131, v131, v227, s[90:91]
	v_mov_b32_dpp v224, v116 row_ror:8 row_mask:0xf bank_mask:0xf
	v_mov_b32_dpp v225, v117 row_ror:8 row_mask:0xf bank_mask:0xf
	v_mov_b32_dpp v226, v118 row_ror:8 row_mask:0xf bank_mask:0xf
	v_mov_b32_dpp v227, v119 row_ror:8 row_mask:0xf bank_mask:0xf
	v_cndmask_b32_e64 v116, v224, v120, s[90:91]
	v_cndmask_b32_e64 v117, v225, v121, s[90:91]
	v_cndmask_b32_e64 v118, v226, v122, s[90:91]
	v_cndmask_b32_e64 v119, v227, v123, s[90:91]
	v_cndmask_b32_e64 v120, v120, v224, s[90:91]
	v_cndmask_b32_e64 v121, v121, v225, s[90:91]
	v_cndmask_b32_e64 v122, v122, v226, s[90:91]
	v_cndmask_b32_e64 v123, v123, v227, s[90:91]
	s_lshl_b32 s94, s1, 8
	s_add_i32 s94, s94, 16
	s_lshl_b32 s94, s94, 14
	s_add_u32 s86, s48, s94
	s_addc_u32 s87, s49, 0
	s_lshl_b32 s94, s1, 8
	s_add_i32 s94, s94, 16
	s_lshl_b32 s94, s94, 13
	s_add_u32 s88, s12, s94
	s_addc_u32 s89, s13, 0
	s_lshl_b32 s94, s1, 8
	s_add_i32 s94, s94, 16
	s_lshl_b32 s94, s94, 8
	s_add_u32 s92, s46, s94
	s_addc_u32 s93, s47, 0
	s_waitcnt vmcnt(4)
	v_pk_add_f32 v[128:129], v[128:129], v[48:49]
	v_pk_add_f32 v[130:131], v[130:131], v[50:51]
	v_pk_add_f32 v[124:125], v[124:125], v[56:57]
	v_pk_add_f32 v[126:127], v[126:127], v[58:59]
	global_store_dwordx4 v182, v[128:131], s[86:87]
	global_store_dwordx4 v183, v[124:127], s[86:87]
	v_mul_f32_e32 v191, v128, v128
	v_fmac_f32_e32 v191, v129, v129
	v_fmac_f32_e32 v191, v130, v130
	v_fmac_f32_e32 v191, v131, v131
	v_mul_f32_e32 v192, v124, v124
	v_fmac_f32_e32 v192, v125, v125
	v_fmac_f32_e32 v192, v126, v126
	v_fmac_f32_e32 v192, v127, v127
	v_pk_mul_f32 v[224:225], v[128:129], v[148:149]
	v_pk_mul_f32 v[226:227], v[130:131], v[150:151]
	v_cvt_pk_bf16_f32 v210, v224, v225
	v_cvt_pk_bf16_f32 v211, v226, v227
	global_store_dwordx2 v184, v[210:211], s[88:89]
	v_pk_mul_f32 v[224:225], v[124:125], v[156:157]
	v_pk_mul_f32 v[226:227], v[126:127], v[158:159]
	v_cvt_pk_bf16_f32 v212, v224, v225
	v_cvt_pk_bf16_f32 v213, v226, v227
	global_store_dwordx2 v185, v[212:213], s[88:89]
	v_pk_add_f32 v[120:121], v[120:121], v[60:61]
	v_pk_add_f32 v[122:123], v[122:123], v[62:63]
	v_pk_add_f32 v[116:117], v[116:117], v[64:65]
	v_pk_add_f32 v[118:119], v[118:119], v[66:67]
	global_store_dwordx4 v182, v[120:123], s[86:87] offset:512
	global_store_dwordx4 v183, v[116:119], s[86:87] offset:512
	v_fmac_f32_e32 v191, v120, v120
	v_fmac_f32_e32 v191, v121, v121
	v_fmac_f32_e32 v191, v122, v122
	v_fmac_f32_e32 v191, v123, v123
	v_fmac_f32_e32 v192, v116, v116
	v_fmac_f32_e32 v192, v117, v117
	v_fmac_f32_e32 v192, v118, v118
	v_fmac_f32_e32 v192, v119, v119
	v_pk_mul_f32 v[224:225], v[120:121], v[152:153]
	v_pk_mul_f32 v[226:227], v[122:123], v[154:155]
	v_cvt_pk_bf16_f32 v210, v224, v225
	v_cvt_pk_bf16_f32 v211, v226, v227
	global_store_dwordx2 v184, v[210:211], s[88:89] offset:256
	v_pk_mul_f32 v[224:225], v[116:117], v[160:161]
	v_pk_mul_f32 v[226:227], v[118:119], v[162:163]
	v_cvt_pk_bf16_f32 v212, v224, v225
	v_cvt_pk_bf16_f32 v213, v226, v227
	global_store_dwordx2 v185, v[212:213], s[88:89] offset:256
	s_nop 1
	v_add_f32_dpp v193, v191, v191 row_ror:8 row_mask:0xf bank_mask:0xf
	v_add_f32_dpp v181, v192, v192 row_ror:8 row_mask:0xf bank_mask:0xf
	v_cndmask_b32_e64 v191, v193, v181, s[90:91]
	v_mov_b32_e32 v192, v191
	s_nop 1
	v_permlane16_swap_b32_e32 v191, v192
	v_add_f32_e32 v191, v191, v192
	v_mov_b32_e32 v192, v191
	s_nop 1
	v_permlane32_swap_b32_e32 v191, v192
	v_add_f32_e32 v191, v191, v192
	s_and_saveexec_b64 s[14:15], s[40:41]
	global_store_dword v188, v191, s[92:93]
	s_or_b64 exec, exec, s[14:15]
	s_lshl_b32 s94, s1, 8
	s_add_i32 s94, s94, 48
	s_lshl_b32 s94, s94, 14
	s_add_u32 s84, s16, s94
	s_addc_u32 s85, s17, 0
	global_load_dwordx4 v[128:131], v182, s[84:85]
	global_load_dwordx4 v[124:127], v183, s[84:85]
	global_load_dwordx4 v[120:123], v182, s[84:85] offset:512
	global_load_dwordx4 v[116:119], v183, s[84:85] offset:512
	v_mov_b32_dpp v224, v108 row_ror:8 row_mask:0xf bank_mask:0xf
	v_mov_b32_dpp v225, v109 row_ror:8 row_mask:0xf bank_mask:0xf
	v_mov_b32_dpp v226, v110 row_ror:8 row_mask:0xf bank_mask:0xf
	v_mov_b32_dpp v227, v111 row_ror:8 row_mask:0xf bank_mask:0xf
	v_cndmask_b32_e64 v108, v224, v112, s[90:91]
	v_cndmask_b32_e64 v109, v225, v113, s[90:91]
	v_cndmask_b32_e64 v110, v226, v114, s[90:91]
	v_cndmask_b32_e64 v111, v227, v115, s[90:91]
	v_cndmask_b32_e64 v112, v112, v224, s[90:91]
	v_cndmask_b32_e64 v113, v113, v225, s[90:91]
	v_cndmask_b32_e64 v114, v114, v226, s[90:91]
	v_cndmask_b32_e64 v115, v115, v227, s[90:91]
	v_mov_b32_dpp v224, v100 row_ror:8 row_mask:0xf bank_mask:0xf
	v_mov_b32_dpp v225, v101 row_ror:8 row_mask:0xf bank_mask:0xf
	v_mov_b32_dpp v226, v102 row_ror:8 row_mask:0xf bank_mask:0xf
	v_mov_b32_dpp v227, v103 row_ror:8 row_mask:0xf bank_mask:0xf
	v_cndmask_b32_e64 v100, v224, v104, s[90:91]
	v_cndmask_b32_e64 v101, v225, v105, s[90:91]
	v_cndmask_b32_e64 v102, v226, v106, s[90:91]
	v_cndmask_b32_e64 v103, v227, v107, s[90:91]
	v_cndmask_b32_e64 v104, v104, v224, s[90:91]
	v_cndmask_b32_e64 v105, v105, v225, s[90:91]
	v_cndmask_b32_e64 v106, v106, v226, s[90:91]
	v_cndmask_b32_e64 v107, v107, v227, s[90:91]
	s_lshl_b32 s94, s1, 8
	s_add_i32 s94, s94, 32
	s_lshl_b32 s94, s94, 14
	s_add_u32 s86, s48, s94
	s_addc_u32 s87, s49, 0
	s_lshl_b32 s94, s1, 8
	s_add_i32 s94, s94, 32
	s_lshl_b32 s94, s94, 13
	s_add_u32 s88, s12, s94
	s_addc_u32 s89, s13, 0
	s_lshl_b32 s94, s1, 8
	s_add_i32 s94, s94, 32
	s_lshl_b32 s94, s94, 8
	s_add_u32 s92, s46, s94
	s_addc_u32 s93, s47, 0
	s_waitcnt vmcnt(13)
	v_pk_add_f32 v[112:113], v[112:113], v[170:171]
	v_pk_add_f32 v[114:115], v[114:115], v[172:173]
	v_pk_add_f32 v[108:109], v[108:109], v[174:175]
	v_pk_add_f32 v[110:111], v[110:111], v[176:177]
	global_store_dwordx4 v182, v[112:115], s[86:87]
	global_store_dwordx4 v183, v[108:111], s[86:87]
	v_mul_f32_e32 v191, v112, v112
	v_fmac_f32_e32 v191, v113, v113
	v_fmac_f32_e32 v191, v114, v114
	v_fmac_f32_e32 v191, v115, v115
	v_mul_f32_e32 v192, v108, v108
	v_fmac_f32_e32 v192, v109, v109
	v_fmac_f32_e32 v192, v110, v110
	v_fmac_f32_e32 v192, v111, v111
	v_pk_mul_f32 v[224:225], v[112:113], v[148:149]
	v_pk_mul_f32 v[226:227], v[114:115], v[150:151]
	v_cvt_pk_bf16_f32 v210, v224, v225
	v_cvt_pk_bf16_f32 v211, v226, v227
	global_store_dwordx2 v184, v[210:211], s[88:89]
	v_pk_mul_f32 v[224:225], v[108:109], v[156:157]
	v_pk_mul_f32 v[226:227], v[110:111], v[158:159]
	v_cvt_pk_bf16_f32 v212, v224, v225
	v_cvt_pk_bf16_f32 v213, v226, v227
	global_store_dwordx2 v185, v[212:213], s[88:89]
	v_pk_add_f32 v[104:105], v[104:105], v[206:207]
	v_pk_add_f32 v[106:107], v[106:107], v[208:209]
	v_pk_add_f32 v[100:101], v[100:101], v[232:233]
	v_pk_add_f32 v[102:103], v[102:103], v[234:235]
	global_store_dwordx4 v182, v[104:107], s[86:87] offset:512
	global_store_dwordx4 v183, v[100:103], s[86:87] offset:512
	v_fmac_f32_e32 v191, v104, v104
	v_fmac_f32_e32 v191, v105, v105
	v_fmac_f32_e32 v191, v106, v106
	v_fmac_f32_e32 v191, v107, v107
	v_fmac_f32_e32 v192, v100, v100
	v_fmac_f32_e32 v192, v101, v101
	v_fmac_f32_e32 v192, v102, v102
	v_fmac_f32_e32 v192, v103, v103
	v_pk_mul_f32 v[224:225], v[104:105], v[152:153]
	v_pk_mul_f32 v[226:227], v[106:107], v[154:155]
	v_cvt_pk_bf16_f32 v210, v224, v225
	v_cvt_pk_bf16_f32 v211, v226, v227
	global_store_dwordx2 v184, v[210:211], s[88:89] offset:256
	v_pk_mul_f32 v[224:225], v[100:101], v[160:161]
	v_pk_mul_f32 v[226:227], v[102:103], v[162:163]
	v_cvt_pk_bf16_f32 v212, v224, v225
	v_cvt_pk_bf16_f32 v213, v226, v227
	global_store_dwordx2 v185, v[212:213], s[88:89] offset:256
	s_nop 1
	v_add_f32_dpp v193, v191, v191 row_ror:8 row_mask:0xf bank_mask:0xf
	v_add_f32_dpp v181, v192, v192 row_ror:8 row_mask:0xf bank_mask:0xf
	v_cndmask_b32_e64 v191, v193, v181, s[90:91]
	v_mov_b32_e32 v192, v191
	s_nop 1
	v_permlane16_swap_b32_e32 v191, v192
	v_add_f32_e32 v191, v191, v192
	v_mov_b32_e32 v192, v191
	s_nop 1
	v_permlane32_swap_b32_e32 v191, v192
	v_add_f32_e32 v191, v191, v192
	s_and_saveexec_b64 s[14:15], s[40:41]
	global_store_dword v188, v191, s[92:93]
	s_or_b64 exec, exec, s[14:15]
	s_lshl_b32 s94, s1, 8
	s_lshl_b32 s94, s94, 14
	s_add_u32 s84, s16, s94
	s_addc_u32 s85, s17, 0
	global_load_dwordx4 v[112:115], v182, s[84:85]
	global_load_dwordx4 v[108:111], v183, s[84:85]
	global_load_dwordx4 v[104:107], v182, s[84:85] offset:512
	global_load_dwordx4 v[100:103], v183, s[84:85] offset:512
	v_mov_b32_dpp v224, v92 row_ror:8 row_mask:0xf bank_mask:0xf
	v_mov_b32_dpp v225, v93 row_ror:8 row_mask:0xf bank_mask:0xf
	v_mov_b32_dpp v226, v94 row_ror:8 row_mask:0xf bank_mask:0xf
	v_mov_b32_dpp v227, v95 row_ror:8 row_mask:0xf bank_mask:0xf
	v_cndmask_b32_e64 v92, v224, v96, s[90:91]
	v_cndmask_b32_e64 v93, v225, v97, s[90:91]
	v_cndmask_b32_e64 v94, v226, v98, s[90:91]
	v_cndmask_b32_e64 v95, v227, v99, s[90:91]
	v_cndmask_b32_e64 v96, v96, v224, s[90:91]
	v_cndmask_b32_e64 v97, v97, v225, s[90:91]
	v_cndmask_b32_e64 v98, v98, v226, s[90:91]
	v_cndmask_b32_e64 v99, v99, v227, s[90:91]
	v_mov_b32_dpp v224, v84 row_ror:8 row_mask:0xf bank_mask:0xf
	v_mov_b32_dpp v225, v85 row_ror:8 row_mask:0xf bank_mask:0xf
	v_mov_b32_dpp v226, v86 row_ror:8 row_mask:0xf bank_mask:0xf
	v_mov_b32_dpp v227, v87 row_ror:8 row_mask:0xf bank_mask:0xf
	v_cndmask_b32_e64 v84, v224, v88, s[90:91]
	v_cndmask_b32_e64 v85, v225, v89, s[90:91]
	v_cndmask_b32_e64 v86, v226, v90, s[90:91]
	v_cndmask_b32_e64 v87, v227, v91, s[90:91]
	v_cndmask_b32_e64 v88, v88, v224, s[90:91]
	v_cndmask_b32_e64 v89, v89, v225, s[90:91]
	v_cndmask_b32_e64 v90, v90, v226, s[90:91]
	v_cndmask_b32_e64 v91, v91, v227, s[90:91]
	s_lshl_b32 s94, s1, 8
	s_add_i32 s94, s94, 48
	s_lshl_b32 s94, s94, 14
	s_add_u32 s86, s48, s94
	s_addc_u32 s87, s49, 0
	s_lshl_b32 s94, s1, 8
	s_add_i32 s94, s94, 48
	s_lshl_b32 s94, s94, 13
	s_add_u32 s88, s12, s94
	s_addc_u32 s89, s13, 0
	s_lshl_b32 s94, s1, 8
	s_add_i32 s94, s94, 48
	s_lshl_b32 s94, s94, 8
	s_add_u32 s92, s46, s94
	s_addc_u32 s93, s47, 0
	s_waitcnt vmcnt(13)
	v_pk_add_f32 v[96:97], v[96:97], v[128:129]
	v_pk_add_f32 v[98:99], v[98:99], v[130:131]
	v_pk_add_f32 v[92:93], v[92:93], v[124:125]
	v_pk_add_f32 v[94:95], v[94:95], v[126:127]
	global_store_dwordx4 v182, v[96:99], s[86:87]
	global_store_dwordx4 v183, v[92:95], s[86:87]
	v_mul_f32_e32 v191, v96, v96
	v_fmac_f32_e32 v191, v97, v97
	v_fmac_f32_e32 v191, v98, v98
	v_fmac_f32_e32 v191, v99, v99
	v_mul_f32_e32 v192, v92, v92
	v_fmac_f32_e32 v192, v93, v93
	v_fmac_f32_e32 v192, v94, v94
	v_fmac_f32_e32 v192, v95, v95
	v_pk_mul_f32 v[224:225], v[96:97], v[148:149]
	v_pk_mul_f32 v[226:227], v[98:99], v[150:151]
	v_cvt_pk_bf16_f32 v210, v224, v225
	v_cvt_pk_bf16_f32 v211, v226, v227
	global_store_dwordx2 v184, v[210:211], s[88:89]
	v_pk_mul_f32 v[224:225], v[92:93], v[156:157]
	v_pk_mul_f32 v[226:227], v[94:95], v[158:159]
	v_cvt_pk_bf16_f32 v212, v224, v225
	v_cvt_pk_bf16_f32 v213, v226, v227
	global_store_dwordx2 v185, v[212:213], s[88:89]
	v_pk_add_f32 v[88:89], v[88:89], v[120:121]
	v_pk_add_f32 v[90:91], v[90:91], v[122:123]
	v_pk_add_f32 v[84:85], v[84:85], v[116:117]
	v_pk_add_f32 v[86:87], v[86:87], v[118:119]
	global_store_dwordx4 v182, v[88:91], s[86:87] offset:512
	global_store_dwordx4 v183, v[84:87], s[86:87] offset:512
	v_fmac_f32_e32 v191, v88, v88
	v_fmac_f32_e32 v191, v89, v89
	v_fmac_f32_e32 v191, v90, v90
	v_fmac_f32_e32 v191, v91, v91
	v_fmac_f32_e32 v192, v84, v84
	v_fmac_f32_e32 v192, v85, v85
	v_fmac_f32_e32 v192, v86, v86
	v_fmac_f32_e32 v192, v87, v87
	v_pk_mul_f32 v[224:225], v[88:89], v[152:153]
	v_pk_mul_f32 v[226:227], v[90:91], v[154:155]
	v_cvt_pk_bf16_f32 v210, v224, v225
	v_cvt_pk_bf16_f32 v211, v226, v227
	global_store_dwordx2 v184, v[210:211], s[88:89] offset:256
	v_pk_mul_f32 v[224:225], v[84:85], v[160:161]
	v_pk_mul_f32 v[226:227], v[86:87], v[162:163]
	v_cvt_pk_bf16_f32 v212, v224, v225
	v_cvt_pk_bf16_f32 v213, v226, v227
	global_store_dwordx2 v185, v[212:213], s[88:89] offset:256
	s_nop 1
	v_add_f32_dpp v193, v191, v191 row_ror:8 row_mask:0xf bank_mask:0xf
	v_add_f32_dpp v181, v192, v192 row_ror:8 row_mask:0xf bank_mask:0xf
	v_cndmask_b32_e64 v191, v193, v181, s[90:91]
	v_mov_b32_e32 v192, v191
	s_nop 1
	v_permlane16_swap_b32_e32 v191, v192
	v_add_f32_e32 v191, v191, v192
	v_mov_b32_e32 v192, v191
	s_nop 1
	v_permlane32_swap_b32_e32 v191, v192
	v_add_f32_e32 v191, v191, v192
	s_and_saveexec_b64 s[14:15], s[40:41]
	global_store_dword v188, v191, s[92:93]
	s_or_b64 exec, exec, s[14:15]
	s_lshl_b32 s94, s1, 8
	s_add_i32 s94, s94, 144
	s_lshl_b32 s94, s94, 14
	s_add_u32 s84, s16, s94
	s_addc_u32 s85, s17, 0
	global_load_dwordx4 v[96:99], v182, s[84:85]
	global_load_dwordx4 v[92:95], v183, s[84:85]
	global_load_dwordx4 v[88:91], v182, s[84:85] offset:512
	global_load_dwordx4 v[84:87], v183, s[84:85] offset:512
	v_mov_b32_dpp v224, v140 row_ror:8 row_mask:0xf bank_mask:0xf
	v_mov_b32_dpp v225, v141 row_ror:8 row_mask:0xf bank_mask:0xf
	v_mov_b32_dpp v226, v142 row_ror:8 row_mask:0xf bank_mask:0xf
	v_mov_b32_dpp v227, v143 row_ror:8 row_mask:0xf bank_mask:0xf
	v_cndmask_b32_e64 v140, v224, v144, s[90:91]
	v_cndmask_b32_e64 v141, v225, v145, s[90:91]
	v_cndmask_b32_e64 v142, v226, v146, s[90:91]
	v_cndmask_b32_e64 v143, v227, v147, s[90:91]
	v_cndmask_b32_e64 v144, v144, v224, s[90:91]
	v_cndmask_b32_e64 v145, v145, v225, s[90:91]
	v_cndmask_b32_e64 v146, v146, v226, s[90:91]
	v_cndmask_b32_e64 v147, v147, v227, s[90:91]
	v_mov_b32_dpp v224, v132 row_ror:8 row_mask:0xf bank_mask:0xf
	v_mov_b32_dpp v225, v133 row_ror:8 row_mask:0xf bank_mask:0xf
	v_mov_b32_dpp v226, v134 row_ror:8 row_mask:0xf bank_mask:0xf
	v_mov_b32_dpp v227, v135 row_ror:8 row_mask:0xf bank_mask:0xf
	v_cndmask_b32_e64 v132, v224, v136, s[90:91]
	v_cndmask_b32_e64 v133, v225, v137, s[90:91]
	v_cndmask_b32_e64 v134, v226, v138, s[90:91]
	v_cndmask_b32_e64 v135, v227, v139, s[90:91]
	v_cndmask_b32_e64 v136, v136, v224, s[90:91]
	v_cndmask_b32_e64 v137, v137, v225, s[90:91]
	v_cndmask_b32_e64 v138, v138, v226, s[90:91]
	v_cndmask_b32_e64 v139, v139, v227, s[90:91]
	s_lshl_b32 s94, s1, 8
	s_lshl_b32 s94, s94, 14
	s_add_u32 s86, s48, s94
	s_addc_u32 s87, s49, 0
	s_lshl_b32 s94, s1, 8
	s_lshl_b32 s94, s94, 13
	s_add_u32 s88, s12, s94
	s_addc_u32 s89, s13, 0
	s_lshl_b32 s94, s1, 8
	s_lshl_b32 s94, s94, 8
	s_add_u32 s92, s46, s94
	s_addc_u32 s93, s47, 0
	s_waitcnt vmcnt(13)
	v_pk_add_f32 v[144:145], v[144:145], v[112:113]
	v_pk_add_f32 v[146:147], v[146:147], v[114:115]
	v_pk_add_f32 v[140:141], v[140:141], v[108:109]
	v_pk_add_f32 v[142:143], v[142:143], v[110:111]
	global_store_dwordx4 v182, v[144:147], s[86:87]
	global_store_dwordx4 v183, v[140:143], s[86:87]
	v_mul_f32_e32 v191, v144, v144
	v_fmac_f32_e32 v191, v145, v145
	v_fmac_f32_e32 v191, v146, v146
	v_fmac_f32_e32 v191, v147, v147
	v_mul_f32_e32 v192, v140, v140
	v_fmac_f32_e32 v192, v141, v141
	v_fmac_f32_e32 v192, v142, v142
	v_fmac_f32_e32 v192, v143, v143
	v_pk_mul_f32 v[224:225], v[144:145], v[148:149]
	v_pk_mul_f32 v[226:227], v[146:147], v[150:151]
	v_cvt_pk_bf16_f32 v210, v224, v225
	v_cvt_pk_bf16_f32 v211, v226, v227
	global_store_dwordx2 v184, v[210:211], s[88:89]
	v_pk_mul_f32 v[224:225], v[140:141], v[156:157]
	v_pk_mul_f32 v[226:227], v[142:143], v[158:159]
	v_cvt_pk_bf16_f32 v212, v224, v225
	v_cvt_pk_bf16_f32 v213, v226, v227
	global_store_dwordx2 v185, v[212:213], s[88:89]
	v_pk_add_f32 v[136:137], v[136:137], v[104:105]
	v_pk_add_f32 v[138:139], v[138:139], v[106:107]
	v_pk_add_f32 v[132:133], v[132:133], v[100:101]
	v_pk_add_f32 v[134:135], v[134:135], v[102:103]
	global_store_dwordx4 v182, v[136:139], s[86:87] offset:512
	global_store_dwordx4 v183, v[132:135], s[86:87] offset:512
	v_fmac_f32_e32 v191, v136, v136
	v_fmac_f32_e32 v191, v137, v137
	v_fmac_f32_e32 v191, v138, v138
	v_fmac_f32_e32 v191, v139, v139
	v_fmac_f32_e32 v192, v132, v132
	v_fmac_f32_e32 v192, v133, v133
	v_fmac_f32_e32 v192, v134, v134
	v_fmac_f32_e32 v192, v135, v135
	v_pk_mul_f32 v[224:225], v[136:137], v[152:153]
	v_pk_mul_f32 v[226:227], v[138:139], v[154:155]
	v_cvt_pk_bf16_f32 v210, v224, v225
	v_cvt_pk_bf16_f32 v211, v226, v227
	global_store_dwordx2 v184, v[210:211], s[88:89] offset:256
	v_pk_mul_f32 v[224:225], v[132:133], v[160:161]
	v_pk_mul_f32 v[226:227], v[134:135], v[162:163]
	v_cvt_pk_bf16_f32 v212, v224, v225
	v_cvt_pk_bf16_f32 v213, v226, v227
	global_store_dwordx2 v185, v[212:213], s[88:89] offset:256
	s_nop 1
	v_add_f32_dpp v193, v191, v191 row_ror:8 row_mask:0xf bank_mask:0xf
	v_add_f32_dpp v181, v192, v192 row_ror:8 row_mask:0xf bank_mask:0xf
	v_cndmask_b32_e64 v191, v193, v181, s[90:91]
	v_mov_b32_e32 v192, v191
	s_nop 1
	v_permlane16_swap_b32_e32 v191, v192
	v_add_f32_e32 v191, v191, v192
	v_mov_b32_e32 v192, v191
	s_nop 1
	v_permlane32_swap_b32_e32 v191, v192
	v_add_f32_e32 v191, v191, v192
	s_and_saveexec_b64 s[14:15], s[40:41]
	global_store_dword v188, v191, s[92:93]
	s_or_b64 exec, exec, s[14:15]
	s_lshl_b32 s94, s1, 8
	s_add_i32 s94, s94, 160
	s_lshl_b32 s94, s94, 14
	s_add_u32 s84, s16, s94
	s_addc_u32 s85, s17, 0
	global_load_dwordx4 v[144:147], v182, s[84:85]
	global_load_dwordx4 v[140:143], v183, s[84:85]
	global_load_dwordx4 v[136:139], v182, s[84:85] offset:512
	global_load_dwordx4 v[132:135], v183, s[84:85] offset:512
	v_mov_b32_dpp v224, v44 row_ror:8 row_mask:0xf bank_mask:0xf
	v_mov_b32_dpp v225, v45 row_ror:8 row_mask:0xf bank_mask:0xf
	v_mov_b32_dpp v226, v46 row_ror:8 row_mask:0xf bank_mask:0xf
	v_mov_b32_dpp v227, v47 row_ror:8 row_mask:0xf bank_mask:0xf
	v_cndmask_b32_e64 v44, v224, v52, s[90:91]
	v_cndmask_b32_e64 v45, v225, v53, s[90:91]
	v_cndmask_b32_e64 v46, v226, v54, s[90:91]
	v_cndmask_b32_e64 v47, v227, v55, s[90:91]
	v_cndmask_b32_e64 v52, v52, v224, s[90:91]
	v_cndmask_b32_e64 v53, v53, v225, s[90:91]
	v_cndmask_b32_e64 v54, v54, v226, s[90:91]
	v_cndmask_b32_e64 v55, v55, v227, s[90:91]
	v_mov_b32_dpp v224, v36 row_ror:8 row_mask:0xf bank_mask:0xf
	v_mov_b32_dpp v225, v37 row_ror:8 row_mask:0xf bank_mask:0xf
	v_mov_b32_dpp v226, v38 row_ror:8 row_mask:0xf bank_mask:0xf
	v_mov_b32_dpp v227, v39 row_ror:8 row_mask:0xf bank_mask:0xf
	v_cndmask_b32_e64 v36, v224, v40, s[90:91]
	v_cndmask_b32_e64 v37, v225, v41, s[90:91]
	v_cndmask_b32_e64 v38, v226, v42, s[90:91]
	v_cndmask_b32_e64 v39, v227, v43, s[90:91]
	v_cndmask_b32_e64 v40, v40, v224, s[90:91]
	v_cndmask_b32_e64 v41, v41, v225, s[90:91]
	v_cndmask_b32_e64 v42, v42, v226, s[90:91]
	v_cndmask_b32_e64 v43, v43, v227, s[90:91]
	s_lshl_b32 s94, s1, 8
	s_add_i32 s94, s94, 144
	s_lshl_b32 s94, s94, 14
	s_add_u32 s86, s48, s94
	s_addc_u32 s87, s49, 0
	s_lshl_b32 s94, s1, 8
	s_add_i32 s94, s94, 144
	s_lshl_b32 s94, s94, 13
	s_add_u32 s88, s12, s94
	s_addc_u32 s89, s13, 0
	s_lshl_b32 s94, s1, 8
	s_add_i32 s94, s94, 144
	s_lshl_b32 s94, s94, 8
	s_add_u32 s92, s46, s94
	s_addc_u32 s93, s47, 0
	s_waitcnt vmcnt(13)
	v_pk_add_f32 v[52:53], v[52:53], v[96:97]
	v_pk_add_f32 v[54:55], v[54:55], v[98:99]
	v_pk_add_f32 v[44:45], v[44:45], v[92:93]
	v_pk_add_f32 v[46:47], v[46:47], v[94:95]
	global_store_dwordx4 v182, v[52:55], s[86:87]
	global_store_dwordx4 v183, v[44:47], s[86:87]
	v_mul_f32_e32 v191, v52, v52
	v_fmac_f32_e32 v191, v53, v53
	v_fmac_f32_e32 v191, v54, v54
	v_fmac_f32_e32 v191, v55, v55
	v_mul_f32_e32 v192, v44, v44
	v_fmac_f32_e32 v192, v45, v45
	v_fmac_f32_e32 v192, v46, v46
	v_fmac_f32_e32 v192, v47, v47
	v_pk_mul_f32 v[224:225], v[52:53], v[148:149]
	v_pk_mul_f32 v[226:227], v[54:55], v[150:151]
	v_cvt_pk_bf16_f32 v210, v224, v225
	v_cvt_pk_bf16_f32 v211, v226, v227
	global_store_dwordx2 v184, v[210:211], s[88:89]
	v_pk_mul_f32 v[224:225], v[44:45], v[156:157]
	v_pk_mul_f32 v[226:227], v[46:47], v[158:159]
	v_cvt_pk_bf16_f32 v212, v224, v225
	v_cvt_pk_bf16_f32 v213, v226, v227
	global_store_dwordx2 v185, v[212:213], s[88:89]
	v_pk_add_f32 v[40:41], v[40:41], v[88:89]
	v_pk_add_f32 v[42:43], v[42:43], v[90:91]
	v_pk_add_f32 v[36:37], v[36:37], v[84:85]
	v_pk_add_f32 v[38:39], v[38:39], v[86:87]
	global_store_dwordx4 v182, v[40:43], s[86:87] offset:512
	global_store_dwordx4 v183, v[36:39], s[86:87] offset:512
	v_fmac_f32_e32 v191, v40, v40
	v_fmac_f32_e32 v191, v41, v41
	v_fmac_f32_e32 v191, v42, v42
	v_fmac_f32_e32 v191, v43, v43
	v_fmac_f32_e32 v192, v36, v36
	v_fmac_f32_e32 v192, v37, v37
	v_fmac_f32_e32 v192, v38, v38
	v_fmac_f32_e32 v192, v39, v39
	v_pk_mul_f32 v[224:225], v[40:41], v[152:153]
	v_pk_mul_f32 v[226:227], v[42:43], v[154:155]
	v_cvt_pk_bf16_f32 v210, v224, v225
	v_cvt_pk_bf16_f32 v211, v226, v227
	global_store_dwordx2 v184, v[210:211], s[88:89] offset:256
	v_pk_mul_f32 v[224:225], v[36:37], v[160:161]
	v_pk_mul_f32 v[226:227], v[38:39], v[162:163]
	v_cvt_pk_bf16_f32 v212, v224, v225
	v_cvt_pk_bf16_f32 v213, v226, v227
	global_store_dwordx2 v185, v[212:213], s[88:89] offset:256
	s_nop 1
	v_add_f32_dpp v193, v191, v191 row_ror:8 row_mask:0xf bank_mask:0xf
	v_add_f32_dpp v181, v192, v192 row_ror:8 row_mask:0xf bank_mask:0xf
	v_cndmask_b32_e64 v191, v193, v181, s[90:91]
	v_mov_b32_e32 v192, v191
	s_nop 1
	v_permlane16_swap_b32_e32 v191, v192
	v_add_f32_e32 v191, v191, v192
	v_mov_b32_e32 v192, v191
	s_nop 1
	v_permlane32_swap_b32_e32 v191, v192
	v_add_f32_e32 v191, v191, v192
	s_and_saveexec_b64 s[14:15], s[40:41]
	global_store_dword v188, v191, s[92:93]
	s_or_b64 exec, exec, s[14:15]
	s_lshl_b32 s94, s1, 8
	s_add_i32 s94, s94, 176
	s_lshl_b32 s94, s94, 14
	s_add_u32 s84, s16, s94
	s_addc_u32 s85, s17, 0
	global_load_dwordx4 v[52:55], v182, s[84:85]
	global_load_dwordx4 v[44:47], v183, s[84:85]
	global_load_dwordx4 v[40:43], v182, s[84:85] offset:512
	global_load_dwordx4 v[36:39], v183, s[84:85] offset:512
	v_mov_b32_dpp v224, v28 row_ror:8 row_mask:0xf bank_mask:0xf
	v_mov_b32_dpp v225, v29 row_ror:8 row_mask:0xf bank_mask:0xf
	v_mov_b32_dpp v226, v30 row_ror:8 row_mask:0xf bank_mask:0xf
	v_mov_b32_dpp v227, v31 row_ror:8 row_mask:0xf bank_mask:0xf
	v_cndmask_b32_e64 v28, v224, v32, s[90:91]
	v_cndmask_b32_e64 v29, v225, v33, s[90:91]
	v_cndmask_b32_e64 v30, v226, v34, s[90:91]
	v_cndmask_b32_e64 v31, v227, v35, s[90:91]
	v_cndmask_b32_e64 v32, v32, v224, s[90:91]
	v_cndmask_b32_e64 v33, v33, v225, s[90:91]
	v_cndmask_b32_e64 v34, v34, v226, s[90:91]
	v_cndmask_b32_e64 v35, v35, v227, s[90:91]
	v_mov_b32_dpp v224, v20 row_ror:8 row_mask:0xf bank_mask:0xf
	v_mov_b32_dpp v225, v21 row_ror:8 row_mask:0xf bank_mask:0xf
	v_mov_b32_dpp v226, v22 row_ror:8 row_mask:0xf bank_mask:0xf
	v_mov_b32_dpp v227, v23 row_ror:8 row_mask:0xf bank_mask:0xf
	v_cndmask_b32_e64 v20, v224, v24, s[90:91]
	v_cndmask_b32_e64 v21, v225, v25, s[90:91]
	v_cndmask_b32_e64 v22, v226, v26, s[90:91]
	v_cndmask_b32_e64 v23, v227, v27, s[90:91]
	v_cndmask_b32_e64 v24, v24, v224, s[90:91]
	v_cndmask_b32_e64 v25, v25, v225, s[90:91]
	v_cndmask_b32_e64 v26, v26, v226, s[90:91]
	v_cndmask_b32_e64 v27, v27, v227, s[90:91]
	s_lshl_b32 s94, s1, 8
	s_add_i32 s94, s94, 160
	s_lshl_b32 s94, s94, 14
	s_add_u32 s86, s48, s94
	s_addc_u32 s87, s49, 0
	s_lshl_b32 s94, s1, 8
	s_add_i32 s94, s94, 160
	s_lshl_b32 s94, s94, 13
	s_add_u32 s88, s12, s94
	s_addc_u32 s89, s13, 0
	s_lshl_b32 s94, s1, 8
	s_add_i32 s94, s94, 160
	s_lshl_b32 s94, s94, 8
	s_add_u32 s92, s46, s94
	s_addc_u32 s93, s47, 0
	s_waitcnt vmcnt(13)
	v_pk_add_f32 v[32:33], v[32:33], v[144:145]
	v_pk_add_f32 v[34:35], v[34:35], v[146:147]
	v_pk_add_f32 v[28:29], v[28:29], v[140:141]
	v_pk_add_f32 v[30:31], v[30:31], v[142:143]
	global_store_dwordx4 v182, v[32:35], s[86:87]
	global_store_dwordx4 v183, v[28:31], s[86:87]
	v_mul_f32_e32 v191, v32, v32
	v_fmac_f32_e32 v191, v33, v33
	v_fmac_f32_e32 v191, v34, v34
	v_fmac_f32_e32 v191, v35, v35
	v_mul_f32_e32 v192, v28, v28
	v_fmac_f32_e32 v192, v29, v29
	v_fmac_f32_e32 v192, v30, v30
	v_fmac_f32_e32 v192, v31, v31
	v_pk_mul_f32 v[224:225], v[32:33], v[148:149]
	v_pk_mul_f32 v[226:227], v[34:35], v[150:151]
	v_cvt_pk_bf16_f32 v210, v224, v225
	v_cvt_pk_bf16_f32 v211, v226, v227
	global_store_dwordx2 v184, v[210:211], s[88:89]
	v_pk_mul_f32 v[224:225], v[28:29], v[156:157]
	v_pk_mul_f32 v[226:227], v[30:31], v[158:159]
	v_cvt_pk_bf16_f32 v212, v224, v225
	v_cvt_pk_bf16_f32 v213, v226, v227
	global_store_dwordx2 v185, v[212:213], s[88:89]
	v_pk_add_f32 v[24:25], v[24:25], v[136:137]
	v_pk_add_f32 v[26:27], v[26:27], v[138:139]
	v_pk_add_f32 v[20:21], v[20:21], v[132:133]
	v_pk_add_f32 v[22:23], v[22:23], v[134:135]
	global_store_dwordx4 v182, v[24:27], s[86:87] offset:512
	global_store_dwordx4 v183, v[20:23], s[86:87] offset:512
	v_fmac_f32_e32 v191, v24, v24
	v_fmac_f32_e32 v191, v25, v25
	v_fmac_f32_e32 v191, v26, v26
	v_fmac_f32_e32 v191, v27, v27
	v_fmac_f32_e32 v192, v20, v20
	v_fmac_f32_e32 v192, v21, v21
	v_fmac_f32_e32 v192, v22, v22
	v_fmac_f32_e32 v192, v23, v23
	v_pk_mul_f32 v[224:225], v[24:25], v[152:153]
	v_pk_mul_f32 v[226:227], v[26:27], v[154:155]
	v_cvt_pk_bf16_f32 v210, v224, v225
	v_cvt_pk_bf16_f32 v211, v226, v227
	global_store_dwordx2 v184, v[210:211], s[88:89] offset:256
	v_pk_mul_f32 v[224:225], v[20:21], v[160:161]
	v_pk_mul_f32 v[226:227], v[22:23], v[162:163]
	v_cvt_pk_bf16_f32 v212, v224, v225
	v_cvt_pk_bf16_f32 v213, v226, v227
	global_store_dwordx2 v185, v[212:213], s[88:89] offset:256
	s_nop 1
	v_add_f32_dpp v193, v191, v191 row_ror:8 row_mask:0xf bank_mask:0xf
	v_add_f32_dpp v181, v192, v192 row_ror:8 row_mask:0xf bank_mask:0xf
	v_cndmask_b32_e64 v191, v193, v181, s[90:91]
	v_mov_b32_e32 v192, v191
	s_nop 1
	v_permlane16_swap_b32_e32 v191, v192
	v_add_f32_e32 v191, v191, v192
	v_mov_b32_e32 v192, v191
	s_nop 1
	v_permlane32_swap_b32_e32 v191, v192
	v_add_f32_e32 v191, v191, v192
	s_and_saveexec_b64 s[14:15], s[40:41]
	global_store_dword v188, v191, s[92:93]
	s_or_b64 exec, exec, s[14:15]
	s_lshl_b32 s94, s1, 8
	s_add_i32 s94, s94, 128
	s_lshl_b32 s94, s94, 14
	s_add_u32 s84, s16, s94
	s_addc_u32 s85, s17, 0
	global_load_dwordx4 v[32:35], v182, s[84:85]
	global_load_dwordx4 v[28:31], v183, s[84:85]
	global_load_dwordx4 v[24:27], v182, s[84:85] offset:512
	global_load_dwordx4 v[20:23], v183, s[84:85] offset:512
	v_mov_b32_dpp v224, v12 row_ror:8 row_mask:0xf bank_mask:0xf
	v_mov_b32_dpp v225, v13 row_ror:8 row_mask:0xf bank_mask:0xf
	v_mov_b32_dpp v226, v14 row_ror:8 row_mask:0xf bank_mask:0xf
	v_mov_b32_dpp v227, v15 row_ror:8 row_mask:0xf bank_mask:0xf
	v_cndmask_b32_e64 v12, v224, v16, s[90:91]
	v_cndmask_b32_e64 v13, v225, v17, s[90:91]
	v_cndmask_b32_e64 v14, v226, v18, s[90:91]
	v_cndmask_b32_e64 v15, v227, v19, s[90:91]
	v_cndmask_b32_e64 v16, v16, v224, s[90:91]
	v_cndmask_b32_e64 v17, v17, v225, s[90:91]
	v_cndmask_b32_e64 v18, v18, v226, s[90:91]
	v_cndmask_b32_e64 v19, v19, v227, s[90:91]
	v_mov_b32_dpp v224, v4 row_ror:8 row_mask:0xf bank_mask:0xf
	v_mov_b32_dpp v225, v5 row_ror:8 row_mask:0xf bank_mask:0xf
	v_mov_b32_dpp v226, v6 row_ror:8 row_mask:0xf bank_mask:0xf
	v_mov_b32_dpp v227, v7 row_ror:8 row_mask:0xf bank_mask:0xf
	v_cndmask_b32_e64 v4, v224, v8, s[90:91]
	v_cndmask_b32_e64 v5, v225, v9, s[90:91]
	v_cndmask_b32_e64 v6, v226, v10, s[90:91]
	v_cndmask_b32_e64 v7, v227, v11, s[90:91]
	v_cndmask_b32_e64 v8, v8, v224, s[90:91]
	v_cndmask_b32_e64 v9, v9, v225, s[90:91]
	v_cndmask_b32_e64 v10, v10, v226, s[90:91]
	v_cndmask_b32_e64 v11, v11, v227, s[90:91]
	s_lshl_b32 s94, s1, 8
	s_add_i32 s94, s94, 176
	s_lshl_b32 s94, s94, 14
	s_add_u32 s86, s48, s94
	s_addc_u32 s87, s49, 0
	s_lshl_b32 s94, s1, 8
	s_add_i32 s94, s94, 176
	s_lshl_b32 s94, s94, 13
	s_add_u32 s88, s12, s94
	s_addc_u32 s89, s13, 0
	s_lshl_b32 s94, s1, 8
	s_add_i32 s94, s94, 176
	s_lshl_b32 s94, s94, 8
	s_add_u32 s92, s46, s94
	s_addc_u32 s93, s47, 0
	s_waitcnt vmcnt(13)
	v_pk_add_f32 v[16:17], v[16:17], v[52:53]
	v_pk_add_f32 v[18:19], v[18:19], v[54:55]
	v_pk_add_f32 v[12:13], v[12:13], v[44:45]
	v_pk_add_f32 v[14:15], v[14:15], v[46:47]
	global_store_dwordx4 v182, v[16:19], s[86:87]
	global_store_dwordx4 v183, v[12:15], s[86:87]
	v_mul_f32_e32 v191, v16, v16
	v_fmac_f32_e32 v191, v17, v17
	v_fmac_f32_e32 v191, v18, v18
	v_fmac_f32_e32 v191, v19, v19
	v_mul_f32_e32 v192, v12, v12
	v_fmac_f32_e32 v192, v13, v13
	v_fmac_f32_e32 v192, v14, v14
	v_fmac_f32_e32 v192, v15, v15
	v_pk_mul_f32 v[224:225], v[16:17], v[148:149]
	v_pk_mul_f32 v[226:227], v[18:19], v[150:151]
	v_cvt_pk_bf16_f32 v210, v224, v225
	v_cvt_pk_bf16_f32 v211, v226, v227
	global_store_dwordx2 v184, v[210:211], s[88:89]
	v_pk_mul_f32 v[224:225], v[12:13], v[156:157]
	v_pk_mul_f32 v[226:227], v[14:15], v[158:159]
	v_cvt_pk_bf16_f32 v212, v224, v225
	v_cvt_pk_bf16_f32 v213, v226, v227
	global_store_dwordx2 v185, v[212:213], s[88:89]
	v_pk_add_f32 v[8:9], v[8:9], v[40:41]
	v_pk_add_f32 v[10:11], v[10:11], v[42:43]
	v_pk_add_f32 v[4:5], v[4:5], v[36:37]
	v_pk_add_f32 v[6:7], v[6:7], v[38:39]
	global_store_dwordx4 v182, v[8:11], s[86:87] offset:512
	global_store_dwordx4 v183, v[4:7], s[86:87] offset:512
	v_fmac_f32_e32 v191, v8, v8
	v_fmac_f32_e32 v191, v9, v9
	v_fmac_f32_e32 v191, v10, v10
	v_fmac_f32_e32 v191, v11, v11
	v_fmac_f32_e32 v192, v4, v4
	v_fmac_f32_e32 v192, v5, v5
	v_fmac_f32_e32 v192, v6, v6
	v_fmac_f32_e32 v192, v7, v7
	v_pk_mul_f32 v[224:225], v[8:9], v[152:153]
	v_pk_mul_f32 v[226:227], v[10:11], v[154:155]
	v_cvt_pk_bf16_f32 v210, v224, v225
	v_cvt_pk_bf16_f32 v211, v226, v227
	global_store_dwordx2 v184, v[210:211], s[88:89] offset:256
	v_pk_mul_f32 v[224:225], v[4:5], v[160:161]
	v_pk_mul_f32 v[226:227], v[6:7], v[162:163]
	v_cvt_pk_bf16_f32 v212, v224, v225
	v_cvt_pk_bf16_f32 v213, v226, v227
	global_store_dwordx2 v185, v[212:213], s[88:89] offset:256
	s_nop 1
	v_add_f32_dpp v193, v191, v191 row_ror:8 row_mask:0xf bank_mask:0xf
	v_add_f32_dpp v181, v192, v192 row_ror:8 row_mask:0xf bank_mask:0xf
	v_cndmask_b32_e64 v191, v193, v181, s[90:91]
	v_mov_b32_e32 v192, v191
	s_nop 1
	v_permlane16_swap_b32_e32 v191, v192
	v_add_f32_e32 v191, v191, v192
	v_mov_b32_e32 v192, v191
	s_nop 1
	v_permlane32_swap_b32_e32 v191, v192
	v_add_f32_e32 v191, v191, v192
	s_and_saveexec_b64 s[14:15], s[40:41]
	global_store_dword v188, v191, s[92:93]
	s_or_b64 exec, exec, s[14:15]
	v_mov_b32_dpp v224, v76 row_ror:8 row_mask:0xf bank_mask:0xf
	v_mov_b32_dpp v225, v77 row_ror:8 row_mask:0xf bank_mask:0xf
	v_mov_b32_dpp v226, v78 row_ror:8 row_mask:0xf bank_mask:0xf
	v_mov_b32_dpp v227, v79 row_ror:8 row_mask:0xf bank_mask:0xf
	v_cndmask_b32_e64 v76, v224, v80, s[90:91]
	v_cndmask_b32_e64 v77, v225, v81, s[90:91]
	v_cndmask_b32_e64 v78, v226, v82, s[90:91]
	v_cndmask_b32_e64 v79, v227, v83, s[90:91]
	v_cndmask_b32_e64 v80, v80, v224, s[90:91]
	v_cndmask_b32_e64 v81, v81, v225, s[90:91]
	v_cndmask_b32_e64 v82, v82, v226, s[90:91]
	v_cndmask_b32_e64 v83, v83, v227, s[90:91]
	v_mov_b32_dpp v224, v68 row_ror:8 row_mask:0xf bank_mask:0xf
	v_mov_b32_dpp v225, v69 row_ror:8 row_mask:0xf bank_mask:0xf
	v_mov_b32_dpp v226, v70 row_ror:8 row_mask:0xf bank_mask:0xf
	v_mov_b32_dpp v227, v71 row_ror:8 row_mask:0xf bank_mask:0xf
	v_cndmask_b32_e64 v68, v224, v72, s[90:91]
	v_cndmask_b32_e64 v69, v225, v73, s[90:91]
	v_cndmask_b32_e64 v70, v226, v74, s[90:91]
	v_cndmask_b32_e64 v71, v227, v75, s[90:91]
	v_cndmask_b32_e64 v72, v72, v224, s[90:91]
	v_cndmask_b32_e64 v73, v73, v225, s[90:91]
	v_cndmask_b32_e64 v74, v74, v226, s[90:91]
	v_cndmask_b32_e64 v75, v75, v227, s[90:91]
	s_lshl_b32 s94, s1, 8
	s_add_i32 s94, s94, 128
	s_lshl_b32 s94, s94, 14
	s_add_u32 s86, s48, s94
	s_addc_u32 s87, s49, 0
	s_lshl_b32 s94, s1, 8
	s_add_i32 s94, s94, 128
	s_lshl_b32 s94, s94, 13
	s_add_u32 s88, s12, s94
	s_addc_u32 s89, s13, 0
	s_lshl_b32 s94, s1, 8
	s_add_i32 s94, s94, 128
	s_lshl_b32 s94, s94, 8
	s_add_u32 s92, s46, s94
	s_addc_u32 s93, s47, 0
	s_waitcnt vmcnt(9)
	v_pk_add_f32 v[80:81], v[80:81], v[32:33]
	v_pk_add_f32 v[82:83], v[82:83], v[34:35]
	v_pk_add_f32 v[76:77], v[76:77], v[28:29]
	v_pk_add_f32 v[78:79], v[78:79], v[30:31]
	global_store_dwordx4 v182, v[80:83], s[86:87]
	global_store_dwordx4 v183, v[76:79], s[86:87]
	v_mul_f32_e32 v191, v80, v80
	v_fmac_f32_e32 v191, v81, v81
	v_fmac_f32_e32 v191, v82, v82
	v_fmac_f32_e32 v191, v83, v83
	v_mul_f32_e32 v192, v76, v76
	v_fmac_f32_e32 v192, v77, v77
	v_fmac_f32_e32 v192, v78, v78
	v_fmac_f32_e32 v192, v79, v79
	v_pk_mul_f32 v[224:225], v[80:81], v[148:149]
	v_pk_mul_f32 v[226:227], v[82:83], v[150:151]
	v_cvt_pk_bf16_f32 v210, v224, v225
	v_cvt_pk_bf16_f32 v211, v226, v227
	global_store_dwordx2 v184, v[210:211], s[88:89]
	v_pk_mul_f32 v[224:225], v[76:77], v[156:157]
	v_pk_mul_f32 v[226:227], v[78:79], v[158:159]
	v_cvt_pk_bf16_f32 v212, v224, v225
	v_cvt_pk_bf16_f32 v213, v226, v227
	global_store_dwordx2 v185, v[212:213], s[88:89]
	v_pk_add_f32 v[72:73], v[72:73], v[24:25]
	v_pk_add_f32 v[74:75], v[74:75], v[26:27]
	v_pk_add_f32 v[68:69], v[68:69], v[20:21]
	v_pk_add_f32 v[70:71], v[70:71], v[22:23]
	global_store_dwordx4 v182, v[72:75], s[86:87] offset:512
	global_store_dwordx4 v183, v[68:71], s[86:87] offset:512
	v_fmac_f32_e32 v191, v72, v72
	v_fmac_f32_e32 v191, v73, v73
	v_fmac_f32_e32 v191, v74, v74
	v_fmac_f32_e32 v191, v75, v75
	v_fmac_f32_e32 v192, v68, v68
	v_fmac_f32_e32 v192, v69, v69
	v_fmac_f32_e32 v192, v70, v70
	v_fmac_f32_e32 v192, v71, v71
	v_pk_mul_f32 v[224:225], v[72:73], v[152:153]
	v_pk_mul_f32 v[226:227], v[74:75], v[154:155]
	v_cvt_pk_bf16_f32 v210, v224, v225
	v_cvt_pk_bf16_f32 v211, v226, v227
	global_store_dwordx2 v184, v[210:211], s[88:89] offset:256
	v_pk_mul_f32 v[224:225], v[68:69], v[160:161]
	v_pk_mul_f32 v[226:227], v[70:71], v[162:163]
	v_cvt_pk_bf16_f32 v212, v224, v225
	v_cvt_pk_bf16_f32 v213, v226, v227
	global_store_dwordx2 v185, v[212:213], s[88:89] offset:256
	s_nop 1
	v_add_f32_dpp v193, v191, v191 row_ror:8 row_mask:0xf bank_mask:0xf
	v_add_f32_dpp v181, v192, v192 row_ror:8 row_mask:0xf bank_mask:0xf
	v_cndmask_b32_e64 v191, v193, v181, s[90:91]
	v_mov_b32_e32 v192, v191
	s_nop 1
	v_permlane16_swap_b32_e32 v191, v192
	v_add_f32_e32 v191, v191, v192
	v_mov_b32_e32 v192, v191
	s_nop 1
	v_permlane32_swap_b32_e32 v191, v192
	v_add_f32_e32 v191, v191, v192
	s_and_saveexec_b64 s[14:15], s[40:41]
	global_store_dword v188, v191, s[92:93]
	s_or_b64 exec, exec, s[14:15]
	s_branch .Lrot_p5_end
.Lrot_p5_2:
	v_and_b32_e32 v181, 8, v219
	v_cmp_ne_u32_e64 s[90:91], 0, v181
	v_sub_u32_e32 v191, v1, v181
	v_lshlrev_b32_e32 v181, 1, v181
	s_lshl_b32 s94, s0, 8
	v_add3_u32 v192, v179, v181, s94
	v_sub_u32_e32 v193, v179, v181
	v_add3_u32 v193, v193, 16, s94
	v_lshlrev_b32_e32 v182, 14, v191
	v_lshl_add_u32 v183, v193, 2, v182
	v_add_u32_e32 v183, 0x20000, v183
	v_lshl_add_u32 v182, v192, 2, v182
	v_lshlrev_b32_e32 v184, 13, v191
	v_lshl_add_u32 v185, v193, 1, v184
	v_add_u32_e32 v185, 0x10000, v185
	v_lshl_add_u32 v184, v192, 1, v184
	v_lshlrev_b32_e32 v186, 2, v192
	v_lshlrev_b32_e32 v187, 2, v193
	global_load_dwordx4 v[148:151], v186, s[44:45]
	global_load_dwordx4 v[156:159], v187, s[44:45]
	global_load_dwordx4 v[152:155], v186, s[44:45] offset:512
	global_load_dwordx4 v[160:163], v187, s[44:45] offset:512
	s_lshl_b32 s94, s0, 4
	s_lshl_b32 s95, s64, 2
	s_add_i32 s94, s94, s95
	v_lshlrev_b32_e32 v188, 8, v1
	v_add_u32_e32 v188, s94, v188
	v_xor_b32_e32 v189, 16, v219
	v_lshlrev_b32_e32 v189, 2, v189
	v_xor_b32_e32 v190, 32, v219
	v_lshlrev_b32_e32 v190, 2, v190
	s_lshl_b32 s94, s1, 8
	s_add_i32 s94, s94, 32
	s_lshl_b32 s94, s94, 14
	s_add_u32 s84, s16, s94
	s_addc_u32 s85, s17, 0
	global_load_dwordx4 v[48:51], v182, s[84:85]
	global_load_dwordx4 v[56:59], v183, s[84:85]
	global_load_dwordx4 v[60:63], v182, s[84:85] offset:512
	global_load_dwordx4 v[64:67], v183, s[84:85] offset:512
	s_lshl_b32 s94, s1, 8
	s_add_i32 s94, s94, 48
	s_lshl_b32 s94, s94, 14
	s_add_u32 s84, s16, s94
	s_addc_u32 s85, s17, 0
	global_load_dwordx4 v[170:173], v182, s[84:85]
	global_load_dwordx4 v[174:177], v183, s[84:85]
	global_load_dwordx4 v[206:209], v182, s[84:85] offset:512
	global_load_dwordx4 v[232:235], v183, s[84:85] offset:512
	v_mov_b32_dpp v224, v108 row_ror:8 row_mask:0xf bank_mask:0xf
	v_mov_b32_dpp v225, v109 row_ror:8 row_mask:0xf bank_mask:0xf
	v_mov_b32_dpp v226, v110 row_ror:8 row_mask:0xf bank_mask:0xf
	v_mov_b32_dpp v227, v111 row_ror:8 row_mask:0xf bank_mask:0xf
	v_cndmask_b32_e64 v108, v224, v112, s[90:91]
	v_cndmask_b32_e64 v109, v225, v113, s[90:91]
	v_cndmask_b32_e64 v110, v226, v114, s[90:91]
	v_cndmask_b32_e64 v111, v227, v115, s[90:91]
	v_cndmask_b32_e64 v112, v112, v224, s[90:91]
	v_cndmask_b32_e64 v113, v113, v225, s[90:91]
	v_cndmask_b32_e64 v114, v114, v226, s[90:91]
	v_cndmask_b32_e64 v115, v115, v227, s[90:91]
	v_mov_b32_dpp v224, v100 row_ror:8 row_mask:0xf bank_mask:0xf
	v_mov_b32_dpp v225, v101 row_ror:8 row_mask:0xf bank_mask:0xf
	v_mov_b32_dpp v226, v102 row_ror:8 row_mask:0xf bank_mask:0xf
	v_mov_b32_dpp v227, v103 row_ror:8 row_mask:0xf bank_mask:0xf
	v_cndmask_b32_e64 v100, v224, v104, s[90:91]
	v_cndmask_b32_e64 v101, v225, v105, s[90:91]
	v_cndmask_b32_e64 v102, v226, v106, s[90:91]
	v_cndmask_b32_e64 v103, v227, v107, s[90:91]
	v_cndmask_b32_e64 v104, v104, v224, s[90:91]
	v_cndmask_b32_e64 v105, v105, v225, s[90:91]
	v_cndmask_b32_e64 v106, v106, v226, s[90:91]
	v_cndmask_b32_e64 v107, v107, v227, s[90:91]
	s_lshl_b32 s94, s1, 8
	s_add_i32 s94, s94, 32
	s_lshl_b32 s94, s94, 14
	s_add_u32 s86, s48, s94
	s_addc_u32 s87, s49, 0
	s_lshl_b32 s94, s1, 8
	s_add_i32 s94, s94, 32
	s_lshl_b32 s94, s94, 13
	s_add_u32 s88, s12, s94
	s_addc_u32 s89, s13, 0
	s_lshl_b32 s94, s1, 8
	s_add_i32 s94, s94, 32
	s_lshl_b32 s94, s94, 8
	s_add_u32 s92, s46, s94
	s_addc_u32 s93, s47, 0
	s_waitcnt vmcnt(4)
	v_pk_add_f32 v[112:113], v[112:113], v[48:49]
	v_pk_add_f32 v[114:115], v[114:115], v[50:51]
	v_pk_add_f32 v[108:109], v[108:109], v[56:57]
	v_pk_add_f32 v[110:111], v[110:111], v[58:59]
	global_store_dwordx4 v182, v[112:115], s[86:87]
	global_store_dwordx4 v183, v[108:111], s[86:87]
	v_mul_f32_e32 v191, v112, v112
	v_fmac_f32_e32 v191, v113, v113
	v_fmac_f32_e32 v191, v114, v114
	v_fmac_f32_e32 v191, v115, v115
	v_mul_f32_e32 v192, v108, v108
	v_fmac_f32_e32 v192, v109, v109
	v_fmac_f32_e32 v192, v110, v110
	v_fmac_f32_e32 v192, v111, v111
	v_pk_mul_f32 v[224:225], v[112:113], v[148:149]
	v_pk_mul_f32 v[226:227], v[114:115], v[150:151]
	v_cvt_pk_bf16_f32 v210, v224, v225
	v_cvt_pk_bf16_f32 v211, v226, v227
	global_store_dwordx2 v184, v[210:211], s[88:89]
	v_pk_mul_f32 v[224:225], v[108:109], v[156:157]
	v_pk_mul_f32 v[226:227], v[110:111], v[158:159]
	v_cvt_pk_bf16_f32 v212, v224, v225
	v_cvt_pk_bf16_f32 v213, v226, v227
	global_store_dwordx2 v185, v[212:213], s[88:89]
	v_pk_add_f32 v[104:105], v[104:105], v[60:61]
	v_pk_add_f32 v[106:107], v[106:107], v[62:63]
	v_pk_add_f32 v[100:101], v[100:101], v[64:65]
	v_pk_add_f32 v[102:103], v[102:103], v[66:67]
	global_store_dwordx4 v182, v[104:107], s[86:87] offset:512
	global_store_dwordx4 v183, v[100:103], s[86:87] offset:512
	v_fmac_f32_e32 v191, v104, v104
	v_fmac_f32_e32 v191, v105, v105
	v_fmac_f32_e32 v191, v106, v106
	v_fmac_f32_e32 v191, v107, v107
	v_fmac_f32_e32 v192, v100, v100
	v_fmac_f32_e32 v192, v101, v101
	v_fmac_f32_e32 v192, v102, v102
	v_fmac_f32_e32 v192, v103, v103
	v_pk_mul_f32 v[224:225], v[104:105], v[152:153]
	v_pk_mul_f32 v[226:227], v[106:107], v[154:155]
	v_cvt_pk_bf16_f32 v210, v224, v225
	v_cvt_pk_bf16_f32 v211, v226, v227
	global_store_dwordx2 v184, v[210:211], s[88:89] offset:256
	v_pk_mul_f32 v[224:225], v[100:101], v[160:161]
	v_pk_mul_f32 v[226:227], v[102:103], v[162:163]
	v_cvt_pk_bf16_f32 v212, v224, v225
	v_cvt_pk_bf16_f32 v213, v226, v227
	global_store_dwordx2 v185, v[212:213], s[88:89] offset:256
	s_nop 1
	v_add_f32_dpp v193, v191, v191 row_ror:8 row_mask:0xf bank_mask:0xf
	v_add_f32_dpp v181, v192, v192 row_ror:8 row_mask:0xf bank_mask:0xf
	v_cndmask_b32_e64 v191, v193, v181, s[90:91]
	v_mov_b32_e32 v192, v191
	s_nop 1
	v_permlane16_swap_b32_e32 v191, v192
	v_add_f32_e32 v191, v191, v192
	v_mov_b32_e32 v192, v191
	s_nop 1
	v_permlane32_swap_b32_e32 v191, v192
	v_add_f32_e32 v191, v191, v192
	s_and_saveexec_b64 s[14:15], s[40:41]
	global_store_dword v188, v191, s[92:93]
	s_or_b64 exec, exec, s[14:15]
	s_lshl_b32 s94, s1, 8
	s_lshl_b32 s94, s94, 14
	s_add_u32 s84, s16, s94
	s_addc_u32 s85, s17, 0
	global_load_dwordx4 v[112:115], v182, s[84:85]
	global_load_dwordx4 v[108:111], v183, s[84:85]
	global_load_dwordx4 v[104:107], v182, s[84:85] offset:512
	global_load_dwordx4 v[100:103], v183, s[84:85] offset:512
	v_mov_b32_dpp v224, v92 row_ror:8 row_mask:0xf bank_mask:0xf
	v_mov_b32_dpp v225, v93 row_ror:8 row_mask:0xf bank_mask:0xf
	v_mov_b32_dpp v226, v94 row_ror:8 row_mask:0xf bank_mask:0xf
	v_mov_b32_dpp v227, v95 row_ror:8 row_mask:0xf bank_mask:0xf
	v_cndmask_b32_e64 v92, v224, v96, s[90:91]
	v_cndmask_b32_e64 v93, v225, v97, s[90:91]
	v_cndmask_b32_e64 v94, v226, v98, s[90:91]
	v_cndmask_b32_e64 v95, v227, v99, s[90:91]
	v_cndmask_b32_e64 v96, v96, v224, s[90:91]
	v_cndmask_b32_e64 v97, v97, v225, s[90:91]
	v_cndmask_b32_e64 v98, v98, v226, s[90:91]
	v_cndmask_b32_e64 v99, v99, v227, s[90:91]
	v_mov_b32_dpp v224, v84 row_ror:8 row_mask:0xf bank_mask:0xf
	v_mov_b32_dpp v225, v85 row_ror:8 row_mask:0xf bank_mask:0xf
	v_mov_b32_dpp v226, v86 row_ror:8 row_mask:0xf bank_mask:0xf
	v_mov_b32_dpp v227, v87 row_ror:8 row_mask:0xf bank_mask:0xf
	v_cndmask_b32_e64 v84, v224, v88, s[90:91]
	v_cndmask_b32_e64 v85, v225, v89, s[90:91]
	v_cndmask_b32_e64 v86, v226, v90, s[90:91]
	v_cndmask_b32_e64 v87, v227, v91, s[90:91]
	v_cndmask_b32_e64 v88, v88, v224, s[90:91]
	v_cndmask_b32_e64 v89, v89, v225, s[90:91]
	v_cndmask_b32_e64 v90, v90, v226, s[90:91]
	v_cndmask_b32_e64 v91, v91, v227, s[90:91]
	s_lshl_b32 s94, s1, 8
	s_add_i32 s94, s94, 48
	s_lshl_b32 s94, s94, 14
	s_add_u32 s86, s48, s94
	s_addc_u32 s87, s49, 0
	s_lshl_b32 s94, s1, 8
	s_add_i32 s94, s94, 48
	s_lshl_b32 s94, s94, 13
	s_add_u32 s88, s12, s94
	s_addc_u32 s89, s13, 0
	s_lshl_b32 s94, s1, 8
	s_add_i32 s94, s94, 48
	s_lshl_b32 s94, s94, 8
	s_add_u32 s92, s46, s94
	s_addc_u32 s93, s47, 0
	s_waitcnt vmcnt(13)
	v_pk_add_f32 v[96:97], v[96:97], v[170:171]
	v_pk_add_f32 v[98:99], v[98:99], v[172:173]
	v_pk_add_f32 v[92:93], v[92:93], v[174:175]
	v_pk_add_f32 v[94:95], v[94:95], v[176:177]
	global_store_dwordx4 v182, v[96:99], s[86:87]
	global_store_dwordx4 v183, v[92:95], s[86:87]
	v_mul_f32_e32 v191, v96, v96
	v_fmac_f32_e32 v191, v97, v97
	v_fmac_f32_e32 v191, v98, v98
	v_fmac_f32_e32 v191, v99, v99
	v_mul_f32_e32 v192, v92, v92
	v_fmac_f32_e32 v192, v93, v93
	v_fmac_f32_e32 v192, v94, v94
	v_fmac_f32_e32 v192, v95, v95
	v_pk_mul_f32 v[224:225], v[96:97], v[148:149]
	v_pk_mul_f32 v[226:227], v[98:99], v[150:151]
	v_cvt_pk_bf16_f32 v210, v224, v225
	v_cvt_pk_bf16_f32 v211, v226, v227
	global_store_dwordx2 v184, v[210:211], s[88:89]
	v_pk_mul_f32 v[224:225], v[92:93], v[156:157]
	v_pk_mul_f32 v[226:227], v[94:95], v[158:159]
	v_cvt_pk_bf16_f32 v212, v224, v225
	v_cvt_pk_bf16_f32 v213, v226, v227
	global_store_dwordx2 v185, v[212:213], s[88:89]
	v_pk_add_f32 v[88:89], v[88:89], v[206:207]
	v_pk_add_f32 v[90:91], v[90:91], v[208:209]
	v_pk_add_f32 v[84:85], v[84:85], v[232:233]
	v_pk_add_f32 v[86:87], v[86:87], v[234:235]
	global_store_dwordx4 v182, v[88:91], s[86:87] offset:512
	global_store_dwordx4 v183, v[84:87], s[86:87] offset:512
	v_fmac_f32_e32 v191, v88, v88
	v_fmac_f32_e32 v191, v89, v89
	v_fmac_f32_e32 v191, v90, v90
	v_fmac_f32_e32 v191, v91, v91
	v_fmac_f32_e32 v192, v84, v84
	v_fmac_f32_e32 v192, v85, v85
	v_fmac_f32_e32 v192, v86, v86
	v_fmac_f32_e32 v192, v87, v87
	v_pk_mul_f32 v[224:225], v[88:89], v[152:153]
	v_pk_mul_f32 v[226:227], v[90:91], v[154:155]
	v_cvt_pk_bf16_f32 v210, v224, v225
	v_cvt_pk_bf16_f32 v211, v226, v227
	global_store_dwordx2 v184, v[210:211], s[88:89] offset:256
	v_pk_mul_f32 v[224:225], v[84:85], v[160:161]
	v_pk_mul_f32 v[226:227], v[86:87], v[162:163]
	v_cvt_pk_bf16_f32 v212, v224, v225
	v_cvt_pk_bf16_f32 v213, v226, v227
	global_store_dwordx2 v185, v[212:213], s[88:89] offset:256
	s_nop 1
	v_add_f32_dpp v193, v191, v191 row_ror:8 row_mask:0xf bank_mask:0xf
	v_add_f32_dpp v181, v192, v192 row_ror:8 row_mask:0xf bank_mask:0xf
	v_cndmask_b32_e64 v191, v193, v181, s[90:91]
	v_mov_b32_e32 v192, v191
	s_nop 1
	v_permlane16_swap_b32_e32 v191, v192
	v_add_f32_e32 v191, v191, v192
	v_mov_b32_e32 v192, v191
	s_nop 1
	v_permlane32_swap_b32_e32 v191, v192
	v_add_f32_e32 v191, v191, v192
	s_and_saveexec_b64 s[14:15], s[40:41]
	global_store_dword v188, v191, s[92:93]
	s_or_b64 exec, exec, s[14:15]
	s_lshl_b32 s94, s1, 8
	s_add_i32 s94, s94, 16
	s_lshl_b32 s94, s94, 14
	s_add_u32 s84, s16, s94
	s_addc_u32 s85, s17, 0
	global_load_dwordx4 v[96:99], v182, s[84:85]
	global_load_dwordx4 v[92:95], v183, s[84:85]
	global_load_dwordx4 v[88:91], v182, s[84:85] offset:512
	global_load_dwordx4 v[84:87], v183, s[84:85] offset:512
	v_mov_b32_dpp v224, v140 row_ror:8 row_mask:0xf bank_mask:0xf
	v_mov_b32_dpp v225, v141 row_ror:8 row_mask:0xf bank_mask:0xf
	v_mov_b32_dpp v226, v142 row_ror:8 row_mask:0xf bank_mask:0xf
	v_mov_b32_dpp v227, v143 row_ror:8 row_mask:0xf bank_mask:0xf
	v_cndmask_b32_e64 v140, v224, v144, s[90:91]
	v_cndmask_b32_e64 v141, v225, v145, s[90:91]
	v_cndmask_b32_e64 v142, v226, v146, s[90:91]
	v_cndmask_b32_e64 v143, v227, v147, s[90:91]
	v_cndmask_b32_e64 v144, v144, v224, s[90:91]
	v_cndmask_b32_e64 v145, v145, v225, s[90:91]
	v_cndmask_b32_e64 v146, v146, v226, s[90:91]
	v_cndmask_b32_e64 v147, v147, v227, s[90:91]
	v_mov_b32_dpp v224, v132 row_ror:8 row_mask:0xf bank_mask:0xf
	v_mov_b32_dpp v225, v133 row_ror:8 row_mask:0xf bank_mask:0xf
	v_mov_b32_dpp v226, v134 row_ror:8 row_mask:0xf bank_mask:0xf
	v_mov_b32_dpp v227, v135 row_ror:8 row_mask:0xf bank_mask:0xf
	v_cndmask_b32_e64 v132, v224, v136, s[90:91]
	v_cndmask_b32_e64 v133, v225, v137, s[90:91]
	v_cndmask_b32_e64 v134, v226, v138, s[90:91]
	v_cndmask_b32_e64 v135, v227, v139, s[90:91]
	v_cndmask_b32_e64 v136, v136, v224, s[90:91]
	v_cndmask_b32_e64 v137, v137, v225, s[90:91]
	v_cndmask_b32_e64 v138, v138, v226, s[90:91]
	v_cndmask_b32_e64 v139, v139, v227, s[90:91]
	s_lshl_b32 s94, s1, 8
	s_lshl_b32 s94, s94, 14
	s_add_u32 s86, s48, s94
	s_addc_u32 s87, s49, 0
	s_lshl_b32 s94, s1, 8
	s_lshl_b32 s94, s94, 13
	s_add_u32 s88, s12, s94
	s_addc_u32 s89, s13, 0
	s_lshl_b32 s94, s1, 8
	s_lshl_b32 s94, s94, 8
	s_add_u32 s92, s46, s94
	s_addc_u32 s93, s47, 0
	s_waitcnt vmcnt(13)
	v_pk_add_f32 v[144:145], v[144:145], v[112:113]
	v_pk_add_f32 v[146:147], v[146:147], v[114:115]
	v_pk_add_f32 v[140:141], v[140:141], v[108:109]
	v_pk_add_f32 v[142:143], v[142:143], v[110:111]
	global_store_dwordx4 v182, v[144:147], s[86:87]
	global_store_dwordx4 v183, v[140:143], s[86:87]
	v_mul_f32_e32 v191, v144, v144
	v_fmac_f32_e32 v191, v145, v145
	v_fmac_f32_e32 v191, v146, v146
	v_fmac_f32_e32 v191, v147, v147
	v_mul_f32_e32 v192, v140, v140
	v_fmac_f32_e32 v192, v141, v141
	v_fmac_f32_e32 v192, v142, v142
	v_fmac_f32_e32 v192, v143, v143
	v_pk_mul_f32 v[224:225], v[144:145], v[148:149]
	v_pk_mul_f32 v[226:227], v[146:147], v[150:151]
	v_cvt_pk_bf16_f32 v210, v224, v225
	v_cvt_pk_bf16_f32 v211, v226, v227
	global_store_dwordx2 v184, v[210:211], s[88:89]
	v_pk_mul_f32 v[224:225], v[140:141], v[156:157]
	v_pk_mul_f32 v[226:227], v[142:143], v[158:159]
	v_cvt_pk_bf16_f32 v212, v224, v225
	v_cvt_pk_bf16_f32 v213, v226, v227
	global_store_dwordx2 v185, v[212:213], s[88:89]
	v_pk_add_f32 v[136:137], v[136:137], v[104:105]
	v_pk_add_f32 v[138:139], v[138:139], v[106:107]
	v_pk_add_f32 v[132:133], v[132:133], v[100:101]
	v_pk_add_f32 v[134:135], v[134:135], v[102:103]
	global_store_dwordx4 v182, v[136:139], s[86:87] offset:512
	global_store_dwordx4 v183, v[132:135], s[86:87] offset:512
	v_fmac_f32_e32 v191, v136, v136
	v_fmac_f32_e32 v191, v137, v137
	v_fmac_f32_e32 v191, v138, v138
	v_fmac_f32_e32 v191, v139, v139
	v_fmac_f32_e32 v192, v132, v132
	v_fmac_f32_e32 v192, v133, v133
	v_fmac_f32_e32 v192, v134, v134
	v_fmac_f32_e32 v192, v135, v135
	v_pk_mul_f32 v[224:225], v[136:137], v[152:153]
	v_pk_mul_f32 v[226:227], v[138:139], v[154:155]
	v_cvt_pk_bf16_f32 v210, v224, v225
	v_cvt_pk_bf16_f32 v211, v226, v227
	global_store_dwordx2 v184, v[210:211], s[88:89] offset:256
	v_pk_mul_f32 v[224:225], v[132:133], v[160:161]
	v_pk_mul_f32 v[226:227], v[134:135], v[162:163]
	v_cvt_pk_bf16_f32 v212, v224, v225
	v_cvt_pk_bf16_f32 v213, v226, v227
	global_store_dwordx2 v185, v[212:213], s[88:89] offset:256
	s_nop 1
	v_add_f32_dpp v193, v191, v191 row_ror:8 row_mask:0xf bank_mask:0xf
	v_add_f32_dpp v181, v192, v192 row_ror:8 row_mask:0xf bank_mask:0xf
	v_cndmask_b32_e64 v191, v193, v181, s[90:91]
	v_mov_b32_e32 v192, v191
	s_nop 1
	v_permlane16_swap_b32_e32 v191, v192
	v_add_f32_e32 v191, v191, v192
	v_mov_b32_e32 v192, v191
	s_nop 1
	v_permlane32_swap_b32_e32 v191, v192
	v_add_f32_e32 v191, v191, v192
	s_and_saveexec_b64 s[14:15], s[40:41]
	global_store_dword v188, v191, s[92:93]
	s_or_b64 exec, exec, s[14:15]
	s_lshl_b32 s94, s1, 8
	s_add_i32 s94, s94, 160
	s_lshl_b32 s94, s94, 14
	s_add_u32 s84, s16, s94
	s_addc_u32 s85, s17, 0
	global_load_dwordx4 v[144:147], v182, s[84:85]
	global_load_dwordx4 v[140:143], v183, s[84:85]
	global_load_dwordx4 v[136:139], v182, s[84:85] offset:512
	global_load_dwordx4 v[132:135], v183, s[84:85] offset:512
	v_mov_b32_dpp v224, v124 row_ror:8 row_mask:0xf bank_mask:0xf
	v_mov_b32_dpp v225, v125 row_ror:8 row_mask:0xf bank_mask:0xf
	v_mov_b32_dpp v226, v126 row_ror:8 row_mask:0xf bank_mask:0xf
	v_mov_b32_dpp v227, v127 row_ror:8 row_mask:0xf bank_mask:0xf
	v_cndmask_b32_e64 v124, v224, v128, s[90:91]
	v_cndmask_b32_e64 v125, v225, v129, s[90:91]
	v_cndmask_b32_e64 v126, v226, v130, s[90:91]
	v_cndmask_b32_e64 v127, v227, v131, s[90:91]
	v_cndmask_b32_e64 v128, v128, v224, s[90:91]
	v_cndmask_b32_e64 v129, v129, v225, s[90:91]
	v_cndmask_b32_e64 v130, v130, v226, s[90:91]
	v_cndmask_b32_e64 v131, v131, v227, s[90:91]
	v_mov_b32_dpp v224, v116 row_ror:8 row_mask:0xf bank_mask:0xf
	v_mov_b32_dpp v225, v117 row_ror:8 row_mask:0xf bank_mask:0xf
	v_mov_b32_dpp v226, v118 row_ror:8 row_mask:0xf bank_mask:0xf
	v_mov_b32_dpp v227, v119 row_ror:8 row_mask:0xf bank_mask:0xf
	v_cndmask_b32_e64 v116, v224, v120, s[90:91]
	v_cndmask_b32_e64 v117, v225, v121, s[90:91]
	v_cndmask_b32_e64 v118, v226, v122, s[90:91]
	v_cndmask_b32_e64 v119, v227, v123, s[90:91]
	v_cndmask_b32_e64 v120, v120, v224, s[90:91]
	v_cndmask_b32_e64 v121, v121, v225, s[90:91]
	v_cndmask_b32_e64 v122, v122, v226, s[90:91]
	v_cndmask_b32_e64 v123, v123, v227, s[90:91]
	s_lshl_b32 s94, s1, 8
	s_add_i32 s94, s94, 16
	s_lshl_b32 s94, s94, 14
	s_add_u32 s86, s48, s94
	s_addc_u32 s87, s49, 0
	s_lshl_b32 s94, s1, 8
	s_add_i32 s94, s94, 16
	s_lshl_b32 s94, s94, 13
	s_add_u32 s88, s12, s94
	s_addc_u32 s89, s13, 0
	s_lshl_b32 s94, s1, 8
	s_add_i32 s94, s94, 16
	s_lshl_b32 s94, s94, 8
	s_add_u32 s92, s46, s94
	s_addc_u32 s93, s47, 0
	s_waitcnt vmcnt(13)
	v_pk_add_f32 v[128:129], v[128:129], v[96:97]
	v_pk_add_f32 v[130:131], v[130:131], v[98:99]
	v_pk_add_f32 v[124:125], v[124:125], v[92:93]
	v_pk_add_f32 v[126:127], v[126:127], v[94:95]
	global_store_dwordx4 v182, v[128:131], s[86:87]
	global_store_dwordx4 v183, v[124:127], s[86:87]
	v_mul_f32_e32 v191, v128, v128
	v_fmac_f32_e32 v191, v129, v129
	v_fmac_f32_e32 v191, v130, v130
	v_fmac_f32_e32 v191, v131, v131
	v_mul_f32_e32 v192, v124, v124
	v_fmac_f32_e32 v192, v125, v125
	v_fmac_f32_e32 v192, v126, v126
	v_fmac_f32_e32 v192, v127, v127
	v_pk_mul_f32 v[224:225], v[128:129], v[148:149]
	v_pk_mul_f32 v[226:227], v[130:131], v[150:151]
	v_cvt_pk_bf16_f32 v210, v224, v225
	v_cvt_pk_bf16_f32 v211, v226, v227
	global_store_dwordx2 v184, v[210:211], s[88:89]
	v_pk_mul_f32 v[224:225], v[124:125], v[156:157]
	v_pk_mul_f32 v[226:227], v[126:127], v[158:159]
	v_cvt_pk_bf16_f32 v212, v224, v225
	v_cvt_pk_bf16_f32 v213, v226, v227
	global_store_dwordx2 v185, v[212:213], s[88:89]
	v_pk_add_f32 v[120:121], v[120:121], v[88:89]
	v_pk_add_f32 v[122:123], v[122:123], v[90:91]
	v_pk_add_f32 v[116:117], v[116:117], v[84:85]
	v_pk_add_f32 v[118:119], v[118:119], v[86:87]
	global_store_dwordx4 v182, v[120:123], s[86:87] offset:512
	global_store_dwordx4 v183, v[116:119], s[86:87] offset:512
	v_fmac_f32_e32 v191, v120, v120
	v_fmac_f32_e32 v191, v121, v121
	v_fmac_f32_e32 v191, v122, v122
	v_fmac_f32_e32 v191, v123, v123
	v_fmac_f32_e32 v192, v116, v116
	v_fmac_f32_e32 v192, v117, v117
	v_fmac_f32_e32 v192, v118, v118
	v_fmac_f32_e32 v192, v119, v119
	v_pk_mul_f32 v[224:225], v[120:121], v[152:153]
	v_pk_mul_f32 v[226:227], v[122:123], v[154:155]
	v_cvt_pk_bf16_f32 v210, v224, v225
	v_cvt_pk_bf16_f32 v211, v226, v227
	global_store_dwordx2 v184, v[210:211], s[88:89] offset:256
	v_pk_mul_f32 v[224:225], v[116:117], v[160:161]
	v_pk_mul_f32 v[226:227], v[118:119], v[162:163]
	v_cvt_pk_bf16_f32 v212, v224, v225
	v_cvt_pk_bf16_f32 v213, v226, v227
	global_store_dwordx2 v185, v[212:213], s[88:89] offset:256
	s_nop 1
	v_add_f32_dpp v193, v191, v191 row_ror:8 row_mask:0xf bank_mask:0xf
	v_add_f32_dpp v181, v192, v192 row_ror:8 row_mask:0xf bank_mask:0xf
	v_cndmask_b32_e64 v191, v193, v181, s[90:91]
	v_mov_b32_e32 v192, v191
	s_nop 1
	v_permlane16_swap_b32_e32 v191, v192
	v_add_f32_e32 v191, v191, v192
	v_mov_b32_e32 v192, v191
	s_nop 1
	v_permlane32_swap_b32_e32 v191, v192
	v_add_f32_e32 v191, v191, v192
	s_and_saveexec_b64 s[14:15], s[40:41]
	global_store_dword v188, v191, s[92:93]
	s_or_b64 exec, exec, s[14:15]
	s_lshl_b32 s94, s1, 8
	s_add_i32 s94, s94, 176
	s_lshl_b32 s94, s94, 14
	s_add_u32 s84, s16, s94
	s_addc_u32 s85, s17, 0
	global_load_dwordx4 v[128:131], v182, s[84:85]
	global_load_dwordx4 v[124:127], v183, s[84:85]
	global_load_dwordx4 v[120:123], v182, s[84:85] offset:512
	global_load_dwordx4 v[116:119], v183, s[84:85] offset:512
	v_mov_b32_dpp v224, v28 row_ror:8 row_mask:0xf bank_mask:0xf
	v_mov_b32_dpp v225, v29 row_ror:8 row_mask:0xf bank_mask:0xf
	v_mov_b32_dpp v226, v30 row_ror:8 row_mask:0xf bank_mask:0xf
	v_mov_b32_dpp v227, v31 row_ror:8 row_mask:0xf bank_mask:0xf
	v_cndmask_b32_e64 v28, v224, v32, s[90:91]
	v_cndmask_b32_e64 v29, v225, v33, s[90:91]
	v_cndmask_b32_e64 v30, v226, v34, s[90:91]
	v_cndmask_b32_e64 v31, v227, v35, s[90:91]
	v_cndmask_b32_e64 v32, v32, v224, s[90:91]
	v_cndmask_b32_e64 v33, v33, v225, s[90:91]
	v_cndmask_b32_e64 v34, v34, v226, s[90:91]
	v_cndmask_b32_e64 v35, v35, v227, s[90:91]
	v_mov_b32_dpp v224, v20 row_ror:8 row_mask:0xf bank_mask:0xf
	v_mov_b32_dpp v225, v21 row_ror:8 row_mask:0xf bank_mask:0xf
	v_mov_b32_dpp v226, v22 row_ror:8 row_mask:0xf bank_mask:0xf
	v_mov_b32_dpp v227, v23 row_ror:8 row_mask:0xf bank_mask:0xf
	v_cndmask_b32_e64 v20, v224, v24, s[90:91]
	v_cndmask_b32_e64 v21, v225, v25, s[90:91]
	v_cndmask_b32_e64 v22, v226, v26, s[90:91]
	v_cndmask_b32_e64 v23, v227, v27, s[90:91]
	v_cndmask_b32_e64 v24, v24, v224, s[90:91]
	v_cndmask_b32_e64 v25, v25, v225, s[90:91]
	v_cndmask_b32_e64 v26, v26, v226, s[90:91]
	v_cndmask_b32_e64 v27, v27, v227, s[90:91]
	s_lshl_b32 s94, s1, 8
	s_add_i32 s94, s94, 160
	s_lshl_b32 s94, s94, 14
	s_add_u32 s86, s48, s94
	s_addc_u32 s87, s49, 0
	s_lshl_b32 s94, s1, 8
	s_add_i32 s94, s94, 160
	s_lshl_b32 s94, s94, 13
	s_add_u32 s88, s12, s94
	s_addc_u32 s89, s13, 0
	s_lshl_b32 s94, s1, 8
	s_add_i32 s94, s94, 160
	s_lshl_b32 s94, s94, 8
	s_add_u32 s92, s46, s94
	s_addc_u32 s93, s47, 0
	s_waitcnt vmcnt(13)
	v_pk_add_f32 v[32:33], v[32:33], v[144:145]
	v_pk_add_f32 v[34:35], v[34:35], v[146:147]
	v_pk_add_f32 v[28:29], v[28:29], v[140:141]
	v_pk_add_f32 v[30:31], v[30:31], v[142:143]
	global_store_dwordx4 v182, v[32:35], s[86:87]
	global_store_dwordx4 v183, v[28:31], s[86:87]
	v_mul_f32_e32 v191, v32, v32
	v_fmac_f32_e32 v191, v33, v33
	v_fmac_f32_e32 v191, v34, v34
	v_fmac_f32_e32 v191, v35, v35
	v_mul_f32_e32 v192, v28, v28
	v_fmac_f32_e32 v192, v29, v29
	v_fmac_f32_e32 v192, v30, v30
	v_fmac_f32_e32 v192, v31, v31
	v_pk_mul_f32 v[224:225], v[32:33], v[148:149]
	v_pk_mul_f32 v[226:227], v[34:35], v[150:151]
	v_cvt_pk_bf16_f32 v210, v224, v225
	v_cvt_pk_bf16_f32 v211, v226, v227
	global_store_dwordx2 v184, v[210:211], s[88:89]
	v_pk_mul_f32 v[224:225], v[28:29], v[156:157]
	v_pk_mul_f32 v[226:227], v[30:31], v[158:159]
	v_cvt_pk_bf16_f32 v212, v224, v225
	v_cvt_pk_bf16_f32 v213, v226, v227
	global_store_dwordx2 v185, v[212:213], s[88:89]
	v_pk_add_f32 v[24:25], v[24:25], v[136:137]
	v_pk_add_f32 v[26:27], v[26:27], v[138:139]
	v_pk_add_f32 v[20:21], v[20:21], v[132:133]
	v_pk_add_f32 v[22:23], v[22:23], v[134:135]
	global_store_dwordx4 v182, v[24:27], s[86:87] offset:512
	global_store_dwordx4 v183, v[20:23], s[86:87] offset:512
	v_fmac_f32_e32 v191, v24, v24
	v_fmac_f32_e32 v191, v25, v25
	v_fmac_f32_e32 v191, v26, v26
	v_fmac_f32_e32 v191, v27, v27
	v_fmac_f32_e32 v192, v20, v20
	v_fmac_f32_e32 v192, v21, v21
	v_fmac_f32_e32 v192, v22, v22
	v_fmac_f32_e32 v192, v23, v23
	v_pk_mul_f32 v[224:225], v[24:25], v[152:153]
	v_pk_mul_f32 v[226:227], v[26:27], v[154:155]
	v_cvt_pk_bf16_f32 v210, v224, v225
	v_cvt_pk_bf16_f32 v211, v226, v227
	global_store_dwordx2 v184, v[210:211], s[88:89] offset:256
	v_pk_mul_f32 v[224:225], v[20:21], v[160:161]
	v_pk_mul_f32 v[226:227], v[22:23], v[162:163]
	v_cvt_pk_bf16_f32 v212, v224, v225
	v_cvt_pk_bf16_f32 v213, v226, v227
	global_store_dwordx2 v185, v[212:213], s[88:89] offset:256
	s_nop 1
	v_add_f32_dpp v193, v191, v191 row_ror:8 row_mask:0xf bank_mask:0xf
	v_add_f32_dpp v181, v192, v192 row_ror:8 row_mask:0xf bank_mask:0xf
	v_cndmask_b32_e64 v191, v193, v181, s[90:91]
	v_mov_b32_e32 v192, v191
	s_nop 1
	v_permlane16_swap_b32_e32 v191, v192
	v_add_f32_e32 v191, v191, v192
	v_mov_b32_e32 v192, v191
	s_nop 1
	v_permlane32_swap_b32_e32 v191, v192
	v_add_f32_e32 v191, v191, v192
	s_and_saveexec_b64 s[14:15], s[40:41]
	global_store_dword v188, v191, s[92:93]
	s_or_b64 exec, exec, s[14:15]
	s_lshl_b32 s94, s1, 8
	s_add_i32 s94, s94, 128
	s_lshl_b32 s94, s94, 14
	s_add_u32 s84, s16, s94
	s_addc_u32 s85, s17, 0
	global_load_dwordx4 v[32:35], v182, s[84:85]
	global_load_dwordx4 v[28:31], v183, s[84:85]
	global_load_dwordx4 v[24:27], v182, s[84:85] offset:512
	global_load_dwordx4 v[20:23], v183, s[84:85] offset:512
	v_mov_b32_dpp v224, v12 row_ror:8 row_mask:0xf bank_mask:0xf
	v_mov_b32_dpp v225, v13 row_ror:8 row_mask:0xf bank_mask:0xf
	v_mov_b32_dpp v226, v14 row_ror:8 row_mask:0xf bank_mask:0xf
	v_mov_b32_dpp v227, v15 row_ror:8 row_mask:0xf bank_mask:0xf
	v_cndmask_b32_e64 v12, v224, v16, s[90:91]
	v_cndmask_b32_e64 v13, v225, v17, s[90:91]
	v_cndmask_b32_e64 v14, v226, v18, s[90:91]
	v_cndmask_b32_e64 v15, v227, v19, s[90:91]
	v_cndmask_b32_e64 v16, v16, v224, s[90:91]
	v_cndmask_b32_e64 v17, v17, v225, s[90:91]
	v_cndmask_b32_e64 v18, v18, v226, s[90:91]
	v_cndmask_b32_e64 v19, v19, v227, s[90:91]
	v_mov_b32_dpp v224, v4 row_ror:8 row_mask:0xf bank_mask:0xf
	v_mov_b32_dpp v225, v5 row_ror:8 row_mask:0xf bank_mask:0xf
	v_mov_b32_dpp v226, v6 row_ror:8 row_mask:0xf bank_mask:0xf
	v_mov_b32_dpp v227, v7 row_ror:8 row_mask:0xf bank_mask:0xf
	v_cndmask_b32_e64 v4, v224, v8, s[90:91]
	v_cndmask_b32_e64 v5, v225, v9, s[90:91]
	v_cndmask_b32_e64 v6, v226, v10, s[90:91]
	v_cndmask_b32_e64 v7, v227, v11, s[90:91]
	v_cndmask_b32_e64 v8, v8, v224, s[90:91]
	v_cndmask_b32_e64 v9, v9, v225, s[90:91]
	v_cndmask_b32_e64 v10, v10, v226, s[90:91]
	v_cndmask_b32_e64 v11, v11, v227, s[90:91]
	s_lshl_b32 s94, s1, 8
	s_add_i32 s94, s94, 176
	s_lshl_b32 s94, s94, 14
	s_add_u32 s86, s48, s94
	s_addc_u32 s87, s49, 0
	s_lshl_b32 s94, s1, 8
	s_add_i32 s94, s94, 176
	s_lshl_b32 s94, s94, 13
	s_add_u32 s88, s12, s94
	s_addc_u32 s89, s13, 0
	s_lshl_b32 s94, s1, 8
	s_add_i32 s94, s94, 176
	s_lshl_b32 s94, s94, 8
	s_add_u32 s92, s46, s94
	s_addc_u32 s93, s47, 0
	s_waitcnt vmcnt(13)
	v_pk_add_f32 v[16:17], v[16:17], v[128:129]
	v_pk_add_f32 v[18:19], v[18:19], v[130:131]
	v_pk_add_f32 v[12:13], v[12:13], v[124:125]
	v_pk_add_f32 v[14:15], v[14:15], v[126:127]
	global_store_dwordx4 v182, v[16:19], s[86:87]
	global_store_dwordx4 v183, v[12:15], s[86:87]
	v_mul_f32_e32 v191, v16, v16
	v_fmac_f32_e32 v191, v17, v17
	v_fmac_f32_e32 v191, v18, v18
	v_fmac_f32_e32 v191, v19, v19
	v_mul_f32_e32 v192, v12, v12
	v_fmac_f32_e32 v192, v13, v13
	v_fmac_f32_e32 v192, v14, v14
	v_fmac_f32_e32 v192, v15, v15
	v_pk_mul_f32 v[224:225], v[16:17], v[148:149]
	v_pk_mul_f32 v[226:227], v[18:19], v[150:151]
	v_cvt_pk_bf16_f32 v210, v224, v225
	v_cvt_pk_bf16_f32 v211, v226, v227
	global_store_dwordx2 v184, v[210:211], s[88:89]
	v_pk_mul_f32 v[224:225], v[12:13], v[156:157]
	v_pk_mul_f32 v[226:227], v[14:15], v[158:159]
	v_cvt_pk_bf16_f32 v212, v224, v225
	v_cvt_pk_bf16_f32 v213, v226, v227
	global_store_dwordx2 v185, v[212:213], s[88:89]
	v_pk_add_f32 v[8:9], v[8:9], v[120:121]
	v_pk_add_f32 v[10:11], v[10:11], v[122:123]
	v_pk_add_f32 v[4:5], v[4:5], v[116:117]
	v_pk_add_f32 v[6:7], v[6:7], v[118:119]
	global_store_dwordx4 v182, v[8:11], s[86:87] offset:512
	global_store_dwordx4 v183, v[4:7], s[86:87] offset:512
	v_fmac_f32_e32 v191, v8, v8
	v_fmac_f32_e32 v191, v9, v9
	v_fmac_f32_e32 v191, v10, v10
	v_fmac_f32_e32 v191, v11, v11
	v_fmac_f32_e32 v192, v4, v4
	v_fmac_f32_e32 v192, v5, v5
	v_fmac_f32_e32 v192, v6, v6
	v_fmac_f32_e32 v192, v7, v7
	v_pk_mul_f32 v[224:225], v[8:9], v[152:153]
	v_pk_mul_f32 v[226:227], v[10:11], v[154:155]
	v_cvt_pk_bf16_f32 v210, v224, v225
	v_cvt_pk_bf16_f32 v211, v226, v227
	global_store_dwordx2 v184, v[210:211], s[88:89] offset:256
	v_pk_mul_f32 v[224:225], v[4:5], v[160:161]
	v_pk_mul_f32 v[226:227], v[6:7], v[162:163]
	v_cvt_pk_bf16_f32 v212, v224, v225
	v_cvt_pk_bf16_f32 v213, v226, v227
	global_store_dwordx2 v185, v[212:213], s[88:89] offset:256
	s_nop 1
	v_add_f32_dpp v193, v191, v191 row_ror:8 row_mask:0xf bank_mask:0xf
	v_add_f32_dpp v181, v192, v192 row_ror:8 row_mask:0xf bank_mask:0xf
	v_cndmask_b32_e64 v191, v193, v181, s[90:91]
	v_mov_b32_e32 v192, v191
	s_nop 1
	v_permlane16_swap_b32_e32 v191, v192
	v_add_f32_e32 v191, v191, v192
	v_mov_b32_e32 v192, v191
	s_nop 1
	v_permlane32_swap_b32_e32 v191, v192
	v_add_f32_e32 v191, v191, v192
	s_and_saveexec_b64 s[14:15], s[40:41]
	global_store_dword v188, v191, s[92:93]
	s_or_b64 exec, exec, s[14:15]
	s_lshl_b32 s94, s1, 8
	s_add_i32 s94, s94, 144
	s_lshl_b32 s94, s94, 14
	s_add_u32 s84, s16, s94
	s_addc_u32 s85, s17, 0
	global_load_dwordx4 v[16:19], v182, s[84:85]
	global_load_dwordx4 v[12:15], v183, s[84:85]
	global_load_dwordx4 v[8:11], v182, s[84:85] offset:512
	global_load_dwordx4 v[4:7], v183, s[84:85] offset:512
	v_mov_b32_dpp v224, v76 row_ror:8 row_mask:0xf bank_mask:0xf
	v_mov_b32_dpp v225, v77 row_ror:8 row_mask:0xf bank_mask:0xf
	v_mov_b32_dpp v226, v78 row_ror:8 row_mask:0xf bank_mask:0xf
	v_mov_b32_dpp v227, v79 row_ror:8 row_mask:0xf bank_mask:0xf
	v_cndmask_b32_e64 v76, v224, v80, s[90:91]
	v_cndmask_b32_e64 v77, v225, v81, s[90:91]
	v_cndmask_b32_e64 v78, v226, v82, s[90:91]
	v_cndmask_b32_e64 v79, v227, v83, s[90:91]
	v_cndmask_b32_e64 v80, v80, v224, s[90:91]
	v_cndmask_b32_e64 v81, v81, v225, s[90:91]
	v_cndmask_b32_e64 v82, v82, v226, s[90:91]
	v_cndmask_b32_e64 v83, v83, v227, s[90:91]
	v_mov_b32_dpp v224, v68 row_ror:8 row_mask:0xf bank_mask:0xf
	v_mov_b32_dpp v225, v69 row_ror:8 row_mask:0xf bank_mask:0xf
	v_mov_b32_dpp v226, v70 row_ror:8 row_mask:0xf bank_mask:0xf
	v_mov_b32_dpp v227, v71 row_ror:8 row_mask:0xf bank_mask:0xf
	v_cndmask_b32_e64 v68, v224, v72, s[90:91]
	v_cndmask_b32_e64 v69, v225, v73, s[90:91]
	v_cndmask_b32_e64 v70, v226, v74, s[90:91]
	v_cndmask_b32_e64 v71, v227, v75, s[90:91]
	v_cndmask_b32_e64 v72, v72, v224, s[90:91]
	v_cndmask_b32_e64 v73, v73, v225, s[90:91]
	v_cndmask_b32_e64 v74, v74, v226, s[90:91]
	v_cndmask_b32_e64 v75, v75, v227, s[90:91]
	s_lshl_b32 s94, s1, 8
	s_add_i32 s94, s94, 128
	s_lshl_b32 s94, s94, 14
	s_add_u32 s86, s48, s94
	s_addc_u32 s87, s49, 0
	s_lshl_b32 s94, s1, 8
	s_add_i32 s94, s94, 128
	s_lshl_b32 s94, s94, 13
	s_add_u32 s88, s12, s94
	s_addc_u32 s89, s13, 0
	s_lshl_b32 s94, s1, 8
	s_add_i32 s94, s94, 128
	s_lshl_b32 s94, s94, 8
	s_add_u32 s92, s46, s94
	s_addc_u32 s93, s47, 0
	s_waitcnt vmcnt(13)
	v_pk_add_f32 v[80:81], v[80:81], v[32:33]
	v_pk_add_f32 v[82:83], v[82:83], v[34:35]
	v_pk_add_f32 v[76:77], v[76:77], v[28:29]
	v_pk_add_f32 v[78:79], v[78:79], v[30:31]
	global_store_dwordx4 v182, v[80:83], s[86:87]
	global_store_dwordx4 v183, v[76:79], s[86:87]
	v_mul_f32_e32 v191, v80, v80
	v_fmac_f32_e32 v191, v81, v81
	v_fmac_f32_e32 v191, v82, v82
	v_fmac_f32_e32 v191, v83, v83
	v_mul_f32_e32 v192, v76, v76
	v_fmac_f32_e32 v192, v77, v77
	v_fmac_f32_e32 v192, v78, v78
	v_fmac_f32_e32 v192, v79, v79
	v_pk_mul_f32 v[224:225], v[80:81], v[148:149]
	v_pk_mul_f32 v[226:227], v[82:83], v[150:151]
	v_cvt_pk_bf16_f32 v210, v224, v225
	v_cvt_pk_bf16_f32 v211, v226, v227
	global_store_dwordx2 v184, v[210:211], s[88:89]
	v_pk_mul_f32 v[224:225], v[76:77], v[156:157]
	v_pk_mul_f32 v[226:227], v[78:79], v[158:159]
	v_cvt_pk_bf16_f32 v212, v224, v225
	v_cvt_pk_bf16_f32 v213, v226, v227
	global_store_dwordx2 v185, v[212:213], s[88:89]
	v_pk_add_f32 v[72:73], v[72:73], v[24:25]
	v_pk_add_f32 v[74:75], v[74:75], v[26:27]
	v_pk_add_f32 v[68:69], v[68:69], v[20:21]
	v_pk_add_f32 v[70:71], v[70:71], v[22:23]
	global_store_dwordx4 v182, v[72:75], s[86:87] offset:512
	global_store_dwordx4 v183, v[68:71], s[86:87] offset:512
	v_fmac_f32_e32 v191, v72, v72
	v_fmac_f32_e32 v191, v73, v73
	v_fmac_f32_e32 v191, v74, v74
	v_fmac_f32_e32 v191, v75, v75
	v_fmac_f32_e32 v192, v68, v68
	v_fmac_f32_e32 v192, v69, v69
	v_fmac_f32_e32 v192, v70, v70
	v_fmac_f32_e32 v192, v71, v71
	v_pk_mul_f32 v[224:225], v[72:73], v[152:153]
	v_pk_mul_f32 v[226:227], v[74:75], v[154:155]
	v_cvt_pk_bf16_f32 v210, v224, v225
	v_cvt_pk_bf16_f32 v211, v226, v227
	global_store_dwordx2 v184, v[210:211], s[88:89] offset:256
	v_pk_mul_f32 v[224:225], v[68:69], v[160:161]
	v_pk_mul_f32 v[226:227], v[70:71], v[162:163]
	v_cvt_pk_bf16_f32 v212, v224, v225
	v_cvt_pk_bf16_f32 v213, v226, v227
	global_store_dwordx2 v185, v[212:213], s[88:89] offset:256
	s_nop 1
	v_add_f32_dpp v193, v191, v191 row_ror:8 row_mask:0xf bank_mask:0xf
	v_add_f32_dpp v181, v192, v192 row_ror:8 row_mask:0xf bank_mask:0xf
	v_cndmask_b32_e64 v191, v193, v181, s[90:91]
	v_mov_b32_e32 v192, v191
	s_nop 1
	v_permlane16_swap_b32_e32 v191, v192
	v_add_f32_e32 v191, v191, v192
	v_mov_b32_e32 v192, v191
	s_nop 1
	v_permlane32_swap_b32_e32 v191, v192
	v_add_f32_e32 v191, v191, v192
	s_and_saveexec_b64 s[14:15], s[40:41]
	global_store_dword v188, v191, s[92:93]
	s_or_b64 exec, exec, s[14:15]
	v_mov_b32_dpp v224, v44 row_ror:8 row_mask:0xf bank_mask:0xf
	v_mov_b32_dpp v225, v45 row_ror:8 row_mask:0xf bank_mask:0xf
	v_mov_b32_dpp v226, v46 row_ror:8 row_mask:0xf bank_mask:0xf
	v_mov_b32_dpp v227, v47 row_ror:8 row_mask:0xf bank_mask:0xf
	v_cndmask_b32_e64 v44, v224, v52, s[90:91]
	v_cndmask_b32_e64 v45, v225, v53, s[90:91]
	v_cndmask_b32_e64 v46, v226, v54, s[90:91]
	v_cndmask_b32_e64 v47, v227, v55, s[90:91]
	v_cndmask_b32_e64 v52, v52, v224, s[90:91]
	v_cndmask_b32_e64 v53, v53, v225, s[90:91]
	v_cndmask_b32_e64 v54, v54, v226, s[90:91]
	v_cndmask_b32_e64 v55, v55, v227, s[90:91]
	v_mov_b32_dpp v224, v36 row_ror:8 row_mask:0xf bank_mask:0xf
	v_mov_b32_dpp v225, v37 row_ror:8 row_mask:0xf bank_mask:0xf
	v_mov_b32_dpp v226, v38 row_ror:8 row_mask:0xf bank_mask:0xf
	v_mov_b32_dpp v227, v39 row_ror:8 row_mask:0xf bank_mask:0xf
	v_cndmask_b32_e64 v36, v224, v40, s[90:91]
	v_cndmask_b32_e64 v37, v225, v41, s[90:91]
	v_cndmask_b32_e64 v38, v226, v42, s[90:91]
	v_cndmask_b32_e64 v39, v227, v43, s[90:91]
	v_cndmask_b32_e64 v40, v40, v224, s[90:91]
	v_cndmask_b32_e64 v41, v41, v225, s[90:91]
	v_cndmask_b32_e64 v42, v42, v226, s[90:91]
	v_cndmask_b32_e64 v43, v43, v227, s[90:91]
	s_lshl_b32 s94, s1, 8
	s_add_i32 s94, s94, 144
	s_lshl_b32 s94, s94, 14
	s_add_u32 s86, s48, s94
	s_addc_u32 s87, s49, 0
	s_lshl_b32 s94, s1, 8
	s_add_i32 s94, s94, 144
	s_lshl_b32 s94, s94, 13
	s_add_u32 s88, s12, s94
	s_addc_u32 s89, s13, 0
	s_lshl_b32 s94, s1, 8
	s_add_i32 s94, s94, 144
	s_lshl_b32 s94, s94, 8
	s_add_u32 s92, s46, s94
	s_addc_u32 s93, s47, 0
	s_waitcnt vmcnt(9)
	v_pk_add_f32 v[52:53], v[52:53], v[16:17]
	v_pk_add_f32 v[54:55], v[54:55], v[18:19]
	v_pk_add_f32 v[44:45], v[44:45], v[12:13]
	v_pk_add_f32 v[46:47], v[46:47], v[14:15]
	global_store_dwordx4 v182, v[52:55], s[86:87]
	global_store_dwordx4 v183, v[44:47], s[86:87]
	v_mul_f32_e32 v191, v52, v52
	v_fmac_f32_e32 v191, v53, v53
	v_fmac_f32_e32 v191, v54, v54
	v_fmac_f32_e32 v191, v55, v55
	v_mul_f32_e32 v192, v44, v44
	v_fmac_f32_e32 v192, v45, v45
	v_fmac_f32_e32 v192, v46, v46
	v_fmac_f32_e32 v192, v47, v47
	v_pk_mul_f32 v[224:225], v[52:53], v[148:149]
	v_pk_mul_f32 v[226:227], v[54:55], v[150:151]
	v_cvt_pk_bf16_f32 v210, v224, v225
	v_cvt_pk_bf16_f32 v211, v226, v227
	global_store_dwordx2 v184, v[210:211], s[88:89]
	v_pk_mul_f32 v[224:225], v[44:45], v[156:157]
	v_pk_mul_f32 v[226:227], v[46:47], v[158:159]
	v_cvt_pk_bf16_f32 v212, v224, v225
	v_cvt_pk_bf16_f32 v213, v226, v227
	global_store_dwordx2 v185, v[212:213], s[88:89]
	v_pk_add_f32 v[40:41], v[40:41], v[8:9]
	v_pk_add_f32 v[42:43], v[42:43], v[10:11]
	v_pk_add_f32 v[36:37], v[36:37], v[4:5]
	v_pk_add_f32 v[38:39], v[38:39], v[6:7]
	global_store_dwordx4 v182, v[40:43], s[86:87] offset:512
	global_store_dwordx4 v183, v[36:39], s[86:87] offset:512
	v_fmac_f32_e32 v191, v40, v40
	v_fmac_f32_e32 v191, v41, v41
	v_fmac_f32_e32 v191, v42, v42
	v_fmac_f32_e32 v191, v43, v43
	v_fmac_f32_e32 v192, v36, v36
	v_fmac_f32_e32 v192, v37, v37
	v_fmac_f32_e32 v192, v38, v38
	v_fmac_f32_e32 v192, v39, v39
	v_pk_mul_f32 v[224:225], v[40:41], v[152:153]
	v_pk_mul_f32 v[226:227], v[42:43], v[154:155]
	v_cvt_pk_bf16_f32 v210, v224, v225
	v_cvt_pk_bf16_f32 v211, v226, v227
	global_store_dwordx2 v184, v[210:211], s[88:89] offset:256
	v_pk_mul_f32 v[224:225], v[36:37], v[160:161]
	v_pk_mul_f32 v[226:227], v[38:39], v[162:163]
	v_cvt_pk_bf16_f32 v212, v224, v225
	v_cvt_pk_bf16_f32 v213, v226, v227
	global_store_dwordx2 v185, v[212:213], s[88:89] offset:256
	s_nop 1
	v_add_f32_dpp v193, v191, v191 row_ror:8 row_mask:0xf bank_mask:0xf
	v_add_f32_dpp v181, v192, v192 row_ror:8 row_mask:0xf bank_mask:0xf
	v_cndmask_b32_e64 v191, v193, v181, s[90:91]
	v_mov_b32_e32 v192, v191
	s_nop 1
	v_permlane16_swap_b32_e32 v191, v192
	v_add_f32_e32 v191, v191, v192
	v_mov_b32_e32 v192, v191
	s_nop 1
	v_permlane32_swap_b32_e32 v191, v192
	v_add_f32_e32 v191, v191, v192
	s_and_saveexec_b64 s[14:15], s[40:41]
	global_store_dword v188, v191, s[92:93]
	s_or_b64 exec, exec, s[14:15]
	s_branch .Lrot_p5_end
.Lrot_p5_3:
	v_and_b32_e32 v181, 8, v219
	v_cmp_ne_u32_e64 s[90:91], 0, v181
	v_sub_u32_e32 v191, v1, v181
	v_lshlrev_b32_e32 v181, 1, v181
	s_lshl_b32 s94, s0, 8
	v_add3_u32 v192, v179, v181, s94
	v_sub_u32_e32 v193, v179, v181
	v_add3_u32 v193, v193, 16, s94
	v_lshlrev_b32_e32 v182, 14, v191
	v_lshl_add_u32 v183, v193, 2, v182
	v_add_u32_e32 v183, 0x20000, v183
	v_lshl_add_u32 v182, v192, 2, v182
	v_lshlrev_b32_e32 v184, 13, v191
	v_lshl_add_u32 v185, v193, 1, v184
	v_add_u32_e32 v185, 0x10000, v185
	v_lshl_add_u32 v184, v192, 1, v184
	v_lshlrev_b32_e32 v186, 2, v192
	v_lshlrev_b32_e32 v187, 2, v193
	global_load_dwordx4 v[148:151], v186, s[44:45]
	global_load_dwordx4 v[156:159], v187, s[44:45]
	global_load_dwordx4 v[152:155], v186, s[44:45] offset:512
	global_load_dwordx4 v[160:163], v187, s[44:45] offset:512
	s_lshl_b32 s94, s0, 4
	s_lshl_b32 s95, s64, 2
	s_add_i32 s94, s94, s95
	v_lshlrev_b32_e32 v188, 8, v1
	v_add_u32_e32 v188, s94, v188
	v_xor_b32_e32 v189, 16, v219
	v_lshlrev_b32_e32 v189, 2, v189
	v_xor_b32_e32 v190, 32, v219
	v_lshlrev_b32_e32 v190, 2, v190
	s_lshl_b32 s94, s1, 8
	s_add_i32 s94, s94, 48
	s_lshl_b32 s94, s94, 14
	s_add_u32 s84, s16, s94
	s_addc_u32 s85, s17, 0
	global_load_dwordx4 v[48:51], v182, s[84:85]
	global_load_dwordx4 v[56:59], v183, s[84:85]
	global_load_dwordx4 v[60:63], v182, s[84:85] offset:512
	global_load_dwordx4 v[64:67], v183, s[84:85] offset:512
	s_lshl_b32 s94, s1, 8
	s_lshl_b32 s94, s94, 14
	s_add_u32 s84, s16, s94
	s_addc_u32 s85, s17, 0
	global_load_dwordx4 v[170:173], v182, s[84:85]
	global_load_dwordx4 v[174:177], v183, s[84:85]
	global_load_dwordx4 v[206:209], v182, s[84:85] offset:512
	global_load_dwordx4 v[232:235], v183, s[84:85] offset:512
	v_mov_b32_dpp v224, v92 row_ror:8 row_mask:0xf bank_mask:0xf
	v_mov_b32_dpp v225, v93 row_ror:8 row_mask:0xf bank_mask:0xf
	v_mov_b32_dpp v226, v94 row_ror:8 row_mask:0xf bank_mask:0xf
	v_mov_b32_dpp v227, v95 row_ror:8 row_mask:0xf bank_mask:0xf
	v_cndmask_b32_e64 v92, v224, v96, s[90:91]
	v_cndmask_b32_e64 v93, v225, v97, s[90:91]
	v_cndmask_b32_e64 v94, v226, v98, s[90:91]
	v_cndmask_b32_e64 v95, v227, v99, s[90:91]
	v_cndmask_b32_e64 v96, v96, v224, s[90:91]
	v_cndmask_b32_e64 v97, v97, v225, s[90:91]
	v_cndmask_b32_e64 v98, v98, v226, s[90:91]
	v_cndmask_b32_e64 v99, v99, v227, s[90:91]
	v_mov_b32_dpp v224, v84 row_ror:8 row_mask:0xf bank_mask:0xf
	v_mov_b32_dpp v225, v85 row_ror:8 row_mask:0xf bank_mask:0xf
	v_mov_b32_dpp v226, v86 row_ror:8 row_mask:0xf bank_mask:0xf
	v_mov_b32_dpp v227, v87 row_ror:8 row_mask:0xf bank_mask:0xf
	v_cndmask_b32_e64 v84, v224, v88, s[90:91]
	v_cndmask_b32_e64 v85, v225, v89, s[90:91]
	v_cndmask_b32_e64 v86, v226, v90, s[90:91]
	v_cndmask_b32_e64 v87, v227, v91, s[90:91]
	v_cndmask_b32_e64 v88, v88, v224, s[90:91]
	v_cndmask_b32_e64 v89, v89, v225, s[90:91]
	v_cndmask_b32_e64 v90, v90, v226, s[90:91]
	v_cndmask_b32_e64 v91, v91, v227, s[90:91]
	s_lshl_b32 s94, s1, 8
	s_add_i32 s94, s94, 48
	s_lshl_b32 s94, s94, 14
	s_add_u32 s86, s48, s94
	s_addc_u32 s87, s49, 0
	s_lshl_b32 s94, s1, 8
	s_add_i32 s94, s94, 48
	s_lshl_b32 s94, s94, 13
	s_add_u32 s88, s12, s94
	s_addc_u32 s89, s13, 0
	s_lshl_b32 s94, s1, 8
	s_add_i32 s94, s94, 48
	s_lshl_b32 s94, s94, 8
	s_add_u32 s92, s46, s94
	s_addc_u32 s93, s47, 0
	s_waitcnt vmcnt(4)
	v_pk_add_f32 v[96:97], v[96:97], v[48:49]
	v_pk_add_f32 v[98:99], v[98:99], v[50:51]
	v_pk_add_f32 v[92:93], v[92:93], v[56:57]
	v_pk_add_f32 v[94:95], v[94:95], v[58:59]
	global_store_dwordx4 v182, v[96:99], s[86:87]
	global_store_dwordx4 v183, v[92:95], s[86:87]
	v_mul_f32_e32 v191, v96, v96
	v_fmac_f32_e32 v191, v97, v97
	v_fmac_f32_e32 v191, v98, v98
	v_fmac_f32_e32 v191, v99, v99
	v_mul_f32_e32 v192, v92, v92
	v_fmac_f32_e32 v192, v93, v93
	v_fmac_f32_e32 v192, v94, v94
	v_fmac_f32_e32 v192, v95, v95
	v_pk_mul_f32 v[224:225], v[96:97], v[148:149]
	v_pk_mul_f32 v[226:227], v[98:99], v[150:151]
	v_cvt_pk_bf16_f32 v210, v224, v225
	v_cvt_pk_bf16_f32 v211, v226, v227
	global_store_dwordx2 v184, v[210:211], s[88:89]
	v_pk_mul_f32 v[224:225], v[92:93], v[156:157]
	v_pk_mul_f32 v[226:227], v[94:95], v[158:159]
	v_cvt_pk_bf16_f32 v212, v224, v225
	v_cvt_pk_bf16_f32 v213, v226, v227
	global_store_dwordx2 v185, v[212:213], s[88:89]
	v_pk_add_f32 v[88:89], v[88:89], v[60:61]
	v_pk_add_f32 v[90:91], v[90:91], v[62:63]
	v_pk_add_f32 v[84:85], v[84:85], v[64:65]
	v_pk_add_f32 v[86:87], v[86:87], v[66:67]
	global_store_dwordx4 v182, v[88:91], s[86:87] offset:512
	global_store_dwordx4 v183, v[84:87], s[86:87] offset:512
	v_fmac_f32_e32 v191, v88, v88
	v_fmac_f32_e32 v191, v89, v89
	v_fmac_f32_e32 v191, v90, v90
	v_fmac_f32_e32 v191, v91, v91
	v_fmac_f32_e32 v192, v84, v84
	v_fmac_f32_e32 v192, v85, v85
	v_fmac_f32_e32 v192, v86, v86
	v_fmac_f32_e32 v192, v87, v87
	v_pk_mul_f32 v[224:225], v[88:89], v[152:153]
	v_pk_mul_f32 v[226:227], v[90:91], v[154:155]
	v_cvt_pk_bf16_f32 v210, v224, v225
	v_cvt_pk_bf16_f32 v211, v226, v227
	global_store_dwordx2 v184, v[210:211], s[88:89] offset:256
	v_pk_mul_f32 v[224:225], v[84:85], v[160:161]
	v_pk_mul_f32 v[226:227], v[86:87], v[162:163]
	v_cvt_pk_bf16_f32 v212, v224, v225
	v_cvt_pk_bf16_f32 v213, v226, v227
	global_store_dwordx2 v185, v[212:213], s[88:89] offset:256
	s_nop 1
	v_add_f32_dpp v193, v191, v191 row_ror:8 row_mask:0xf bank_mask:0xf
	v_add_f32_dpp v181, v192, v192 row_ror:8 row_mask:0xf bank_mask:0xf
	v_cndmask_b32_e64 v191, v193, v181, s[90:91]
	v_mov_b32_e32 v192, v191
	s_nop 1
	v_permlane16_swap_b32_e32 v191, v192
	v_add_f32_e32 v191, v191, v192
	v_mov_b32_e32 v192, v191
	s_nop 1
	v_permlane32_swap_b32_e32 v191, v192
	v_add_f32_e32 v191, v191, v192
	s_and_saveexec_b64 s[14:15], s[40:41]
	global_store_dword v188, v191, s[92:93]
	s_or_b64 exec, exec, s[14:15]
	s_lshl_b32 s94, s1, 8
	s_add_i32 s94, s94, 16
	s_lshl_b32 s94, s94, 14
	s_add_u32 s84, s16, s94
	s_addc_u32 s85, s17, 0
	global_load_dwordx4 v[96:99], v182, s[84:85]
	global_load_dwordx4 v[92:95], v183, s[84:85]
	global_load_dwordx4 v[88:91], v182, s[84:85] offset:512
	global_load_dwordx4 v[84:87], v183, s[84:85] offset:512
	v_mov_b32_dpp v224, v140 row_ror:8 row_mask:0xf bank_mask:0xf
	v_mov_b32_dpp v225, v141 row_ror:8 row_mask:0xf bank_mask:0xf
	v_mov_b32_dpp v226, v142 row_ror:8 row_mask:0xf bank_mask:0xf
	v_mov_b32_dpp v227, v143 row_ror:8 row_mask:0xf bank_mask:0xf
	v_cndmask_b32_e64 v140, v224, v144, s[90:91]
	v_cndmask_b32_e64 v141, v225, v145, s[90:91]
	v_cndmask_b32_e64 v142, v226, v146, s[90:91]
	v_cndmask_b32_e64 v143, v227, v147, s[90:91]
	v_cndmask_b32_e64 v144, v144, v224, s[90:91]
	v_cndmask_b32_e64 v145, v145, v225, s[90:91]
	v_cndmask_b32_e64 v146, v146, v226, s[90:91]
	v_cndmask_b32_e64 v147, v147, v227, s[90:91]
	v_mov_b32_dpp v224, v132 row_ror:8 row_mask:0xf bank_mask:0xf
	v_mov_b32_dpp v225, v133 row_ror:8 row_mask:0xf bank_mask:0xf
	v_mov_b32_dpp v226, v134 row_ror:8 row_mask:0xf bank_mask:0xf
	v_mov_b32_dpp v227, v135 row_ror:8 row_mask:0xf bank_mask:0xf
	v_cndmask_b32_e64 v132, v224, v136, s[90:91]
	v_cndmask_b32_e64 v133, v225, v137, s[90:91]
	v_cndmask_b32_e64 v134, v226, v138, s[90:91]
	v_cndmask_b32_e64 v135, v227, v139, s[90:91]
	v_cndmask_b32_e64 v136, v136, v224, s[90:91]
	v_cndmask_b32_e64 v137, v137, v225, s[90:91]
	v_cndmask_b32_e64 v138, v138, v226, s[90:91]
	v_cndmask_b32_e64 v139, v139, v227, s[90:91]
	s_lshl_b32 s94, s1, 8
	s_lshl_b32 s94, s94, 14
	s_add_u32 s86, s48, s94
	s_addc_u32 s87, s49, 0
	s_lshl_b32 s94, s1, 8
	s_lshl_b32 s94, s94, 13
	s_add_u32 s88, s12, s94
	s_addc_u32 s89, s13, 0
	s_lshl_b32 s94, s1, 8
	s_lshl_b32 s94, s94, 8
	s_add_u32 s92, s46, s94
	s_addc_u32 s93, s47, 0
	s_waitcnt vmcnt(13)
	v_pk_add_f32 v[144:145], v[144:145], v[170:171]
	v_pk_add_f32 v[146:147], v[146:147], v[172:173]
	v_pk_add_f32 v[140:141], v[140:141], v[174:175]
	v_pk_add_f32 v[142:143], v[142:143], v[176:177]
	global_store_dwordx4 v182, v[144:147], s[86:87]
	global_store_dwordx4 v183, v[140:143], s[86:87]
	v_mul_f32_e32 v191, v144, v144
	v_fmac_f32_e32 v191, v145, v145
	v_fmac_f32_e32 v191, v146, v146
	v_fmac_f32_e32 v191, v147, v147
	v_mul_f32_e32 v192, v140, v140
	v_fmac_f32_e32 v192, v141, v141
	v_fmac_f32_e32 v192, v142, v142
	v_fmac_f32_e32 v192, v143, v143
	v_pk_mul_f32 v[224:225], v[144:145], v[148:149]
	v_pk_mul_f32 v[226:227], v[146:147], v[150:151]
	v_cvt_pk_bf16_f32 v210, v224, v225
	v_cvt_pk_bf16_f32 v211, v226, v227
	global_store_dwordx2 v184, v[210:211], s[88:89]
	v_pk_mul_f32 v[224:225], v[140:141], v[156:157]
	v_pk_mul_f32 v[226:227], v[142:143], v[158:159]
	v_cvt_pk_bf16_f32 v212, v224, v225
	v_cvt_pk_bf16_f32 v213, v226, v227
	global_store_dwordx2 v185, v[212:213], s[88:89]
	v_pk_add_f32 v[136:137], v[136:137], v[206:207]
	v_pk_add_f32 v[138:139], v[138:139], v[208:209]
	v_pk_add_f32 v[132:133], v[132:133], v[232:233]
	v_pk_add_f32 v[134:135], v[134:135], v[234:235]
	global_store_dwordx4 v182, v[136:139], s[86:87] offset:512
	global_store_dwordx4 v183, v[132:135], s[86:87] offset:512
	v_fmac_f32_e32 v191, v136, v136
	v_fmac_f32_e32 v191, v137, v137
	v_fmac_f32_e32 v191, v138, v138
	v_fmac_f32_e32 v191, v139, v139
	v_fmac_f32_e32 v192, v132, v132
	v_fmac_f32_e32 v192, v133, v133
	v_fmac_f32_e32 v192, v134, v134
	v_fmac_f32_e32 v192, v135, v135
	v_pk_mul_f32 v[224:225], v[136:137], v[152:153]
	v_pk_mul_f32 v[226:227], v[138:139], v[154:155]
	v_cvt_pk_bf16_f32 v210, v224, v225
	v_cvt_pk_bf16_f32 v211, v226, v227
	global_store_dwordx2 v184, v[210:211], s[88:89] offset:256
	v_pk_mul_f32 v[224:225], v[132:133], v[160:161]
	v_pk_mul_f32 v[226:227], v[134:135], v[162:163]
	v_cvt_pk_bf16_f32 v212, v224, v225
	v_cvt_pk_bf16_f32 v213, v226, v227
	global_store_dwordx2 v185, v[212:213], s[88:89] offset:256
	s_nop 1
	v_add_f32_dpp v193, v191, v191 row_ror:8 row_mask:0xf bank_mask:0xf
	v_add_f32_dpp v181, v192, v192 row_ror:8 row_mask:0xf bank_mask:0xf
	v_cndmask_b32_e64 v191, v193, v181, s[90:91]
	v_mov_b32_e32 v192, v191
	s_nop 1
	v_permlane16_swap_b32_e32 v191, v192
	v_add_f32_e32 v191, v191, v192
	v_mov_b32_e32 v192, v191
	s_nop 1
	v_permlane32_swap_b32_e32 v191, v192
	v_add_f32_e32 v191, v191, v192
	s_and_saveexec_b64 s[14:15], s[40:41]
	global_store_dword v188, v191, s[92:93]
	s_or_b64 exec, exec, s[14:15]
	s_lshl_b32 s94, s1, 8
	s_add_i32 s94, s94, 32
	s_lshl_b32 s94, s94, 14
	s_add_u32 s84, s16, s94
	s_addc_u32 s85, s17, 0
	global_load_dwordx4 v[144:147], v182, s[84:85]
	global_load_dwordx4 v[140:143], v183, s[84:85]
	global_load_dwordx4 v[136:139], v182, s[84:85] offset:512
	global_load_dwordx4 v[132:135], v183, s[84:85] offset:512
	v_mov_b32_dpp v224, v124 row_ror:8 row_mask:0xf bank_mask:0xf
	v_mov_b32_dpp v225, v125 row_ror:8 row_mask:0xf bank_mask:0xf
	v_mov_b32_dpp v226, v126 row_ror:8 row_mask:0xf bank_mask:0xf
	v_mov_b32_dpp v227, v127 row_ror:8 row_mask:0xf bank_mask:0xf
	v_cndmask_b32_e64 v124, v224, v128, s[90:91]
	v_cndmask_b32_e64 v125, v225, v129, s[90:91]
	v_cndmask_b32_e64 v126, v226, v130, s[90:91]
	v_cndmask_b32_e64 v127, v227, v131, s[90:91]
	v_cndmask_b32_e64 v128, v128, v224, s[90:91]
	v_cndmask_b32_e64 v129, v129, v225, s[90:91]
	v_cndmask_b32_e64 v130, v130, v226, s[90:91]
	v_cndmask_b32_e64 v131, v131, v227, s[90:91]
	v_mov_b32_dpp v224, v116 row_ror:8 row_mask:0xf bank_mask:0xf
	v_mov_b32_dpp v225, v117 row_ror:8 row_mask:0xf bank_mask:0xf
	v_mov_b32_dpp v226, v118 row_ror:8 row_mask:0xf bank_mask:0xf
	v_mov_b32_dpp v227, v119 row_ror:8 row_mask:0xf bank_mask:0xf
	v_cndmask_b32_e64 v116, v224, v120, s[90:91]
	v_cndmask_b32_e64 v117, v225, v121, s[90:91]
	v_cndmask_b32_e64 v118, v226, v122, s[90:91]
	v_cndmask_b32_e64 v119, v227, v123, s[90:91]
	v_cndmask_b32_e64 v120, v120, v224, s[90:91]
	v_cndmask_b32_e64 v121, v121, v225, s[90:91]
	v_cndmask_b32_e64 v122, v122, v226, s[90:91]
	v_cndmask_b32_e64 v123, v123, v227, s[90:91]
	s_lshl_b32 s94, s1, 8
	s_add_i32 s94, s94, 16
	s_lshl_b32 s94, s94, 14
	s_add_u32 s86, s48, s94
	s_addc_u32 s87, s49, 0
	s_lshl_b32 s94, s1, 8
	s_add_i32 s94, s94, 16
	s_lshl_b32 s94, s94, 13
	s_add_u32 s88, s12, s94
	s_addc_u32 s89, s13, 0
	s_lshl_b32 s94, s1, 8
	s_add_i32 s94, s94, 16
	s_lshl_b32 s94, s94, 8
	s_add_u32 s92, s46, s94
	s_addc_u32 s93, s47, 0
	s_waitcnt vmcnt(13)
	v_pk_add_f32 v[128:129], v[128:129], v[96:97]
	v_pk_add_f32 v[130:131], v[130:131], v[98:99]
	v_pk_add_f32 v[124:125], v[124:125], v[92:93]
	v_pk_add_f32 v[126:127], v[126:127], v[94:95]
	global_store_dwordx4 v182, v[128:131], s[86:87]
	global_store_dwordx4 v183, v[124:127], s[86:87]
	v_mul_f32_e32 v191, v128, v128
	v_fmac_f32_e32 v191, v129, v129
	v_fmac_f32_e32 v191, v130, v130
	v_fmac_f32_e32 v191, v131, v131
	v_mul_f32_e32 v192, v124, v124
	v_fmac_f32_e32 v192, v125, v125
	v_fmac_f32_e32 v192, v126, v126
	v_fmac_f32_e32 v192, v127, v127
	v_pk_mul_f32 v[224:225], v[128:129], v[148:149]
	v_pk_mul_f32 v[226:227], v[130:131], v[150:151]
	v_cvt_pk_bf16_f32 v210, v224, v225
	v_cvt_pk_bf16_f32 v211, v226, v227
	global_store_dwordx2 v184, v[210:211], s[88:89]
	v_pk_mul_f32 v[224:225], v[124:125], v[156:157]
	v_pk_mul_f32 v[226:227], v[126:127], v[158:159]
	v_cvt_pk_bf16_f32 v212, v224, v225
	v_cvt_pk_bf16_f32 v213, v226, v227
	global_store_dwordx2 v185, v[212:213], s[88:89]
	v_pk_add_f32 v[120:121], v[120:121], v[88:89]
	v_pk_add_f32 v[122:123], v[122:123], v[90:91]
	v_pk_add_f32 v[116:117], v[116:117], v[84:85]
	v_pk_add_f32 v[118:119], v[118:119], v[86:87]
	global_store_dwordx4 v182, v[120:123], s[86:87] offset:512
	global_store_dwordx4 v183, v[116:119], s[86:87] offset:512
	v_fmac_f32_e32 v191, v120, v120
	v_fmac_f32_e32 v191, v121, v121
	v_fmac_f32_e32 v191, v122, v122
	v_fmac_f32_e32 v191, v123, v123
	v_fmac_f32_e32 v192, v116, v116
	v_fmac_f32_e32 v192, v117, v117
	v_fmac_f32_e32 v192, v118, v118
	v_fmac_f32_e32 v192, v119, v119
	v_pk_mul_f32 v[224:225], v[120:121], v[152:153]
	v_pk_mul_f32 v[226:227], v[122:123], v[154:155]
	v_cvt_pk_bf16_f32 v210, v224, v225
	v_cvt_pk_bf16_f32 v211, v226, v227
	global_store_dwordx2 v184, v[210:211], s[88:89] offset:256
	v_pk_mul_f32 v[224:225], v[116:117], v[160:161]
	v_pk_mul_f32 v[226:227], v[118:119], v[162:163]
	v_cvt_pk_bf16_f32 v212, v224, v225
	v_cvt_pk_bf16_f32 v213, v226, v227
	global_store_dwordx2 v185, v[212:213], s[88:89] offset:256
	s_nop 1
	v_add_f32_dpp v193, v191, v191 row_ror:8 row_mask:0xf bank_mask:0xf
	v_add_f32_dpp v181, v192, v192 row_ror:8 row_mask:0xf bank_mask:0xf
	v_cndmask_b32_e64 v191, v193, v181, s[90:91]
	v_mov_b32_e32 v192, v191
	s_nop 1
	v_permlane16_swap_b32_e32 v191, v192
	v_add_f32_e32 v191, v191, v192
	v_mov_b32_e32 v192, v191
	s_nop 1
	v_permlane32_swap_b32_e32 v191, v192
	v_add_f32_e32 v191, v191, v192
	s_and_saveexec_b64 s[14:15], s[40:41]
	global_store_dword v188, v191, s[92:93]
	s_or_b64 exec, exec, s[14:15]
	s_lshl_b32 s94, s1, 8
	s_add_i32 s94, s94, 176
	s_lshl_b32 s94, s94, 14
	s_add_u32 s84, s16, s94
	s_addc_u32 s85, s17, 0
	global_load_dwordx4 v[128:131], v182, s[84:85]
	global_load_dwordx4 v[124:127], v183, s[84:85]
	global_load_dwordx4 v[120:123], v182, s[84:85] offset:512
	global_load_dwordx4 v[116:119], v183, s[84:85] offset:512
	v_mov_b32_dpp v224, v108 row_ror:8 row_mask:0xf bank_mask:0xf
	v_mov_b32_dpp v225, v109 row_ror:8 row_mask:0xf bank_mask:0xf
	v_mov_b32_dpp v226, v110 row_ror:8 row_mask:0xf bank_mask:0xf
	v_mov_b32_dpp v227, v111 row_ror:8 row_mask:0xf bank_mask:0xf
	v_cndmask_b32_e64 v108, v224, v112, s[90:91]
	v_cndmask_b32_e64 v109, v225, v113, s[90:91]
	v_cndmask_b32_e64 v110, v226, v114, s[90:91]
	v_cndmask_b32_e64 v111, v227, v115, s[90:91]
	v_cndmask_b32_e64 v112, v112, v224, s[90:91]
	v_cndmask_b32_e64 v113, v113, v225, s[90:91]
	v_cndmask_b32_e64 v114, v114, v226, s[90:91]
	v_cndmask_b32_e64 v115, v115, v227, s[90:91]
	v_mov_b32_dpp v224, v100 row_ror:8 row_mask:0xf bank_mask:0xf
	v_mov_b32_dpp v225, v101 row_ror:8 row_mask:0xf bank_mask:0xf
	v_mov_b32_dpp v226, v102 row_ror:8 row_mask:0xf bank_mask:0xf
	v_mov_b32_dpp v227, v103 row_ror:8 row_mask:0xf bank_mask:0xf
	v_cndmask_b32_e64 v100, v224, v104, s[90:91]
	v_cndmask_b32_e64 v101, v225, v105, s[90:91]
	v_cndmask_b32_e64 v102, v226, v106, s[90:91]
	v_cndmask_b32_e64 v103, v227, v107, s[90:91]
	v_cndmask_b32_e64 v104, v104, v224, s[90:91]
	v_cndmask_b32_e64 v105, v105, v225, s[90:91]
	v_cndmask_b32_e64 v106, v106, v226, s[90:91]
	v_cndmask_b32_e64 v107, v107, v227, s[90:91]
	s_lshl_b32 s94, s1, 8
	s_add_i32 s94, s94, 32
	s_lshl_b32 s94, s94, 14
	s_add_u32 s86, s48, s94
	s_addc_u32 s87, s49, 0
	s_lshl_b32 s94, s1, 8
	s_add_i32 s94, s94, 32
	s_lshl_b32 s94, s94, 13
	s_add_u32 s88, s12, s94
	s_addc_u32 s89, s13, 0
	s_lshl_b32 s94, s1, 8
	s_add_i32 s94, s94, 32
	s_lshl_b32 s94, s94, 8
	s_add_u32 s92, s46, s94
	s_addc_u32 s93, s47, 0
	s_waitcnt vmcnt(13)
	v_pk_add_f32 v[112:113], v[112:113], v[144:145]
	v_pk_add_f32 v[114:115], v[114:115], v[146:147]
	v_pk_add_f32 v[108:109], v[108:109], v[140:141]
	v_pk_add_f32 v[110:111], v[110:111], v[142:143]
	global_store_dwordx4 v182, v[112:115], s[86:87]
	global_store_dwordx4 v183, v[108:111], s[86:87]
	v_mul_f32_e32 v191, v112, v112
	v_fmac_f32_e32 v191, v113, v113
	v_fmac_f32_e32 v191, v114, v114
	v_fmac_f32_e32 v191, v115, v115
	v_mul_f32_e32 v192, v108, v108
	v_fmac_f32_e32 v192, v109, v109
	v_fmac_f32_e32 v192, v110, v110
	v_fmac_f32_e32 v192, v111, v111
	v_pk_mul_f32 v[224:225], v[112:113], v[148:149]
	v_pk_mul_f32 v[226:227], v[114:115], v[150:151]
	v_cvt_pk_bf16_f32 v210, v224, v225
	v_cvt_pk_bf16_f32 v211, v226, v227
	global_store_dwordx2 v184, v[210:211], s[88:89]
	v_pk_mul_f32 v[224:225], v[108:109], v[156:157]
	v_pk_mul_f32 v[226:227], v[110:111], v[158:159]
	v_cvt_pk_bf16_f32 v212, v224, v225
	v_cvt_pk_bf16_f32 v213, v226, v227
	global_store_dwordx2 v185, v[212:213], s[88:89]
	v_pk_add_f32 v[104:105], v[104:105], v[136:137]
	v_pk_add_f32 v[106:107], v[106:107], v[138:139]
	v_pk_add_f32 v[100:101], v[100:101], v[132:133]
	v_pk_add_f32 v[102:103], v[102:103], v[134:135]
	global_store_dwordx4 v182, v[104:107], s[86:87] offset:512
	global_store_dwordx4 v183, v[100:103], s[86:87] offset:512
	v_fmac_f32_e32 v191, v104, v104
	v_fmac_f32_e32 v191, v105, v105
	v_fmac_f32_e32 v191, v106, v106
	v_fmac_f32_e32 v191, v107, v107
	v_fmac_f32_e32 v192, v100, v100
	v_fmac_f32_e32 v192, v101, v101
	v_fmac_f32_e32 v192, v102, v102
	v_fmac_f32_e32 v192, v103, v103
	v_pk_mul_f32 v[224:225], v[104:105], v[152:153]
	v_pk_mul_f32 v[226:227], v[106:107], v[154:155]
	v_cvt_pk_bf16_f32 v210, v224, v225
	v_cvt_pk_bf16_f32 v211, v226, v227
	global_store_dwordx2 v184, v[210:211], s[88:89] offset:256
	v_pk_mul_f32 v[224:225], v[100:101], v[160:161]
	v_pk_mul_f32 v[226:227], v[102:103], v[162:163]
	v_cvt_pk_bf16_f32 v212, v224, v225
	v_cvt_pk_bf16_f32 v213, v226, v227
	global_store_dwordx2 v185, v[212:213], s[88:89] offset:256
	s_nop 1
	v_add_f32_dpp v193, v191, v191 row_ror:8 row_mask:0xf bank_mask:0xf
	v_add_f32_dpp v181, v192, v192 row_ror:8 row_mask:0xf bank_mask:0xf
	v_cndmask_b32_e64 v191, v193, v181, s[90:91]
	v_mov_b32_e32 v192, v191
	s_nop 1
	v_permlane16_swap_b32_e32 v191, v192
	v_add_f32_e32 v191, v191, v192
	v_mov_b32_e32 v192, v191
	s_nop 1
	v_permlane32_swap_b32_e32 v191, v192
	v_add_f32_e32 v191, v191, v192
	s_and_saveexec_b64 s[14:15], s[40:41]
	global_store_dword v188, v191, s[92:93]
	s_or_b64 exec, exec, s[14:15]
	s_lshl_b32 s94, s1, 8
	s_add_i32 s94, s94, 128
	s_lshl_b32 s94, s94, 14
	s_add_u32 s84, s16, s94
	s_addc_u32 s85, s17, 0
	global_load_dwordx4 v[112:115], v182, s[84:85]
	global_load_dwordx4 v[108:111], v183, s[84:85]
	global_load_dwordx4 v[104:107], v182, s[84:85] offset:512
	global_load_dwordx4 v[100:103], v183, s[84:85] offset:512
	v_mov_b32_dpp v224, v12 row_ror:8 row_mask:0xf bank_mask:0xf
	v_mov_b32_dpp v225, v13 row_ror:8 row_mask:0xf bank_mask:0xf
	v_mov_b32_dpp v226, v14 row_ror:8 row_mask:0xf bank_mask:0xf
	v_mov_b32_dpp v227, v15 row_ror:8 row_mask:0xf bank_mask:0xf
	v_cndmask_b32_e64 v12, v224, v16, s[90:91]
	v_cndmask_b32_e64 v13, v225, v17, s[90:91]
	v_cndmask_b32_e64 v14, v226, v18, s[90:91]
	v_cndmask_b32_e64 v15, v227, v19, s[90:91]
	v_cndmask_b32_e64 v16, v16, v224, s[90:91]
	v_cndmask_b32_e64 v17, v17, v225, s[90:91]
	v_cndmask_b32_e64 v18, v18, v226, s[90:91]
	v_cndmask_b32_e64 v19, v19, v227, s[90:91]
	v_mov_b32_dpp v224, v4 row_ror:8 row_mask:0xf bank_mask:0xf
	v_mov_b32_dpp v225, v5 row_ror:8 row_mask:0xf bank_mask:0xf
	v_mov_b32_dpp v226, v6 row_ror:8 row_mask:0xf bank_mask:0xf
	v_mov_b32_dpp v227, v7 row_ror:8 row_mask:0xf bank_mask:0xf
	v_cndmask_b32_e64 v4, v224, v8, s[90:91]
	v_cndmask_b32_e64 v5, v225, v9, s[90:91]
	v_cndmask_b32_e64 v6, v226, v10, s[90:91]
	v_cndmask_b32_e64 v7, v227, v11, s[90:91]
	v_cndmask_b32_e64 v8, v8, v224, s[90:91]
	v_cndmask_b32_e64 v9, v9, v225, s[90:91]
	v_cndmask_b32_e64 v10, v10, v226, s[90:91]
	v_cndmask_b32_e64 v11, v11, v227, s[90:91]
	s_lshl_b32 s94, s1, 8
	s_add_i32 s94, s94, 176
	s_lshl_b32 s94, s94, 14
	s_add_u32 s86, s48, s94
	s_addc_u32 s87, s49, 0
	s_lshl_b32 s94, s1, 8
	s_add_i32 s94, s94, 176
	s_lshl_b32 s94, s94, 13
	s_add_u32 s88, s12, s94
	s_addc_u32 s89, s13, 0
	s_lshl_b32 s94, s1, 8
	s_add_i32 s94, s94, 176
	s_lshl_b32 s94, s94, 8
	s_add_u32 s92, s46, s94
	s_addc_u32 s93, s47, 0
	s_waitcnt vmcnt(13)
	v_pk_add_f32 v[16:17], v[16:17], v[128:129]
	v_pk_add_f32 v[18:19], v[18:19], v[130:131]
	v_pk_add_f32 v[12:13], v[12:13], v[124:125]
	v_pk_add_f32 v[14:15], v[14:15], v[126:127]
	global_store_dwordx4 v182, v[16:19], s[86:87]
	global_store_dwordx4 v183, v[12:15], s[86:87]
	v_mul_f32_e32 v191, v16, v16
	v_fmac_f32_e32 v191, v17, v17
	v_fmac_f32_e32 v191, v18, v18
	v_fmac_f32_e32 v191, v19, v19
	v_mul_f32_e32 v192, v12, v12
	v_fmac_f32_e32 v192, v13, v13
	v_fmac_f32_e32 v192, v14, v14
	v_fmac_f32_e32 v192, v15, v15
	v_pk_mul_f32 v[224:225], v[16:17], v[148:149]
	v_pk_mul_f32 v[226:227], v[18:19], v[150:151]
	v_cvt_pk_bf16_f32 v210, v224, v225
	v_cvt_pk_bf16_f32 v211, v226, v227
	global_store_dwordx2 v184, v[210:211], s[88:89]
	v_pk_mul_f32 v[224:225], v[12:13], v[156:157]
	v_pk_mul_f32 v[226:227], v[14:15], v[158:159]
	v_cvt_pk_bf16_f32 v212, v224, v225
	v_cvt_pk_bf16_f32 v213, v226, v227
	global_store_dwordx2 v185, v[212:213], s[88:89]
	v_pk_add_f32 v[8:9], v[8:9], v[120:121]
	v_pk_add_f32 v[10:11], v[10:11], v[122:123]
	v_pk_add_f32 v[4:5], v[4:5], v[116:117]
	v_pk_add_f32 v[6:7], v[6:7], v[118:119]
	global_store_dwordx4 v182, v[8:11], s[86:87] offset:512
	global_store_dwordx4 v183, v[4:7], s[86:87] offset:512
	v_fmac_f32_e32 v191, v8, v8
	v_fmac_f32_e32 v191, v9, v9
	v_fmac_f32_e32 v191, v10, v10
	v_fmac_f32_e32 v191, v11, v11
	v_fmac_f32_e32 v192, v4, v4
	v_fmac_f32_e32 v192, v5, v5
	v_fmac_f32_e32 v192, v6, v6
	v_fmac_f32_e32 v192, v7, v7
	v_pk_mul_f32 v[224:225], v[8:9], v[152:153]
	v_pk_mul_f32 v[226:227], v[10:11], v[154:155]
	v_cvt_pk_bf16_f32 v210, v224, v225
	v_cvt_pk_bf16_f32 v211, v226, v227
	global_store_dwordx2 v184, v[210:211], s[88:89] offset:256
	v_pk_mul_f32 v[224:225], v[4:5], v[160:161]
	v_pk_mul_f32 v[226:227], v[6:7], v[162:163]
	v_cvt_pk_bf16_f32 v212, v224, v225
	v_cvt_pk_bf16_f32 v213, v226, v227
	global_store_dwordx2 v185, v[212:213], s[88:89] offset:256
	s_nop 1
	v_add_f32_dpp v193, v191, v191 row_ror:8 row_mask:0xf bank_mask:0xf
	v_add_f32_dpp v181, v192, v192 row_ror:8 row_mask:0xf bank_mask:0xf
	v_cndmask_b32_e64 v191, v193, v181, s[90:91]
	v_mov_b32_e32 v192, v191
	s_nop 1
	v_permlane16_swap_b32_e32 v191, v192
	v_add_f32_e32 v191, v191, v192
	v_mov_b32_e32 v192, v191
	s_nop 1
	v_permlane32_swap_b32_e32 v191, v192
	v_add_f32_e32 v191, v191, v192
	s_and_saveexec_b64 s[14:15], s[40:41]
	global_store_dword v188, v191, s[92:93]
	s_or_b64 exec, exec, s[14:15]
	s_lshl_b32 s94, s1, 8
	s_add_i32 s94, s94, 144
	s_lshl_b32 s94, s94, 14
	s_add_u32 s84, s16, s94
	s_addc_u32 s85, s17, 0
	global_load_dwordx4 v[16:19], v182, s[84:85]
	global_load_dwordx4 v[12:15], v183, s[84:85]
	global_load_dwordx4 v[8:11], v182, s[84:85] offset:512
	global_load_dwordx4 v[4:7], v183, s[84:85] offset:512
	v_mov_b32_dpp v224, v76 row_ror:8 row_mask:0xf bank_mask:0xf
	v_mov_b32_dpp v225, v77 row_ror:8 row_mask:0xf bank_mask:0xf
	v_mov_b32_dpp v226, v78 row_ror:8 row_mask:0xf bank_mask:0xf
	v_mov_b32_dpp v227, v79 row_ror:8 row_mask:0xf bank_mask:0xf
	v_cndmask_b32_e64 v76, v224, v80, s[90:91]
	v_cndmask_b32_e64 v77, v225, v81, s[90:91]
	v_cndmask_b32_e64 v78, v226, v82, s[90:91]
	v_cndmask_b32_e64 v79, v227, v83, s[90:91]
	v_cndmask_b32_e64 v80, v80, v224, s[90:91]
	v_cndmask_b32_e64 v81, v81, v225, s[90:91]
	v_cndmask_b32_e64 v82, v82, v226, s[90:91]
	v_cndmask_b32_e64 v83, v83, v227, s[90:91]
	v_mov_b32_dpp v224, v68 row_ror:8 row_mask:0xf bank_mask:0xf
	v_mov_b32_dpp v225, v69 row_ror:8 row_mask:0xf bank_mask:0xf
	v_mov_b32_dpp v226, v70 row_ror:8 row_mask:0xf bank_mask:0xf
	v_mov_b32_dpp v227, v71 row_ror:8 row_mask:0xf bank_mask:0xf
	v_cndmask_b32_e64 v68, v224, v72, s[90:91]
	v_cndmask_b32_e64 v69, v225, v73, s[90:91]
	v_cndmask_b32_e64 v70, v226, v74, s[90:91]
	v_cndmask_b32_e64 v71, v227, v75, s[90:91]
	v_cndmask_b32_e64 v72, v72, v224, s[90:91]
	v_cndmask_b32_e64 v73, v73, v225, s[90:91]
	v_cndmask_b32_e64 v74, v74, v226, s[90:91]
	v_cndmask_b32_e64 v75, v75, v227, s[90:91]
	s_lshl_b32 s94, s1, 8
	s_add_i32 s94, s94, 128
	s_lshl_b32 s94, s94, 14
	s_add_u32 s86, s48, s94
	s_addc_u32 s87, s49, 0
	s_lshl_b32 s94, s1, 8
	s_add_i32 s94, s94, 128
	s_lshl_b32 s94, s94, 13
	s_add_u32 s88, s12, s94
	s_addc_u32 s89, s13, 0
	s_lshl_b32 s94, s1, 8
	s_add_i32 s94, s94, 128
	s_lshl_b32 s94, s94, 8
	s_add_u32 s92, s46, s94
	s_addc_u32 s93, s47, 0
	s_waitcnt vmcnt(13)
	v_pk_add_f32 v[80:81], v[80:81], v[112:113]
	v_pk_add_f32 v[82:83], v[82:83], v[114:115]
	v_pk_add_f32 v[76:77], v[76:77], v[108:109]
	v_pk_add_f32 v[78:79], v[78:79], v[110:111]
	global_store_dwordx4 v182, v[80:83], s[86:87]
	global_store_dwordx4 v183, v[76:79], s[86:87]
	v_mul_f32_e32 v191, v80, v80
	v_fmac_f32_e32 v191, v81, v81
	v_fmac_f32_e32 v191, v82, v82
	v_fmac_f32_e32 v191, v83, v83
	v_mul_f32_e32 v192, v76, v76
	v_fmac_f32_e32 v192, v77, v77
	v_fmac_f32_e32 v192, v78, v78
	v_fmac_f32_e32 v192, v79, v79
	v_pk_mul_f32 v[224:225], v[80:81], v[148:149]
	v_pk_mul_f32 v[226:227], v[82:83], v[150:151]
	v_cvt_pk_bf16_f32 v210, v224, v225
	v_cvt_pk_bf16_f32 v211, v226, v227
	global_store_dwordx2 v184, v[210:211], s[88:89]
	v_pk_mul_f32 v[224:225], v[76:77], v[156:157]
	v_pk_mul_f32 v[226:227], v[78:79], v[158:159]
	v_cvt_pk_bf16_f32 v212, v224, v225
	v_cvt_pk_bf16_f32 v213, v226, v227
	global_store_dwordx2 v185, v[212:213], s[88:89]
	v_pk_add_f32 v[72:73], v[72:73], v[104:105]
	v_pk_add_f32 v[74:75], v[74:75], v[106:107]
	v_pk_add_f32 v[68:69], v[68:69], v[100:101]
	v_pk_add_f32 v[70:71], v[70:71], v[102:103]
	global_store_dwordx4 v182, v[72:75], s[86:87] offset:512
	global_store_dwordx4 v183, v[68:71], s[86:87] offset:512
	v_fmac_f32_e32 v191, v72, v72
	v_fmac_f32_e32 v191, v73, v73
	v_fmac_f32_e32 v191, v74, v74
	v_fmac_f32_e32 v191, v75, v75
	v_fmac_f32_e32 v192, v68, v68
	v_fmac_f32_e32 v192, v69, v69
	v_fmac_f32_e32 v192, v70, v70
	v_fmac_f32_e32 v192, v71, v71
	v_pk_mul_f32 v[224:225], v[72:73], v[152:153]
	v_pk_mul_f32 v[226:227], v[74:75], v[154:155]
	v_cvt_pk_bf16_f32 v210, v224, v225
	v_cvt_pk_bf16_f32 v211, v226, v227
	global_store_dwordx2 v184, v[210:211], s[88:89] offset:256
	v_pk_mul_f32 v[224:225], v[68:69], v[160:161]
	v_pk_mul_f32 v[226:227], v[70:71], v[162:163]
	v_cvt_pk_bf16_f32 v212, v224, v225
	v_cvt_pk_bf16_f32 v213, v226, v227
	global_store_dwordx2 v185, v[212:213], s[88:89] offset:256
	s_nop 1
	v_add_f32_dpp v193, v191, v191 row_ror:8 row_mask:0xf bank_mask:0xf
	v_add_f32_dpp v181, v192, v192 row_ror:8 row_mask:0xf bank_mask:0xf
	v_cndmask_b32_e64 v191, v193, v181, s[90:91]
	v_mov_b32_e32 v192, v191
	s_nop 1
	v_permlane16_swap_b32_e32 v191, v192
	v_add_f32_e32 v191, v191, v192
	v_mov_b32_e32 v192, v191
	s_nop 1
	v_permlane32_swap_b32_e32 v191, v192
	v_add_f32_e32 v191, v191, v192
	s_and_saveexec_b64 s[14:15], s[40:41]
	global_store_dword v188, v191, s[92:93]
	s_or_b64 exec, exec, s[14:15]
	s_lshl_b32 s94, s1, 8
	s_add_i32 s94, s94, 160
	s_lshl_b32 s94, s94, 14
	s_add_u32 s84, s16, s94
	s_addc_u32 s85, s17, 0
	global_load_dwordx4 v[80:83], v182, s[84:85]
	global_load_dwordx4 v[76:79], v183, s[84:85]
	global_load_dwordx4 v[72:75], v182, s[84:85] offset:512
	global_load_dwordx4 v[68:71], v183, s[84:85] offset:512
	v_mov_b32_dpp v224, v44 row_ror:8 row_mask:0xf bank_mask:0xf
	v_mov_b32_dpp v225, v45 row_ror:8 row_mask:0xf bank_mask:0xf
	v_mov_b32_dpp v226, v46 row_ror:8 row_mask:0xf bank_mask:0xf
	v_mov_b32_dpp v227, v47 row_ror:8 row_mask:0xf bank_mask:0xf
	v_cndmask_b32_e64 v44, v224, v52, s[90:91]
	v_cndmask_b32_e64 v45, v225, v53, s[90:91]
	v_cndmask_b32_e64 v46, v226, v54, s[90:91]
	v_cndmask_b32_e64 v47, v227, v55, s[90:91]
	v_cndmask_b32_e64 v52, v52, v224, s[90:91]
	v_cndmask_b32_e64 v53, v53, v225, s[90:91]
	v_cndmask_b32_e64 v54, v54, v226, s[90:91]
	v_cndmask_b32_e64 v55, v55, v227, s[90:91]
	v_mov_b32_dpp v224, v36 row_ror:8 row_mask:0xf bank_mask:0xf
	v_mov_b32_dpp v225, v37 row_ror:8 row_mask:0xf bank_mask:0xf
	v_mov_b32_dpp v226, v38 row_ror:8 row_mask:0xf bank_mask:0xf
	v_mov_b32_dpp v227, v39 row_ror:8 row_mask:0xf bank_mask:0xf
	v_cndmask_b32_e64 v36, v224, v40, s[90:91]
	v_cndmask_b32_e64 v37, v225, v41, s[90:91]
	v_cndmask_b32_e64 v38, v226, v42, s[90:91]
	v_cndmask_b32_e64 v39, v227, v43, s[90:91]
	v_cndmask_b32_e64 v40, v40, v224, s[90:91]
	v_cndmask_b32_e64 v41, v41, v225, s[90:91]
	v_cndmask_b32_e64 v42, v42, v226, s[90:91]
	v_cndmask_b32_e64 v43, v43, v227, s[90:91]
	s_lshl_b32 s94, s1, 8
	s_add_i32 s94, s94, 144
	s_lshl_b32 s94, s94, 14
	s_add_u32 s86, s48, s94
	s_addc_u32 s87, s49, 0
	s_lshl_b32 s94, s1, 8
	s_add_i32 s94, s94, 144
	s_lshl_b32 s94, s94, 13
	s_add_u32 s88, s12, s94
	s_addc_u32 s89, s13, 0
	s_lshl_b32 s94, s1, 8
	s_add_i32 s94, s94, 144
	s_lshl_b32 s94, s94, 8
	s_add_u32 s92, s46, s94
	s_addc_u32 s93, s47, 0
	s_waitcnt vmcnt(13)
	v_pk_add_f32 v[52:53], v[52:53], v[16:17]
	v_pk_add_f32 v[54:55], v[54:55], v[18:19]
	v_pk_add_f32 v[44:45], v[44:45], v[12:13]
	v_pk_add_f32 v[46:47], v[46:47], v[14:15]
	global_store_dwordx4 v182, v[52:55], s[86:87]
	global_store_dwordx4 v183, v[44:47], s[86:87]
	v_mul_f32_e32 v191, v52, v52
	v_fmac_f32_e32 v191, v53, v53
	v_fmac_f32_e32 v191, v54, v54
	v_fmac_f32_e32 v191, v55, v55
	v_mul_f32_e32 v192, v44, v44
	v_fmac_f32_e32 v192, v45, v45
	v_fmac_f32_e32 v192, v46, v46
	v_fmac_f32_e32 v192, v47, v47
	v_pk_mul_f32 v[224:225], v[52:53], v[148:149]
	v_pk_mul_f32 v[226:227], v[54:55], v[150:151]
	v_cvt_pk_bf16_f32 v210, v224, v225
	v_cvt_pk_bf16_f32 v211, v226, v227
	global_store_dwordx2 v184, v[210:211], s[88:89]
	v_pk_mul_f32 v[224:225], v[44:45], v[156:157]
	v_pk_mul_f32 v[226:227], v[46:47], v[158:159]
	v_cvt_pk_bf16_f32 v212, v224, v225
	v_cvt_pk_bf16_f32 v213, v226, v227
	global_store_dwordx2 v185, v[212:213], s[88:89]
	v_pk_add_f32 v[40:41], v[40:41], v[8:9]
	v_pk_add_f32 v[42:43], v[42:43], v[10:11]
	v_pk_add_f32 v[36:37], v[36:37], v[4:5]
	v_pk_add_f32 v[38:39], v[38:39], v[6:7]
	global_store_dwordx4 v182, v[40:43], s[86:87] offset:512
	global_store_dwordx4 v183, v[36:39], s[86:87] offset:512
	v_fmac_f32_e32 v191, v40, v40
	v_fmac_f32_e32 v191, v41, v41
	v_fmac_f32_e32 v191, v42, v42
	v_fmac_f32_e32 v191, v43, v43
	v_fmac_f32_e32 v192, v36, v36
	v_fmac_f32_e32 v192, v37, v37
	v_fmac_f32_e32 v192, v38, v38
	v_fmac_f32_e32 v192, v39, v39
	v_pk_mul_f32 v[224:225], v[40:41], v[152:153]
	v_pk_mul_f32 v[226:227], v[42:43], v[154:155]
	v_cvt_pk_bf16_f32 v210, v224, v225
	v_cvt_pk_bf16_f32 v211, v226, v227
	global_store_dwordx2 v184, v[210:211], s[88:89] offset:256
	v_pk_mul_f32 v[224:225], v[36:37], v[160:161]
	v_pk_mul_f32 v[226:227], v[38:39], v[162:163]
	v_cvt_pk_bf16_f32 v212, v224, v225
	v_cvt_pk_bf16_f32 v213, v226, v227
	global_store_dwordx2 v185, v[212:213], s[88:89] offset:256
	s_nop 1
	v_add_f32_dpp v193, v191, v191 row_ror:8 row_mask:0xf bank_mask:0xf
	v_add_f32_dpp v181, v192, v192 row_ror:8 row_mask:0xf bank_mask:0xf
	v_cndmask_b32_e64 v191, v193, v181, s[90:91]
	v_mov_b32_e32 v192, v191
	s_nop 1
	v_permlane16_swap_b32_e32 v191, v192
	v_add_f32_e32 v191, v191, v192
	v_mov_b32_e32 v192, v191
	s_nop 1
	v_permlane32_swap_b32_e32 v191, v192
	v_add_f32_e32 v191, v191, v192
	s_and_saveexec_b64 s[14:15], s[40:41]
	global_store_dword v188, v191, s[92:93]
	s_or_b64 exec, exec, s[14:15]
	v_mov_b32_dpp v224, v28 row_ror:8 row_mask:0xf bank_mask:0xf
	v_mov_b32_dpp v225, v29 row_ror:8 row_mask:0xf bank_mask:0xf
	v_mov_b32_dpp v226, v30 row_ror:8 row_mask:0xf bank_mask:0xf
	v_mov_b32_dpp v227, v31 row_ror:8 row_mask:0xf bank_mask:0xf
	v_cndmask_b32_e64 v28, v224, v32, s[90:91]
	v_cndmask_b32_e64 v29, v225, v33, s[90:91]
	v_cndmask_b32_e64 v30, v226, v34, s[90:91]
	v_cndmask_b32_e64 v31, v227, v35, s[90:91]
	v_cndmask_b32_e64 v32, v32, v224, s[90:91]
	v_cndmask_b32_e64 v33, v33, v225, s[90:91]
	v_cndmask_b32_e64 v34, v34, v226, s[90:91]
	v_cndmask_b32_e64 v35, v35, v227, s[90:91]
	v_mov_b32_dpp v224, v20 row_ror:8 row_mask:0xf bank_mask:0xf
	v_mov_b32_dpp v225, v21 row_ror:8 row_mask:0xf bank_mask:0xf
	v_mov_b32_dpp v226, v22 row_ror:8 row_mask:0xf bank_mask:0xf
	v_mov_b32_dpp v227, v23 row_ror:8 row_mask:0xf bank_mask:0xf
	v_cndmask_b32_e64 v20, v224, v24, s[90:91]
	v_cndmask_b32_e64 v21, v225, v25, s[90:91]
	v_cndmask_b32_e64 v22, v226, v26, s[90:91]
	v_cndmask_b32_e64 v23, v227, v27, s[90:91]
	v_cndmask_b32_e64 v24, v24, v224, s[90:91]
	v_cndmask_b32_e64 v25, v25, v225, s[90:91]
	v_cndmask_b32_e64 v26, v26, v226, s[90:91]
	v_cndmask_b32_e64 v27, v27, v227, s[90:91]
	s_lshl_b32 s94, s1, 8
	s_add_i32 s94, s94, 160
	s_lshl_b32 s94, s94, 14
	s_add_u32 s86, s48, s94
	s_addc_u32 s87, s49, 0
	s_lshl_b32 s94, s1, 8
	s_add_i32 s94, s94, 160
	s_lshl_b32 s94, s94, 13
	s_add_u32 s88, s12, s94
	s_addc_u32 s89, s13, 0
	s_lshl_b32 s94, s1, 8
	s_add_i32 s94, s94, 160
	s_lshl_b32 s94, s94, 8
	s_add_u32 s92, s46, s94
	s_addc_u32 s93, s47, 0
	s_waitcnt vmcnt(9)
	v_pk_add_f32 v[32:33], v[32:33], v[80:81]
	v_pk_add_f32 v[34:35], v[34:35], v[82:83]
	v_pk_add_f32 v[28:29], v[28:29], v[76:77]
	v_pk_add_f32 v[30:31], v[30:31], v[78:79]
	global_store_dwordx4 v182, v[32:35], s[86:87]
	global_store_dwordx4 v183, v[28:31], s[86:87]
	v_mul_f32_e32 v191, v32, v32
	v_fmac_f32_e32 v191, v33, v33
	v_fmac_f32_e32 v191, v34, v34
	v_fmac_f32_e32 v191, v35, v35
	v_mul_f32_e32 v192, v28, v28
	v_fmac_f32_e32 v192, v29, v29
	v_fmac_f32_e32 v192, v30, v30
	v_fmac_f32_e32 v192, v31, v31
	v_pk_mul_f32 v[224:225], v[32:33], v[148:149]
	v_pk_mul_f32 v[226:227], v[34:35], v[150:151]
	v_cvt_pk_bf16_f32 v210, v224, v225
	v_cvt_pk_bf16_f32 v211, v226, v227
	global_store_dwordx2 v184, v[210:211], s[88:89]
	v_pk_mul_f32 v[224:225], v[28:29], v[156:157]
	v_pk_mul_f32 v[226:227], v[30:31], v[158:159]
	v_cvt_pk_bf16_f32 v212, v224, v225
	v_cvt_pk_bf16_f32 v213, v226, v227
	global_store_dwordx2 v185, v[212:213], s[88:89]
	v_pk_add_f32 v[24:25], v[24:25], v[72:73]
	v_pk_add_f32 v[26:27], v[26:27], v[74:75]
	v_pk_add_f32 v[20:21], v[20:21], v[68:69]
	v_pk_add_f32 v[22:23], v[22:23], v[70:71]
	global_store_dwordx4 v182, v[24:27], s[86:87] offset:512
	global_store_dwordx4 v183, v[20:23], s[86:87] offset:512
	v_fmac_f32_e32 v191, v24, v24
	v_fmac_f32_e32 v191, v25, v25
	v_fmac_f32_e32 v191, v26, v26
	v_fmac_f32_e32 v191, v27, v27
	v_fmac_f32_e32 v192, v20, v20
	v_fmac_f32_e32 v192, v21, v21
	v_fmac_f32_e32 v192, v22, v22
	v_fmac_f32_e32 v192, v23, v23
	v_pk_mul_f32 v[224:225], v[24:25], v[152:153]
	v_pk_mul_f32 v[226:227], v[26:27], v[154:155]
	v_cvt_pk_bf16_f32 v210, v224, v225
	v_cvt_pk_bf16_f32 v211, v226, v227
	global_store_dwordx2 v184, v[210:211], s[88:89] offset:256
	v_pk_mul_f32 v[224:225], v[20:21], v[160:161]
	v_pk_mul_f32 v[226:227], v[22:23], v[162:163]
	v_cvt_pk_bf16_f32 v212, v224, v225
	v_cvt_pk_bf16_f32 v213, v226, v227
	global_store_dwordx2 v185, v[212:213], s[88:89] offset:256
	s_nop 1
	v_add_f32_dpp v193, v191, v191 row_ror:8 row_mask:0xf bank_mask:0xf
	v_add_f32_dpp v181, v192, v192 row_ror:8 row_mask:0xf bank_mask:0xf
	v_cndmask_b32_e64 v191, v193, v181, s[90:91]
	v_mov_b32_e32 v192, v191
	s_nop 1
	v_permlane16_swap_b32_e32 v191, v192
	v_add_f32_e32 v191, v191, v192
	v_mov_b32_e32 v192, v191
	s_nop 1
	v_permlane32_swap_b32_e32 v191, v192
	v_add_f32_e32 v191, v191, v192
	s_and_saveexec_b64 s[14:15], s[40:41]
	global_store_dword v188, v191, s[92:93]
	s_or_b64 exec, exec, s[14:15]
.Lrot_p5_end:
	v_readlane_b32 s68, v254, 45
	v_readlane_b32 s69, v254, 48
	v_mov_b32_e32 v232, 0x6c0
	v_mov_b32_e32 v233, 0x750
	v_mov_b32_e32 v234, 0x7e0
	v_mov_b32_e32 v235, 0x870

.LBB0_1240:
	v_readlane_b32 s14, v254, 62
	v_readlane_b32 s15, v254, 63
	v_readlane_b32 s58, v254, 57
	v_readlane_b32 s59, v254, 58
	s_mov_b64 s[56:57], 0x5b000000
	v_readlane_b32 s24, v255, 0
	v_readlane_b32 s25, v255, 1
	s_and_b64 vcc, exec, s[14:15]
	s_cbranch_vccz .Lp8epi_noxg
	s_bfe_u32 s94, s50, 0x20002
	s_cmp_eq_u32 s94, 1
	s_cbranch_scc1 .Lrot_p8x_1
	s_cmp_eq_u32 s94, 2
	s_cbranch_scc1 .Lrot_p8x_2
	s_cmp_eq_u32 s94, 3
	s_cbranch_scc1 .Lrot_p8x_3
	v_and_b32_e32 v192, 8, v219
	v_cmp_ne_u32_e64 s[90:91], 0, v192
	v_sub_u32_e32 v214, v1, v192
	v_lshlrev_b32_e32 v192, 1, v192
	s_lshl_b32 s94, s50, 8
	v_add3_u32 v215, v240, v192, s94
	v_sub_u32_e32 v180, v240, v192
	v_add3_u32 v180, v180, 16, s94
	v_lshlrev_b32_e32 v193, 14, v214
	v_lshl_add_u32 v206, v180, 2, v193
	v_add_u32_e32 v206, 0x20000, v206
	v_lshl_add_u32 v193, v215, 2, v193
	v_lshlrev_b32_e32 v207, 13, v214
	v_lshl_add_u32 v208, v180, 1, v207
	v_add_u32_e32 v208, 0x10000, v208
	v_lshl_add_u32 v207, v215, 1, v207
	v_lshlrev_b32_e32 v209, 2, v215
	v_lshlrev_b32_e32 v210, 2, v180
	global_load_dwordx4 v[148:151], v209, s[16:17]
	global_load_dwordx4 v[156:159], v210, s[16:17]
	global_load_dwordx4 v[152:155], v209, s[16:17] offset:512
	global_load_dwordx4 v[160:163], v210, s[16:17] offset:512
	s_lshl_b32 s94, s50, 4
	s_lshl_b32 s95, s34, 2
	s_add_i32 s94, s94, s95
	v_lshlrev_b32_e32 v211, 8, v1
	v_add_u32_e32 v211, s94, v211
	v_xor_b32_e32 v212, 16, v219
	v_lshlrev_b32_e32 v212, 2, v212
	v_xor_b32_e32 v213, 32, v219
	v_lshlrev_b32_e32 v213, 2, v213
	s_lshl_b32 s94, s51, 8
	s_lshl_b32 s94, s94, 14
	s_add_u32 s84, s48, s94
	s_addc_u32 s85, s49, 0
	global_load_dwordx4 v[60:63], v193, s[84:85]
	global_load_dwordx4 v[68:71], v206, s[84:85]
	global_load_dwordx4 v[76:79], v193, s[84:85] offset:512
	global_load_dwordx4 v[80:83], v206, s[84:85] offset:512
	s_lshl_b32 s94, s51, 8
	s_add_i32 s94, s94, 16
	s_lshl_b32 s94, s94, 14
	s_add_u32 s84, s48, s94
	s_addc_u32 s85, s49, 0
	global_load_dwordx4 v[172:175], v193, s[84:85]
	global_load_dwordx4 v[176:179], v206, s[84:85]
	global_load_dwordx4 v[182:185], v193, s[84:85] offset:512
	global_load_dwordx4 v[232:235], v206, s[84:85] offset:512
	v_mov_b32_dpp v164, v140 row_ror:8 row_mask:0xf bank_mask:0xf
	v_mov_b32_dpp v165, v141 row_ror:8 row_mask:0xf bank_mask:0xf
	v_mov_b32_dpp v166, v142 row_ror:8 row_mask:0xf bank_mask:0xf
	v_mov_b32_dpp v167, v143 row_ror:8 row_mask:0xf bank_mask:0xf
	v_cndmask_b32_e64 v140, v164, v144, s[90:91]
	v_cndmask_b32_e64 v141, v165, v145, s[90:91]
	v_cndmask_b32_e64 v142, v166, v146, s[90:91]
	v_cndmask_b32_e64 v143, v167, v147, s[90:91]
	v_cndmask_b32_e64 v144, v144, v164, s[90:91]
	v_cndmask_b32_e64 v145, v145, v165, s[90:91]
	v_cndmask_b32_e64 v146, v146, v166, s[90:91]
	v_cndmask_b32_e64 v147, v147, v167, s[90:91]
	v_mov_b32_dpp v164, v132 row_ror:8 row_mask:0xf bank_mask:0xf
	v_mov_b32_dpp v165, v133 row_ror:8 row_mask:0xf bank_mask:0xf
	v_mov_b32_dpp v166, v134 row_ror:8 row_mask:0xf bank_mask:0xf
	v_mov_b32_dpp v167, v135 row_ror:8 row_mask:0xf bank_mask:0xf
	v_cndmask_b32_e64 v132, v164, v136, s[90:91]
	v_cndmask_b32_e64 v133, v165, v137, s[90:91]
	v_cndmask_b32_e64 v134, v166, v138, s[90:91]
	v_cndmask_b32_e64 v135, v167, v139, s[90:91]
	v_cndmask_b32_e64 v136, v136, v164, s[90:91]
	v_cndmask_b32_e64 v137, v137, v165, s[90:91]
	v_cndmask_b32_e64 v138, v138, v166, s[90:91]
	v_cndmask_b32_e64 v139, v139, v167, s[90:91]
	s_lshl_b32 s94, s51, 8
	s_lshl_b32 s94, s94, 14
	s_add_u32 s86, s48, s94
	s_addc_u32 s87, s49, 0
	s_lshl_b32 s94, s51, 8
	s_lshl_b32 s94, s94, 13
	s_add_u32 s88, s12, s94
	s_addc_u32 s89, s13, 0
	s_lshl_b32 s94, s51, 8
	s_lshl_b32 s94, s94, 8
	s_add_u32 s92, s22, s94
	s_addc_u32 s93, s23, 0
	s_waitcnt vmcnt(4)
	v_pk_add_f32 v[144:145], v[144:145], v[60:61]
	v_pk_add_f32 v[146:147], v[146:147], v[62:63]
	v_pk_add_f32 v[140:141], v[140:141], v[68:69]
	v_pk_add_f32 v[142:143], v[142:143], v[70:71]
	global_store_dwordx4 v193, v[144:147], s[86:87]
	global_store_dwordx4 v206, v[140:143], s[86:87]
	v_mul_f32_e32 v214, v144, v144
	v_fmac_f32_e32 v214, v145, v145
	v_fmac_f32_e32 v214, v146, v146
	v_fmac_f32_e32 v214, v147, v147
	v_mul_f32_e32 v215, v140, v140
	v_fmac_f32_e32 v215, v141, v141
	v_fmac_f32_e32 v215, v142, v142
	v_fmac_f32_e32 v215, v143, v143
	v_pk_mul_f32 v[164:165], v[144:145], v[148:149]
	v_pk_mul_f32 v[166:167], v[146:147], v[150:151]
	v_cvt_pk_bf16_f32 v168, v164, v165
	v_cvt_pk_bf16_f32 v169, v166, v167
	global_store_dwordx2 v207, v[168:169], s[88:89]
	v_pk_mul_f32 v[164:165], v[140:141], v[156:157]
	v_pk_mul_f32 v[166:167], v[142:143], v[158:159]
	v_cvt_pk_bf16_f32 v170, v164, v165
	v_cvt_pk_bf16_f32 v171, v166, v167
	global_store_dwordx2 v208, v[170:171], s[88:89]
	v_pk_add_f32 v[136:137], v[136:137], v[76:77]
	v_pk_add_f32 v[138:139], v[138:139], v[78:79]
	v_pk_add_f32 v[132:133], v[132:133], v[80:81]
	v_pk_add_f32 v[134:135], v[134:135], v[82:83]
	global_store_dwordx4 v193, v[136:139], s[86:87] offset:512
	global_store_dwordx4 v206, v[132:135], s[86:87] offset:512
	v_fmac_f32_e32 v214, v136, v136
	v_fmac_f32_e32 v214, v137, v137
	v_fmac_f32_e32 v214, v138, v138
	v_fmac_f32_e32 v214, v139, v139
	v_fmac_f32_e32 v215, v132, v132
	v_fmac_f32_e32 v215, v133, v133
	v_fmac_f32_e32 v215, v134, v134
	v_fmac_f32_e32 v215, v135, v135
	v_pk_mul_f32 v[164:165], v[136:137], v[152:153]
	v_pk_mul_f32 v[166:167], v[138:139], v[154:155]
	v_cvt_pk_bf16_f32 v168, v164, v165
	v_cvt_pk_bf16_f32 v169, v166, v167
	global_store_dwordx2 v207, v[168:169], s[88:89] offset:256
	v_pk_mul_f32 v[164:165], v[132:133], v[160:161]
	v_pk_mul_f32 v[166:167], v[134:135], v[162:163]
	v_cvt_pk_bf16_f32 v170, v164, v165
	v_cvt_pk_bf16_f32 v171, v166, v167
	global_store_dwordx2 v208, v[170:171], s[88:89] offset:256
	s_nop 1
	v_add_f32_dpp v180, v214, v214 row_ror:8 row_mask:0xf bank_mask:0xf
	v_add_f32_dpp v192, v215, v215 row_ror:8 row_mask:0xf bank_mask:0xf
	v_cndmask_b32_e64 v214, v180, v192, s[90:91]
	v_mov_b32_e32 v215, v214
	s_nop 1
	v_permlane16_swap_b32_e32 v214, v215
	v_add_f32_e32 v214, v214, v215
	v_mov_b32_e32 v215, v214
	s_nop 1
	v_permlane32_swap_b32_e32 v214, v215
	v_add_f32_e32 v214, v214, v215
	s_and_saveexec_b64 s[14:15], s[38:39]
	global_store_dword v211, v214, s[92:93]
	s_or_b64 exec, exec, s[14:15]
	s_lshl_b32 s94, s51, 8
	s_add_i32 s94, s94, 32
	s_lshl_b32 s94, s94, 14
	s_add_u32 s84, s48, s94
	s_addc_u32 s85, s49, 0
	global_load_dwordx4 v[144:147], v193, s[84:85]
	global_load_dwordx4 v[140:143], v206, s[84:85]
	global_load_dwordx4 v[136:139], v193, s[84:85] offset:512
	global_load_dwordx4 v[132:135], v206, s[84:85] offset:512
	v_mov_b32_dpp v164, v124 row_ror:8 row_mask:0xf bank_mask:0xf
	v_mov_b32_dpp v165, v125 row_ror:8 row_mask:0xf bank_mask:0xf
	v_mov_b32_dpp v166, v126 row_ror:8 row_mask:0xf bank_mask:0xf
	v_mov_b32_dpp v167, v127 row_ror:8 row_mask:0xf bank_mask:0xf
	v_cndmask_b32_e64 v124, v164, v128, s[90:91]
	v_cndmask_b32_e64 v125, v165, v129, s[90:91]
	v_cndmask_b32_e64 v126, v166, v130, s[90:91]
	v_cndmask_b32_e64 v127, v167, v131, s[90:91]
	v_cndmask_b32_e64 v128, v128, v164, s[90:91]
	v_cndmask_b32_e64 v129, v129, v165, s[90:91]
	v_cndmask_b32_e64 v130, v130, v166, s[90:91]
	v_cndmask_b32_e64 v131, v131, v167, s[90:91]
	v_mov_b32_dpp v164, v116 row_ror:8 row_mask:0xf bank_mask:0xf
	v_mov_b32_dpp v165, v117 row_ror:8 row_mask:0xf bank_mask:0xf
	v_mov_b32_dpp v166, v118 row_ror:8 row_mask:0xf bank_mask:0xf
	v_mov_b32_dpp v167, v119 row_ror:8 row_mask:0xf bank_mask:0xf
	v_cndmask_b32_e64 v116, v164, v120, s[90:91]
	v_cndmask_b32_e64 v117, v165, v121, s[90:91]
	v_cndmask_b32_e64 v118, v166, v122, s[90:91]
	v_cndmask_b32_e64 v119, v167, v123, s[90:91]
	v_cndmask_b32_e64 v120, v120, v164, s[90:91]
	v_cndmask_b32_e64 v121, v121, v165, s[90:91]
	v_cndmask_b32_e64 v122, v122, v166, s[90:91]
	v_cndmask_b32_e64 v123, v123, v167, s[90:91]
	s_lshl_b32 s94, s51, 8
	s_add_i32 s94, s94, 16
	s_lshl_b32 s94, s94, 14
	s_add_u32 s86, s48, s94
	s_addc_u32 s87, s49, 0
	s_lshl_b32 s94, s51, 8
	s_add_i32 s94, s94, 16
	s_lshl_b32 s94, s94, 13
	s_add_u32 s88, s12, s94
	s_addc_u32 s89, s13, 0
	s_lshl_b32 s94, s51, 8
	s_add_i32 s94, s94, 16
	s_lshl_b32 s94, s94, 8
	s_add_u32 s92, s22, s94
	s_addc_u32 s93, s23, 0
	s_waitcnt vmcnt(13)
	v_pk_add_f32 v[128:129], v[128:129], v[172:173]
	v_pk_add_f32 v[130:131], v[130:131], v[174:175]
	v_pk_add_f32 v[124:125], v[124:125], v[176:177]
	v_pk_add_f32 v[126:127], v[126:127], v[178:179]
	global_store_dwordx4 v193, v[128:131], s[86:87]
	global_store_dwordx4 v206, v[124:127], s[86:87]
	v_mul_f32_e32 v214, v128, v128
	v_fmac_f32_e32 v214, v129, v129
	v_fmac_f32_e32 v214, v130, v130
	v_fmac_f32_e32 v214, v131, v131
	v_mul_f32_e32 v215, v124, v124
	v_fmac_f32_e32 v215, v125, v125
	v_fmac_f32_e32 v215, v126, v126
	v_fmac_f32_e32 v215, v127, v127
	v_pk_mul_f32 v[164:165], v[128:129], v[148:149]
	v_pk_mul_f32 v[166:167], v[130:131], v[150:151]
	v_cvt_pk_bf16_f32 v168, v164, v165
	v_cvt_pk_bf16_f32 v169, v166, v167
	global_store_dwordx2 v207, v[168:169], s[88:89]
	v_pk_mul_f32 v[164:165], v[124:125], v[156:157]
	v_pk_mul_f32 v[166:167], v[126:127], v[158:159]
	v_cvt_pk_bf16_f32 v170, v164, v165
	v_cvt_pk_bf16_f32 v171, v166, v167
	global_store_dwordx2 v208, v[170:171], s[88:89]
	v_pk_add_f32 v[120:121], v[120:121], v[182:183]
	v_pk_add_f32 v[122:123], v[122:123], v[184:185]
	v_pk_add_f32 v[116:117], v[116:117], v[232:233]
	v_pk_add_f32 v[118:119], v[118:119], v[234:235]
	global_store_dwordx4 v193, v[120:123], s[86:87] offset:512
	global_store_dwordx4 v206, v[116:119], s[86:87] offset:512
	v_fmac_f32_e32 v214, v120, v120
	v_fmac_f32_e32 v214, v121, v121
	v_fmac_f32_e32 v214, v122, v122
	v_fmac_f32_e32 v214, v123, v123
	v_fmac_f32_e32 v215, v116, v116
	v_fmac_f32_e32 v215, v117, v117
	v_fmac_f32_e32 v215, v118, v118
	v_fmac_f32_e32 v215, v119, v119
	v_pk_mul_f32 v[164:165], v[120:121], v[152:153]
	v_pk_mul_f32 v[166:167], v[122:123], v[154:155]
	v_cvt_pk_bf16_f32 v168, v164, v165
	v_cvt_pk_bf16_f32 v169, v166, v167
	global_store_dwordx2 v207, v[168:169], s[88:89] offset:256
	v_pk_mul_f32 v[164:165], v[116:117], v[160:161]
	v_pk_mul_f32 v[166:167], v[118:119], v[162:163]
	v_cvt_pk_bf16_f32 v170, v164, v165
	v_cvt_pk_bf16_f32 v171, v166, v167
	global_store_dwordx2 v208, v[170:171], s[88:89] offset:256
	s_nop 1
	v_add_f32_dpp v180, v214, v214 row_ror:8 row_mask:0xf bank_mask:0xf
	v_add_f32_dpp v192, v215, v215 row_ror:8 row_mask:0xf bank_mask:0xf
	v_cndmask_b32_e64 v214, v180, v192, s[90:91]
	v_mov_b32_e32 v215, v214
	s_nop 1
	v_permlane16_swap_b32_e32 v214, v215
	v_add_f32_e32 v214, v214, v215
	v_mov_b32_e32 v215, v214
	s_nop 1
	v_permlane32_swap_b32_e32 v214, v215
	v_add_f32_e32 v214, v214, v215
	s_and_saveexec_b64 s[14:15], s[38:39]
	global_store_dword v211, v214, s[92:93]
	s_or_b64 exec, exec, s[14:15]
	s_lshl_b32 s94, s51, 8
	s_add_i32 s94, s94, 48
	s_lshl_b32 s94, s94, 14
	s_add_u32 s84, s48, s94
	s_addc_u32 s85, s49, 0
	global_load_dwordx4 v[128:131], v193, s[84:85]
	global_load_dwordx4 v[124:127], v206, s[84:85]
	global_load_dwordx4 v[120:123], v193, s[84:85] offset:512
	global_load_dwordx4 v[116:119], v206, s[84:85] offset:512
	v_mov_b32_dpp v164, v108 row_ror:8 row_mask:0xf bank_mask:0xf
	v_mov_b32_dpp v165, v109 row_ror:8 row_mask:0xf bank_mask:0xf
	v_mov_b32_dpp v166, v110 row_ror:8 row_mask:0xf bank_mask:0xf
	v_mov_b32_dpp v167, v111 row_ror:8 row_mask:0xf bank_mask:0xf
	v_cndmask_b32_e64 v108, v164, v112, s[90:91]
	v_cndmask_b32_e64 v109, v165, v113, s[90:91]
	v_cndmask_b32_e64 v110, v166, v114, s[90:91]
	v_cndmask_b32_e64 v111, v167, v115, s[90:91]
	v_cndmask_b32_e64 v112, v112, v164, s[90:91]
	v_cndmask_b32_e64 v113, v113, v165, s[90:91]
	v_cndmask_b32_e64 v114, v114, v166, s[90:91]
	v_cndmask_b32_e64 v115, v115, v167, s[90:91]
	v_mov_b32_dpp v164, v100 row_ror:8 row_mask:0xf bank_mask:0xf
	v_mov_b32_dpp v165, v101 row_ror:8 row_mask:0xf bank_mask:0xf
	v_mov_b32_dpp v166, v102 row_ror:8 row_mask:0xf bank_mask:0xf
	v_mov_b32_dpp v167, v103 row_ror:8 row_mask:0xf bank_mask:0xf
	v_cndmask_b32_e64 v100, v164, v104, s[90:91]
	v_cndmask_b32_e64 v101, v165, v105, s[90:91]
	v_cndmask_b32_e64 v102, v166, v106, s[90:91]
	v_cndmask_b32_e64 v103, v167, v107, s[90:91]
	v_cndmask_b32_e64 v104, v104, v164, s[90:91]
	v_cndmask_b32_e64 v105, v105, v165, s[90:91]
	v_cndmask_b32_e64 v106, v106, v166, s[90:91]
	v_cndmask_b32_e64 v107, v107, v167, s[90:91]
	s_lshl_b32 s94, s51, 8
	s_add_i32 s94, s94, 32
	s_lshl_b32 s94, s94, 14
	s_add_u32 s86, s48, s94
	s_addc_u32 s87, s49, 0
	s_lshl_b32 s94, s51, 8
	s_add_i32 s94, s94, 32
	s_lshl_b32 s94, s94, 13
	s_add_u32 s88, s12, s94
	s_addc_u32 s89, s13, 0
	s_lshl_b32 s94, s51, 8
	s_add_i32 s94, s94, 32
	s_lshl_b32 s94, s94, 8
	s_add_u32 s92, s22, s94
	s_addc_u32 s93, s23, 0
	s_waitcnt vmcnt(13)
	v_pk_add_f32 v[112:113], v[112:113], v[144:145]
	v_pk_add_f32 v[114:115], v[114:115], v[146:147]
	v_pk_add_f32 v[108:109], v[108:109], v[140:141]
	v_pk_add_f32 v[110:111], v[110:111], v[142:143]
	global_store_dwordx4 v193, v[112:115], s[86:87]
	global_store_dwordx4 v206, v[108:111], s[86:87]
	v_mul_f32_e32 v214, v112, v112
	v_fmac_f32_e32 v214, v113, v113
	v_fmac_f32_e32 v214, v114, v114
	v_fmac_f32_e32 v214, v115, v115
	v_mul_f32_e32 v215, v108, v108
	v_fmac_f32_e32 v215, v109, v109
	v_fmac_f32_e32 v215, v110, v110
	v_fmac_f32_e32 v215, v111, v111
	v_pk_mul_f32 v[164:165], v[112:113], v[148:149]
	v_pk_mul_f32 v[166:167], v[114:115], v[150:151]
	v_cvt_pk_bf16_f32 v168, v164, v165
	v_cvt_pk_bf16_f32 v169, v166, v167
	global_store_dwordx2 v207, v[168:169], s[88:89]
	v_pk_mul_f32 v[164:165], v[108:109], v[156:157]
	v_pk_mul_f32 v[166:167], v[110:111], v[158:159]
	v_cvt_pk_bf16_f32 v170, v164, v165
	v_cvt_pk_bf16_f32 v171, v166, v167
	global_store_dwordx2 v208, v[170:171], s[88:89]
	v_pk_add_f32 v[104:105], v[104:105], v[136:137]
	v_pk_add_f32 v[106:107], v[106:107], v[138:139]
	v_pk_add_f32 v[100:101], v[100:101], v[132:133]
	v_pk_add_f32 v[102:103], v[102:103], v[134:135]
	global_store_dwordx4 v193, v[104:107], s[86:87] offset:512
	global_store_dwordx4 v206, v[100:103], s[86:87] offset:512
	v_fmac_f32_e32 v214, v104, v104
	v_fmac_f32_e32 v214, v105, v105
	v_fmac_f32_e32 v214, v106, v106
	v_fmac_f32_e32 v214, v107, v107
	v_fmac_f32_e32 v215, v100, v100
	v_fmac_f32_e32 v215, v101, v101
	v_fmac_f32_e32 v215, v102, v102
	v_fmac_f32_e32 v215, v103, v103
	v_pk_mul_f32 v[164:165], v[104:105], v[152:153]
	v_pk_mul_f32 v[166:167], v[106:107], v[154:155]
	v_cvt_pk_bf16_f32 v168, v164, v165
	v_cvt_pk_bf16_f32 v169, v166, v167
	global_store_dwordx2 v207, v[168:169], s[88:89] offset:256
	v_pk_mul_f32 v[164:165], v[100:101], v[160:161]
	v_pk_mul_f32 v[166:167], v[102:103], v[162:163]
	v_cvt_pk_bf16_f32 v170, v164, v165
	v_cvt_pk_bf16_f32 v171, v166, v167
	global_store_dwordx2 v208, v[170:171], s[88:89] offset:256
	s_nop 1
	v_add_f32_dpp v180, v214, v214 row_ror:8 row_mask:0xf bank_mask:0xf
	v_add_f32_dpp v192, v215, v215 row_ror:8 row_mask:0xf bank_mask:0xf
	v_cndmask_b32_e64 v214, v180, v192, s[90:91]
	v_mov_b32_e32 v215, v214
	s_nop 1
	v_permlane16_swap_b32_e32 v214, v215
	v_add_f32_e32 v214, v214, v215
	v_mov_b32_e32 v215, v214
	s_nop 1
	v_permlane32_swap_b32_e32 v214, v215
	v_add_f32_e32 v214, v214, v215
	s_and_saveexec_b64 s[14:15], s[38:39]
	global_store_dword v211, v214, s[92:93]
	s_or_b64 exec, exec, s[14:15]
	s_lshl_b32 s94, s51, 8
	s_add_i32 s94, s94, 128
	s_lshl_b32 s94, s94, 14
	s_add_u32 s84, s48, s94
	s_addc_u32 s85, s49, 0
	global_load_dwordx4 v[112:115], v193, s[84:85]
	global_load_dwordx4 v[108:111], v206, s[84:85]
	global_load_dwordx4 v[104:107], v193, s[84:85] offset:512
	global_load_dwordx4 v[100:103], v206, s[84:85] offset:512
	v_mov_b32_dpp v164, v92 row_ror:8 row_mask:0xf bank_mask:0xf
	v_mov_b32_dpp v165, v93 row_ror:8 row_mask:0xf bank_mask:0xf
	v_mov_b32_dpp v166, v94 row_ror:8 row_mask:0xf bank_mask:0xf
	v_mov_b32_dpp v167, v95 row_ror:8 row_mask:0xf bank_mask:0xf
	v_cndmask_b32_e64 v92, v164, v96, s[90:91]
	v_cndmask_b32_e64 v93, v165, v97, s[90:91]
	v_cndmask_b32_e64 v94, v166, v98, s[90:91]
	v_cndmask_b32_e64 v95, v167, v99, s[90:91]
	v_cndmask_b32_e64 v96, v96, v164, s[90:91]
	v_cndmask_b32_e64 v97, v97, v165, s[90:91]
	v_cndmask_b32_e64 v98, v98, v166, s[90:91]
	v_cndmask_b32_e64 v99, v99, v167, s[90:91]
	v_mov_b32_dpp v164, v84 row_ror:8 row_mask:0xf bank_mask:0xf
	v_mov_b32_dpp v165, v85 row_ror:8 row_mask:0xf bank_mask:0xf
	v_mov_b32_dpp v166, v86 row_ror:8 row_mask:0xf bank_mask:0xf
	v_mov_b32_dpp v167, v87 row_ror:8 row_mask:0xf bank_mask:0xf
	v_cndmask_b32_e64 v84, v164, v88, s[90:91]
	v_cndmask_b32_e64 v85, v165, v89, s[90:91]
	v_cndmask_b32_e64 v86, v166, v90, s[90:91]
	v_cndmask_b32_e64 v87, v167, v91, s[90:91]
	v_cndmask_b32_e64 v88, v88, v164, s[90:91]
	v_cndmask_b32_e64 v89, v89, v165, s[90:91]
	v_cndmask_b32_e64 v90, v90, v166, s[90:91]
	v_cndmask_b32_e64 v91, v91, v167, s[90:91]
	s_lshl_b32 s94, s51, 8
	s_add_i32 s94, s94, 48
	s_lshl_b32 s94, s94, 14
	s_add_u32 s86, s48, s94
	s_addc_u32 s87, s49, 0
	s_lshl_b32 s94, s51, 8
	s_add_i32 s94, s94, 48
	s_lshl_b32 s94, s94, 13
	s_add_u32 s88, s12, s94
	s_addc_u32 s89, s13, 0
	s_lshl_b32 s94, s51, 8
	s_add_i32 s94, s94, 48
	s_lshl_b32 s94, s94, 8
	s_add_u32 s92, s22, s94
	s_addc_u32 s93, s23, 0
	s_waitcnt vmcnt(13)
	v_pk_add_f32 v[96:97], v[96:97], v[128:129]
	v_pk_add_f32 v[98:99], v[98:99], v[130:131]
	v_pk_add_f32 v[92:93], v[92:93], v[124:125]
	v_pk_add_f32 v[94:95], v[94:95], v[126:127]
	global_store_dwordx4 v193, v[96:99], s[86:87]
	global_store_dwordx4 v206, v[92:95], s[86:87]
	v_mul_f32_e32 v214, v96, v96
	v_fmac_f32_e32 v214, v97, v97
	v_fmac_f32_e32 v214, v98, v98
	v_fmac_f32_e32 v214, v99, v99
	v_mul_f32_e32 v215, v92, v92
	v_fmac_f32_e32 v215, v93, v93
	v_fmac_f32_e32 v215, v94, v94
	v_fmac_f32_e32 v215, v95, v95
	v_pk_mul_f32 v[164:165], v[96:97], v[148:149]
	v_pk_mul_f32 v[166:167], v[98:99], v[150:151]
	v_cvt_pk_bf16_f32 v168, v164, v165
	v_cvt_pk_bf16_f32 v169, v166, v167
	global_store_dwordx2 v207, v[168:169], s[88:89]
	v_pk_mul_f32 v[164:165], v[92:93], v[156:157]
	v_pk_mul_f32 v[166:167], v[94:95], v[158:159]
	v_cvt_pk_bf16_f32 v170, v164, v165
	v_cvt_pk_bf16_f32 v171, v166, v167
	global_store_dwordx2 v208, v[170:171], s[88:89]
	v_pk_add_f32 v[88:89], v[88:89], v[120:121]
	v_pk_add_f32 v[90:91], v[90:91], v[122:123]
	v_pk_add_f32 v[84:85], v[84:85], v[116:117]
	v_pk_add_f32 v[86:87], v[86:87], v[118:119]
	global_store_dwordx4 v193, v[88:91], s[86:87] offset:512
	global_store_dwordx4 v206, v[84:87], s[86:87] offset:512
	v_fmac_f32_e32 v214, v88, v88
	v_fmac_f32_e32 v214, v89, v89
	v_fmac_f32_e32 v214, v90, v90
	v_fmac_f32_e32 v214, v91, v91
	v_fmac_f32_e32 v215, v84, v84
	v_fmac_f32_e32 v215, v85, v85
	v_fmac_f32_e32 v215, v86, v86
	v_fmac_f32_e32 v215, v87, v87
	v_pk_mul_f32 v[164:165], v[88:89], v[152:153]
	v_pk_mul_f32 v[166:167], v[90:91], v[154:155]
	v_cvt_pk_bf16_f32 v168, v164, v165
	v_cvt_pk_bf16_f32 v169, v166, v167
	global_store_dwordx2 v207, v[168:169], s[88:89] offset:256
	v_pk_mul_f32 v[164:165], v[84:85], v[160:161]
	v_pk_mul_f32 v[166:167], v[86:87], v[162:163]
	v_cvt_pk_bf16_f32 v170, v164, v165
	v_cvt_pk_bf16_f32 v171, v166, v167
	global_store_dwordx2 v208, v[170:171], s[88:89] offset:256
	s_nop 1
	v_add_f32_dpp v180, v214, v214 row_ror:8 row_mask:0xf bank_mask:0xf
	v_add_f32_dpp v192, v215, v215 row_ror:8 row_mask:0xf bank_mask:0xf
	v_cndmask_b32_e64 v214, v180, v192, s[90:91]
	v_mov_b32_e32 v215, v214
	s_nop 1
	v_permlane16_swap_b32_e32 v214, v215
	v_add_f32_e32 v214, v214, v215
	v_mov_b32_e32 v215, v214
	s_nop 1
	v_permlane32_swap_b32_e32 v214, v215
	v_add_f32_e32 v214, v214, v215
	s_and_saveexec_b64 s[14:15], s[38:39]
	global_store_dword v211, v214, s[92:93]
	s_or_b64 exec, exec, s[14:15]
	s_lshl_b32 s94, s51, 8
	s_add_i32 s94, s94, 144
	s_lshl_b32 s94, s94, 14
	s_add_u32 s84, s48, s94
	s_addc_u32 s85, s49, 0
	global_load_dwordx4 v[96:99], v193, s[84:85]
	global_load_dwordx4 v[92:95], v206, s[84:85]
	global_load_dwordx4 v[88:91], v193, s[84:85] offset:512
	global_load_dwordx4 v[84:87], v206, s[84:85] offset:512
	v_mov_b32_dpp v164, v64 row_ror:8 row_mask:0xf bank_mask:0xf
	v_mov_b32_dpp v165, v65 row_ror:8 row_mask:0xf bank_mask:0xf
	v_mov_b32_dpp v166, v66 row_ror:8 row_mask:0xf bank_mask:0xf
	v_mov_b32_dpp v167, v67 row_ror:8 row_mask:0xf bank_mask:0xf
	v_cndmask_b32_e64 v64, v164, v72, s[90:91]
	v_cndmask_b32_e64 v65, v165, v73, s[90:91]
	v_cndmask_b32_e64 v66, v166, v74, s[90:91]
	v_cndmask_b32_e64 v67, v167, v75, s[90:91]
	v_cndmask_b32_e64 v72, v72, v164, s[90:91]
	v_cndmask_b32_e64 v73, v73, v165, s[90:91]
	v_cndmask_b32_e64 v74, v74, v166, s[90:91]
	v_cndmask_b32_e64 v75, v75, v167, s[90:91]
	v_mov_b32_dpp v164, v52 row_ror:8 row_mask:0xf bank_mask:0xf
	v_mov_b32_dpp v165, v53 row_ror:8 row_mask:0xf bank_mask:0xf
	v_mov_b32_dpp v166, v54 row_ror:8 row_mask:0xf bank_mask:0xf
	v_mov_b32_dpp v167, v55 row_ror:8 row_mask:0xf bank_mask:0xf
	v_cndmask_b32_e64 v52, v164, v56, s[90:91]
	v_cndmask_b32_e64 v53, v165, v57, s[90:91]
	v_cndmask_b32_e64 v54, v166, v58, s[90:91]
	v_cndmask_b32_e64 v55, v167, v59, s[90:91]
	v_cndmask_b32_e64 v56, v56, v164, s[90:91]
	v_cndmask_b32_e64 v57, v57, v165, s[90:91]
	v_cndmask_b32_e64 v58, v58, v166, s[90:91]
	v_cndmask_b32_e64 v59, v59, v167, s[90:91]
	s_lshl_b32 s94, s51, 8
	s_add_i32 s94, s94, 128
	s_lshl_b32 s94, s94, 14
	s_add_u32 s86, s48, s94
	s_addc_u32 s87, s49, 0
	s_lshl_b32 s94, s51, 8
	s_add_i32 s94, s94, 128
	s_lshl_b32 s94, s94, 13
	s_add_u32 s88, s12, s94
	s_addc_u32 s89, s13, 0
	s_lshl_b32 s94, s51, 8
	s_add_i32 s94, s94, 128
	s_lshl_b32 s94, s94, 8
	s_add_u32 s92, s22, s94
	s_addc_u32 s93, s23, 0
	s_waitcnt vmcnt(13)
	v_pk_add_f32 v[72:73], v[72:73], v[112:113]
	v_pk_add_f32 v[74:75], v[74:75], v[114:115]
	v_pk_add_f32 v[64:65], v[64:65], v[108:109]
	v_pk_add_f32 v[66:67], v[66:67], v[110:111]
	global_store_dwordx4 v193, v[72:75], s[86:87]
	global_store_dwordx4 v206, v[64:67], s[86:87]
	v_mul_f32_e32 v214, v72, v72
	v_fmac_f32_e32 v214, v73, v73
	v_fmac_f32_e32 v214, v74, v74
	v_fmac_f32_e32 v214, v75, v75
	v_mul_f32_e32 v215, v64, v64
	v_fmac_f32_e32 v215, v65, v65
	v_fmac_f32_e32 v215, v66, v66
	v_fmac_f32_e32 v215, v67, v67
	v_pk_mul_f32 v[164:165], v[72:73], v[148:149]
	v_pk_mul_f32 v[166:167], v[74:75], v[150:151]
	v_cvt_pk_bf16_f32 v168, v164, v165
	v_cvt_pk_bf16_f32 v169, v166, v167
	global_store_dwordx2 v207, v[168:169], s[88:89]
	v_pk_mul_f32 v[164:165], v[64:65], v[156:157]
	v_pk_mul_f32 v[166:167], v[66:67], v[158:159]
	v_cvt_pk_bf16_f32 v170, v164, v165
	v_cvt_pk_bf16_f32 v171, v166, v167
	global_store_dwordx2 v208, v[170:171], s[88:89]
	v_pk_add_f32 v[56:57], v[56:57], v[104:105]
	v_pk_add_f32 v[58:59], v[58:59], v[106:107]
	v_pk_add_f32 v[52:53], v[52:53], v[100:101]
	v_pk_add_f32 v[54:55], v[54:55], v[102:103]
	global_store_dwordx4 v193, v[56:59], s[86:87] offset:512
	global_store_dwordx4 v206, v[52:55], s[86:87] offset:512
	v_fmac_f32_e32 v214, v56, v56
	v_fmac_f32_e32 v214, v57, v57
	v_fmac_f32_e32 v214, v58, v58
	v_fmac_f32_e32 v214, v59, v59
	v_fmac_f32_e32 v215, v52, v52
	v_fmac_f32_e32 v215, v53, v53
	v_fmac_f32_e32 v215, v54, v54
	v_fmac_f32_e32 v215, v55, v55
	v_pk_mul_f32 v[164:165], v[56:57], v[152:153]
	v_pk_mul_f32 v[166:167], v[58:59], v[154:155]
	v_cvt_pk_bf16_f32 v168, v164, v165
	v_cvt_pk_bf16_f32 v169, v166, v167
	global_store_dwordx2 v207, v[168:169], s[88:89] offset:256
	v_pk_mul_f32 v[164:165], v[52:53], v[160:161]
	v_pk_mul_f32 v[166:167], v[54:55], v[162:163]
	v_cvt_pk_bf16_f32 v170, v164, v165
	v_cvt_pk_bf16_f32 v171, v166, v167
	global_store_dwordx2 v208, v[170:171], s[88:89] offset:256
	s_nop 1
	v_add_f32_dpp v180, v214, v214 row_ror:8 row_mask:0xf bank_mask:0xf
	v_add_f32_dpp v192, v215, v215 row_ror:8 row_mask:0xf bank_mask:0xf
	v_cndmask_b32_e64 v214, v180, v192, s[90:91]
	v_mov_b32_e32 v215, v214
	s_nop 1
	v_permlane16_swap_b32_e32 v214, v215
	v_add_f32_e32 v214, v214, v215
	v_mov_b32_e32 v215, v214
	s_nop 1
	v_permlane32_swap_b32_e32 v214, v215
	v_add_f32_e32 v214, v214, v215
	s_and_saveexec_b64 s[14:15], s[38:39]
	global_store_dword v211, v214, s[92:93]
	s_or_b64 exec, exec, s[14:15]
	s_lshl_b32 s94, s51, 8
	s_add_i32 s94, s94, 160
	s_lshl_b32 s94, s94, 14
	s_add_u32 s84, s48, s94
	s_addc_u32 s85, s49, 0
	global_load_dwordx4 v[72:75], v193, s[84:85]
	global_load_dwordx4 v[64:67], v206, s[84:85]
	global_load_dwordx4 v[56:59], v193, s[84:85] offset:512
	global_load_dwordx4 v[52:55], v206, s[84:85] offset:512
	v_mov_b32_dpp v164, v44 row_ror:8 row_mask:0xf bank_mask:0xf
	v_mov_b32_dpp v165, v45 row_ror:8 row_mask:0xf bank_mask:0xf
	v_mov_b32_dpp v166, v46 row_ror:8 row_mask:0xf bank_mask:0xf
	v_mov_b32_dpp v167, v47 row_ror:8 row_mask:0xf bank_mask:0xf
	v_cndmask_b32_e64 v44, v164, v48, s[90:91]
	v_cndmask_b32_e64 v45, v165, v49, s[90:91]
	v_cndmask_b32_e64 v46, v166, v50, s[90:91]
	v_cndmask_b32_e64 v47, v167, v51, s[90:91]
	v_cndmask_b32_e64 v48, v48, v164, s[90:91]
	v_cndmask_b32_e64 v49, v49, v165, s[90:91]
	v_cndmask_b32_e64 v50, v50, v166, s[90:91]
	v_cndmask_b32_e64 v51, v51, v167, s[90:91]
	v_mov_b32_dpp v164, v36 row_ror:8 row_mask:0xf bank_mask:0xf
	v_mov_b32_dpp v165, v37 row_ror:8 row_mask:0xf bank_mask:0xf
	v_mov_b32_dpp v166, v38 row_ror:8 row_mask:0xf bank_mask:0xf
	v_mov_b32_dpp v167, v39 row_ror:8 row_mask:0xf bank_mask:0xf
	v_cndmask_b32_e64 v36, v164, v40, s[90:91]
	v_cndmask_b32_e64 v37, v165, v41, s[90:91]
	v_cndmask_b32_e64 v38, v166, v42, s[90:91]
	v_cndmask_b32_e64 v39, v167, v43, s[90:91]
	v_cndmask_b32_e64 v40, v40, v164, s[90:91]
	v_cndmask_b32_e64 v41, v41, v165, s[90:91]
	v_cndmask_b32_e64 v42, v42, v166, s[90:91]
	v_cndmask_b32_e64 v43, v43, v167, s[90:91]
	s_lshl_b32 s94, s51, 8
	s_add_i32 s94, s94, 144
	s_lshl_b32 s94, s94, 14
	s_add_u32 s86, s48, s94
	s_addc_u32 s87, s49, 0
	s_lshl_b32 s94, s51, 8
	s_add_i32 s94, s94, 144
	s_lshl_b32 s94, s94, 13
	s_add_u32 s88, s12, s94
	s_addc_u32 s89, s13, 0
	s_lshl_b32 s94, s51, 8
	s_add_i32 s94, s94, 144
	s_lshl_b32 s94, s94, 8
	s_add_u32 s92, s22, s94
	s_addc_u32 s93, s23, 0
	s_waitcnt vmcnt(13)
	v_pk_add_f32 v[48:49], v[48:49], v[96:97]
	v_pk_add_f32 v[50:51], v[50:51], v[98:99]
	v_pk_add_f32 v[44:45], v[44:45], v[92:93]
	v_pk_add_f32 v[46:47], v[46:47], v[94:95]
	global_store_dwordx4 v193, v[48:51], s[86:87]
	global_store_dwordx4 v206, v[44:47], s[86:87]
	v_mul_f32_e32 v214, v48, v48
	v_fmac_f32_e32 v214, v49, v49
	v_fmac_f32_e32 v214, v50, v50
	v_fmac_f32_e32 v214, v51, v51
	v_mul_f32_e32 v215, v44, v44
	v_fmac_f32_e32 v215, v45, v45
	v_fmac_f32_e32 v215, v46, v46
	v_fmac_f32_e32 v215, v47, v47
	v_pk_mul_f32 v[164:165], v[48:49], v[148:149]
	v_pk_mul_f32 v[166:167], v[50:51], v[150:151]
	v_cvt_pk_bf16_f32 v168, v164, v165
	v_cvt_pk_bf16_f32 v169, v166, v167
	global_store_dwordx2 v207, v[168:169], s[88:89]
	v_pk_mul_f32 v[164:165], v[44:45], v[156:157]
	v_pk_mul_f32 v[166:167], v[46:47], v[158:159]
	v_cvt_pk_bf16_f32 v170, v164, v165
	v_cvt_pk_bf16_f32 v171, v166, v167
	global_store_dwordx2 v208, v[170:171], s[88:89]
	v_pk_add_f32 v[40:41], v[40:41], v[88:89]
	v_pk_add_f32 v[42:43], v[42:43], v[90:91]
	v_pk_add_f32 v[36:37], v[36:37], v[84:85]
	v_pk_add_f32 v[38:39], v[38:39], v[86:87]
	global_store_dwordx4 v193, v[40:43], s[86:87] offset:512
	global_store_dwordx4 v206, v[36:39], s[86:87] offset:512
	v_fmac_f32_e32 v214, v40, v40
	v_fmac_f32_e32 v214, v41, v41
	v_fmac_f32_e32 v214, v42, v42
	v_fmac_f32_e32 v214, v43, v43
	v_fmac_f32_e32 v215, v36, v36
	v_fmac_f32_e32 v215, v37, v37
	v_fmac_f32_e32 v215, v38, v38
	v_fmac_f32_e32 v215, v39, v39
	v_pk_mul_f32 v[164:165], v[40:41], v[152:153]
	v_pk_mul_f32 v[166:167], v[42:43], v[154:155]
	v_cvt_pk_bf16_f32 v168, v164, v165
	v_cvt_pk_bf16_f32 v169, v166, v167
	global_store_dwordx2 v207, v[168:169], s[88:89] offset:256
	v_pk_mul_f32 v[164:165], v[36:37], v[160:161]
	v_pk_mul_f32 v[166:167], v[38:39], v[162:163]
	v_cvt_pk_bf16_f32 v170, v164, v165
	v_cvt_pk_bf16_f32 v171, v166, v167
	global_store_dwordx2 v208, v[170:171], s[88:89] offset:256
	s_nop 1
	v_add_f32_dpp v180, v214, v214 row_ror:8 row_mask:0xf bank_mask:0xf
	v_add_f32_dpp v192, v215, v215 row_ror:8 row_mask:0xf bank_mask:0xf
	v_cndmask_b32_e64 v214, v180, v192, s[90:91]
	v_mov_b32_e32 v215, v214
	s_nop 1
	v_permlane16_swap_b32_e32 v214, v215
	v_add_f32_e32 v214, v214, v215
	v_mov_b32_e32 v215, v214
	s_nop 1
	v_permlane32_swap_b32_e32 v214, v215
	v_add_f32_e32 v214, v214, v215
	s_and_saveexec_b64 s[14:15], s[38:39]
	global_store_dword v211, v214, s[92:93]
	s_or_b64 exec, exec, s[14:15]
	s_lshl_b32 s94, s51, 8
	s_add_i32 s94, s94, 176
	s_lshl_b32 s94, s94, 14
	s_add_u32 s84, s48, s94
	s_addc_u32 s85, s49, 0
	global_load_dwordx4 v[48:51], v193, s[84:85]
	global_load_dwordx4 v[44:47], v206, s[84:85]
	global_load_dwordx4 v[40:43], v193, s[84:85] offset:512
	global_load_dwordx4 v[36:39], v206, s[84:85] offset:512
	v_mov_b32_dpp v164, v28 row_ror:8 row_mask:0xf bank_mask:0xf
	v_mov_b32_dpp v165, v29 row_ror:8 row_mask:0xf bank_mask:0xf
	v_mov_b32_dpp v166, v30 row_ror:8 row_mask:0xf bank_mask:0xf
	v_mov_b32_dpp v167, v31 row_ror:8 row_mask:0xf bank_mask:0xf
	v_cndmask_b32_e64 v28, v164, v32, s[90:91]
	v_cndmask_b32_e64 v29, v165, v33, s[90:91]
	v_cndmask_b32_e64 v30, v166, v34, s[90:91]
	v_cndmask_b32_e64 v31, v167, v35, s[90:91]
	v_cndmask_b32_e64 v32, v32, v164, s[90:91]
	v_cndmask_b32_e64 v33, v33, v165, s[90:91]
	v_cndmask_b32_e64 v34, v34, v166, s[90:91]
	v_cndmask_b32_e64 v35, v35, v167, s[90:91]
	v_mov_b32_dpp v164, v20 row_ror:8 row_mask:0xf bank_mask:0xf
	v_mov_b32_dpp v165, v21 row_ror:8 row_mask:0xf bank_mask:0xf
	v_mov_b32_dpp v166, v22 row_ror:8 row_mask:0xf bank_mask:0xf
	v_mov_b32_dpp v167, v23 row_ror:8 row_mask:0xf bank_mask:0xf
	v_cndmask_b32_e64 v20, v164, v24, s[90:91]
	v_cndmask_b32_e64 v21, v165, v25, s[90:91]
	v_cndmask_b32_e64 v22, v166, v26, s[90:91]
	v_cndmask_b32_e64 v23, v167, v27, s[90:91]
	v_cndmask_b32_e64 v24, v24, v164, s[90:91]
	v_cndmask_b32_e64 v25, v25, v165, s[90:91]
	v_cndmask_b32_e64 v26, v26, v166, s[90:91]
	v_cndmask_b32_e64 v27, v27, v167, s[90:91]
	s_lshl_b32 s94, s51, 8
	s_add_i32 s94, s94, 160
	s_lshl_b32 s94, s94, 14
	s_add_u32 s86, s48, s94
	s_addc_u32 s87, s49, 0
	s_lshl_b32 s94, s51, 8
	s_add_i32 s94, s94, 160
	s_lshl_b32 s94, s94, 13
	s_add_u32 s88, s12, s94
	s_addc_u32 s89, s13, 0
	s_lshl_b32 s94, s51, 8
	s_add_i32 s94, s94, 160
	s_lshl_b32 s94, s94, 8
	s_add_u32 s92, s22, s94
	s_addc_u32 s93, s23, 0
	s_waitcnt vmcnt(13)
	v_pk_add_f32 v[32:33], v[32:33], v[72:73]
	v_pk_add_f32 v[34:35], v[34:35], v[74:75]
	v_pk_add_f32 v[28:29], v[28:29], v[64:65]
	v_pk_add_f32 v[30:31], v[30:31], v[66:67]
	global_store_dwordx4 v193, v[32:35], s[86:87]
	global_store_dwordx4 v206, v[28:31], s[86:87]
	v_mul_f32_e32 v214, v32, v32
	v_fmac_f32_e32 v214, v33, v33
	v_fmac_f32_e32 v214, v34, v34
	v_fmac_f32_e32 v214, v35, v35
	v_mul_f32_e32 v215, v28, v28
	v_fmac_f32_e32 v215, v29, v29
	v_fmac_f32_e32 v215, v30, v30
	v_fmac_f32_e32 v215, v31, v31
	v_pk_mul_f32 v[164:165], v[32:33], v[148:149]
	v_pk_mul_f32 v[166:167], v[34:35], v[150:151]
	v_cvt_pk_bf16_f32 v168, v164, v165
	v_cvt_pk_bf16_f32 v169, v166, v167
	global_store_dwordx2 v207, v[168:169], s[88:89]
	v_pk_mul_f32 v[164:165], v[28:29], v[156:157]
	v_pk_mul_f32 v[166:167], v[30:31], v[158:159]
	v_cvt_pk_bf16_f32 v170, v164, v165
	v_cvt_pk_bf16_f32 v171, v166, v167
	global_store_dwordx2 v208, v[170:171], s[88:89]
	v_pk_add_f32 v[24:25], v[24:25], v[56:57]
	v_pk_add_f32 v[26:27], v[26:27], v[58:59]
	v_pk_add_f32 v[20:21], v[20:21], v[52:53]
	v_pk_add_f32 v[22:23], v[22:23], v[54:55]
	global_store_dwordx4 v193, v[24:27], s[86:87] offset:512
	global_store_dwordx4 v206, v[20:23], s[86:87] offset:512
	v_fmac_f32_e32 v214, v24, v24
	v_fmac_f32_e32 v214, v25, v25
	v_fmac_f32_e32 v214, v26, v26
	v_fmac_f32_e32 v214, v27, v27
	v_fmac_f32_e32 v215, v20, v20
	v_fmac_f32_e32 v215, v21, v21
	v_fmac_f32_e32 v215, v22, v22
	v_fmac_f32_e32 v215, v23, v23
	v_pk_mul_f32 v[164:165], v[24:25], v[152:153]
	v_pk_mul_f32 v[166:167], v[26:27], v[154:155]
	v_cvt_pk_bf16_f32 v168, v164, v165
	v_cvt_pk_bf16_f32 v169, v166, v167
	global_store_dwordx2 v207, v[168:169], s[88:89] offset:256
	v_pk_mul_f32 v[164:165], v[20:21], v[160:161]
	v_pk_mul_f32 v[166:167], v[22:23], v[162:163]
	v_cvt_pk_bf16_f32 v170, v164, v165
	v_cvt_pk_bf16_f32 v171, v166, v167
	global_store_dwordx2 v208, v[170:171], s[88:89] offset:256
	s_nop 1
	v_add_f32_dpp v180, v214, v214 row_ror:8 row_mask:0xf bank_mask:0xf
	v_add_f32_dpp v192, v215, v215 row_ror:8 row_mask:0xf bank_mask:0xf
	v_cndmask_b32_e64 v214, v180, v192, s[90:91]
	v_mov_b32_e32 v215, v214
	s_nop 1
	v_permlane16_swap_b32_e32 v214, v215
	v_add_f32_e32 v214, v214, v215
	v_mov_b32_e32 v215, v214
	s_nop 1
	v_permlane32_swap_b32_e32 v214, v215
	v_add_f32_e32 v214, v214, v215
	s_and_saveexec_b64 s[14:15], s[38:39]
	global_store_dword v211, v214, s[92:93]
	s_or_b64 exec, exec, s[14:15]
	v_mov_b32_dpp v164, v12 row_ror:8 row_mask:0xf bank_mask:0xf
	v_mov_b32_dpp v165, v13 row_ror:8 row_mask:0xf bank_mask:0xf
	v_mov_b32_dpp v166, v14 row_ror:8 row_mask:0xf bank_mask:0xf
	v_mov_b32_dpp v167, v15 row_ror:8 row_mask:0xf bank_mask:0xf
	v_cndmask_b32_e64 v12, v164, v16, s[90:91]
	v_cndmask_b32_e64 v13, v165, v17, s[90:91]
	v_cndmask_b32_e64 v14, v166, v18, s[90:91]
	v_cndmask_b32_e64 v15, v167, v19, s[90:91]
	v_cndmask_b32_e64 v16, v16, v164, s[90:91]
	v_cndmask_b32_e64 v17, v17, v165, s[90:91]
	v_cndmask_b32_e64 v18, v18, v166, s[90:91]
	v_cndmask_b32_e64 v19, v19, v167, s[90:91]
	v_mov_b32_dpp v164, v4 row_ror:8 row_mask:0xf bank_mask:0xf
	v_mov_b32_dpp v165, v5 row_ror:8 row_mask:0xf bank_mask:0xf
	v_mov_b32_dpp v166, v6 row_ror:8 row_mask:0xf bank_mask:0xf
	v_mov_b32_dpp v167, v7 row_ror:8 row_mask:0xf bank_mask:0xf
	v_cndmask_b32_e64 v4, v164, v8, s[90:91]
	v_cndmask_b32_e64 v5, v165, v9, s[90:91]
	v_cndmask_b32_e64 v6, v166, v10, s[90:91]
	v_cndmask_b32_e64 v7, v167, v11, s[90:91]
	v_cndmask_b32_e64 v8, v8, v164, s[90:91]
	v_cndmask_b32_e64 v9, v9, v165, s[90:91]
	v_cndmask_b32_e64 v10, v10, v166, s[90:91]
	v_cndmask_b32_e64 v11, v11, v167, s[90:91]
	s_lshl_b32 s94, s51, 8
	s_add_i32 s94, s94, 176
	s_lshl_b32 s94, s94, 14
	s_add_u32 s86, s48, s94
	s_addc_u32 s87, s49, 0
	s_lshl_b32 s94, s51, 8
	s_add_i32 s94, s94, 176
	s_lshl_b32 s94, s94, 13
	s_add_u32 s88, s12, s94
	s_addc_u32 s89, s13, 0
	s_lshl_b32 s94, s51, 8
	s_add_i32 s94, s94, 176
	s_lshl_b32 s94, s94, 8
	s_add_u32 s92, s22, s94
	s_addc_u32 s93, s23, 0
	s_waitcnt vmcnt(9)
	v_pk_add_f32 v[16:17], v[16:17], v[48:49]
	v_pk_add_f32 v[18:19], v[18:19], v[50:51]
	v_pk_add_f32 v[12:13], v[12:13], v[44:45]
	v_pk_add_f32 v[14:15], v[14:15], v[46:47]
	global_store_dwordx4 v193, v[16:19], s[86:87]
	global_store_dwordx4 v206, v[12:15], s[86:87]
	v_mul_f32_e32 v214, v16, v16
	v_fmac_f32_e32 v214, v17, v17
	v_fmac_f32_e32 v214, v18, v18
	v_fmac_f32_e32 v214, v19, v19
	v_mul_f32_e32 v215, v12, v12
	v_fmac_f32_e32 v215, v13, v13
	v_fmac_f32_e32 v215, v14, v14
	v_fmac_f32_e32 v215, v15, v15
	v_pk_mul_f32 v[164:165], v[16:17], v[148:149]
	v_pk_mul_f32 v[166:167], v[18:19], v[150:151]
	v_cvt_pk_bf16_f32 v168, v164, v165
	v_cvt_pk_bf16_f32 v169, v166, v167
	global_store_dwordx2 v207, v[168:169], s[88:89]
	v_pk_mul_f32 v[164:165], v[12:13], v[156:157]
	v_pk_mul_f32 v[166:167], v[14:15], v[158:159]
	v_cvt_pk_bf16_f32 v170, v164, v165
	v_cvt_pk_bf16_f32 v171, v166, v167
	global_store_dwordx2 v208, v[170:171], s[88:89]
	v_pk_add_f32 v[8:9], v[8:9], v[40:41]
	v_pk_add_f32 v[10:11], v[10:11], v[42:43]
	v_pk_add_f32 v[4:5], v[4:5], v[36:37]
	v_pk_add_f32 v[6:7], v[6:7], v[38:39]
	global_store_dwordx4 v193, v[8:11], s[86:87] offset:512
	global_store_dwordx4 v206, v[4:7], s[86:87] offset:512
	v_fmac_f32_e32 v214, v8, v8
	v_fmac_f32_e32 v214, v9, v9
	v_fmac_f32_e32 v214, v10, v10
	v_fmac_f32_e32 v214, v11, v11
	v_fmac_f32_e32 v215, v4, v4
	v_fmac_f32_e32 v215, v5, v5
	v_fmac_f32_e32 v215, v6, v6
	v_fmac_f32_e32 v215, v7, v7
	v_pk_mul_f32 v[164:165], v[8:9], v[152:153]
	v_pk_mul_f32 v[166:167], v[10:11], v[154:155]
	v_cvt_pk_bf16_f32 v168, v164, v165
	v_cvt_pk_bf16_f32 v169, v166, v167
	global_store_dwordx2 v207, v[168:169], s[88:89] offset:256
	v_pk_mul_f32 v[164:165], v[4:5], v[160:161]
	v_pk_mul_f32 v[166:167], v[6:7], v[162:163]
	v_cvt_pk_bf16_f32 v170, v164, v165
	v_cvt_pk_bf16_f32 v171, v166, v167
	global_store_dwordx2 v208, v[170:171], s[88:89] offset:256
	s_nop 1
	v_add_f32_dpp v180, v214, v214 row_ror:8 row_mask:0xf bank_mask:0xf
	v_add_f32_dpp v192, v215, v215 row_ror:8 row_mask:0xf bank_mask:0xf
	v_cndmask_b32_e64 v214, v180, v192, s[90:91]
	v_mov_b32_e32 v215, v214
	s_nop 1
	v_permlane16_swap_b32_e32 v214, v215
	v_add_f32_e32 v214, v214, v215
	v_mov_b32_e32 v215, v214
	s_nop 1
	v_permlane32_swap_b32_e32 v214, v215
	v_add_f32_e32 v214, v214, v215
	s_and_saveexec_b64 s[14:15], s[38:39]
	global_store_dword v211, v214, s[92:93]
	s_or_b64 exec, exec, s[14:15]
	s_branch .Lrot_p8x_end
.Lrot_p8x_1:
	v_and_b32_e32 v192, 8, v219
	v_cmp_ne_u32_e64 s[90:91], 0, v192
	v_sub_u32_e32 v214, v1, v192
	v_lshlrev_b32_e32 v192, 1, v192
	s_lshl_b32 s94, s50, 8
	v_add3_u32 v215, v240, v192, s94
	v_sub_u32_e32 v180, v240, v192
	v_add3_u32 v180, v180, 16, s94
	v_lshlrev_b32_e32 v193, 14, v214
	v_lshl_add_u32 v206, v180, 2, v193
	v_add_u32_e32 v206, 0x20000, v206
	v_lshl_add_u32 v193, v215, 2, v193
	v_lshlrev_b32_e32 v207, 13, v214
	v_lshl_add_u32 v208, v180, 1, v207
	v_add_u32_e32 v208, 0x10000, v208
	v_lshl_add_u32 v207, v215, 1, v207
	v_lshlrev_b32_e32 v209, 2, v215
	v_lshlrev_b32_e32 v210, 2, v180
	global_load_dwordx4 v[148:151], v209, s[16:17]
	global_load_dwordx4 v[156:159], v210, s[16:17]
	global_load_dwordx4 v[152:155], v209, s[16:17] offset:512
	global_load_dwordx4 v[160:163], v210, s[16:17] offset:512
	s_lshl_b32 s94, s50, 4
	s_lshl_b32 s95, s34, 2
	s_add_i32 s94, s94, s95
	v_lshlrev_b32_e32 v211, 8, v1
	v_add_u32_e32 v211, s94, v211
	v_xor_b32_e32 v212, 16, v219
	v_lshlrev_b32_e32 v212, 2, v212
	v_xor_b32_e32 v213, 32, v219
	v_lshlrev_b32_e32 v213, 2, v213
	s_lshl_b32 s94, s51, 8
	s_add_i32 s94, s94, 16
	s_lshl_b32 s94, s94, 14
	s_add_u32 s84, s48, s94
	s_addc_u32 s85, s49, 0
	global_load_dwordx4 v[60:63], v193, s[84:85]
	global_load_dwordx4 v[68:71], v206, s[84:85]
	global_load_dwordx4 v[76:79], v193, s[84:85] offset:512
	global_load_dwordx4 v[80:83], v206, s[84:85] offset:512
	s_lshl_b32 s94, s51, 8
	s_add_i32 s94, s94, 32
	s_lshl_b32 s94, s94, 14
	s_add_u32 s84, s48, s94
	s_addc_u32 s85, s49, 0
	global_load_dwordx4 v[172:175], v193, s[84:85]
	global_load_dwordx4 v[176:179], v206, s[84:85]
	global_load_dwordx4 v[182:185], v193, s[84:85] offset:512
	global_load_dwordx4 v[232:235], v206, s[84:85] offset:512
	v_mov_b32_dpp v164, v124 row_ror:8 row_mask:0xf bank_mask:0xf
	v_mov_b32_dpp v165, v125 row_ror:8 row_mask:0xf bank_mask:0xf
	v_mov_b32_dpp v166, v126 row_ror:8 row_mask:0xf bank_mask:0xf
	v_mov_b32_dpp v167, v127 row_ror:8 row_mask:0xf bank_mask:0xf
	v_cndmask_b32_e64 v124, v164, v128, s[90:91]
	v_cndmask_b32_e64 v125, v165, v129, s[90:91]
	v_cndmask_b32_e64 v126, v166, v130, s[90:91]
	v_cndmask_b32_e64 v127, v167, v131, s[90:91]
	v_cndmask_b32_e64 v128, v128, v164, s[90:91]
	v_cndmask_b32_e64 v129, v129, v165, s[90:91]
	v_cndmask_b32_e64 v130, v130, v166, s[90:91]
	v_cndmask_b32_e64 v131, v131, v167, s[90:91]
	v_mov_b32_dpp v164, v116 row_ror:8 row_mask:0xf bank_mask:0xf
	v_mov_b32_dpp v165, v117 row_ror:8 row_mask:0xf bank_mask:0xf
	v_mov_b32_dpp v166, v118 row_ror:8 row_mask:0xf bank_mask:0xf
	v_mov_b32_dpp v167, v119 row_ror:8 row_mask:0xf bank_mask:0xf
	v_cndmask_b32_e64 v116, v164, v120, s[90:91]
	v_cndmask_b32_e64 v117, v165, v121, s[90:91]
	v_cndmask_b32_e64 v118, v166, v122, s[90:91]
	v_cndmask_b32_e64 v119, v167, v123, s[90:91]
	v_cndmask_b32_e64 v120, v120, v164, s[90:91]
	v_cndmask_b32_e64 v121, v121, v165, s[90:91]
	v_cndmask_b32_e64 v122, v122, v166, s[90:91]
	v_cndmask_b32_e64 v123, v123, v167, s[90:91]
	s_lshl_b32 s94, s51, 8
	s_add_i32 s94, s94, 16
	s_lshl_b32 s94, s94, 14
	s_add_u32 s86, s48, s94
	s_addc_u32 s87, s49, 0
	s_lshl_b32 s94, s51, 8
	s_add_i32 s94, s94, 16
	s_lshl_b32 s94, s94, 13
	s_add_u32 s88, s12, s94
	s_addc_u32 s89, s13, 0
	s_lshl_b32 s94, s51, 8
	s_add_i32 s94, s94, 16
	s_lshl_b32 s94, s94, 8
	s_add_u32 s92, s22, s94
	s_addc_u32 s93, s23, 0
	s_waitcnt vmcnt(4)
	v_pk_add_f32 v[128:129], v[128:129], v[60:61]
	v_pk_add_f32 v[130:131], v[130:131], v[62:63]
	v_pk_add_f32 v[124:125], v[124:125], v[68:69]
	v_pk_add_f32 v[126:127], v[126:127], v[70:71]
	global_store_dwordx4 v193, v[128:131], s[86:87]
	global_store_dwordx4 v206, v[124:127], s[86:87]
	v_mul_f32_e32 v214, v128, v128
	v_fmac_f32_e32 v214, v129, v129
	v_fmac_f32_e32 v214, v130, v130
	v_fmac_f32_e32 v214, v131, v131
	v_mul_f32_e32 v215, v124, v124
	v_fmac_f32_e32 v215, v125, v125
	v_fmac_f32_e32 v215, v126, v126
	v_fmac_f32_e32 v215, v127, v127
	v_pk_mul_f32 v[164:165], v[128:129], v[148:149]
	v_pk_mul_f32 v[166:167], v[130:131], v[150:151]
	v_cvt_pk_bf16_f32 v168, v164, v165
	v_cvt_pk_bf16_f32 v169, v166, v167
	global_store_dwordx2 v207, v[168:169], s[88:89]
	v_pk_mul_f32 v[164:165], v[124:125], v[156:157]
	v_pk_mul_f32 v[166:167], v[126:127], v[158:159]
	v_cvt_pk_bf16_f32 v170, v164, v165
	v_cvt_pk_bf16_f32 v171, v166, v167
	global_store_dwordx2 v208, v[170:171], s[88:89]
	v_pk_add_f32 v[120:121], v[120:121], v[76:77]
	v_pk_add_f32 v[122:123], v[122:123], v[78:79]
	v_pk_add_f32 v[116:117], v[116:117], v[80:81]
	v_pk_add_f32 v[118:119], v[118:119], v[82:83]
	global_store_dwordx4 v193, v[120:123], s[86:87] offset:512
	global_store_dwordx4 v206, v[116:119], s[86:87] offset:512
	v_fmac_f32_e32 v214, v120, v120
	v_fmac_f32_e32 v214, v121, v121
	v_fmac_f32_e32 v214, v122, v122
	v_fmac_f32_e32 v214, v123, v123
	v_fmac_f32_e32 v215, v116, v116
	v_fmac_f32_e32 v215, v117, v117
	v_fmac_f32_e32 v215, v118, v118
	v_fmac_f32_e32 v215, v119, v119
	v_pk_mul_f32 v[164:165], v[120:121], v[152:153]
	v_pk_mul_f32 v[166:167], v[122:123], v[154:155]
	v_cvt_pk_bf16_f32 v168, v164, v165
	v_cvt_pk_bf16_f32 v169, v166, v167
	global_store_dwordx2 v207, v[168:169], s[88:89] offset:256
	v_pk_mul_f32 v[164:165], v[116:117], v[160:161]
	v_pk_mul_f32 v[166:167], v[118:119], v[162:163]
	v_cvt_pk_bf16_f32 v170, v164, v165
	v_cvt_pk_bf16_f32 v171, v166, v167
	global_store_dwordx2 v208, v[170:171], s[88:89] offset:256
	s_nop 1
	v_add_f32_dpp v180, v214, v214 row_ror:8 row_mask:0xf bank_mask:0xf
	v_add_f32_dpp v192, v215, v215 row_ror:8 row_mask:0xf bank_mask:0xf
	v_cndmask_b32_e64 v214, v180, v192, s[90:91]
	v_mov_b32_e32 v215, v214
	s_nop 1
	v_permlane16_swap_b32_e32 v214, v215
	v_add_f32_e32 v214, v214, v215
	v_mov_b32_e32 v215, v214
	s_nop 1
	v_permlane32_swap_b32_e32 v214, v215
	v_add_f32_e32 v214, v214, v215
	s_and_saveexec_b64 s[14:15], s[38:39]
	global_store_dword v211, v214, s[92:93]
	s_or_b64 exec, exec, s[14:15]
	s_lshl_b32 s94, s51, 8
	s_add_i32 s94, s94, 48
	s_lshl_b32 s94, s94, 14
	s_add_u32 s84, s48, s94
	s_addc_u32 s85, s49, 0
	global_load_dwordx4 v[128:131], v193, s[84:85]
	global_load_dwordx4 v[124:127], v206, s[84:85]
	global_load_dwordx4 v[120:123], v193, s[84:85] offset:512
	global_load_dwordx4 v[116:119], v206, s[84:85] offset:512
	v_mov_b32_dpp v164, v108 row_ror:8 row_mask:0xf bank_mask:0xf
	v_mov_b32_dpp v165, v109 row_ror:8 row_mask:0xf bank_mask:0xf
	v_mov_b32_dpp v166, v110 row_ror:8 row_mask:0xf bank_mask:0xf
	v_mov_b32_dpp v167, v111 row_ror:8 row_mask:0xf bank_mask:0xf
	v_cndmask_b32_e64 v108, v164, v112, s[90:91]
	v_cndmask_b32_e64 v109, v165, v113, s[90:91]
	v_cndmask_b32_e64 v110, v166, v114, s[90:91]
	v_cndmask_b32_e64 v111, v167, v115, s[90:91]
	v_cndmask_b32_e64 v112, v112, v164, s[90:91]
	v_cndmask_b32_e64 v113, v113, v165, s[90:91]
	v_cndmask_b32_e64 v114, v114, v166, s[90:91]
	v_cndmask_b32_e64 v115, v115, v167, s[90:91]
	v_mov_b32_dpp v164, v100 row_ror:8 row_mask:0xf bank_mask:0xf
	v_mov_b32_dpp v165, v101 row_ror:8 row_mask:0xf bank_mask:0xf
	v_mov_b32_dpp v166, v102 row_ror:8 row_mask:0xf bank_mask:0xf
	v_mov_b32_dpp v167, v103 row_ror:8 row_mask:0xf bank_mask:0xf
	v_cndmask_b32_e64 v100, v164, v104, s[90:91]
	v_cndmask_b32_e64 v101, v165, v105, s[90:91]
	v_cndmask_b32_e64 v102, v166, v106, s[90:91]
	v_cndmask_b32_e64 v103, v167, v107, s[90:91]
	v_cndmask_b32_e64 v104, v104, v164, s[90:91]
	v_cndmask_b32_e64 v105, v105, v165, s[90:91]
	v_cndmask_b32_e64 v106, v106, v166, s[90:91]
	v_cndmask_b32_e64 v107, v107, v167, s[90:91]
	s_lshl_b32 s94, s51, 8
	s_add_i32 s94, s94, 32
	s_lshl_b32 s94, s94, 14
	s_add_u32 s86, s48, s94
	s_addc_u32 s87, s49, 0
	s_lshl_b32 s94, s51, 8
	s_add_i32 s94, s94, 32
	s_lshl_b32 s94, s94, 13
	s_add_u32 s88, s12, s94
	s_addc_u32 s89, s13, 0
	s_lshl_b32 s94, s51, 8
	s_add_i32 s94, s94, 32
	s_lshl_b32 s94, s94, 8
	s_add_u32 s92, s22, s94
	s_addc_u32 s93, s23, 0
	s_waitcnt vmcnt(13)
	v_pk_add_f32 v[112:113], v[112:113], v[172:173]
	v_pk_add_f32 v[114:115], v[114:115], v[174:175]
	v_pk_add_f32 v[108:109], v[108:109], v[176:177]
	v_pk_add_f32 v[110:111], v[110:111], v[178:179]
	global_store_dwordx4 v193, v[112:115], s[86:87]
	global_store_dwordx4 v206, v[108:111], s[86:87]
	v_mul_f32_e32 v214, v112, v112
	v_fmac_f32_e32 v214, v113, v113
	v_fmac_f32_e32 v214, v114, v114
	v_fmac_f32_e32 v214, v115, v115
	v_mul_f32_e32 v215, v108, v108
	v_fmac_f32_e32 v215, v109, v109
	v_fmac_f32_e32 v215, v110, v110
	v_fmac_f32_e32 v215, v111, v111
	v_pk_mul_f32 v[164:165], v[112:113], v[148:149]
	v_pk_mul_f32 v[166:167], v[114:115], v[150:151]
	v_cvt_pk_bf16_f32 v168, v164, v165
	v_cvt_pk_bf16_f32 v169, v166, v167
	global_store_dwordx2 v207, v[168:169], s[88:89]
	v_pk_mul_f32 v[164:165], v[108:109], v[156:157]
	v_pk_mul_f32 v[166:167], v[110:111], v[158:159]
	v_cvt_pk_bf16_f32 v170, v164, v165
	v_cvt_pk_bf16_f32 v171, v166, v167
	global_store_dwordx2 v208, v[170:171], s[88:89]
	v_pk_add_f32 v[104:105], v[104:105], v[182:183]
	v_pk_add_f32 v[106:107], v[106:107], v[184:185]
	v_pk_add_f32 v[100:101], v[100:101], v[232:233]
	v_pk_add_f32 v[102:103], v[102:103], v[234:235]
	global_store_dwordx4 v193, v[104:107], s[86:87] offset:512
	global_store_dwordx4 v206, v[100:103], s[86:87] offset:512
	v_fmac_f32_e32 v214, v104, v104
	v_fmac_f32_e32 v214, v105, v105
	v_fmac_f32_e32 v214, v106, v106
	v_fmac_f32_e32 v214, v107, v107
	v_fmac_f32_e32 v215, v100, v100
	v_fmac_f32_e32 v215, v101, v101
	v_fmac_f32_e32 v215, v102, v102
	v_fmac_f32_e32 v215, v103, v103
	v_pk_mul_f32 v[164:165], v[104:105], v[152:153]
	v_pk_mul_f32 v[166:167], v[106:107], v[154:155]
	v_cvt_pk_bf16_f32 v168, v164, v165
	v_cvt_pk_bf16_f32 v169, v166, v167
	global_store_dwordx2 v207, v[168:169], s[88:89] offset:256
	v_pk_mul_f32 v[164:165], v[100:101], v[160:161]
	v_pk_mul_f32 v[166:167], v[102:103], v[162:163]
	v_cvt_pk_bf16_f32 v170, v164, v165
	v_cvt_pk_bf16_f32 v171, v166, v167
	global_store_dwordx2 v208, v[170:171], s[88:89] offset:256
	s_nop 1
	v_add_f32_dpp v180, v214, v214 row_ror:8 row_mask:0xf bank_mask:0xf
	v_add_f32_dpp v192, v215, v215 row_ror:8 row_mask:0xf bank_mask:0xf
	v_cndmask_b32_e64 v214, v180, v192, s[90:91]
	v_mov_b32_e32 v215, v214
	s_nop 1
	v_permlane16_swap_b32_e32 v214, v215
	v_add_f32_e32 v214, v214, v215
	v_mov_b32_e32 v215, v214
	s_nop 1
	v_permlane32_swap_b32_e32 v214, v215
	v_add_f32_e32 v214, v214, v215
	s_and_saveexec_b64 s[14:15], s[38:39]
	global_store_dword v211, v214, s[92:93]
	s_or_b64 exec, exec, s[14:15]
	s_lshl_b32 s94, s51, 8
	s_lshl_b32 s94, s94, 14
	s_add_u32 s84, s48, s94
	s_addc_u32 s85, s49, 0
	global_load_dwordx4 v[112:115], v193, s[84:85]
	global_load_dwordx4 v[108:111], v206, s[84:85]
	global_load_dwordx4 v[104:107], v193, s[84:85] offset:512
	global_load_dwordx4 v[100:103], v206, s[84:85] offset:512
	v_mov_b32_dpp v164, v92 row_ror:8 row_mask:0xf bank_mask:0xf
	v_mov_b32_dpp v165, v93 row_ror:8 row_mask:0xf bank_mask:0xf
	v_mov_b32_dpp v166, v94 row_ror:8 row_mask:0xf bank_mask:0xf
	v_mov_b32_dpp v167, v95 row_ror:8 row_mask:0xf bank_mask:0xf
	v_cndmask_b32_e64 v92, v164, v96, s[90:91]
	v_cndmask_b32_e64 v93, v165, v97, s[90:91]
	v_cndmask_b32_e64 v94, v166, v98, s[90:91]
	v_cndmask_b32_e64 v95, v167, v99, s[90:91]
	v_cndmask_b32_e64 v96, v96, v164, s[90:91]
	v_cndmask_b32_e64 v97, v97, v165, s[90:91]
	v_cndmask_b32_e64 v98, v98, v166, s[90:91]
	v_cndmask_b32_e64 v99, v99, v167, s[90:91]
	v_mov_b32_dpp v164, v84 row_ror:8 row_mask:0xf bank_mask:0xf
	v_mov_b32_dpp v165, v85 row_ror:8 row_mask:0xf bank_mask:0xf
	v_mov_b32_dpp v166, v86 row_ror:8 row_mask:0xf bank_mask:0xf
	v_mov_b32_dpp v167, v87 row_ror:8 row_mask:0xf bank_mask:0xf
	v_cndmask_b32_e64 v84, v164, v88, s[90:91]
	v_cndmask_b32_e64 v85, v165, v89, s[90:91]
	v_cndmask_b32_e64 v86, v166, v90, s[90:91]
	v_cndmask_b32_e64 v87, v167, v91, s[90:91]
	v_cndmask_b32_e64 v88, v88, v164, s[90:91]
	v_cndmask_b32_e64 v89, v89, v165, s[90:91]
	v_cndmask_b32_e64 v90, v90, v166, s[90:91]
	v_cndmask_b32_e64 v91, v91, v167, s[90:91]
	s_lshl_b32 s94, s51, 8
	s_add_i32 s94, s94, 48
	s_lshl_b32 s94, s94, 14
	s_add_u32 s86, s48, s94
	s_addc_u32 s87, s49, 0
	s_lshl_b32 s94, s51, 8
	s_add_i32 s94, s94, 48
	s_lshl_b32 s94, s94, 13
	s_add_u32 s88, s12, s94
	s_addc_u32 s89, s13, 0
	s_lshl_b32 s94, s51, 8
	s_add_i32 s94, s94, 48
	s_lshl_b32 s94, s94, 8
	s_add_u32 s92, s22, s94
	s_addc_u32 s93, s23, 0
	s_waitcnt vmcnt(13)
	v_pk_add_f32 v[96:97], v[96:97], v[128:129]
	v_pk_add_f32 v[98:99], v[98:99], v[130:131]
	v_pk_add_f32 v[92:93], v[92:93], v[124:125]
	v_pk_add_f32 v[94:95], v[94:95], v[126:127]
	global_store_dwordx4 v193, v[96:99], s[86:87]
	global_store_dwordx4 v206, v[92:95], s[86:87]
	v_mul_f32_e32 v214, v96, v96
	v_fmac_f32_e32 v214, v97, v97
	v_fmac_f32_e32 v214, v98, v98
	v_fmac_f32_e32 v214, v99, v99
	v_mul_f32_e32 v215, v92, v92
	v_fmac_f32_e32 v215, v93, v93
	v_fmac_f32_e32 v215, v94, v94
	v_fmac_f32_e32 v215, v95, v95
	v_pk_mul_f32 v[164:165], v[96:97], v[148:149]
	v_pk_mul_f32 v[166:167], v[98:99], v[150:151]
	v_cvt_pk_bf16_f32 v168, v164, v165
	v_cvt_pk_bf16_f32 v169, v166, v167
	global_store_dwordx2 v207, v[168:169], s[88:89]
	v_pk_mul_f32 v[164:165], v[92:93], v[156:157]
	v_pk_mul_f32 v[166:167], v[94:95], v[158:159]
	v_cvt_pk_bf16_f32 v170, v164, v165
	v_cvt_pk_bf16_f32 v171, v166, v167
	global_store_dwordx2 v208, v[170:171], s[88:89]
	v_pk_add_f32 v[88:89], v[88:89], v[120:121]
	v_pk_add_f32 v[90:91], v[90:91], v[122:123]
	v_pk_add_f32 v[84:85], v[84:85], v[116:117]
	v_pk_add_f32 v[86:87], v[86:87], v[118:119]
	global_store_dwordx4 v193, v[88:91], s[86:87] offset:512
	global_store_dwordx4 v206, v[84:87], s[86:87] offset:512
	v_fmac_f32_e32 v214, v88, v88
	v_fmac_f32_e32 v214, v89, v89
	v_fmac_f32_e32 v214, v90, v90
	v_fmac_f32_e32 v214, v91, v91
	v_fmac_f32_e32 v215, v84, v84
	v_fmac_f32_e32 v215, v85, v85
	v_fmac_f32_e32 v215, v86, v86
	v_fmac_f32_e32 v215, v87, v87
	v_pk_mul_f32 v[164:165], v[88:89], v[152:153]
	v_pk_mul_f32 v[166:167], v[90:91], v[154:155]
	v_cvt_pk_bf16_f32 v168, v164, v165
	v_cvt_pk_bf16_f32 v169, v166, v167
	global_store_dwordx2 v207, v[168:169], s[88:89] offset:256
	v_pk_mul_f32 v[164:165], v[84:85], v[160:161]
	v_pk_mul_f32 v[166:167], v[86:87], v[162:163]
	v_cvt_pk_bf16_f32 v170, v164, v165
	v_cvt_pk_bf16_f32 v171, v166, v167
	global_store_dwordx2 v208, v[170:171], s[88:89] offset:256
	s_nop 1
	v_add_f32_dpp v180, v214, v214 row_ror:8 row_mask:0xf bank_mask:0xf
	v_add_f32_dpp v192, v215, v215 row_ror:8 row_mask:0xf bank_mask:0xf
	v_cndmask_b32_e64 v214, v180, v192, s[90:91]
	v_mov_b32_e32 v215, v214
	s_nop 1
	v_permlane16_swap_b32_e32 v214, v215
	v_add_f32_e32 v214, v214, v215
	v_mov_b32_e32 v215, v214
	s_nop 1
	v_permlane32_swap_b32_e32 v214, v215
	v_add_f32_e32 v214, v214, v215
	s_and_saveexec_b64 s[14:15], s[38:39]
	global_store_dword v211, v214, s[92:93]
	s_or_b64 exec, exec, s[14:15]
	s_lshl_b32 s94, s51, 8
	s_add_i32 s94, s94, 144
	s_lshl_b32 s94, s94, 14
	s_add_u32 s84, s48, s94
	s_addc_u32 s85, s49, 0
	global_load_dwordx4 v[96:99], v193, s[84:85]
	global_load_dwordx4 v[92:95], v206, s[84:85]
	global_load_dwordx4 v[88:91], v193, s[84:85] offset:512
	global_load_dwordx4 v[84:87], v206, s[84:85] offset:512
	v_mov_b32_dpp v164, v140 row_ror:8 row_mask:0xf bank_mask:0xf
	v_mov_b32_dpp v165, v141 row_ror:8 row_mask:0xf bank_mask:0xf
	v_mov_b32_dpp v166, v142 row_ror:8 row_mask:0xf bank_mask:0xf
	v_mov_b32_dpp v167, v143 row_ror:8 row_mask:0xf bank_mask:0xf
	v_cndmask_b32_e64 v140, v164, v144, s[90:91]
	v_cndmask_b32_e64 v141, v165, v145, s[90:91]
	v_cndmask_b32_e64 v142, v166, v146, s[90:91]
	v_cndmask_b32_e64 v143, v167, v147, s[90:91]
	v_cndmask_b32_e64 v144, v144, v164, s[90:91]
	v_cndmask_b32_e64 v145, v145, v165, s[90:91]
	v_cndmask_b32_e64 v146, v146, v166, s[90:91]
	v_cndmask_b32_e64 v147, v147, v167, s[90:91]
	v_mov_b32_dpp v164, v132 row_ror:8 row_mask:0xf bank_mask:0xf
	v_mov_b32_dpp v165, v133 row_ror:8 row_mask:0xf bank_mask:0xf
	v_mov_b32_dpp v166, v134 row_ror:8 row_mask:0xf bank_mask:0xf
	v_mov_b32_dpp v167, v135 row_ror:8 row_mask:0xf bank_mask:0xf
	v_cndmask_b32_e64 v132, v164, v136, s[90:91]
	v_cndmask_b32_e64 v133, v165, v137, s[90:91]
	v_cndmask_b32_e64 v134, v166, v138, s[90:91]
	v_cndmask_b32_e64 v135, v167, v139, s[90:91]
	v_cndmask_b32_e64 v136, v136, v164, s[90:91]
	v_cndmask_b32_e64 v137, v137, v165, s[90:91]
	v_cndmask_b32_e64 v138, v138, v166, s[90:91]
	v_cndmask_b32_e64 v139, v139, v167, s[90:91]
	s_lshl_b32 s94, s51, 8
	s_lshl_b32 s94, s94, 14
	s_add_u32 s86, s48, s94
	s_addc_u32 s87, s49, 0
	s_lshl_b32 s94, s51, 8
	s_lshl_b32 s94, s94, 13
	s_add_u32 s88, s12, s94
	s_addc_u32 s89, s13, 0
	s_lshl_b32 s94, s51, 8
	s_lshl_b32 s94, s94, 8
	s_add_u32 s92, s22, s94
	s_addc_u32 s93, s23, 0
	s_waitcnt vmcnt(13)
	v_pk_add_f32 v[144:145], v[144:145], v[112:113]
	v_pk_add_f32 v[146:147], v[146:147], v[114:115]
	v_pk_add_f32 v[140:141], v[140:141], v[108:109]
	v_pk_add_f32 v[142:143], v[142:143], v[110:111]
	global_store_dwordx4 v193, v[144:147], s[86:87]
	global_store_dwordx4 v206, v[140:143], s[86:87]
	v_mul_f32_e32 v214, v144, v144
	v_fmac_f32_e32 v214, v145, v145
	v_fmac_f32_e32 v214, v146, v146
	v_fmac_f32_e32 v214, v147, v147
	v_mul_f32_e32 v215, v140, v140
	v_fmac_f32_e32 v215, v141, v141
	v_fmac_f32_e32 v215, v142, v142
	v_fmac_f32_e32 v215, v143, v143
	v_pk_mul_f32 v[164:165], v[144:145], v[148:149]
	v_pk_mul_f32 v[166:167], v[146:147], v[150:151]
	v_cvt_pk_bf16_f32 v168, v164, v165
	v_cvt_pk_bf16_f32 v169, v166, v167
	global_store_dwordx2 v207, v[168:169], s[88:89]
	v_pk_mul_f32 v[164:165], v[140:141], v[156:157]
	v_pk_mul_f32 v[166:167], v[142:143], v[158:159]
	v_cvt_pk_bf16_f32 v170, v164, v165
	v_cvt_pk_bf16_f32 v171, v166, v167
	global_store_dwordx2 v208, v[170:171], s[88:89]
	v_pk_add_f32 v[136:137], v[136:137], v[104:105]
	v_pk_add_f32 v[138:139], v[138:139], v[106:107]
	v_pk_add_f32 v[132:133], v[132:133], v[100:101]
	v_pk_add_f32 v[134:135], v[134:135], v[102:103]
	global_store_dwordx4 v193, v[136:139], s[86:87] offset:512
	global_store_dwordx4 v206, v[132:135], s[86:87] offset:512
	v_fmac_f32_e32 v214, v136, v136
	v_fmac_f32_e32 v214, v137, v137
	v_fmac_f32_e32 v214, v138, v138
	v_fmac_f32_e32 v214, v139, v139
	v_fmac_f32_e32 v215, v132, v132
	v_fmac_f32_e32 v215, v133, v133
	v_fmac_f32_e32 v215, v134, v134
	v_fmac_f32_e32 v215, v135, v135
	v_pk_mul_f32 v[164:165], v[136:137], v[152:153]
	v_pk_mul_f32 v[166:167], v[138:139], v[154:155]
	v_cvt_pk_bf16_f32 v168, v164, v165
	v_cvt_pk_bf16_f32 v169, v166, v167
	global_store_dwordx2 v207, v[168:169], s[88:89] offset:256
	v_pk_mul_f32 v[164:165], v[132:133], v[160:161]
	v_pk_mul_f32 v[166:167], v[134:135], v[162:163]
	v_cvt_pk_bf16_f32 v170, v164, v165
	v_cvt_pk_bf16_f32 v171, v166, v167
	global_store_dwordx2 v208, v[170:171], s[88:89] offset:256
	s_nop 1
	v_add_f32_dpp v180, v214, v214 row_ror:8 row_mask:0xf bank_mask:0xf
	v_add_f32_dpp v192, v215, v215 row_ror:8 row_mask:0xf bank_mask:0xf
	v_cndmask_b32_e64 v214, v180, v192, s[90:91]
	v_mov_b32_e32 v215, v214
	s_nop 1
	v_permlane16_swap_b32_e32 v214, v215
	v_add_f32_e32 v214, v214, v215
	v_mov_b32_e32 v215, v214
	s_nop 1
	v_permlane32_swap_b32_e32 v214, v215
	v_add_f32_e32 v214, v214, v215
	s_and_saveexec_b64 s[14:15], s[38:39]
	global_store_dword v211, v214, s[92:93]
	s_or_b64 exec, exec, s[14:15]
	s_lshl_b32 s94, s51, 8
	s_add_i32 s94, s94, 160
	s_lshl_b32 s94, s94, 14
	s_add_u32 s84, s48, s94
	s_addc_u32 s85, s49, 0
	global_load_dwordx4 v[144:147], v193, s[84:85]
	global_load_dwordx4 v[140:143], v206, s[84:85]
	global_load_dwordx4 v[136:139], v193, s[84:85] offset:512
	global_load_dwordx4 v[132:135], v206, s[84:85] offset:512
	v_mov_b32_dpp v164, v44 row_ror:8 row_mask:0xf bank_mask:0xf
	v_mov_b32_dpp v165, v45 row_ror:8 row_mask:0xf bank_mask:0xf
	v_mov_b32_dpp v166, v46 row_ror:8 row_mask:0xf bank_mask:0xf
	v_mov_b32_dpp v167, v47 row_ror:8 row_mask:0xf bank_mask:0xf
	v_cndmask_b32_e64 v44, v164, v48, s[90:91]
	v_cndmask_b32_e64 v45, v165, v49, s[90:91]
	v_cndmask_b32_e64 v46, v166, v50, s[90:91]
	v_cndmask_b32_e64 v47, v167, v51, s[90:91]
	v_cndmask_b32_e64 v48, v48, v164, s[90:91]
	v_cndmask_b32_e64 v49, v49, v165, s[90:91]
	v_cndmask_b32_e64 v50, v50, v166, s[90:91]
	v_cndmask_b32_e64 v51, v51, v167, s[90:91]
	v_mov_b32_dpp v164, v36 row_ror:8 row_mask:0xf bank_mask:0xf
	v_mov_b32_dpp v165, v37 row_ror:8 row_mask:0xf bank_mask:0xf
	v_mov_b32_dpp v166, v38 row_ror:8 row_mask:0xf bank_mask:0xf
	v_mov_b32_dpp v167, v39 row_ror:8 row_mask:0xf bank_mask:0xf
	v_cndmask_b32_e64 v36, v164, v40, s[90:91]
	v_cndmask_b32_e64 v37, v165, v41, s[90:91]
	v_cndmask_b32_e64 v38, v166, v42, s[90:91]
	v_cndmask_b32_e64 v39, v167, v43, s[90:91]
	v_cndmask_b32_e64 v40, v40, v164, s[90:91]
	v_cndmask_b32_e64 v41, v41, v165, s[90:91]
	v_cndmask_b32_e64 v42, v42, v166, s[90:91]
	v_cndmask_b32_e64 v43, v43, v167, s[90:91]
	s_lshl_b32 s94, s51, 8
	s_add_i32 s94, s94, 144
	s_lshl_b32 s94, s94, 14
	s_add_u32 s86, s48, s94
	s_addc_u32 s87, s49, 0
	s_lshl_b32 s94, s51, 8
	s_add_i32 s94, s94, 144
	s_lshl_b32 s94, s94, 13
	s_add_u32 s88, s12, s94
	s_addc_u32 s89, s13, 0
	s_lshl_b32 s94, s51, 8
	s_add_i32 s94, s94, 144
	s_lshl_b32 s94, s94, 8
	s_add_u32 s92, s22, s94
	s_addc_u32 s93, s23, 0
	s_waitcnt vmcnt(13)
	v_pk_add_f32 v[48:49], v[48:49], v[96:97]
	v_pk_add_f32 v[50:51], v[50:51], v[98:99]
	v_pk_add_f32 v[44:45], v[44:45], v[92:93]
	v_pk_add_f32 v[46:47], v[46:47], v[94:95]
	global_store_dwordx4 v193, v[48:51], s[86:87]
	global_store_dwordx4 v206, v[44:47], s[86:87]
	v_mul_f32_e32 v214, v48, v48
	v_fmac_f32_e32 v214, v49, v49
	v_fmac_f32_e32 v214, v50, v50
	v_fmac_f32_e32 v214, v51, v51
	v_mul_f32_e32 v215, v44, v44
	v_fmac_f32_e32 v215, v45, v45
	v_fmac_f32_e32 v215, v46, v46
	v_fmac_f32_e32 v215, v47, v47
	v_pk_mul_f32 v[164:165], v[48:49], v[148:149]
	v_pk_mul_f32 v[166:167], v[50:51], v[150:151]
	v_cvt_pk_bf16_f32 v168, v164, v165
	v_cvt_pk_bf16_f32 v169, v166, v167
	global_store_dwordx2 v207, v[168:169], s[88:89]
	v_pk_mul_f32 v[164:165], v[44:45], v[156:157]
	v_pk_mul_f32 v[166:167], v[46:47], v[158:159]
	v_cvt_pk_bf16_f32 v170, v164, v165
	v_cvt_pk_bf16_f32 v171, v166, v167
	global_store_dwordx2 v208, v[170:171], s[88:89]
	v_pk_add_f32 v[40:41], v[40:41], v[88:89]
	v_pk_add_f32 v[42:43], v[42:43], v[90:91]
	v_pk_add_f32 v[36:37], v[36:37], v[84:85]
	v_pk_add_f32 v[38:39], v[38:39], v[86:87]
	global_store_dwordx4 v193, v[40:43], s[86:87] offset:512
	global_store_dwordx4 v206, v[36:39], s[86:87] offset:512
	v_fmac_f32_e32 v214, v40, v40
	v_fmac_f32_e32 v214, v41, v41
	v_fmac_f32_e32 v214, v42, v42
	v_fmac_f32_e32 v214, v43, v43
	v_fmac_f32_e32 v215, v36, v36
	v_fmac_f32_e32 v215, v37, v37
	v_fmac_f32_e32 v215, v38, v38
	v_fmac_f32_e32 v215, v39, v39
	v_pk_mul_f32 v[164:165], v[40:41], v[152:153]
	v_pk_mul_f32 v[166:167], v[42:43], v[154:155]
	v_cvt_pk_bf16_f32 v168, v164, v165
	v_cvt_pk_bf16_f32 v169, v166, v167
	global_store_dwordx2 v207, v[168:169], s[88:89] offset:256
	v_pk_mul_f32 v[164:165], v[36:37], v[160:161]
	v_pk_mul_f32 v[166:167], v[38:39], v[162:163]
	v_cvt_pk_bf16_f32 v170, v164, v165
	v_cvt_pk_bf16_f32 v171, v166, v167
	global_store_dwordx2 v208, v[170:171], s[88:89] offset:256
	s_nop 1
	v_add_f32_dpp v180, v214, v214 row_ror:8 row_mask:0xf bank_mask:0xf
	v_add_f32_dpp v192, v215, v215 row_ror:8 row_mask:0xf bank_mask:0xf
	v_cndmask_b32_e64 v214, v180, v192, s[90:91]
	v_mov_b32_e32 v215, v214
	s_nop 1
	v_permlane16_swap_b32_e32 v214, v215
	v_add_f32_e32 v214, v214, v215
	v_mov_b32_e32 v215, v214
	s_nop 1
	v_permlane32_swap_b32_e32 v214, v215
	v_add_f32_e32 v214, v214, v215
	s_and_saveexec_b64 s[14:15], s[38:39]
	global_store_dword v211, v214, s[92:93]
	s_or_b64 exec, exec, s[14:15]
	s_lshl_b32 s94, s51, 8
	s_add_i32 s94, s94, 176
	s_lshl_b32 s94, s94, 14
	s_add_u32 s84, s48, s94
	s_addc_u32 s85, s49, 0
	global_load_dwordx4 v[48:51], v193, s[84:85]
	global_load_dwordx4 v[44:47], v206, s[84:85]
	global_load_dwordx4 v[40:43], v193, s[84:85] offset:512
	global_load_dwordx4 v[36:39], v206, s[84:85] offset:512
	v_mov_b32_dpp v164, v28 row_ror:8 row_mask:0xf bank_mask:0xf
	v_mov_b32_dpp v165, v29 row_ror:8 row_mask:0xf bank_mask:0xf
	v_mov_b32_dpp v166, v30 row_ror:8 row_mask:0xf bank_mask:0xf
	v_mov_b32_dpp v167, v31 row_ror:8 row_mask:0xf bank_mask:0xf
	v_cndmask_b32_e64 v28, v164, v32, s[90:91]
	v_cndmask_b32_e64 v29, v165, v33, s[90:91]
	v_cndmask_b32_e64 v30, v166, v34, s[90:91]
	v_cndmask_b32_e64 v31, v167, v35, s[90:91]
	v_cndmask_b32_e64 v32, v32, v164, s[90:91]
	v_cndmask_b32_e64 v33, v33, v165, s[90:91]
	v_cndmask_b32_e64 v34, v34, v166, s[90:91]
	v_cndmask_b32_e64 v35, v35, v167, s[90:91]
	v_mov_b32_dpp v164, v20 row_ror:8 row_mask:0xf bank_mask:0xf
	v_mov_b32_dpp v165, v21 row_ror:8 row_mask:0xf bank_mask:0xf
	v_mov_b32_dpp v166, v22 row_ror:8 row_mask:0xf bank_mask:0xf
	v_mov_b32_dpp v167, v23 row_ror:8 row_mask:0xf bank_mask:0xf
	v_cndmask_b32_e64 v20, v164, v24, s[90:91]
	v_cndmask_b32_e64 v21, v165, v25, s[90:91]
	v_cndmask_b32_e64 v22, v166, v26, s[90:91]
	v_cndmask_b32_e64 v23, v167, v27, s[90:91]
	v_cndmask_b32_e64 v24, v24, v164, s[90:91]
	v_cndmask_b32_e64 v25, v25, v165, s[90:91]
	v_cndmask_b32_e64 v26, v26, v166, s[90:91]
	v_cndmask_b32_e64 v27, v27, v167, s[90:91]
	s_lshl_b32 s94, s51, 8
	s_add_i32 s94, s94, 160
	s_lshl_b32 s94, s94, 14
	s_add_u32 s86, s48, s94
	s_addc_u32 s87, s49, 0
	s_lshl_b32 s94, s51, 8
	s_add_i32 s94, s94, 160
	s_lshl_b32 s94, s94, 13
	s_add_u32 s88, s12, s94
	s_addc_u32 s89, s13, 0
	s_lshl_b32 s94, s51, 8
	s_add_i32 s94, s94, 160
	s_lshl_b32 s94, s94, 8
	s_add_u32 s92, s22, s94
	s_addc_u32 s93, s23, 0
	s_waitcnt vmcnt(13)
	v_pk_add_f32 v[32:33], v[32:33], v[144:145]
	v_pk_add_f32 v[34:35], v[34:35], v[146:147]
	v_pk_add_f32 v[28:29], v[28:29], v[140:141]
	v_pk_add_f32 v[30:31], v[30:31], v[142:143]
	global_store_dwordx4 v193, v[32:35], s[86:87]
	global_store_dwordx4 v206, v[28:31], s[86:87]
	v_mul_f32_e32 v214, v32, v32
	v_fmac_f32_e32 v214, v33, v33
	v_fmac_f32_e32 v214, v34, v34
	v_fmac_f32_e32 v214, v35, v35
	v_mul_f32_e32 v215, v28, v28
	v_fmac_f32_e32 v215, v29, v29
	v_fmac_f32_e32 v215, v30, v30
	v_fmac_f32_e32 v215, v31, v31
	v_pk_mul_f32 v[164:165], v[32:33], v[148:149]
	v_pk_mul_f32 v[166:167], v[34:35], v[150:151]
	v_cvt_pk_bf16_f32 v168, v164, v165
	v_cvt_pk_bf16_f32 v169, v166, v167
	global_store_dwordx2 v207, v[168:169], s[88:89]
	v_pk_mul_f32 v[164:165], v[28:29], v[156:157]
	v_pk_mul_f32 v[166:167], v[30:31], v[158:159]
	v_cvt_pk_bf16_f32 v170, v164, v165
	v_cvt_pk_bf16_f32 v171, v166, v167
	global_store_dwordx2 v208, v[170:171], s[88:89]
	v_pk_add_f32 v[24:25], v[24:25], v[136:137]
	v_pk_add_f32 v[26:27], v[26:27], v[138:139]
	v_pk_add_f32 v[20:21], v[20:21], v[132:133]
	v_pk_add_f32 v[22:23], v[22:23], v[134:135]
	global_store_dwordx4 v193, v[24:27], s[86:87] offset:512
	global_store_dwordx4 v206, v[20:23], s[86:87] offset:512
	v_fmac_f32_e32 v214, v24, v24
	v_fmac_f32_e32 v214, v25, v25
	v_fmac_f32_e32 v214, v26, v26
	v_fmac_f32_e32 v214, v27, v27
	v_fmac_f32_e32 v215, v20, v20
	v_fmac_f32_e32 v215, v21, v21
	v_fmac_f32_e32 v215, v22, v22
	v_fmac_f32_e32 v215, v23, v23
	v_pk_mul_f32 v[164:165], v[24:25], v[152:153]
	v_pk_mul_f32 v[166:167], v[26:27], v[154:155]
	v_cvt_pk_bf16_f32 v168, v164, v165
	v_cvt_pk_bf16_f32 v169, v166, v167
	global_store_dwordx2 v207, v[168:169], s[88:89] offset:256
	v_pk_mul_f32 v[164:165], v[20:21], v[160:161]
	v_pk_mul_f32 v[166:167], v[22:23], v[162:163]
	v_cvt_pk_bf16_f32 v170, v164, v165
	v_cvt_pk_bf16_f32 v171, v166, v167
	global_store_dwordx2 v208, v[170:171], s[88:89] offset:256
	s_nop 1
	v_add_f32_dpp v180, v214, v214 row_ror:8 row_mask:0xf bank_mask:0xf
	v_add_f32_dpp v192, v215, v215 row_ror:8 row_mask:0xf bank_mask:0xf
	v_cndmask_b32_e64 v214, v180, v192, s[90:91]
	v_mov_b32_e32 v215, v214
	s_nop 1
	v_permlane16_swap_b32_e32 v214, v215
	v_add_f32_e32 v214, v214, v215
	v_mov_b32_e32 v215, v214
	s_nop 1
	v_permlane32_swap_b32_e32 v214, v215
	v_add_f32_e32 v214, v214, v215
	s_and_saveexec_b64 s[14:15], s[38:39]
	global_store_dword v211, v214, s[92:93]
	s_or_b64 exec, exec, s[14:15]
	s_lshl_b32 s94, s51, 8
	s_add_i32 s94, s94, 128
	s_lshl_b32 s94, s94, 14
	s_add_u32 s84, s48, s94
	s_addc_u32 s85, s49, 0
	global_load_dwordx4 v[32:35], v193, s[84:85]
	global_load_dwordx4 v[28:31], v206, s[84:85]
	global_load_dwordx4 v[24:27], v193, s[84:85] offset:512
	global_load_dwordx4 v[20:23], v206, s[84:85] offset:512
	v_mov_b32_dpp v164, v12 row_ror:8 row_mask:0xf bank_mask:0xf
	v_mov_b32_dpp v165, v13 row_ror:8 row_mask:0xf bank_mask:0xf
	v_mov_b32_dpp v166, v14 row_ror:8 row_mask:0xf bank_mask:0xf
	v_mov_b32_dpp v167, v15 row_ror:8 row_mask:0xf bank_mask:0xf
	v_cndmask_b32_e64 v12, v164, v16, s[90:91]
	v_cndmask_b32_e64 v13, v165, v17, s[90:91]
	v_cndmask_b32_e64 v14, v166, v18, s[90:91]
	v_cndmask_b32_e64 v15, v167, v19, s[90:91]
	v_cndmask_b32_e64 v16, v16, v164, s[90:91]
	v_cndmask_b32_e64 v17, v17, v165, s[90:91]
	v_cndmask_b32_e64 v18, v18, v166, s[90:91]
	v_cndmask_b32_e64 v19, v19, v167, s[90:91]
	v_mov_b32_dpp v164, v4 row_ror:8 row_mask:0xf bank_mask:0xf
	v_mov_b32_dpp v165, v5 row_ror:8 row_mask:0xf bank_mask:0xf
	v_mov_b32_dpp v166, v6 row_ror:8 row_mask:0xf bank_mask:0xf
	v_mov_b32_dpp v167, v7 row_ror:8 row_mask:0xf bank_mask:0xf
	v_cndmask_b32_e64 v4, v164, v8, s[90:91]
	v_cndmask_b32_e64 v5, v165, v9, s[90:91]
	v_cndmask_b32_e64 v6, v166, v10, s[90:91]
	v_cndmask_b32_e64 v7, v167, v11, s[90:91]
	v_cndmask_b32_e64 v8, v8, v164, s[90:91]
	v_cndmask_b32_e64 v9, v9, v165, s[90:91]
	v_cndmask_b32_e64 v10, v10, v166, s[90:91]
	v_cndmask_b32_e64 v11, v11, v167, s[90:91]
	s_lshl_b32 s94, s51, 8
	s_add_i32 s94, s94, 176
	s_lshl_b32 s94, s94, 14
	s_add_u32 s86, s48, s94
	s_addc_u32 s87, s49, 0
	s_lshl_b32 s94, s51, 8
	s_add_i32 s94, s94, 176
	s_lshl_b32 s94, s94, 13
	s_add_u32 s88, s12, s94
	s_addc_u32 s89, s13, 0
	s_lshl_b32 s94, s51, 8
	s_add_i32 s94, s94, 176
	s_lshl_b32 s94, s94, 8
	s_add_u32 s92, s22, s94
	s_addc_u32 s93, s23, 0
	s_waitcnt vmcnt(13)
	v_pk_add_f32 v[16:17], v[16:17], v[48:49]
	v_pk_add_f32 v[18:19], v[18:19], v[50:51]
	v_pk_add_f32 v[12:13], v[12:13], v[44:45]
	v_pk_add_f32 v[14:15], v[14:15], v[46:47]
	global_store_dwordx4 v193, v[16:19], s[86:87]
	global_store_dwordx4 v206, v[12:15], s[86:87]
	v_mul_f32_e32 v214, v16, v16
	v_fmac_f32_e32 v214, v17, v17
	v_fmac_f32_e32 v214, v18, v18
	v_fmac_f32_e32 v214, v19, v19
	v_mul_f32_e32 v215, v12, v12
	v_fmac_f32_e32 v215, v13, v13
	v_fmac_f32_e32 v215, v14, v14
	v_fmac_f32_e32 v215, v15, v15
	v_pk_mul_f32 v[164:165], v[16:17], v[148:149]
	v_pk_mul_f32 v[166:167], v[18:19], v[150:151]
	v_cvt_pk_bf16_f32 v168, v164, v165
	v_cvt_pk_bf16_f32 v169, v166, v167
	global_store_dwordx2 v207, v[168:169], s[88:89]
	v_pk_mul_f32 v[164:165], v[12:13], v[156:157]
	v_pk_mul_f32 v[166:167], v[14:15], v[158:159]
	v_cvt_pk_bf16_f32 v170, v164, v165
	v_cvt_pk_bf16_f32 v171, v166, v167
	global_store_dwordx2 v208, v[170:171], s[88:89]
	v_pk_add_f32 v[8:9], v[8:9], v[40:41]
	v_pk_add_f32 v[10:11], v[10:11], v[42:43]
	v_pk_add_f32 v[4:5], v[4:5], v[36:37]
	v_pk_add_f32 v[6:7], v[6:7], v[38:39]
	global_store_dwordx4 v193, v[8:11], s[86:87] offset:512
	global_store_dwordx4 v206, v[4:7], s[86:87] offset:512
	v_fmac_f32_e32 v214, v8, v8
	v_fmac_f32_e32 v214, v9, v9
	v_fmac_f32_e32 v214, v10, v10
	v_fmac_f32_e32 v214, v11, v11
	v_fmac_f32_e32 v215, v4, v4
	v_fmac_f32_e32 v215, v5, v5
	v_fmac_f32_e32 v215, v6, v6
	v_fmac_f32_e32 v215, v7, v7
	v_pk_mul_f32 v[164:165], v[8:9], v[152:153]
	v_pk_mul_f32 v[166:167], v[10:11], v[154:155]
	v_cvt_pk_bf16_f32 v168, v164, v165
	v_cvt_pk_bf16_f32 v169, v166, v167
	global_store_dwordx2 v207, v[168:169], s[88:89] offset:256
	v_pk_mul_f32 v[164:165], v[4:5], v[160:161]
	v_pk_mul_f32 v[166:167], v[6:7], v[162:163]
	v_cvt_pk_bf16_f32 v170, v164, v165
	v_cvt_pk_bf16_f32 v171, v166, v167
	global_store_dwordx2 v208, v[170:171], s[88:89] offset:256
	s_nop 1
	v_add_f32_dpp v180, v214, v214 row_ror:8 row_mask:0xf bank_mask:0xf
	v_add_f32_dpp v192, v215, v215 row_ror:8 row_mask:0xf bank_mask:0xf
	v_cndmask_b32_e64 v214, v180, v192, s[90:91]
	v_mov_b32_e32 v215, v214
	s_nop 1
	v_permlane16_swap_b32_e32 v214, v215
	v_add_f32_e32 v214, v214, v215
	v_mov_b32_e32 v215, v214
	s_nop 1
	v_permlane32_swap_b32_e32 v214, v215
	v_add_f32_e32 v214, v214, v215
	s_and_saveexec_b64 s[14:15], s[38:39]
	global_store_dword v211, v214, s[92:93]
	s_or_b64 exec, exec, s[14:15]
	v_mov_b32_dpp v164, v64 row_ror:8 row_mask:0xf bank_mask:0xf
	v_mov_b32_dpp v165, v65 row_ror:8 row_mask:0xf bank_mask:0xf
	v_mov_b32_dpp v166, v66 row_ror:8 row_mask:0xf bank_mask:0xf
	v_mov_b32_dpp v167, v67 row_ror:8 row_mask:0xf bank_mask:0xf
	v_cndmask_b32_e64 v64, v164, v72, s[90:91]
	v_cndmask_b32_e64 v65, v165, v73, s[90:91]
	v_cndmask_b32_e64 v66, v166, v74, s[90:91]
	v_cndmask_b32_e64 v67, v167, v75, s[90:91]
	v_cndmask_b32_e64 v72, v72, v164, s[90:91]
	v_cndmask_b32_e64 v73, v73, v165, s[90:91]
	v_cndmask_b32_e64 v74, v74, v166, s[90:91]
	v_cndmask_b32_e64 v75, v75, v167, s[90:91]
	v_mov_b32_dpp v164, v52 row_ror:8 row_mask:0xf bank_mask:0xf
	v_mov_b32_dpp v165, v53 row_ror:8 row_mask:0xf bank_mask:0xf
	v_mov_b32_dpp v166, v54 row_ror:8 row_mask:0xf bank_mask:0xf
	v_mov_b32_dpp v167, v55 row_ror:8 row_mask:0xf bank_mask:0xf
	v_cndmask_b32_e64 v52, v164, v56, s[90:91]
	v_cndmask_b32_e64 v53, v165, v57, s[90:91]
	v_cndmask_b32_e64 v54, v166, v58, s[90:91]
	v_cndmask_b32_e64 v55, v167, v59, s[90:91]
	v_cndmask_b32_e64 v56, v56, v164, s[90:91]
	v_cndmask_b32_e64 v57, v57, v165, s[90:91]
	v_cndmask_b32_e64 v58, v58, v166, s[90:91]
	v_cndmask_b32_e64 v59, v59, v167, s[90:91]
	s_lshl_b32 s94, s51, 8
	s_add_i32 s94, s94, 128
	s_lshl_b32 s94, s94, 14
	s_add_u32 s86, s48, s94
	s_addc_u32 s87, s49, 0
	s_lshl_b32 s94, s51, 8
	s_add_i32 s94, s94, 128
	s_lshl_b32 s94, s94, 13
	s_add_u32 s88, s12, s94
	s_addc_u32 s89, s13, 0
	s_lshl_b32 s94, s51, 8
	s_add_i32 s94, s94, 128
	s_lshl_b32 s94, s94, 8
	s_add_u32 s92, s22, s94
	s_addc_u32 s93, s23, 0
	s_waitcnt vmcnt(9)
	v_pk_add_f32 v[72:73], v[72:73], v[32:33]
	v_pk_add_f32 v[74:75], v[74:75], v[34:35]
	v_pk_add_f32 v[64:65], v[64:65], v[28:29]
	v_pk_add_f32 v[66:67], v[66:67], v[30:31]
	global_store_dwordx4 v193, v[72:75], s[86:87]
	global_store_dwordx4 v206, v[64:67], s[86:87]
	v_mul_f32_e32 v214, v72, v72
	v_fmac_f32_e32 v214, v73, v73
	v_fmac_f32_e32 v214, v74, v74
	v_fmac_f32_e32 v214, v75, v75
	v_mul_f32_e32 v215, v64, v64
	v_fmac_f32_e32 v215, v65, v65
	v_fmac_f32_e32 v215, v66, v66
	v_fmac_f32_e32 v215, v67, v67
	v_pk_mul_f32 v[164:165], v[72:73], v[148:149]
	v_pk_mul_f32 v[166:167], v[74:75], v[150:151]
	v_cvt_pk_bf16_f32 v168, v164, v165
	v_cvt_pk_bf16_f32 v169, v166, v167
	global_store_dwordx2 v207, v[168:169], s[88:89]
	v_pk_mul_f32 v[164:165], v[64:65], v[156:157]
	v_pk_mul_f32 v[166:167], v[66:67], v[158:159]
	v_cvt_pk_bf16_f32 v170, v164, v165
	v_cvt_pk_bf16_f32 v171, v166, v167
	global_store_dwordx2 v208, v[170:171], s[88:89]
	v_pk_add_f32 v[56:57], v[56:57], v[24:25]
	v_pk_add_f32 v[58:59], v[58:59], v[26:27]
	v_pk_add_f32 v[52:53], v[52:53], v[20:21]
	v_pk_add_f32 v[54:55], v[54:55], v[22:23]
	global_store_dwordx4 v193, v[56:59], s[86:87] offset:512
	global_store_dwordx4 v206, v[52:55], s[86:87] offset:512
	v_fmac_f32_e32 v214, v56, v56
	v_fmac_f32_e32 v214, v57, v57
	v_fmac_f32_e32 v214, v58, v58
	v_fmac_f32_e32 v214, v59, v59
	v_fmac_f32_e32 v215, v52, v52
	v_fmac_f32_e32 v215, v53, v53
	v_fmac_f32_e32 v215, v54, v54
	v_fmac_f32_e32 v215, v55, v55
	v_pk_mul_f32 v[164:165], v[56:57], v[152:153]
	v_pk_mul_f32 v[166:167], v[58:59], v[154:155]
	v_cvt_pk_bf16_f32 v168, v164, v165
	v_cvt_pk_bf16_f32 v169, v166, v167
	global_store_dwordx2 v207, v[168:169], s[88:89] offset:256
	v_pk_mul_f32 v[164:165], v[52:53], v[160:161]
	v_pk_mul_f32 v[166:167], v[54:55], v[162:163]
	v_cvt_pk_bf16_f32 v170, v164, v165
	v_cvt_pk_bf16_f32 v171, v166, v167
	global_store_dwordx2 v208, v[170:171], s[88:89] offset:256
	s_nop 1
	v_add_f32_dpp v180, v214, v214 row_ror:8 row_mask:0xf bank_mask:0xf
	v_add_f32_dpp v192, v215, v215 row_ror:8 row_mask:0xf bank_mask:0xf
	v_cndmask_b32_e64 v214, v180, v192, s[90:91]
	v_mov_b32_e32 v215, v214
	s_nop 1
	v_permlane16_swap_b32_e32 v214, v215
	v_add_f32_e32 v214, v214, v215
	v_mov_b32_e32 v215, v214
	s_nop 1
	v_permlane32_swap_b32_e32 v214, v215
	v_add_f32_e32 v214, v214, v215
	s_and_saveexec_b64 s[14:15], s[38:39]
	global_store_dword v211, v214, s[92:93]
	s_or_b64 exec, exec, s[14:15]
	s_branch .Lrot_p8x_end
.Lrot_p8x_2:
	v_and_b32_e32 v192, 8, v219
	v_cmp_ne_u32_e64 s[90:91], 0, v192
	v_sub_u32_e32 v214, v1, v192
	v_lshlrev_b32_e32 v192, 1, v192
	s_lshl_b32 s94, s50, 8
	v_add3_u32 v215, v240, v192, s94
	v_sub_u32_e32 v180, v240, v192
	v_add3_u32 v180, v180, 16, s94
	v_lshlrev_b32_e32 v193, 14, v214
	v_lshl_add_u32 v206, v180, 2, v193
	v_add_u32_e32 v206, 0x20000, v206
	v_lshl_add_u32 v193, v215, 2, v193
	v_lshlrev_b32_e32 v207, 13, v214
	v_lshl_add_u32 v208, v180, 1, v207
	v_add_u32_e32 v208, 0x10000, v208
	v_lshl_add_u32 v207, v215, 1, v207
	v_lshlrev_b32_e32 v209, 2, v215
	v_lshlrev_b32_e32 v210, 2, v180
	global_load_dwordx4 v[148:151], v209, s[16:17]
	global_load_dwordx4 v[156:159], v210, s[16:17]
	global_load_dwordx4 v[152:155], v209, s[16:17] offset:512
	global_load_dwordx4 v[160:163], v210, s[16:17] offset:512
	s_lshl_b32 s94, s50, 4
	s_lshl_b32 s95, s34, 2
	s_add_i32 s94, s94, s95
	v_lshlrev_b32_e32 v211, 8, v1
	v_add_u32_e32 v211, s94, v211
	v_xor_b32_e32 v212, 16, v219
	v_lshlrev_b32_e32 v212, 2, v212
	v_xor_b32_e32 v213, 32, v219
	v_lshlrev_b32_e32 v213, 2, v213
	s_lshl_b32 s94, s51, 8
	s_add_i32 s94, s94, 32
	s_lshl_b32 s94, s94, 14
	s_add_u32 s84, s48, s94
	s_addc_u32 s85, s49, 0
	global_load_dwordx4 v[60:63], v193, s[84:85]
	global_load_dwordx4 v[68:71], v206, s[84:85]
	global_load_dwordx4 v[76:79], v193, s[84:85] offset:512
	global_load_dwordx4 v[80:83], v206, s[84:85] offset:512
	s_lshl_b32 s94, s51, 8
	s_add_i32 s94, s94, 48
	s_lshl_b32 s94, s94, 14
	s_add_u32 s84, s48, s94
	s_addc_u32 s85, s49, 0
	global_load_dwordx4 v[172:175], v193, s[84:85]
	global_load_dwordx4 v[176:179], v206, s[84:85]
	global_load_dwordx4 v[182:185], v193, s[84:85] offset:512
	global_load_dwordx4 v[232:235], v206, s[84:85] offset:512
	v_mov_b32_dpp v164, v108 row_ror:8 row_mask:0xf bank_mask:0xf
	v_mov_b32_dpp v165, v109 row_ror:8 row_mask:0xf bank_mask:0xf
	v_mov_b32_dpp v166, v110 row_ror:8 row_mask:0xf bank_mask:0xf
	v_mov_b32_dpp v167, v111 row_ror:8 row_mask:0xf bank_mask:0xf
	v_cndmask_b32_e64 v108, v164, v112, s[90:91]
	v_cndmask_b32_e64 v109, v165, v113, s[90:91]
	v_cndmask_b32_e64 v110, v166, v114, s[90:91]
	v_cndmask_b32_e64 v111, v167, v115, s[90:91]
	v_cndmask_b32_e64 v112, v112, v164, s[90:91]
	v_cndmask_b32_e64 v113, v113, v165, s[90:91]
	v_cndmask_b32_e64 v114, v114, v166, s[90:91]
	v_cndmask_b32_e64 v115, v115, v167, s[90:91]
	v_mov_b32_dpp v164, v100 row_ror:8 row_mask:0xf bank_mask:0xf
	v_mov_b32_dpp v165, v101 row_ror:8 row_mask:0xf bank_mask:0xf
	v_mov_b32_dpp v166, v102 row_ror:8 row_mask:0xf bank_mask:0xf
	v_mov_b32_dpp v167, v103 row_ror:8 row_mask:0xf bank_mask:0xf
	v_cndmask_b32_e64 v100, v164, v104, s[90:91]
	v_cndmask_b32_e64 v101, v165, v105, s[90:91]
	v_cndmask_b32_e64 v102, v166, v106, s[90:91]
	v_cndmask_b32_e64 v103, v167, v107, s[90:91]
	v_cndmask_b32_e64 v104, v104, v164, s[90:91]
	v_cndmask_b32_e64 v105, v105, v165, s[90:91]
	v_cndmask_b32_e64 v106, v106, v166, s[90:91]
	v_cndmask_b32_e64 v107, v107, v167, s[90:91]
	s_lshl_b32 s94, s51, 8
	s_add_i32 s94, s94, 32
	s_lshl_b32 s94, s94, 14
	s_add_u32 s86, s48, s94
	s_addc_u32 s87, s49, 0
	s_lshl_b32 s94, s51, 8
	s_add_i32 s94, s94, 32
	s_lshl_b32 s94, s94, 13
	s_add_u32 s88, s12, s94
	s_addc_u32 s89, s13, 0
	s_lshl_b32 s94, s51, 8
	s_add_i32 s94, s94, 32
	s_lshl_b32 s94, s94, 8
	s_add_u32 s92, s22, s94
	s_addc_u32 s93, s23, 0
	s_waitcnt vmcnt(4)
	v_pk_add_f32 v[112:113], v[112:113], v[60:61]
	v_pk_add_f32 v[114:115], v[114:115], v[62:63]
	v_pk_add_f32 v[108:109], v[108:109], v[68:69]
	v_pk_add_f32 v[110:111], v[110:111], v[70:71]
	global_store_dwordx4 v193, v[112:115], s[86:87]
	global_store_dwordx4 v206, v[108:111], s[86:87]
	v_mul_f32_e32 v214, v112, v112
	v_fmac_f32_e32 v214, v113, v113
	v_fmac_f32_e32 v214, v114, v114
	v_fmac_f32_e32 v214, v115, v115
	v_mul_f32_e32 v215, v108, v108
	v_fmac_f32_e32 v215, v109, v109
	v_fmac_f32_e32 v215, v110, v110
	v_fmac_f32_e32 v215, v111, v111
	v_pk_mul_f32 v[164:165], v[112:113], v[148:149]
	v_pk_mul_f32 v[166:167], v[114:115], v[150:151]
	v_cvt_pk_bf16_f32 v168, v164, v165
	v_cvt_pk_bf16_f32 v169, v166, v167
	global_store_dwordx2 v207, v[168:169], s[88:89]
	v_pk_mul_f32 v[164:165], v[108:109], v[156:157]
	v_pk_mul_f32 v[166:167], v[110:111], v[158:159]
	v_cvt_pk_bf16_f32 v170, v164, v165
	v_cvt_pk_bf16_f32 v171, v166, v167
	global_store_dwordx2 v208, v[170:171], s[88:89]
	v_pk_add_f32 v[104:105], v[104:105], v[76:77]
	v_pk_add_f32 v[106:107], v[106:107], v[78:79]
	v_pk_add_f32 v[100:101], v[100:101], v[80:81]
	v_pk_add_f32 v[102:103], v[102:103], v[82:83]
	global_store_dwordx4 v193, v[104:107], s[86:87] offset:512
	global_store_dwordx4 v206, v[100:103], s[86:87] offset:512
	v_fmac_f32_e32 v214, v104, v104
	v_fmac_f32_e32 v214, v105, v105
	v_fmac_f32_e32 v214, v106, v106
	v_fmac_f32_e32 v214, v107, v107
	v_fmac_f32_e32 v215, v100, v100
	v_fmac_f32_e32 v215, v101, v101
	v_fmac_f32_e32 v215, v102, v102
	v_fmac_f32_e32 v215, v103, v103
	v_pk_mul_f32 v[164:165], v[104:105], v[152:153]
	v_pk_mul_f32 v[166:167], v[106:107], v[154:155]
	v_cvt_pk_bf16_f32 v168, v164, v165
	v_cvt_pk_bf16_f32 v169, v166, v167
	global_store_dwordx2 v207, v[168:169], s[88:89] offset:256
	v_pk_mul_f32 v[164:165], v[100:101], v[160:161]
	v_pk_mul_f32 v[166:167], v[102:103], v[162:163]
	v_cvt_pk_bf16_f32 v170, v164, v165
	v_cvt_pk_bf16_f32 v171, v166, v167
	global_store_dwordx2 v208, v[170:171], s[88:89] offset:256
	s_nop 1
	v_add_f32_dpp v180, v214, v214 row_ror:8 row_mask:0xf bank_mask:0xf
	v_add_f32_dpp v192, v215, v215 row_ror:8 row_mask:0xf bank_mask:0xf
	v_cndmask_b32_e64 v214, v180, v192, s[90:91]
	v_mov_b32_e32 v215, v214
	s_nop 1
	v_permlane16_swap_b32_e32 v214, v215
	v_add_f32_e32 v214, v214, v215
	v_mov_b32_e32 v215, v214
	s_nop 1
	v_permlane32_swap_b32_e32 v214, v215
	v_add_f32_e32 v214, v214, v215
	s_and_saveexec_b64 s[14:15], s[38:39]
	global_store_dword v211, v214, s[92:93]
	s_or_b64 exec, exec, s[14:15]
	s_lshl_b32 s94, s51, 8
	s_lshl_b32 s94, s94, 14
	s_add_u32 s84, s48, s94
	s_addc_u32 s85, s49, 0
	global_load_dwordx4 v[112:115], v193, s[84:85]
	global_load_dwordx4 v[108:111], v206, s[84:85]
	global_load_dwordx4 v[104:107], v193, s[84:85] offset:512
	global_load_dwordx4 v[100:103], v206, s[84:85] offset:512
	v_mov_b32_dpp v164, v92 row_ror:8 row_mask:0xf bank_mask:0xf
	v_mov_b32_dpp v165, v93 row_ror:8 row_mask:0xf bank_mask:0xf
	v_mov_b32_dpp v166, v94 row_ror:8 row_mask:0xf bank_mask:0xf
	v_mov_b32_dpp v167, v95 row_ror:8 row_mask:0xf bank_mask:0xf
	v_cndmask_b32_e64 v92, v164, v96, s[90:91]
	v_cndmask_b32_e64 v93, v165, v97, s[90:91]
	v_cndmask_b32_e64 v94, v166, v98, s[90:91]
	v_cndmask_b32_e64 v95, v167, v99, s[90:91]
	v_cndmask_b32_e64 v96, v96, v164, s[90:91]
	v_cndmask_b32_e64 v97, v97, v165, s[90:91]
	v_cndmask_b32_e64 v98, v98, v166, s[90:91]
	v_cndmask_b32_e64 v99, v99, v167, s[90:91]
	v_mov_b32_dpp v164, v84 row_ror:8 row_mask:0xf bank_mask:0xf
	v_mov_b32_dpp v165, v85 row_ror:8 row_mask:0xf bank_mask:0xf
	v_mov_b32_dpp v166, v86 row_ror:8 row_mask:0xf bank_mask:0xf
	v_mov_b32_dpp v167, v87 row_ror:8 row_mask:0xf bank_mask:0xf
	v_cndmask_b32_e64 v84, v164, v88, s[90:91]
	v_cndmask_b32_e64 v85, v165, v89, s[90:91]
	v_cndmask_b32_e64 v86, v166, v90, s[90:91]
	v_cndmask_b32_e64 v87, v167, v91, s[90:91]
	v_cndmask_b32_e64 v88, v88, v164, s[90:91]
	v_cndmask_b32_e64 v89, v89, v165, s[90:91]
	v_cndmask_b32_e64 v90, v90, v166, s[90:91]
	v_cndmask_b32_e64 v91, v91, v167, s[90:91]
	s_lshl_b32 s94, s51, 8
	s_add_i32 s94, s94, 48
	s_lshl_b32 s94, s94, 14
	s_add_u32 s86, s48, s94
	s_addc_u32 s87, s49, 0
	s_lshl_b32 s94, s51, 8
	s_add_i32 s94, s94, 48
	s_lshl_b32 s94, s94, 13
	s_add_u32 s88, s12, s94
	s_addc_u32 s89, s13, 0
	s_lshl_b32 s94, s51, 8
	s_add_i32 s94, s94, 48
	s_lshl_b32 s94, s94, 8
	s_add_u32 s92, s22, s94
	s_addc_u32 s93, s23, 0
	s_waitcnt vmcnt(13)
	v_pk_add_f32 v[96:97], v[96:97], v[172:173]
	v_pk_add_f32 v[98:99], v[98:99], v[174:175]
	v_pk_add_f32 v[92:93], v[92:93], v[176:177]
	v_pk_add_f32 v[94:95], v[94:95], v[178:179]
	global_store_dwordx4 v193, v[96:99], s[86:87]
	global_store_dwordx4 v206, v[92:95], s[86:87]
	v_mul_f32_e32 v214, v96, v96
	v_fmac_f32_e32 v214, v97, v97
	v_fmac_f32_e32 v214, v98, v98
	v_fmac_f32_e32 v214, v99, v99
	v_mul_f32_e32 v215, v92, v92
	v_fmac_f32_e32 v215, v93, v93
	v_fmac_f32_e32 v215, v94, v94
	v_fmac_f32_e32 v215, v95, v95
	v_pk_mul_f32 v[164:165], v[96:97], v[148:149]
	v_pk_mul_f32 v[166:167], v[98:99], v[150:151]
	v_cvt_pk_bf16_f32 v168, v164, v165
	v_cvt_pk_bf16_f32 v169, v166, v167
	global_store_dwordx2 v207, v[168:169], s[88:89]
	v_pk_mul_f32 v[164:165], v[92:93], v[156:157]
	v_pk_mul_f32 v[166:167], v[94:95], v[158:159]
	v_cvt_pk_bf16_f32 v170, v164, v165
	v_cvt_pk_bf16_f32 v171, v166, v167
	global_store_dwordx2 v208, v[170:171], s[88:89]
	v_pk_add_f32 v[88:89], v[88:89], v[182:183]
	v_pk_add_f32 v[90:91], v[90:91], v[184:185]
	v_pk_add_f32 v[84:85], v[84:85], v[232:233]
	v_pk_add_f32 v[86:87], v[86:87], v[234:235]
	global_store_dwordx4 v193, v[88:91], s[86:87] offset:512
	global_store_dwordx4 v206, v[84:87], s[86:87] offset:512
	v_fmac_f32_e32 v214, v88, v88
	v_fmac_f32_e32 v214, v89, v89
	v_fmac_f32_e32 v214, v90, v90
	v_fmac_f32_e32 v214, v91, v91
	v_fmac_f32_e32 v215, v84, v84
	v_fmac_f32_e32 v215, v85, v85
	v_fmac_f32_e32 v215, v86, v86
	v_fmac_f32_e32 v215, v87, v87
	v_pk_mul_f32 v[164:165], v[88:89], v[152:153]
	v_pk_mul_f32 v[166:167], v[90:91], v[154:155]
	v_cvt_pk_bf16_f32 v168, v164, v165
	v_cvt_pk_bf16_f32 v169, v166, v167
	global_store_dwordx2 v207, v[168:169], s[88:89] offset:256
	v_pk_mul_f32 v[164:165], v[84:85], v[160:161]
	v_pk_mul_f32 v[166:167], v[86:87], v[162:163]
	v_cvt_pk_bf16_f32 v170, v164, v165
	v_cvt_pk_bf16_f32 v171, v166, v167
	global_store_dwordx2 v208, v[170:171], s[88:89] offset:256
	s_nop 1
	v_add_f32_dpp v180, v214, v214 row_ror:8 row_mask:0xf bank_mask:0xf
	v_add_f32_dpp v192, v215, v215 row_ror:8 row_mask:0xf bank_mask:0xf
	v_cndmask_b32_e64 v214, v180, v192, s[90:91]
	v_mov_b32_e32 v215, v214
	s_nop 1
	v_permlane16_swap_b32_e32 v214, v215
	v_add_f32_e32 v214, v214, v215
	v_mov_b32_e32 v215, v214
	s_nop 1
	v_permlane32_swap_b32_e32 v214, v215
	v_add_f32_e32 v214, v214, v215
	s_and_saveexec_b64 s[14:15], s[38:39]
	global_store_dword v211, v214, s[92:93]
	s_or_b64 exec, exec, s[14:15]
	s_lshl_b32 s94, s51, 8
	s_add_i32 s94, s94, 16
	s_lshl_b32 s94, s94, 14
	s_add_u32 s84, s48, s94
	s_addc_u32 s85, s49, 0
	global_load_dwordx4 v[96:99], v193, s[84:85]
	global_load_dwordx4 v[92:95], v206, s[84:85]
	global_load_dwordx4 v[88:91], v193, s[84:85] offset:512
	global_load_dwordx4 v[84:87], v206, s[84:85] offset:512
	v_mov_b32_dpp v164, v140 row_ror:8 row_mask:0xf bank_mask:0xf
	v_mov_b32_dpp v165, v141 row_ror:8 row_mask:0xf bank_mask:0xf
	v_mov_b32_dpp v166, v142 row_ror:8 row_mask:0xf bank_mask:0xf
	v_mov_b32_dpp v167, v143 row_ror:8 row_mask:0xf bank_mask:0xf
	v_cndmask_b32_e64 v140, v164, v144, s[90:91]
	v_cndmask_b32_e64 v141, v165, v145, s[90:91]
	v_cndmask_b32_e64 v142, v166, v146, s[90:91]
	v_cndmask_b32_e64 v143, v167, v147, s[90:91]
	v_cndmask_b32_e64 v144, v144, v164, s[90:91]
	v_cndmask_b32_e64 v145, v145, v165, s[90:91]
	v_cndmask_b32_e64 v146, v146, v166, s[90:91]
	v_cndmask_b32_e64 v147, v147, v167, s[90:91]
	v_mov_b32_dpp v164, v132 row_ror:8 row_mask:0xf bank_mask:0xf
	v_mov_b32_dpp v165, v133 row_ror:8 row_mask:0xf bank_mask:0xf
	v_mov_b32_dpp v166, v134 row_ror:8 row_mask:0xf bank_mask:0xf
	v_mov_b32_dpp v167, v135 row_ror:8 row_mask:0xf bank_mask:0xf
	v_cndmask_b32_e64 v132, v164, v136, s[90:91]
	v_cndmask_b32_e64 v133, v165, v137, s[90:91]
	v_cndmask_b32_e64 v134, v166, v138, s[90:91]
	v_cndmask_b32_e64 v135, v167, v139, s[90:91]
	v_cndmask_b32_e64 v136, v136, v164, s[90:91]
	v_cndmask_b32_e64 v137, v137, v165, s[90:91]
	v_cndmask_b32_e64 v138, v138, v166, s[90:91]
	v_cndmask_b32_e64 v139, v139, v167, s[90:91]
	s_lshl_b32 s94, s51, 8
	s_lshl_b32 s94, s94, 14
	s_add_u32 s86, s48, s94
	s_addc_u32 s87, s49, 0
	s_lshl_b32 s94, s51, 8
	s_lshl_b32 s94, s94, 13
	s_add_u32 s88, s12, s94
	s_addc_u32 s89, s13, 0
	s_lshl_b32 s94, s51, 8
	s_lshl_b32 s94, s94, 8
	s_add_u32 s92, s22, s94
	s_addc_u32 s93, s23, 0
	s_waitcnt vmcnt(13)
	v_pk_add_f32 v[144:145], v[144:145], v[112:113]
	v_pk_add_f32 v[146:147], v[146:147], v[114:115]
	v_pk_add_f32 v[140:141], v[140:141], v[108:109]
	v_pk_add_f32 v[142:143], v[142:143], v[110:111]
	global_store_dwordx4 v193, v[144:147], s[86:87]
	global_store_dwordx4 v206, v[140:143], s[86:87]
	v_mul_f32_e32 v214, v144, v144
	v_fmac_f32_e32 v214, v145, v145
	v_fmac_f32_e32 v214, v146, v146
	v_fmac_f32_e32 v214, v147, v147
	v_mul_f32_e32 v215, v140, v140
	v_fmac_f32_e32 v215, v141, v141
	v_fmac_f32_e32 v215, v142, v142
	v_fmac_f32_e32 v215, v143, v143
	v_pk_mul_f32 v[164:165], v[144:145], v[148:149]
	v_pk_mul_f32 v[166:167], v[146:147], v[150:151]
	v_cvt_pk_bf16_f32 v168, v164, v165
	v_cvt_pk_bf16_f32 v169, v166, v167
	global_store_dwordx2 v207, v[168:169], s[88:89]
	v_pk_mul_f32 v[164:165], v[140:141], v[156:157]
	v_pk_mul_f32 v[166:167], v[142:143], v[158:159]
	v_cvt_pk_bf16_f32 v170, v164, v165
	v_cvt_pk_bf16_f32 v171, v166, v167
	global_store_dwordx2 v208, v[170:171], s[88:89]
	v_pk_add_f32 v[136:137], v[136:137], v[104:105]
	v_pk_add_f32 v[138:139], v[138:139], v[106:107]
	v_pk_add_f32 v[132:133], v[132:133], v[100:101]
	v_pk_add_f32 v[134:135], v[134:135], v[102:103]
	global_store_dwordx4 v193, v[136:139], s[86:87] offset:512
	global_store_dwordx4 v206, v[132:135], s[86:87] offset:512
	v_fmac_f32_e32 v214, v136, v136
	v_fmac_f32_e32 v214, v137, v137
	v_fmac_f32_e32 v214, v138, v138
	v_fmac_f32_e32 v214, v139, v139
	v_fmac_f32_e32 v215, v132, v132
	v_fmac_f32_e32 v215, v133, v133
	v_fmac_f32_e32 v215, v134, v134
	v_fmac_f32_e32 v215, v135, v135
	v_pk_mul_f32 v[164:165], v[136:137], v[152:153]
	v_pk_mul_f32 v[166:167], v[138:139], v[154:155]
	v_cvt_pk_bf16_f32 v168, v164, v165
	v_cvt_pk_bf16_f32 v169, v166, v167
	global_store_dwordx2 v207, v[168:169], s[88:89] offset:256
	v_pk_mul_f32 v[164:165], v[132:133], v[160:161]
	v_pk_mul_f32 v[166:167], v[134:135], v[162:163]
	v_cvt_pk_bf16_f32 v170, v164, v165
	v_cvt_pk_bf16_f32 v171, v166, v167
	global_store_dwordx2 v208, v[170:171], s[88:89] offset:256
	s_nop 1
	v_add_f32_dpp v180, v214, v214 row_ror:8 row_mask:0xf bank_mask:0xf
	v_add_f32_dpp v192, v215, v215 row_ror:8 row_mask:0xf bank_mask:0xf
	v_cndmask_b32_e64 v214, v180, v192, s[90:91]
	v_mov_b32_e32 v215, v214
	s_nop 1
	v_permlane16_swap_b32_e32 v214, v215
	v_add_f32_e32 v214, v214, v215
	v_mov_b32_e32 v215, v214
	s_nop 1
	v_permlane32_swap_b32_e32 v214, v215
	v_add_f32_e32 v214, v214, v215
	s_and_saveexec_b64 s[14:15], s[38:39]
	global_store_dword v211, v214, s[92:93]
	s_or_b64 exec, exec, s[14:15]
	s_lshl_b32 s94, s51, 8
	s_add_i32 s94, s94, 160
	s_lshl_b32 s94, s94, 14
	s_add_u32 s84, s48, s94
	s_addc_u32 s85, s49, 0
	global_load_dwordx4 v[144:147], v193, s[84:85]
	global_load_dwordx4 v[140:143], v206, s[84:85]
	global_load_dwordx4 v[136:139], v193, s[84:85] offset:512
	global_load_dwordx4 v[132:135], v206, s[84:85] offset:512
	v_mov_b32_dpp v164, v124 row_ror:8 row_mask:0xf bank_mask:0xf
	v_mov_b32_dpp v165, v125 row_ror:8 row_mask:0xf bank_mask:0xf
	v_mov_b32_dpp v166, v126 row_ror:8 row_mask:0xf bank_mask:0xf
	v_mov_b32_dpp v167, v127 row_ror:8 row_mask:0xf bank_mask:0xf
	v_cndmask_b32_e64 v124, v164, v128, s[90:91]
	v_cndmask_b32_e64 v125, v165, v129, s[90:91]
	v_cndmask_b32_e64 v126, v166, v130, s[90:91]
	v_cndmask_b32_e64 v127, v167, v131, s[90:91]
	v_cndmask_b32_e64 v128, v128, v164, s[90:91]
	v_cndmask_b32_e64 v129, v129, v165, s[90:91]
	v_cndmask_b32_e64 v130, v130, v166, s[90:91]
	v_cndmask_b32_e64 v131, v131, v167, s[90:91]
	v_mov_b32_dpp v164, v116 row_ror:8 row_mask:0xf bank_mask:0xf
	v_mov_b32_dpp v165, v117 row_ror:8 row_mask:0xf bank_mask:0xf
	v_mov_b32_dpp v166, v118 row_ror:8 row_mask:0xf bank_mask:0xf
	v_mov_b32_dpp v167, v119 row_ror:8 row_mask:0xf bank_mask:0xf
	v_cndmask_b32_e64 v116, v164, v120, s[90:91]
	v_cndmask_b32_e64 v117, v165, v121, s[90:91]
	v_cndmask_b32_e64 v118, v166, v122, s[90:91]
	v_cndmask_b32_e64 v119, v167, v123, s[90:91]
	v_cndmask_b32_e64 v120, v120, v164, s[90:91]
	v_cndmask_b32_e64 v121, v121, v165, s[90:91]
	v_cndmask_b32_e64 v122, v122, v166, s[90:91]
	v_cndmask_b32_e64 v123, v123, v167, s[90:91]
	s_lshl_b32 s94, s51, 8
	s_add_i32 s94, s94, 16
	s_lshl_b32 s94, s94, 14
	s_add_u32 s86, s48, s94
	s_addc_u32 s87, s49, 0
	s_lshl_b32 s94, s51, 8
	s_add_i32 s94, s94, 16
	s_lshl_b32 s94, s94, 13
	s_add_u32 s88, s12, s94
	s_addc_u32 s89, s13, 0
	s_lshl_b32 s94, s51, 8
	s_add_i32 s94, s94, 16
	s_lshl_b32 s94, s94, 8
	s_add_u32 s92, s22, s94
	s_addc_u32 s93, s23, 0
	s_waitcnt vmcnt(13)
	v_pk_add_f32 v[128:129], v[128:129], v[96:97]
	v_pk_add_f32 v[130:131], v[130:131], v[98:99]
	v_pk_add_f32 v[124:125], v[124:125], v[92:93]
	v_pk_add_f32 v[126:127], v[126:127], v[94:95]
	global_store_dwordx4 v193, v[128:131], s[86:87]
	global_store_dwordx4 v206, v[124:127], s[86:87]
	v_mul_f32_e32 v214, v128, v128
	v_fmac_f32_e32 v214, v129, v129
	v_fmac_f32_e32 v214, v130, v130
	v_fmac_f32_e32 v214, v131, v131
	v_mul_f32_e32 v215, v124, v124
	v_fmac_f32_e32 v215, v125, v125
	v_fmac_f32_e32 v215, v126, v126
	v_fmac_f32_e32 v215, v127, v127
	v_pk_mul_f32 v[164:165], v[128:129], v[148:149]
	v_pk_mul_f32 v[166:167], v[130:131], v[150:151]
	v_cvt_pk_bf16_f32 v168, v164, v165
	v_cvt_pk_bf16_f32 v169, v166, v167
	global_store_dwordx2 v207, v[168:169], s[88:89]
	v_pk_mul_f32 v[164:165], v[124:125], v[156:157]
	v_pk_mul_f32 v[166:167], v[126:127], v[158:159]
	v_cvt_pk_bf16_f32 v170, v164, v165
	v_cvt_pk_bf16_f32 v171, v166, v167
	global_store_dwordx2 v208, v[170:171], s[88:89]
	v_pk_add_f32 v[120:121], v[120:121], v[88:89]
	v_pk_add_f32 v[122:123], v[122:123], v[90:91]
	v_pk_add_f32 v[116:117], v[116:117], v[84:85]
	v_pk_add_f32 v[118:119], v[118:119], v[86:87]
	global_store_dwordx4 v193, v[120:123], s[86:87] offset:512
	global_store_dwordx4 v206, v[116:119], s[86:87] offset:512
	v_fmac_f32_e32 v214, v120, v120
	v_fmac_f32_e32 v214, v121, v121
	v_fmac_f32_e32 v214, v122, v122
	v_fmac_f32_e32 v214, v123, v123
	v_fmac_f32_e32 v215, v116, v116
	v_fmac_f32_e32 v215, v117, v117
	v_fmac_f32_e32 v215, v118, v118
	v_fmac_f32_e32 v215, v119, v119
	v_pk_mul_f32 v[164:165], v[120:121], v[152:153]
	v_pk_mul_f32 v[166:167], v[122:123], v[154:155]
	v_cvt_pk_bf16_f32 v168, v164, v165
	v_cvt_pk_bf16_f32 v169, v166, v167
	global_store_dwordx2 v207, v[168:169], s[88:89] offset:256
	v_pk_mul_f32 v[164:165], v[116:117], v[160:161]
	v_pk_mul_f32 v[166:167], v[118:119], v[162:163]
	v_cvt_pk_bf16_f32 v170, v164, v165
	v_cvt_pk_bf16_f32 v171, v166, v167
	global_store_dwordx2 v208, v[170:171], s[88:89] offset:256
	s_nop 1
	v_add_f32_dpp v180, v214, v214 row_ror:8 row_mask:0xf bank_mask:0xf
	v_add_f32_dpp v192, v215, v215 row_ror:8 row_mask:0xf bank_mask:0xf
	v_cndmask_b32_e64 v214, v180, v192, s[90:91]
	v_mov_b32_e32 v215, v214
	s_nop 1
	v_permlane16_swap_b32_e32 v214, v215
	v_add_f32_e32 v214, v214, v215
	v_mov_b32_e32 v215, v214
	s_nop 1
	v_permlane32_swap_b32_e32 v214, v215
	v_add_f32_e32 v214, v214, v215
	s_and_saveexec_b64 s[14:15], s[38:39]
	global_store_dword v211, v214, s[92:93]
	s_or_b64 exec, exec, s[14:15]
	s_lshl_b32 s94, s51, 8
	s_add_i32 s94, s94, 176
	s_lshl_b32 s94, s94, 14
	s_add_u32 s84, s48, s94
	s_addc_u32 s85, s49, 0
	global_load_dwordx4 v[128:131], v193, s[84:85]
	global_load_dwordx4 v[124:127], v206, s[84:85]
	global_load_dwordx4 v[120:123], v193, s[84:85] offset:512
	global_load_dwordx4 v[116:119], v206, s[84:85] offset:512
	v_mov_b32_dpp v164, v28 row_ror:8 row_mask:0xf bank_mask:0xf
	v_mov_b32_dpp v165, v29 row_ror:8 row_mask:0xf bank_mask:0xf
	v_mov_b32_dpp v166, v30 row_ror:8 row_mask:0xf bank_mask:0xf
	v_mov_b32_dpp v167, v31 row_ror:8 row_mask:0xf bank_mask:0xf
	v_cndmask_b32_e64 v28, v164, v32, s[90:91]
	v_cndmask_b32_e64 v29, v165, v33, s[90:91]
	v_cndmask_b32_e64 v30, v166, v34, s[90:91]
	v_cndmask_b32_e64 v31, v167, v35, s[90:91]
	v_cndmask_b32_e64 v32, v32, v164, s[90:91]
	v_cndmask_b32_e64 v33, v33, v165, s[90:91]
	v_cndmask_b32_e64 v34, v34, v166, s[90:91]
	v_cndmask_b32_e64 v35, v35, v167, s[90:91]
	v_mov_b32_dpp v164, v20 row_ror:8 row_mask:0xf bank_mask:0xf
	v_mov_b32_dpp v165, v21 row_ror:8 row_mask:0xf bank_mask:0xf
	v_mov_b32_dpp v166, v22 row_ror:8 row_mask:0xf bank_mask:0xf
	v_mov_b32_dpp v167, v23 row_ror:8 row_mask:0xf bank_mask:0xf
	v_cndmask_b32_e64 v20, v164, v24, s[90:91]
	v_cndmask_b32_e64 v21, v165, v25, s[90:91]
	v_cndmask_b32_e64 v22, v166, v26, s[90:91]
	v_cndmask_b32_e64 v23, v167, v27, s[90:91]
	v_cndmask_b32_e64 v24, v24, v164, s[90:91]
	v_cndmask_b32_e64 v25, v25, v165, s[90:91]
	v_cndmask_b32_e64 v26, v26, v166, s[90:91]
	v_cndmask_b32_e64 v27, v27, v167, s[90:91]
	s_lshl_b32 s94, s51, 8
	s_add_i32 s94, s94, 160
	s_lshl_b32 s94, s94, 14
	s_add_u32 s86, s48, s94
	s_addc_u32 s87, s49, 0
	s_lshl_b32 s94, s51, 8
	s_add_i32 s94, s94, 160
	s_lshl_b32 s94, s94, 13
	s_add_u32 s88, s12, s94
	s_addc_u32 s89, s13, 0
	s_lshl_b32 s94, s51, 8
	s_add_i32 s94, s94, 160
	s_lshl_b32 s94, s94, 8
	s_add_u32 s92, s22, s94
	s_addc_u32 s93, s23, 0
	s_waitcnt vmcnt(13)
	v_pk_add_f32 v[32:33], v[32:33], v[144:145]
	v_pk_add_f32 v[34:35], v[34:35], v[146:147]
	v_pk_add_f32 v[28:29], v[28:29], v[140:141]
	v_pk_add_f32 v[30:31], v[30:31], v[142:143]
	global_store_dwordx4 v193, v[32:35], s[86:87]
	global_store_dwordx4 v206, v[28:31], s[86:87]
	v_mul_f32_e32 v214, v32, v32
	v_fmac_f32_e32 v214, v33, v33
	v_fmac_f32_e32 v214, v34, v34
	v_fmac_f32_e32 v214, v35, v35
	v_mul_f32_e32 v215, v28, v28
	v_fmac_f32_e32 v215, v29, v29
	v_fmac_f32_e32 v215, v30, v30
	v_fmac_f32_e32 v215, v31, v31
	v_pk_mul_f32 v[164:165], v[32:33], v[148:149]
	v_pk_mul_f32 v[166:167], v[34:35], v[150:151]
	v_cvt_pk_bf16_f32 v168, v164, v165
	v_cvt_pk_bf16_f32 v169, v166, v167
	global_store_dwordx2 v207, v[168:169], s[88:89]
	v_pk_mul_f32 v[164:165], v[28:29], v[156:157]
	v_pk_mul_f32 v[166:167], v[30:31], v[158:159]
	v_cvt_pk_bf16_f32 v170, v164, v165
	v_cvt_pk_bf16_f32 v171, v166, v167
	global_store_dwordx2 v208, v[170:171], s[88:89]
	v_pk_add_f32 v[24:25], v[24:25], v[136:137]
	v_pk_add_f32 v[26:27], v[26:27], v[138:139]
	v_pk_add_f32 v[20:21], v[20:21], v[132:133]
	v_pk_add_f32 v[22:23], v[22:23], v[134:135]
	global_store_dwordx4 v193, v[24:27], s[86:87] offset:512
	global_store_dwordx4 v206, v[20:23], s[86:87] offset:512
	v_fmac_f32_e32 v214, v24, v24
	v_fmac_f32_e32 v214, v25, v25
	v_fmac_f32_e32 v214, v26, v26
	v_fmac_f32_e32 v214, v27, v27
	v_fmac_f32_e32 v215, v20, v20
	v_fmac_f32_e32 v215, v21, v21
	v_fmac_f32_e32 v215, v22, v22
	v_fmac_f32_e32 v215, v23, v23
	v_pk_mul_f32 v[164:165], v[24:25], v[152:153]
	v_pk_mul_f32 v[166:167], v[26:27], v[154:155]
	v_cvt_pk_bf16_f32 v168, v164, v165
	v_cvt_pk_bf16_f32 v169, v166, v167
	global_store_dwordx2 v207, v[168:169], s[88:89] offset:256
	v_pk_mul_f32 v[164:165], v[20:21], v[160:161]
	v_pk_mul_f32 v[166:167], v[22:23], v[162:163]
	v_cvt_pk_bf16_f32 v170, v164, v165
	v_cvt_pk_bf16_f32 v171, v166, v167
	global_store_dwordx2 v208, v[170:171], s[88:89] offset:256
	s_nop 1
	v_add_f32_dpp v180, v214, v214 row_ror:8 row_mask:0xf bank_mask:0xf
	v_add_f32_dpp v192, v215, v215 row_ror:8 row_mask:0xf bank_mask:0xf
	v_cndmask_b32_e64 v214, v180, v192, s[90:91]
	v_mov_b32_e32 v215, v214
	s_nop 1
	v_permlane16_swap_b32_e32 v214, v215
	v_add_f32_e32 v214, v214, v215
	v_mov_b32_e32 v215, v214
	s_nop 1
	v_permlane32_swap_b32_e32 v214, v215
	v_add_f32_e32 v214, v214, v215
	s_and_saveexec_b64 s[14:15], s[38:39]
	global_store_dword v211, v214, s[92:93]
	s_or_b64 exec, exec, s[14:15]
	s_lshl_b32 s94, s51, 8
	s_add_i32 s94, s94, 128
	s_lshl_b32 s94, s94, 14
	s_add_u32 s84, s48, s94
	s_addc_u32 s85, s49, 0
	global_load_dwordx4 v[32:35], v193, s[84:85]
	global_load_dwordx4 v[28:31], v206, s[84:85]
	global_load_dwordx4 v[24:27], v193, s[84:85] offset:512
	global_load_dwordx4 v[20:23], v206, s[84:85] offset:512
	v_mov_b32_dpp v164, v12 row_ror:8 row_mask:0xf bank_mask:0xf
	v_mov_b32_dpp v165, v13 row_ror:8 row_mask:0xf bank_mask:0xf
	v_mov_b32_dpp v166, v14 row_ror:8 row_mask:0xf bank_mask:0xf
	v_mov_b32_dpp v167, v15 row_ror:8 row_mask:0xf bank_mask:0xf
	v_cndmask_b32_e64 v12, v164, v16, s[90:91]
	v_cndmask_b32_e64 v13, v165, v17, s[90:91]
	v_cndmask_b32_e64 v14, v166, v18, s[90:91]
	v_cndmask_b32_e64 v15, v167, v19, s[90:91]
	v_cndmask_b32_e64 v16, v16, v164, s[90:91]
	v_cndmask_b32_e64 v17, v17, v165, s[90:91]
	v_cndmask_b32_e64 v18, v18, v166, s[90:91]
	v_cndmask_b32_e64 v19, v19, v167, s[90:91]
	v_mov_b32_dpp v164, v4 row_ror:8 row_mask:0xf bank_mask:0xf
	v_mov_b32_dpp v165, v5 row_ror:8 row_mask:0xf bank_mask:0xf
	v_mov_b32_dpp v166, v6 row_ror:8 row_mask:0xf bank_mask:0xf
	v_mov_b32_dpp v167, v7 row_ror:8 row_mask:0xf bank_mask:0xf
	v_cndmask_b32_e64 v4, v164, v8, s[90:91]
	v_cndmask_b32_e64 v5, v165, v9, s[90:91]
	v_cndmask_b32_e64 v6, v166, v10, s[90:91]
	v_cndmask_b32_e64 v7, v167, v11, s[90:91]
	v_cndmask_b32_e64 v8, v8, v164, s[90:91]
	v_cndmask_b32_e64 v9, v9, v165, s[90:91]
	v_cndmask_b32_e64 v10, v10, v166, s[90:91]
	v_cndmask_b32_e64 v11, v11, v167, s[90:91]
	s_lshl_b32 s94, s51, 8
	s_add_i32 s94, s94, 176
	s_lshl_b32 s94, s94, 14
	s_add_u32 s86, s48, s94
	s_addc_u32 s87, s49, 0
	s_lshl_b32 s94, s51, 8
	s_add_i32 s94, s94, 176
	s_lshl_b32 s94, s94, 13
	s_add_u32 s88, s12, s94
	s_addc_u32 s89, s13, 0
	s_lshl_b32 s94, s51, 8
	s_add_i32 s94, s94, 176
	s_lshl_b32 s94, s94, 8
	s_add_u32 s92, s22, s94
	s_addc_u32 s93, s23, 0
	s_waitcnt vmcnt(13)
	v_pk_add_f32 v[16:17], v[16:17], v[128:129]
	v_pk_add_f32 v[18:19], v[18:19], v[130:131]
	v_pk_add_f32 v[12:13], v[12:13], v[124:125]
	v_pk_add_f32 v[14:15], v[14:15], v[126:127]
	global_store_dwordx4 v193, v[16:19], s[86:87]
	global_store_dwordx4 v206, v[12:15], s[86:87]
	v_mul_f32_e32 v214, v16, v16
	v_fmac_f32_e32 v214, v17, v17
	v_fmac_f32_e32 v214, v18, v18
	v_fmac_f32_e32 v214, v19, v19
	v_mul_f32_e32 v215, v12, v12
	v_fmac_f32_e32 v215, v13, v13
	v_fmac_f32_e32 v215, v14, v14
	v_fmac_f32_e32 v215, v15, v15
	v_pk_mul_f32 v[164:165], v[16:17], v[148:149]
	v_pk_mul_f32 v[166:167], v[18:19], v[150:151]
	v_cvt_pk_bf16_f32 v168, v164, v165
	v_cvt_pk_bf16_f32 v169, v166, v167
	global_store_dwordx2 v207, v[168:169], s[88:89]
	v_pk_mul_f32 v[164:165], v[12:13], v[156:157]
	v_pk_mul_f32 v[166:167], v[14:15], v[158:159]
	v_cvt_pk_bf16_f32 v170, v164, v165
	v_cvt_pk_bf16_f32 v171, v166, v167
	global_store_dwordx2 v208, v[170:171], s[88:89]
	v_pk_add_f32 v[8:9], v[8:9], v[120:121]
	v_pk_add_f32 v[10:11], v[10:11], v[122:123]
	v_pk_add_f32 v[4:5], v[4:5], v[116:117]
	v_pk_add_f32 v[6:7], v[6:7], v[118:119]
	global_store_dwordx4 v193, v[8:11], s[86:87] offset:512
	global_store_dwordx4 v206, v[4:7], s[86:87] offset:512
	v_fmac_f32_e32 v214, v8, v8
	v_fmac_f32_e32 v214, v9, v9
	v_fmac_f32_e32 v214, v10, v10
	v_fmac_f32_e32 v214, v11, v11
	v_fmac_f32_e32 v215, v4, v4
	v_fmac_f32_e32 v215, v5, v5
	v_fmac_f32_e32 v215, v6, v6
	v_fmac_f32_e32 v215, v7, v7
	v_pk_mul_f32 v[164:165], v[8:9], v[152:153]
	v_pk_mul_f32 v[166:167], v[10:11], v[154:155]
	v_cvt_pk_bf16_f32 v168, v164, v165
	v_cvt_pk_bf16_f32 v169, v166, v167
	global_store_dwordx2 v207, v[168:169], s[88:89] offset:256
	v_pk_mul_f32 v[164:165], v[4:5], v[160:161]
	v_pk_mul_f32 v[166:167], v[6:7], v[162:163]
	v_cvt_pk_bf16_f32 v170, v164, v165
	v_cvt_pk_bf16_f32 v171, v166, v167
	global_store_dwordx2 v208, v[170:171], s[88:89] offset:256
	s_nop 1
	v_add_f32_dpp v180, v214, v214 row_ror:8 row_mask:0xf bank_mask:0xf
	v_add_f32_dpp v192, v215, v215 row_ror:8 row_mask:0xf bank_mask:0xf
	v_cndmask_b32_e64 v214, v180, v192, s[90:91]
	v_mov_b32_e32 v215, v214
	s_nop 1
	v_permlane16_swap_b32_e32 v214, v215
	v_add_f32_e32 v214, v214, v215
	v_mov_b32_e32 v215, v214
	s_nop 1
	v_permlane32_swap_b32_e32 v214, v215
	v_add_f32_e32 v214, v214, v215
	s_and_saveexec_b64 s[14:15], s[38:39]
	global_store_dword v211, v214, s[92:93]
	s_or_b64 exec, exec, s[14:15]
	s_lshl_b32 s94, s51, 8
	s_add_i32 s94, s94, 144
	s_lshl_b32 s94, s94, 14
	s_add_u32 s84, s48, s94
	s_addc_u32 s85, s49, 0
	global_load_dwordx4 v[16:19], v193, s[84:85]
	global_load_dwordx4 v[12:15], v206, s[84:85]
	global_load_dwordx4 v[8:11], v193, s[84:85] offset:512
	global_load_dwordx4 v[4:7], v206, s[84:85] offset:512
	v_mov_b32_dpp v164, v64 row_ror:8 row_mask:0xf bank_mask:0xf
	v_mov_b32_dpp v165, v65 row_ror:8 row_mask:0xf bank_mask:0xf
	v_mov_b32_dpp v166, v66 row_ror:8 row_mask:0xf bank_mask:0xf
	v_mov_b32_dpp v167, v67 row_ror:8 row_mask:0xf bank_mask:0xf
	v_cndmask_b32_e64 v64, v164, v72, s[90:91]
	v_cndmask_b32_e64 v65, v165, v73, s[90:91]
	v_cndmask_b32_e64 v66, v166, v74, s[90:91]
	v_cndmask_b32_e64 v67, v167, v75, s[90:91]
	v_cndmask_b32_e64 v72, v72, v164, s[90:91]
	v_cndmask_b32_e64 v73, v73, v165, s[90:91]
	v_cndmask_b32_e64 v74, v74, v166, s[90:91]
	v_cndmask_b32_e64 v75, v75, v167, s[90:91]
	v_mov_b32_dpp v164, v52 row_ror:8 row_mask:0xf bank_mask:0xf
	v_mov_b32_dpp v165, v53 row_ror:8 row_mask:0xf bank_mask:0xf
	v_mov_b32_dpp v166, v54 row_ror:8 row_mask:0xf bank_mask:0xf
	v_mov_b32_dpp v167, v55 row_ror:8 row_mask:0xf bank_mask:0xf
	v_cndmask_b32_e64 v52, v164, v56, s[90:91]
	v_cndmask_b32_e64 v53, v165, v57, s[90:91]
	v_cndmask_b32_e64 v54, v166, v58, s[90:91]
	v_cndmask_b32_e64 v55, v167, v59, s[90:91]
	v_cndmask_b32_e64 v56, v56, v164, s[90:91]
	v_cndmask_b32_e64 v57, v57, v165, s[90:91]
	v_cndmask_b32_e64 v58, v58, v166, s[90:91]
	v_cndmask_b32_e64 v59, v59, v167, s[90:91]
	s_lshl_b32 s94, s51, 8
	s_add_i32 s94, s94, 128
	s_lshl_b32 s94, s94, 14
	s_add_u32 s86, s48, s94
	s_addc_u32 s87, s49, 0
	s_lshl_b32 s94, s51, 8
	s_add_i32 s94, s94, 128
	s_lshl_b32 s94, s94, 13
	s_add_u32 s88, s12, s94
	s_addc_u32 s89, s13, 0
	s_lshl_b32 s94, s51, 8
	s_add_i32 s94, s94, 128
	s_lshl_b32 s94, s94, 8
	s_add_u32 s92, s22, s94
	s_addc_u32 s93, s23, 0
	s_waitcnt vmcnt(13)
	v_pk_add_f32 v[72:73], v[72:73], v[32:33]
	v_pk_add_f32 v[74:75], v[74:75], v[34:35]
	v_pk_add_f32 v[64:65], v[64:65], v[28:29]
	v_pk_add_f32 v[66:67], v[66:67], v[30:31]
	global_store_dwordx4 v193, v[72:75], s[86:87]
	global_store_dwordx4 v206, v[64:67], s[86:87]
	v_mul_f32_e32 v214, v72, v72
	v_fmac_f32_e32 v214, v73, v73
	v_fmac_f32_e32 v214, v74, v74
	v_fmac_f32_e32 v214, v75, v75
	v_mul_f32_e32 v215, v64, v64
	v_fmac_f32_e32 v215, v65, v65
	v_fmac_f32_e32 v215, v66, v66
	v_fmac_f32_e32 v215, v67, v67
	v_pk_mul_f32 v[164:165], v[72:73], v[148:149]
	v_pk_mul_f32 v[166:167], v[74:75], v[150:151]
	v_cvt_pk_bf16_f32 v168, v164, v165
	v_cvt_pk_bf16_f32 v169, v166, v167
	global_store_dwordx2 v207, v[168:169], s[88:89]
	v_pk_mul_f32 v[164:165], v[64:65], v[156:157]
	v_pk_mul_f32 v[166:167], v[66:67], v[158:159]
	v_cvt_pk_bf16_f32 v170, v164, v165
	v_cvt_pk_bf16_f32 v171, v166, v167
	global_store_dwordx2 v208, v[170:171], s[88:89]
	v_pk_add_f32 v[56:57], v[56:57], v[24:25]
	v_pk_add_f32 v[58:59], v[58:59], v[26:27]
	v_pk_add_f32 v[52:53], v[52:53], v[20:21]
	v_pk_add_f32 v[54:55], v[54:55], v[22:23]
	global_store_dwordx4 v193, v[56:59], s[86:87] offset:512
	global_store_dwordx4 v206, v[52:55], s[86:87] offset:512
	v_fmac_f32_e32 v214, v56, v56
	v_fmac_f32_e32 v214, v57, v57
	v_fmac_f32_e32 v214, v58, v58
	v_fmac_f32_e32 v214, v59, v59
	v_fmac_f32_e32 v215, v52, v52
	v_fmac_f32_e32 v215, v53, v53
	v_fmac_f32_e32 v215, v54, v54
	v_fmac_f32_e32 v215, v55, v55
	v_pk_mul_f32 v[164:165], v[56:57], v[152:153]
	v_pk_mul_f32 v[166:167], v[58:59], v[154:155]
	v_cvt_pk_bf16_f32 v168, v164, v165
	v_cvt_pk_bf16_f32 v169, v166, v167
	global_store_dwordx2 v207, v[168:169], s[88:89] offset:256
	v_pk_mul_f32 v[164:165], v[52:53], v[160:161]
	v_pk_mul_f32 v[166:167], v[54:55], v[162:163]
	v_cvt_pk_bf16_f32 v170, v164, v165
	v_cvt_pk_bf16_f32 v171, v166, v167
	global_store_dwordx2 v208, v[170:171], s[88:89] offset:256
	s_nop 1
	v_add_f32_dpp v180, v214, v214 row_ror:8 row_mask:0xf bank_mask:0xf
	v_add_f32_dpp v192, v215, v215 row_ror:8 row_mask:0xf bank_mask:0xf
	v_cndmask_b32_e64 v214, v180, v192, s[90:91]
	v_mov_b32_e32 v215, v214
	s_nop 1
	v_permlane16_swap_b32_e32 v214, v215
	v_add_f32_e32 v214, v214, v215
	v_mov_b32_e32 v215, v214
	s_nop 1
	v_permlane32_swap_b32_e32 v214, v215
	v_add_f32_e32 v214, v214, v215
	s_and_saveexec_b64 s[14:15], s[38:39]
	global_store_dword v211, v214, s[92:93]
	s_or_b64 exec, exec, s[14:15]
	v_mov_b32_dpp v164, v44 row_ror:8 row_mask:0xf bank_mask:0xf
	v_mov_b32_dpp v165, v45 row_ror:8 row_mask:0xf bank_mask:0xf
	v_mov_b32_dpp v166, v46 row_ror:8 row_mask:0xf bank_mask:0xf
	v_mov_b32_dpp v167, v47 row_ror:8 row_mask:0xf bank_mask:0xf
	v_cndmask_b32_e64 v44, v164, v48, s[90:91]
	v_cndmask_b32_e64 v45, v165, v49, s[90:91]
	v_cndmask_b32_e64 v46, v166, v50, s[90:91]
	v_cndmask_b32_e64 v47, v167, v51, s[90:91]
	v_cndmask_b32_e64 v48, v48, v164, s[90:91]
	v_cndmask_b32_e64 v49, v49, v165, s[90:91]
	v_cndmask_b32_e64 v50, v50, v166, s[90:91]
	v_cndmask_b32_e64 v51, v51, v167, s[90:91]
	v_mov_b32_dpp v164, v36 row_ror:8 row_mask:0xf bank_mask:0xf
	v_mov_b32_dpp v165, v37 row_ror:8 row_mask:0xf bank_mask:0xf
	v_mov_b32_dpp v166, v38 row_ror:8 row_mask:0xf bank_mask:0xf
	v_mov_b32_dpp v167, v39 row_ror:8 row_mask:0xf bank_mask:0xf
	v_cndmask_b32_e64 v36, v164, v40, s[90:91]
	v_cndmask_b32_e64 v37, v165, v41, s[90:91]
	v_cndmask_b32_e64 v38, v166, v42, s[90:91]
	v_cndmask_b32_e64 v39, v167, v43, s[90:91]
	v_cndmask_b32_e64 v40, v40, v164, s[90:91]
	v_cndmask_b32_e64 v41, v41, v165, s[90:91]
	v_cndmask_b32_e64 v42, v42, v166, s[90:91]
	v_cndmask_b32_e64 v43, v43, v167, s[90:91]
	s_lshl_b32 s94, s51, 8
	s_add_i32 s94, s94, 144
	s_lshl_b32 s94, s94, 14
	s_add_u32 s86, s48, s94
	s_addc_u32 s87, s49, 0
	s_lshl_b32 s94, s51, 8
	s_add_i32 s94, s94, 144
	s_lshl_b32 s94, s94, 13
	s_add_u32 s88, s12, s94
	s_addc_u32 s89, s13, 0
	s_lshl_b32 s94, s51, 8
	s_add_i32 s94, s94, 144
	s_lshl_b32 s94, s94, 8
	s_add_u32 s92, s22, s94
	s_addc_u32 s93, s23, 0
	s_waitcnt vmcnt(9)
	v_pk_add_f32 v[48:49], v[48:49], v[16:17]
	v_pk_add_f32 v[50:51], v[50:51], v[18:19]
	v_pk_add_f32 v[44:45], v[44:45], v[12:13]
	v_pk_add_f32 v[46:47], v[46:47], v[14:15]
	global_store_dwordx4 v193, v[48:51], s[86:87]
	global_store_dwordx4 v206, v[44:47], s[86:87]
	v_mul_f32_e32 v214, v48, v48
	v_fmac_f32_e32 v214, v49, v49
	v_fmac_f32_e32 v214, v50, v50
	v_fmac_f32_e32 v214, v51, v51
	v_mul_f32_e32 v215, v44, v44
	v_fmac_f32_e32 v215, v45, v45
	v_fmac_f32_e32 v215, v46, v46
	v_fmac_f32_e32 v215, v47, v47
	v_pk_mul_f32 v[164:165], v[48:49], v[148:149]
	v_pk_mul_f32 v[166:167], v[50:51], v[150:151]
	v_cvt_pk_bf16_f32 v168, v164, v165
	v_cvt_pk_bf16_f32 v169, v166, v167
	global_store_dwordx2 v207, v[168:169], s[88:89]
	v_pk_mul_f32 v[164:165], v[44:45], v[156:157]
	v_pk_mul_f32 v[166:167], v[46:47], v[158:159]
	v_cvt_pk_bf16_f32 v170, v164, v165
	v_cvt_pk_bf16_f32 v171, v166, v167
	global_store_dwordx2 v208, v[170:171], s[88:89]
	v_pk_add_f32 v[40:41], v[40:41], v[8:9]
	v_pk_add_f32 v[42:43], v[42:43], v[10:11]
	v_pk_add_f32 v[36:37], v[36:37], v[4:5]
	v_pk_add_f32 v[38:39], v[38:39], v[6:7]
	global_store_dwordx4 v193, v[40:43], s[86:87] offset:512
	global_store_dwordx4 v206, v[36:39], s[86:87] offset:512
	v_fmac_f32_e32 v214, v40, v40
	v_fmac_f32_e32 v214, v41, v41
	v_fmac_f32_e32 v214, v42, v42
	v_fmac_f32_e32 v214, v43, v43
	v_fmac_f32_e32 v215, v36, v36
	v_fmac_f32_e32 v215, v37, v37
	v_fmac_f32_e32 v215, v38, v38
	v_fmac_f32_e32 v215, v39, v39
	v_pk_mul_f32 v[164:165], v[40:41], v[152:153]
	v_pk_mul_f32 v[166:167], v[42:43], v[154:155]
	v_cvt_pk_bf16_f32 v168, v164, v165
	v_cvt_pk_bf16_f32 v169, v166, v167
	global_store_dwordx2 v207, v[168:169], s[88:89] offset:256
	v_pk_mul_f32 v[164:165], v[36:37], v[160:161]
	v_pk_mul_f32 v[166:167], v[38:39], v[162:163]
	v_cvt_pk_bf16_f32 v170, v164, v165
	v_cvt_pk_bf16_f32 v171, v166, v167
	global_store_dwordx2 v208, v[170:171], s[88:89] offset:256
	s_nop 1
	v_add_f32_dpp v180, v214, v214 row_ror:8 row_mask:0xf bank_mask:0xf
	v_add_f32_dpp v192, v215, v215 row_ror:8 row_mask:0xf bank_mask:0xf
	v_cndmask_b32_e64 v214, v180, v192, s[90:91]
	v_mov_b32_e32 v215, v214
	s_nop 1
	v_permlane16_swap_b32_e32 v214, v215
	v_add_f32_e32 v214, v214, v215
	v_mov_b32_e32 v215, v214
	s_nop 1
	v_permlane32_swap_b32_e32 v214, v215
	v_add_f32_e32 v214, v214, v215
	s_and_saveexec_b64 s[14:15], s[38:39]
	global_store_dword v211, v214, s[92:93]
	s_or_b64 exec, exec, s[14:15]
	s_branch .Lrot_p8x_end
.Lrot_p8x_3:
	v_and_b32_e32 v192, 8, v219
	v_cmp_ne_u32_e64 s[90:91], 0, v192
	v_sub_u32_e32 v214, v1, v192
	v_lshlrev_b32_e32 v192, 1, v192
	s_lshl_b32 s94, s50, 8
	v_add3_u32 v215, v240, v192, s94
	v_sub_u32_e32 v180, v240, v192
	v_add3_u32 v180, v180, 16, s94
	v_lshlrev_b32_e32 v193, 14, v214
	v_lshl_add_u32 v206, v180, 2, v193
	v_add_u32_e32 v206, 0x20000, v206
	v_lshl_add_u32 v193, v215, 2, v193
	v_lshlrev_b32_e32 v207, 13, v214
	v_lshl_add_u32 v208, v180, 1, v207
	v_add_u32_e32 v208, 0x10000, v208
	v_lshl_add_u32 v207, v215, 1, v207
	v_lshlrev_b32_e32 v209, 2, v215
	v_lshlrev_b32_e32 v210, 2, v180
	global_load_dwordx4 v[148:151], v209, s[16:17]
	global_load_dwordx4 v[156:159], v210, s[16:17]
	global_load_dwordx4 v[152:155], v209, s[16:17] offset:512
	global_load_dwordx4 v[160:163], v210, s[16:17] offset:512
	s_lshl_b32 s94, s50, 4
	s_lshl_b32 s95, s34, 2
	s_add_i32 s94, s94, s95
	v_lshlrev_b32_e32 v211, 8, v1
	v_add_u32_e32 v211, s94, v211
	v_xor_b32_e32 v212, 16, v219
	v_lshlrev_b32_e32 v212, 2, v212
	v_xor_b32_e32 v213, 32, v219
	v_lshlrev_b32_e32 v213, 2, v213
	s_lshl_b32 s94, s51, 8
	s_add_i32 s94, s94, 48
	s_lshl_b32 s94, s94, 14
	s_add_u32 s84, s48, s94
	s_addc_u32 s85, s49, 0
	global_load_dwordx4 v[60:63], v193, s[84:85]
	global_load_dwordx4 v[68:71], v206, s[84:85]
	global_load_dwordx4 v[76:79], v193, s[84:85] offset:512
	global_load_dwordx4 v[80:83], v206, s[84:85] offset:512
	s_lshl_b32 s94, s51, 8
	s_lshl_b32 s94, s94, 14
	s_add_u32 s84, s48, s94
	s_addc_u32 s85, s49, 0
	global_load_dwordx4 v[172:175], v193, s[84:85]
	global_load_dwordx4 v[176:179], v206, s[84:85]
	global_load_dwordx4 v[182:185], v193, s[84:85] offset:512
	global_load_dwordx4 v[232:235], v206, s[84:85] offset:512
	v_mov_b32_dpp v164, v92 row_ror:8 row_mask:0xf bank_mask:0xf
	v_mov_b32_dpp v165, v93 row_ror:8 row_mask:0xf bank_mask:0xf
	v_mov_b32_dpp v166, v94 row_ror:8 row_mask:0xf bank_mask:0xf
	v_mov_b32_dpp v167, v95 row_ror:8 row_mask:0xf bank_mask:0xf
	v_cndmask_b32_e64 v92, v164, v96, s[90:91]
	v_cndmask_b32_e64 v93, v165, v97, s[90:91]
	v_cndmask_b32_e64 v94, v166, v98, s[90:91]
	v_cndmask_b32_e64 v95, v167, v99, s[90:91]
	v_cndmask_b32_e64 v96, v96, v164, s[90:91]
	v_cndmask_b32_e64 v97, v97, v165, s[90:91]
	v_cndmask_b32_e64 v98, v98, v166, s[90:91]
	v_cndmask_b32_e64 v99, v99, v167, s[90:91]
	v_mov_b32_dpp v164, v84 row_ror:8 row_mask:0xf bank_mask:0xf
	v_mov_b32_dpp v165, v85 row_ror:8 row_mask:0xf bank_mask:0xf
	v_mov_b32_dpp v166, v86 row_ror:8 row_mask:0xf bank_mask:0xf
	v_mov_b32_dpp v167, v87 row_ror:8 row_mask:0xf bank_mask:0xf
	v_cndmask_b32_e64 v84, v164, v88, s[90:91]
	v_cndmask_b32_e64 v85, v165, v89, s[90:91]
	v_cndmask_b32_e64 v86, v166, v90, s[90:91]
	v_cndmask_b32_e64 v87, v167, v91, s[90:91]
	v_cndmask_b32_e64 v88, v88, v164, s[90:91]
	v_cndmask_b32_e64 v89, v89, v165, s[90:91]
	v_cndmask_b32_e64 v90, v90, v166, s[90:91]
	v_cndmask_b32_e64 v91, v91, v167, s[90:91]
	s_lshl_b32 s94, s51, 8
	s_add_i32 s94, s94, 48
	s_lshl_b32 s94, s94, 14
	s_add_u32 s86, s48, s94
	s_addc_u32 s87, s49, 0
	s_lshl_b32 s94, s51, 8
	s_add_i32 s94, s94, 48
	s_lshl_b32 s94, s94, 13
	s_add_u32 s88, s12, s94
	s_addc_u32 s89, s13, 0
	s_lshl_b32 s94, s51, 8
	s_add_i32 s94, s94, 48
	s_lshl_b32 s94, s94, 8
	s_add_u32 s92, s22, s94
	s_addc_u32 s93, s23, 0
	s_waitcnt vmcnt(4)
	v_pk_add_f32 v[96:97], v[96:97], v[60:61]
	v_pk_add_f32 v[98:99], v[98:99], v[62:63]
	v_pk_add_f32 v[92:93], v[92:93], v[68:69]
	v_pk_add_f32 v[94:95], v[94:95], v[70:71]
	global_store_dwordx4 v193, v[96:99], s[86:87]
	global_store_dwordx4 v206, v[92:95], s[86:87]
	v_mul_f32_e32 v214, v96, v96
	v_fmac_f32_e32 v214, v97, v97
	v_fmac_f32_e32 v214, v98, v98
	v_fmac_f32_e32 v214, v99, v99
	v_mul_f32_e32 v215, v92, v92
	v_fmac_f32_e32 v215, v93, v93
	v_fmac_f32_e32 v215, v94, v94
	v_fmac_f32_e32 v215, v95, v95
	v_pk_mul_f32 v[164:165], v[96:97], v[148:149]
	v_pk_mul_f32 v[166:167], v[98:99], v[150:151]
	v_cvt_pk_bf16_f32 v168, v164, v165
	v_cvt_pk_bf16_f32 v169, v166, v167
	global_store_dwordx2 v207, v[168:169], s[88:89]
	v_pk_mul_f32 v[164:165], v[92:93], v[156:157]
	v_pk_mul_f32 v[166:167], v[94:95], v[158:159]
	v_cvt_pk_bf16_f32 v170, v164, v165
	v_cvt_pk_bf16_f32 v171, v166, v167
	global_store_dwordx2 v208, v[170:171], s[88:89]
	v_pk_add_f32 v[88:89], v[88:89], v[76:77]
	v_pk_add_f32 v[90:91], v[90:91], v[78:79]
	v_pk_add_f32 v[84:85], v[84:85], v[80:81]
	v_pk_add_f32 v[86:87], v[86:87], v[82:83]
	global_store_dwordx4 v193, v[88:91], s[86:87] offset:512
	global_store_dwordx4 v206, v[84:87], s[86:87] offset:512
	v_fmac_f32_e32 v214, v88, v88
	v_fmac_f32_e32 v214, v89, v89
	v_fmac_f32_e32 v214, v90, v90
	v_fmac_f32_e32 v214, v91, v91
	v_fmac_f32_e32 v215, v84, v84
	v_fmac_f32_e32 v215, v85, v85
	v_fmac_f32_e32 v215, v86, v86
	v_fmac_f32_e32 v215, v87, v87
	v_pk_mul_f32 v[164:165], v[88:89], v[152:153]
	v_pk_mul_f32 v[166:167], v[90:91], v[154:155]
	v_cvt_pk_bf16_f32 v168, v164, v165
	v_cvt_pk_bf16_f32 v169, v166, v167
	global_store_dwordx2 v207, v[168:169], s[88:89] offset:256
	v_pk_mul_f32 v[164:165], v[84:85], v[160:161]
	v_pk_mul_f32 v[166:167], v[86:87], v[162:163]
	v_cvt_pk_bf16_f32 v170, v164, v165
	v_cvt_pk_bf16_f32 v171, v166, v167
	global_store_dwordx2 v208, v[170:171], s[88:89] offset:256
	s_nop 1
	v_add_f32_dpp v180, v214, v214 row_ror:8 row_mask:0xf bank_mask:0xf
	v_add_f32_dpp v192, v215, v215 row_ror:8 row_mask:0xf bank_mask:0xf
	v_cndmask_b32_e64 v214, v180, v192, s[90:91]
	v_mov_b32_e32 v215, v214
	s_nop 1
	v_permlane16_swap_b32_e32 v214, v215
	v_add_f32_e32 v214, v214, v215
	v_mov_b32_e32 v215, v214
	s_nop 1
	v_permlane32_swap_b32_e32 v214, v215
	v_add_f32_e32 v214, v214, v215
	s_and_saveexec_b64 s[14:15], s[38:39]
	global_store_dword v211, v214, s[92:93]
	s_or_b64 exec, exec, s[14:15]
	s_lshl_b32 s94, s51, 8
	s_add_i32 s94, s94, 16
	s_lshl_b32 s94, s94, 14
	s_add_u32 s84, s48, s94
	s_addc_u32 s85, s49, 0
	global_load_dwordx4 v[96:99], v193, s[84:85]
	global_load_dwordx4 v[92:95], v206, s[84:85]
	global_load_dwordx4 v[88:91], v193, s[84:85] offset:512
	global_load_dwordx4 v[84:87], v206, s[84:85] offset:512
	v_mov_b32_dpp v164, v140 row_ror:8 row_mask:0xf bank_mask:0xf
	v_mov_b32_dpp v165, v141 row_ror:8 row_mask:0xf bank_mask:0xf
	v_mov_b32_dpp v166, v142 row_ror:8 row_mask:0xf bank_mask:0xf
	v_mov_b32_dpp v167, v143 row_ror:8 row_mask:0xf bank_mask:0xf
	v_cndmask_b32_e64 v140, v164, v144, s[90:91]
	v_cndmask_b32_e64 v141, v165, v145, s[90:91]
	v_cndmask_b32_e64 v142, v166, v146, s[90:91]
	v_cndmask_b32_e64 v143, v167, v147, s[90:91]
	v_cndmask_b32_e64 v144, v144, v164, s[90:91]
	v_cndmask_b32_e64 v145, v145, v165, s[90:91]
	v_cndmask_b32_e64 v146, v146, v166, s[90:91]
	v_cndmask_b32_e64 v147, v147, v167, s[90:91]
	v_mov_b32_dpp v164, v132 row_ror:8 row_mask:0xf bank_mask:0xf
	v_mov_b32_dpp v165, v133 row_ror:8 row_mask:0xf bank_mask:0xf
	v_mov_b32_dpp v166, v134 row_ror:8 row_mask:0xf bank_mask:0xf
	v_mov_b32_dpp v167, v135 row_ror:8 row_mask:0xf bank_mask:0xf
	v_cndmask_b32_e64 v132, v164, v136, s[90:91]
	v_cndmask_b32_e64 v133, v165, v137, s[90:91]
	v_cndmask_b32_e64 v134, v166, v138, s[90:91]
	v_cndmask_b32_e64 v135, v167, v139, s[90:91]
	v_cndmask_b32_e64 v136, v136, v164, s[90:91]
	v_cndmask_b32_e64 v137, v137, v165, s[90:91]
	v_cndmask_b32_e64 v138, v138, v166, s[90:91]
	v_cndmask_b32_e64 v139, v139, v167, s[90:91]
	s_lshl_b32 s94, s51, 8
	s_lshl_b32 s94, s94, 14
	s_add_u32 s86, s48, s94
	s_addc_u32 s87, s49, 0
	s_lshl_b32 s94, s51, 8
	s_lshl_b32 s94, s94, 13
	s_add_u32 s88, s12, s94
	s_addc_u32 s89, s13, 0
	s_lshl_b32 s94, s51, 8
	s_lshl_b32 s94, s94, 8
	s_add_u32 s92, s22, s94
	s_addc_u32 s93, s23, 0
	s_waitcnt vmcnt(13)
	v_pk_add_f32 v[144:145], v[144:145], v[172:173]
	v_pk_add_f32 v[146:147], v[146:147], v[174:175]
	v_pk_add_f32 v[140:141], v[140:141], v[176:177]
	v_pk_add_f32 v[142:143], v[142:143], v[178:179]
	global_store_dwordx4 v193, v[144:147], s[86:87]
	global_store_dwordx4 v206, v[140:143], s[86:87]
	v_mul_f32_e32 v214, v144, v144
	v_fmac_f32_e32 v214, v145, v145
	v_fmac_f32_e32 v214, v146, v146
	v_fmac_f32_e32 v214, v147, v147
	v_mul_f32_e32 v215, v140, v140
	v_fmac_f32_e32 v215, v141, v141
	v_fmac_f32_e32 v215, v142, v142
	v_fmac_f32_e32 v215, v143, v143
	v_pk_mul_f32 v[164:165], v[144:145], v[148:149]
	v_pk_mul_f32 v[166:167], v[146:147], v[150:151]
	v_cvt_pk_bf16_f32 v168, v164, v165
	v_cvt_pk_bf16_f32 v169, v166, v167
	global_store_dwordx2 v207, v[168:169], s[88:89]
	v_pk_mul_f32 v[164:165], v[140:141], v[156:157]
	v_pk_mul_f32 v[166:167], v[142:143], v[158:159]
	v_cvt_pk_bf16_f32 v170, v164, v165
	v_cvt_pk_bf16_f32 v171, v166, v167
	global_store_dwordx2 v208, v[170:171], s[88:89]
	v_pk_add_f32 v[136:137], v[136:137], v[182:183]
	v_pk_add_f32 v[138:139], v[138:139], v[184:185]
	v_pk_add_f32 v[132:133], v[132:133], v[232:233]
	v_pk_add_f32 v[134:135], v[134:135], v[234:235]
	global_store_dwordx4 v193, v[136:139], s[86:87] offset:512
	global_store_dwordx4 v206, v[132:135], s[86:87] offset:512
	v_fmac_f32_e32 v214, v136, v136
	v_fmac_f32_e32 v214, v137, v137
	v_fmac_f32_e32 v214, v138, v138
	v_fmac_f32_e32 v214, v139, v139
	v_fmac_f32_e32 v215, v132, v132
	v_fmac_f32_e32 v215, v133, v133
	v_fmac_f32_e32 v215, v134, v134
	v_fmac_f32_e32 v215, v135, v135
	v_pk_mul_f32 v[164:165], v[136:137], v[152:153]
	v_pk_mul_f32 v[166:167], v[138:139], v[154:155]
	v_cvt_pk_bf16_f32 v168, v164, v165
	v_cvt_pk_bf16_f32 v169, v166, v167
	global_store_dwordx2 v207, v[168:169], s[88:89] offset:256
	v_pk_mul_f32 v[164:165], v[132:133], v[160:161]
	v_pk_mul_f32 v[166:167], v[134:135], v[162:163]
	v_cvt_pk_bf16_f32 v170, v164, v165
	v_cvt_pk_bf16_f32 v171, v166, v167
	global_store_dwordx2 v208, v[170:171], s[88:89] offset:256
	s_nop 1
	v_add_f32_dpp v180, v214, v214 row_ror:8 row_mask:0xf bank_mask:0xf
	v_add_f32_dpp v192, v215, v215 row_ror:8 row_mask:0xf bank_mask:0xf
	v_cndmask_b32_e64 v214, v180, v192, s[90:91]
	v_mov_b32_e32 v215, v214
	s_nop 1
	v_permlane16_swap_b32_e32 v214, v215
	v_add_f32_e32 v214, v214, v215
	v_mov_b32_e32 v215, v214
	s_nop 1
	v_permlane32_swap_b32_e32 v214, v215
	v_add_f32_e32 v214, v214, v215
	s_and_saveexec_b64 s[14:15], s[38:39]
	global_store_dword v211, v214, s[92:93]
	s_or_b64 exec, exec, s[14:15]
	s_lshl_b32 s94, s51, 8
	s_add_i32 s94, s94, 32
	s_lshl_b32 s94, s94, 14
	s_add_u32 s84, s48, s94
	s_addc_u32 s85, s49, 0
	global_load_dwordx4 v[144:147], v193, s[84:85]
	global_load_dwordx4 v[140:143], v206, s[84:85]
	global_load_dwordx4 v[136:139], v193, s[84:85] offset:512
	global_load_dwordx4 v[132:135], v206, s[84:85] offset:512
	v_mov_b32_dpp v164, v124 row_ror:8 row_mask:0xf bank_mask:0xf
	v_mov_b32_dpp v165, v125 row_ror:8 row_mask:0xf bank_mask:0xf
	v_mov_b32_dpp v166, v126 row_ror:8 row_mask:0xf bank_mask:0xf
	v_mov_b32_dpp v167, v127 row_ror:8 row_mask:0xf bank_mask:0xf
	v_cndmask_b32_e64 v124, v164, v128, s[90:91]
	v_cndmask_b32_e64 v125, v165, v129, s[90:91]
	v_cndmask_b32_e64 v126, v166, v130, s[90:91]
	v_cndmask_b32_e64 v127, v167, v131, s[90:91]
	v_cndmask_b32_e64 v128, v128, v164, s[90:91]
	v_cndmask_b32_e64 v129, v129, v165, s[90:91]
	v_cndmask_b32_e64 v130, v130, v166, s[90:91]
	v_cndmask_b32_e64 v131, v131, v167, s[90:91]
	v_mov_b32_dpp v164, v116 row_ror:8 row_mask:0xf bank_mask:0xf
	v_mov_b32_dpp v165, v117 row_ror:8 row_mask:0xf bank_mask:0xf
	v_mov_b32_dpp v166, v118 row_ror:8 row_mask:0xf bank_mask:0xf
	v_mov_b32_dpp v167, v119 row_ror:8 row_mask:0xf bank_mask:0xf
	v_cndmask_b32_e64 v116, v164, v120, s[90:91]
	v_cndmask_b32_e64 v117, v165, v121, s[90:91]
	v_cndmask_b32_e64 v118, v166, v122, s[90:91]
	v_cndmask_b32_e64 v119, v167, v123, s[90:91]
	v_cndmask_b32_e64 v120, v120, v164, s[90:91]
	v_cndmask_b32_e64 v121, v121, v165, s[90:91]
	v_cndmask_b32_e64 v122, v122, v166, s[90:91]
	v_cndmask_b32_e64 v123, v123, v167, s[90:91]
	s_lshl_b32 s94, s51, 8
	s_add_i32 s94, s94, 16
	s_lshl_b32 s94, s94, 14
	s_add_u32 s86, s48, s94
	s_addc_u32 s87, s49, 0
	s_lshl_b32 s94, s51, 8
	s_add_i32 s94, s94, 16
	s_lshl_b32 s94, s94, 13
	s_add_u32 s88, s12, s94
	s_addc_u32 s89, s13, 0
	s_lshl_b32 s94, s51, 8
	s_add_i32 s94, s94, 16
	s_lshl_b32 s94, s94, 8
	s_add_u32 s92, s22, s94
	s_addc_u32 s93, s23, 0
	s_waitcnt vmcnt(13)
	v_pk_add_f32 v[128:129], v[128:129], v[96:97]
	v_pk_add_f32 v[130:131], v[130:131], v[98:99]
	v_pk_add_f32 v[124:125], v[124:125], v[92:93]
	v_pk_add_f32 v[126:127], v[126:127], v[94:95]
	global_store_dwordx4 v193, v[128:131], s[86:87]
	global_store_dwordx4 v206, v[124:127], s[86:87]
	v_mul_f32_e32 v214, v128, v128
	v_fmac_f32_e32 v214, v129, v129
	v_fmac_f32_e32 v214, v130, v130
	v_fmac_f32_e32 v214, v131, v131
	v_mul_f32_e32 v215, v124, v124
	v_fmac_f32_e32 v215, v125, v125
	v_fmac_f32_e32 v215, v126, v126
	v_fmac_f32_e32 v215, v127, v127
	v_pk_mul_f32 v[164:165], v[128:129], v[148:149]
	v_pk_mul_f32 v[166:167], v[130:131], v[150:151]
	v_cvt_pk_bf16_f32 v168, v164, v165
	v_cvt_pk_bf16_f32 v169, v166, v167
	global_store_dwordx2 v207, v[168:169], s[88:89]
	v_pk_mul_f32 v[164:165], v[124:125], v[156:157]
	v_pk_mul_f32 v[166:167], v[126:127], v[158:159]
	v_cvt_pk_bf16_f32 v170, v164, v165
	v_cvt_pk_bf16_f32 v171, v166, v167
	global_store_dwordx2 v208, v[170:171], s[88:89]
	v_pk_add_f32 v[120:121], v[120:121], v[88:89]
	v_pk_add_f32 v[122:123], v[122:123], v[90:91]
	v_pk_add_f32 v[116:117], v[116:117], v[84:85]
	v_pk_add_f32 v[118:119], v[118:119], v[86:87]
	global_store_dwordx4 v193, v[120:123], s[86:87] offset:512
	global_store_dwordx4 v206, v[116:119], s[86:87] offset:512
	v_fmac_f32_e32 v214, v120, v120
	v_fmac_f32_e32 v214, v121, v121
	v_fmac_f32_e32 v214, v122, v122
	v_fmac_f32_e32 v214, v123, v123
	v_fmac_f32_e32 v215, v116, v116
	v_fmac_f32_e32 v215, v117, v117
	v_fmac_f32_e32 v215, v118, v118
	v_fmac_f32_e32 v215, v119, v119
	v_pk_mul_f32 v[164:165], v[120:121], v[152:153]
	v_pk_mul_f32 v[166:167], v[122:123], v[154:155]
	v_cvt_pk_bf16_f32 v168, v164, v165
	v_cvt_pk_bf16_f32 v169, v166, v167
	global_store_dwordx2 v207, v[168:169], s[88:89] offset:256
	v_pk_mul_f32 v[164:165], v[116:117], v[160:161]
	v_pk_mul_f32 v[166:167], v[118:119], v[162:163]
	v_cvt_pk_bf16_f32 v170, v164, v165
	v_cvt_pk_bf16_f32 v171, v166, v167
	global_store_dwordx2 v208, v[170:171], s[88:89] offset:256
	s_nop 1
	v_add_f32_dpp v180, v214, v214 row_ror:8 row_mask:0xf bank_mask:0xf
	v_add_f32_dpp v192, v215, v215 row_ror:8 row_mask:0xf bank_mask:0xf
	v_cndmask_b32_e64 v214, v180, v192, s[90:91]
	v_mov_b32_e32 v215, v214
	s_nop 1
	v_permlane16_swap_b32_e32 v214, v215
	v_add_f32_e32 v214, v214, v215
	v_mov_b32_e32 v215, v214
	s_nop 1
	v_permlane32_swap_b32_e32 v214, v215
	v_add_f32_e32 v214, v214, v215
	s_and_saveexec_b64 s[14:15], s[38:39]
	global_store_dword v211, v214, s[92:93]
	s_or_b64 exec, exec, s[14:15]
	s_lshl_b32 s94, s51, 8
	s_add_i32 s94, s94, 176
	s_lshl_b32 s94, s94, 14
	s_add_u32 s84, s48, s94
	s_addc_u32 s85, s49, 0
	global_load_dwordx4 v[128:131], v193, s[84:85]
	global_load_dwordx4 v[124:127], v206, s[84:85]
	global_load_dwordx4 v[120:123], v193, s[84:85] offset:512
	global_load_dwordx4 v[116:119], v206, s[84:85] offset:512
	v_mov_b32_dpp v164, v108 row_ror:8 row_mask:0xf bank_mask:0xf
	v_mov_b32_dpp v165, v109 row_ror:8 row_mask:0xf bank_mask:0xf
	v_mov_b32_dpp v166, v110 row_ror:8 row_mask:0xf bank_mask:0xf
	v_mov_b32_dpp v167, v111 row_ror:8 row_mask:0xf bank_mask:0xf
	v_cndmask_b32_e64 v108, v164, v112, s[90:91]
	v_cndmask_b32_e64 v109, v165, v113, s[90:91]
	v_cndmask_b32_e64 v110, v166, v114, s[90:91]
	v_cndmask_b32_e64 v111, v167, v115, s[90:91]
	v_cndmask_b32_e64 v112, v112, v164, s[90:91]
	v_cndmask_b32_e64 v113, v113, v165, s[90:91]
	v_cndmask_b32_e64 v114, v114, v166, s[90:91]
	v_cndmask_b32_e64 v115, v115, v167, s[90:91]
	v_mov_b32_dpp v164, v100 row_ror:8 row_mask:0xf bank_mask:0xf
	v_mov_b32_dpp v165, v101 row_ror:8 row_mask:0xf bank_mask:0xf
	v_mov_b32_dpp v166, v102 row_ror:8 row_mask:0xf bank_mask:0xf
	v_mov_b32_dpp v167, v103 row_ror:8 row_mask:0xf bank_mask:0xf
	v_cndmask_b32_e64 v100, v164, v104, s[90:91]
	v_cndmask_b32_e64 v101, v165, v105, s[90:91]
	v_cndmask_b32_e64 v102, v166, v106, s[90:91]
	v_cndmask_b32_e64 v103, v167, v107, s[90:91]
	v_cndmask_b32_e64 v104, v104, v164, s[90:91]
	v_cndmask_b32_e64 v105, v105, v165, s[90:91]
	v_cndmask_b32_e64 v106, v106, v166, s[90:91]
	v_cndmask_b32_e64 v107, v107, v167, s[90:91]
	s_lshl_b32 s94, s51, 8
	s_add_i32 s94, s94, 32
	s_lshl_b32 s94, s94, 14
	s_add_u32 s86, s48, s94
	s_addc_u32 s87, s49, 0
	s_lshl_b32 s94, s51, 8
	s_add_i32 s94, s94, 32
	s_lshl_b32 s94, s94, 13
	s_add_u32 s88, s12, s94
	s_addc_u32 s89, s13, 0
	s_lshl_b32 s94, s51, 8
	s_add_i32 s94, s94, 32
	s_lshl_b32 s94, s94, 8
	s_add_u32 s92, s22, s94
	s_addc_u32 s93, s23, 0
	s_waitcnt vmcnt(13)
	v_pk_add_f32 v[112:113], v[112:113], v[144:145]
	v_pk_add_f32 v[114:115], v[114:115], v[146:147]
	v_pk_add_f32 v[108:109], v[108:109], v[140:141]
	v_pk_add_f32 v[110:111], v[110:111], v[142:143]
	global_store_dwordx4 v193, v[112:115], s[86:87]
	global_store_dwordx4 v206, v[108:111], s[86:87]
	v_mul_f32_e32 v214, v112, v112
	v_fmac_f32_e32 v214, v113, v113
	v_fmac_f32_e32 v214, v114, v114
	v_fmac_f32_e32 v214, v115, v115
	v_mul_f32_e32 v215, v108, v108
	v_fmac_f32_e32 v215, v109, v109
	v_fmac_f32_e32 v215, v110, v110
	v_fmac_f32_e32 v215, v111, v111
	v_pk_mul_f32 v[164:165], v[112:113], v[148:149]
	v_pk_mul_f32 v[166:167], v[114:115], v[150:151]
	v_cvt_pk_bf16_f32 v168, v164, v165
	v_cvt_pk_bf16_f32 v169, v166, v167
	global_store_dwordx2 v207, v[168:169], s[88:89]
	v_pk_mul_f32 v[164:165], v[108:109], v[156:157]
	v_pk_mul_f32 v[166:167], v[110:111], v[158:159]
	v_cvt_pk_bf16_f32 v170, v164, v165
	v_cvt_pk_bf16_f32 v171, v166, v167
	global_store_dwordx2 v208, v[170:171], s[88:89]
	v_pk_add_f32 v[104:105], v[104:105], v[136:137]
	v_pk_add_f32 v[106:107], v[106:107], v[138:139]
	v_pk_add_f32 v[100:101], v[100:101], v[132:133]
	v_pk_add_f32 v[102:103], v[102:103], v[134:135]
	global_store_dwordx4 v193, v[104:107], s[86:87] offset:512
	global_store_dwordx4 v206, v[100:103], s[86:87] offset:512
	v_fmac_f32_e32 v214, v104, v104
	v_fmac_f32_e32 v214, v105, v105
	v_fmac_f32_e32 v214, v106, v106
	v_fmac_f32_e32 v214, v107, v107
	v_fmac_f32_e32 v215, v100, v100
	v_fmac_f32_e32 v215, v101, v101
	v_fmac_f32_e32 v215, v102, v102
	v_fmac_f32_e32 v215, v103, v103
	v_pk_mul_f32 v[164:165], v[104:105], v[152:153]
	v_pk_mul_f32 v[166:167], v[106:107], v[154:155]
	v_cvt_pk_bf16_f32 v168, v164, v165
	v_cvt_pk_bf16_f32 v169, v166, v167
	global_store_dwordx2 v207, v[168:169], s[88:89] offset:256
	v_pk_mul_f32 v[164:165], v[100:101], v[160:161]
	v_pk_mul_f32 v[166:167], v[102:103], v[162:163]
	v_cvt_pk_bf16_f32 v170, v164, v165
	v_cvt_pk_bf16_f32 v171, v166, v167
	global_store_dwordx2 v208, v[170:171], s[88:89] offset:256
	s_nop 1
	v_add_f32_dpp v180, v214, v214 row_ror:8 row_mask:0xf bank_mask:0xf
	v_add_f32_dpp v192, v215, v215 row_ror:8 row_mask:0xf bank_mask:0xf
	v_cndmask_b32_e64 v214, v180, v192, s[90:91]
	v_mov_b32_e32 v215, v214
	s_nop 1
	v_permlane16_swap_b32_e32 v214, v215
	v_add_f32_e32 v214, v214, v215
	v_mov_b32_e32 v215, v214
	s_nop 1
	v_permlane32_swap_b32_e32 v214, v215
	v_add_f32_e32 v214, v214, v215
	s_and_saveexec_b64 s[14:15], s[38:39]
	global_store_dword v211, v214, s[92:93]
	s_or_b64 exec, exec, s[14:15]
	s_lshl_b32 s94, s51, 8
	s_add_i32 s94, s94, 128
	s_lshl_b32 s94, s94, 14
	s_add_u32 s84, s48, s94
	s_addc_u32 s85, s49, 0
	global_load_dwordx4 v[112:115], v193, s[84:85]
	global_load_dwordx4 v[108:111], v206, s[84:85]
	global_load_dwordx4 v[104:107], v193, s[84:85] offset:512
	global_load_dwordx4 v[100:103], v206, s[84:85] offset:512
	v_mov_b32_dpp v164, v12 row_ror:8 row_mask:0xf bank_mask:0xf
	v_mov_b32_dpp v165, v13 row_ror:8 row_mask:0xf bank_mask:0xf
	v_mov_b32_dpp v166, v14 row_ror:8 row_mask:0xf bank_mask:0xf
	v_mov_b32_dpp v167, v15 row_ror:8 row_mask:0xf bank_mask:0xf
	v_cndmask_b32_e64 v12, v164, v16, s[90:91]
	v_cndmask_b32_e64 v13, v165, v17, s[90:91]
	v_cndmask_b32_e64 v14, v166, v18, s[90:91]
	v_cndmask_b32_e64 v15, v167, v19, s[90:91]
	v_cndmask_b32_e64 v16, v16, v164, s[90:91]
	v_cndmask_b32_e64 v17, v17, v165, s[90:91]
	v_cndmask_b32_e64 v18, v18, v166, s[90:91]
	v_cndmask_b32_e64 v19, v19, v167, s[90:91]
	v_mov_b32_dpp v164, v4 row_ror:8 row_mask:0xf bank_mask:0xf
	v_mov_b32_dpp v165, v5 row_ror:8 row_mask:0xf bank_mask:0xf
	v_mov_b32_dpp v166, v6 row_ror:8 row_mask:0xf bank_mask:0xf
	v_mov_b32_dpp v167, v7 row_ror:8 row_mask:0xf bank_mask:0xf
	v_cndmask_b32_e64 v4, v164, v8, s[90:91]
	v_cndmask_b32_e64 v5, v165, v9, s[90:91]
	v_cndmask_b32_e64 v6, v166, v10, s[90:91]
	v_cndmask_b32_e64 v7, v167, v11, s[90:91]
	v_cndmask_b32_e64 v8, v8, v164, s[90:91]
	v_cndmask_b32_e64 v9, v9, v165, s[90:91]
	v_cndmask_b32_e64 v10, v10, v166, s[90:91]
	v_cndmask_b32_e64 v11, v11, v167, s[90:91]
	s_lshl_b32 s94, s51, 8
	s_add_i32 s94, s94, 176
	s_lshl_b32 s94, s94, 14
	s_add_u32 s86, s48, s94
	s_addc_u32 s87, s49, 0
	s_lshl_b32 s94, s51, 8
	s_add_i32 s94, s94, 176
	s_lshl_b32 s94, s94, 13
	s_add_u32 s88, s12, s94
	s_addc_u32 s89, s13, 0
	s_lshl_b32 s94, s51, 8
	s_add_i32 s94, s94, 176
	s_lshl_b32 s94, s94, 8
	s_add_u32 s92, s22, s94
	s_addc_u32 s93, s23, 0
	s_waitcnt vmcnt(13)
	v_pk_add_f32 v[16:17], v[16:17], v[128:129]
	v_pk_add_f32 v[18:19], v[18:19], v[130:131]
	v_pk_add_f32 v[12:13], v[12:13], v[124:125]
	v_pk_add_f32 v[14:15], v[14:15], v[126:127]
	global_store_dwordx4 v193, v[16:19], s[86:87]
	global_store_dwordx4 v206, v[12:15], s[86:87]
	v_mul_f32_e32 v214, v16, v16
	v_fmac_f32_e32 v214, v17, v17
	v_fmac_f32_e32 v214, v18, v18
	v_fmac_f32_e32 v214, v19, v19
	v_mul_f32_e32 v215, v12, v12
	v_fmac_f32_e32 v215, v13, v13
	v_fmac_f32_e32 v215, v14, v14
	v_fmac_f32_e32 v215, v15, v15
	v_pk_mul_f32 v[164:165], v[16:17], v[148:149]
	v_pk_mul_f32 v[166:167], v[18:19], v[150:151]
	v_cvt_pk_bf16_f32 v168, v164, v165
	v_cvt_pk_bf16_f32 v169, v166, v167
	global_store_dwordx2 v207, v[168:169], s[88:89]
	v_pk_mul_f32 v[164:165], v[12:13], v[156:157]
	v_pk_mul_f32 v[166:167], v[14:15], v[158:159]
	v_cvt_pk_bf16_f32 v170, v164, v165
	v_cvt_pk_bf16_f32 v171, v166, v167
	global_store_dwordx2 v208, v[170:171], s[88:89]
	v_pk_add_f32 v[8:9], v[8:9], v[120:121]
	v_pk_add_f32 v[10:11], v[10:11], v[122:123]
	v_pk_add_f32 v[4:5], v[4:5], v[116:117]
	v_pk_add_f32 v[6:7], v[6:7], v[118:119]
	global_store_dwordx4 v193, v[8:11], s[86:87] offset:512
	global_store_dwordx4 v206, v[4:7], s[86:87] offset:512
	v_fmac_f32_e32 v214, v8, v8
	v_fmac_f32_e32 v214, v9, v9
	v_fmac_f32_e32 v214, v10, v10
	v_fmac_f32_e32 v214, v11, v11
	v_fmac_f32_e32 v215, v4, v4
	v_fmac_f32_e32 v215, v5, v5
	v_fmac_f32_e32 v215, v6, v6
	v_fmac_f32_e32 v215, v7, v7
	v_pk_mul_f32 v[164:165], v[8:9], v[152:153]
	v_pk_mul_f32 v[166:167], v[10:11], v[154:155]
	v_cvt_pk_bf16_f32 v168, v164, v165
	v_cvt_pk_bf16_f32 v169, v166, v167
	global_store_dwordx2 v207, v[168:169], s[88:89] offset:256
	v_pk_mul_f32 v[164:165], v[4:5], v[160:161]
	v_pk_mul_f32 v[166:167], v[6:7], v[162:163]
	v_cvt_pk_bf16_f32 v170, v164, v165
	v_cvt_pk_bf16_f32 v171, v166, v167
	global_store_dwordx2 v208, v[170:171], s[88:89] offset:256
	s_nop 1
	v_add_f32_dpp v180, v214, v214 row_ror:8 row_mask:0xf bank_mask:0xf
	v_add_f32_dpp v192, v215, v215 row_ror:8 row_mask:0xf bank_mask:0xf
	v_cndmask_b32_e64 v214, v180, v192, s[90:91]
	v_mov_b32_e32 v215, v214
	s_nop 1
	v_permlane16_swap_b32_e32 v214, v215
	v_add_f32_e32 v214, v214, v215
	v_mov_b32_e32 v215, v214
	s_nop 1
	v_permlane32_swap_b32_e32 v214, v215
	v_add_f32_e32 v214, v214, v215
	s_and_saveexec_b64 s[14:15], s[38:39]
	global_store_dword v211, v214, s[92:93]
	s_or_b64 exec, exec, s[14:15]
	s_lshl_b32 s94, s51, 8
	s_add_i32 s94, s94, 144
	s_lshl_b32 s94, s94, 14
	s_add_u32 s84, s48, s94
	s_addc_u32 s85, s49, 0
	global_load_dwordx4 v[16:19], v193, s[84:85]
	global_load_dwordx4 v[12:15], v206, s[84:85]
	global_load_dwordx4 v[8:11], v193, s[84:85] offset:512
	global_load_dwordx4 v[4:7], v206, s[84:85] offset:512
	v_mov_b32_dpp v164, v64 row_ror:8 row_mask:0xf bank_mask:0xf
	v_mov_b32_dpp v165, v65 row_ror:8 row_mask:0xf bank_mask:0xf
	v_mov_b32_dpp v166, v66 row_ror:8 row_mask:0xf bank_mask:0xf
	v_mov_b32_dpp v167, v67 row_ror:8 row_mask:0xf bank_mask:0xf
	v_cndmask_b32_e64 v64, v164, v72, s[90:91]
	v_cndmask_b32_e64 v65, v165, v73, s[90:91]
	v_cndmask_b32_e64 v66, v166, v74, s[90:91]
	v_cndmask_b32_e64 v67, v167, v75, s[90:91]
	v_cndmask_b32_e64 v72, v72, v164, s[90:91]
	v_cndmask_b32_e64 v73, v73, v165, s[90:91]
	v_cndmask_b32_e64 v74, v74, v166, s[90:91]
	v_cndmask_b32_e64 v75, v75, v167, s[90:91]
	v_mov_b32_dpp v164, v52 row_ror:8 row_mask:0xf bank_mask:0xf
	v_mov_b32_dpp v165, v53 row_ror:8 row_mask:0xf bank_mask:0xf
	v_mov_b32_dpp v166, v54 row_ror:8 row_mask:0xf bank_mask:0xf
	v_mov_b32_dpp v167, v55 row_ror:8 row_mask:0xf bank_mask:0xf
	v_cndmask_b32_e64 v52, v164, v56, s[90:91]
	v_cndmask_b32_e64 v53, v165, v57, s[90:91]
	v_cndmask_b32_e64 v54, v166, v58, s[90:91]
	v_cndmask_b32_e64 v55, v167, v59, s[90:91]
	v_cndmask_b32_e64 v56, v56, v164, s[90:91]
	v_cndmask_b32_e64 v57, v57, v165, s[90:91]
	v_cndmask_b32_e64 v58, v58, v166, s[90:91]
	v_cndmask_b32_e64 v59, v59, v167, s[90:91]
	s_lshl_b32 s94, s51, 8
	s_add_i32 s94, s94, 128
	s_lshl_b32 s94, s94, 14
	s_add_u32 s86, s48, s94
	s_addc_u32 s87, s49, 0
	s_lshl_b32 s94, s51, 8
	s_add_i32 s94, s94, 128
	s_lshl_b32 s94, s94, 13
	s_add_u32 s88, s12, s94
	s_addc_u32 s89, s13, 0
	s_lshl_b32 s94, s51, 8
	s_add_i32 s94, s94, 128
	s_lshl_b32 s94, s94, 8
	s_add_u32 s92, s22, s94
	s_addc_u32 s93, s23, 0
	s_waitcnt vmcnt(13)
	v_pk_add_f32 v[72:73], v[72:73], v[112:113]
	v_pk_add_f32 v[74:75], v[74:75], v[114:115]
	v_pk_add_f32 v[64:65], v[64:65], v[108:109]
	v_pk_add_f32 v[66:67], v[66:67], v[110:111]
	global_store_dwordx4 v193, v[72:75], s[86:87]
	global_store_dwordx4 v206, v[64:67], s[86:87]
	v_mul_f32_e32 v214, v72, v72
	v_fmac_f32_e32 v214, v73, v73
	v_fmac_f32_e32 v214, v74, v74
	v_fmac_f32_e32 v214, v75, v75
	v_mul_f32_e32 v215, v64, v64
	v_fmac_f32_e32 v215, v65, v65
	v_fmac_f32_e32 v215, v66, v66
	v_fmac_f32_e32 v215, v67, v67
	v_pk_mul_f32 v[164:165], v[72:73], v[148:149]
	v_pk_mul_f32 v[166:167], v[74:75], v[150:151]
	v_cvt_pk_bf16_f32 v168, v164, v165
	v_cvt_pk_bf16_f32 v169, v166, v167
	global_store_dwordx2 v207, v[168:169], s[88:89]
	v_pk_mul_f32 v[164:165], v[64:65], v[156:157]
	v_pk_mul_f32 v[166:167], v[66:67], v[158:159]
	v_cvt_pk_bf16_f32 v170, v164, v165
	v_cvt_pk_bf16_f32 v171, v166, v167
	global_store_dwordx2 v208, v[170:171], s[88:89]
	v_pk_add_f32 v[56:57], v[56:57], v[104:105]
	v_pk_add_f32 v[58:59], v[58:59], v[106:107]
	v_pk_add_f32 v[52:53], v[52:53], v[100:101]
	v_pk_add_f32 v[54:55], v[54:55], v[102:103]
	global_store_dwordx4 v193, v[56:59], s[86:87] offset:512
	global_store_dwordx4 v206, v[52:55], s[86:87] offset:512
	v_fmac_f32_e32 v214, v56, v56
	v_fmac_f32_e32 v214, v57, v57
	v_fmac_f32_e32 v214, v58, v58
	v_fmac_f32_e32 v214, v59, v59
	v_fmac_f32_e32 v215, v52, v52
	v_fmac_f32_e32 v215, v53, v53
	v_fmac_f32_e32 v215, v54, v54
	v_fmac_f32_e32 v215, v55, v55
	v_pk_mul_f32 v[164:165], v[56:57], v[152:153]
	v_pk_mul_f32 v[166:167], v[58:59], v[154:155]
	v_cvt_pk_bf16_f32 v168, v164, v165
	v_cvt_pk_bf16_f32 v169, v166, v167
	global_store_dwordx2 v207, v[168:169], s[88:89] offset:256
	v_pk_mul_f32 v[164:165], v[52:53], v[160:161]
	v_pk_mul_f32 v[166:167], v[54:55], v[162:163]
	v_cvt_pk_bf16_f32 v170, v164, v165
	v_cvt_pk_bf16_f32 v171, v166, v167
	global_store_dwordx2 v208, v[170:171], s[88:89] offset:256
	s_nop 1
	v_add_f32_dpp v180, v214, v214 row_ror:8 row_mask:0xf bank_mask:0xf
	v_add_f32_dpp v192, v215, v215 row_ror:8 row_mask:0xf bank_mask:0xf
	v_cndmask_b32_e64 v214, v180, v192, s[90:91]
	v_mov_b32_e32 v215, v214
	s_nop 1
	v_permlane16_swap_b32_e32 v214, v215
	v_add_f32_e32 v214, v214, v215
	v_mov_b32_e32 v215, v214
	s_nop 1
	v_permlane32_swap_b32_e32 v214, v215
	v_add_f32_e32 v214, v214, v215
	s_and_saveexec_b64 s[14:15], s[38:39]
	global_store_dword v211, v214, s[92:93]
	s_or_b64 exec, exec, s[14:15]
	s_lshl_b32 s94, s51, 8
	s_add_i32 s94, s94, 160
	s_lshl_b32 s94, s94, 14
	s_add_u32 s84, s48, s94
	s_addc_u32 s85, s49, 0
	global_load_dwordx4 v[72:75], v193, s[84:85]
	global_load_dwordx4 v[64:67], v206, s[84:85]
	global_load_dwordx4 v[56:59], v193, s[84:85] offset:512
	global_load_dwordx4 v[52:55], v206, s[84:85] offset:512
	v_mov_b32_dpp v164, v44 row_ror:8 row_mask:0xf bank_mask:0xf
	v_mov_b32_dpp v165, v45 row_ror:8 row_mask:0xf bank_mask:0xf
	v_mov_b32_dpp v166, v46 row_ror:8 row_mask:0xf bank_mask:0xf
	v_mov_b32_dpp v167, v47 row_ror:8 row_mask:0xf bank_mask:0xf
	v_cndmask_b32_e64 v44, v164, v48, s[90:91]
	v_cndmask_b32_e64 v45, v165, v49, s[90:91]
	v_cndmask_b32_e64 v46, v166, v50, s[90:91]
	v_cndmask_b32_e64 v47, v167, v51, s[90:91]
	v_cndmask_b32_e64 v48, v48, v164, s[90:91]
	v_cndmask_b32_e64 v49, v49, v165, s[90:91]
	v_cndmask_b32_e64 v50, v50, v166, s[90:91]
	v_cndmask_b32_e64 v51, v51, v167, s[90:91]
	v_mov_b32_dpp v164, v36 row_ror:8 row_mask:0xf bank_mask:0xf
	v_mov_b32_dpp v165, v37 row_ror:8 row_mask:0xf bank_mask:0xf
	v_mov_b32_dpp v166, v38 row_ror:8 row_mask:0xf bank_mask:0xf
	v_mov_b32_dpp v167, v39 row_ror:8 row_mask:0xf bank_mask:0xf
	v_cndmask_b32_e64 v36, v164, v40, s[90:91]
	v_cndmask_b32_e64 v37, v165, v41, s[90:91]
	v_cndmask_b32_e64 v38, v166, v42, s[90:91]
	v_cndmask_b32_e64 v39, v167, v43, s[90:91]
	v_cndmask_b32_e64 v40, v40, v164, s[90:91]
	v_cndmask_b32_e64 v41, v41, v165, s[90:91]
	v_cndmask_b32_e64 v42, v42, v166, s[90:91]
	v_cndmask_b32_e64 v43, v43, v167, s[90:91]
	s_lshl_b32 s94, s51, 8
	s_add_i32 s94, s94, 144
	s_lshl_b32 s94, s94, 14
	s_add_u32 s86, s48, s94
	s_addc_u32 s87, s49, 0
	s_lshl_b32 s94, s51, 8
	s_add_i32 s94, s94, 144
	s_lshl_b32 s94, s94, 13
	s_add_u32 s88, s12, s94
	s_addc_u32 s89, s13, 0
	s_lshl_b32 s94, s51, 8
	s_add_i32 s94, s94, 144
	s_lshl_b32 s94, s94, 8
	s_add_u32 s92, s22, s94
	s_addc_u32 s93, s23, 0
	s_waitcnt vmcnt(13)
	v_pk_add_f32 v[48:49], v[48:49], v[16:17]
	v_pk_add_f32 v[50:51], v[50:51], v[18:19]
	v_pk_add_f32 v[44:45], v[44:45], v[12:13]
	v_pk_add_f32 v[46:47], v[46:47], v[14:15]
	global_store_dwordx4 v193, v[48:51], s[86:87]
	global_store_dwordx4 v206, v[44:47], s[86:87]
	v_mul_f32_e32 v214, v48, v48
	v_fmac_f32_e32 v214, v49, v49
	v_fmac_f32_e32 v214, v50, v50
	v_fmac_f32_e32 v214, v51, v51
	v_mul_f32_e32 v215, v44, v44
	v_fmac_f32_e32 v215, v45, v45
	v_fmac_f32_e32 v215, v46, v46
	v_fmac_f32_e32 v215, v47, v47
	v_pk_mul_f32 v[164:165], v[48:49], v[148:149]
	v_pk_mul_f32 v[166:167], v[50:51], v[150:151]
	v_cvt_pk_bf16_f32 v168, v164, v165
	v_cvt_pk_bf16_f32 v169, v166, v167
	global_store_dwordx2 v207, v[168:169], s[88:89]
	v_pk_mul_f32 v[164:165], v[44:45], v[156:157]
	v_pk_mul_f32 v[166:167], v[46:47], v[158:159]
	v_cvt_pk_bf16_f32 v170, v164, v165
	v_cvt_pk_bf16_f32 v171, v166, v167
	global_store_dwordx2 v208, v[170:171], s[88:89]
	v_pk_add_f32 v[40:41], v[40:41], v[8:9]
	v_pk_add_f32 v[42:43], v[42:43], v[10:11]
	v_pk_add_f32 v[36:37], v[36:37], v[4:5]
	v_pk_add_f32 v[38:39], v[38:39], v[6:7]
	global_store_dwordx4 v193, v[40:43], s[86:87] offset:512
	global_store_dwordx4 v206, v[36:39], s[86:87] offset:512
	v_fmac_f32_e32 v214, v40, v40
	v_fmac_f32_e32 v214, v41, v41
	v_fmac_f32_e32 v214, v42, v42
	v_fmac_f32_e32 v214, v43, v43
	v_fmac_f32_e32 v215, v36, v36
	v_fmac_f32_e32 v215, v37, v37
	v_fmac_f32_e32 v215, v38, v38
	v_fmac_f32_e32 v215, v39, v39
	v_pk_mul_f32 v[164:165], v[40:41], v[152:153]
	v_pk_mul_f32 v[166:167], v[42:43], v[154:155]
	v_cvt_pk_bf16_f32 v168, v164, v165
	v_cvt_pk_bf16_f32 v169, v166, v167
	global_store_dwordx2 v207, v[168:169], s[88:89] offset:256
	v_pk_mul_f32 v[164:165], v[36:37], v[160:161]
	v_pk_mul_f32 v[166:167], v[38:39], v[162:163]
	v_cvt_pk_bf16_f32 v170, v164, v165
	v_cvt_pk_bf16_f32 v171, v166, v167
	global_store_dwordx2 v208, v[170:171], s[88:89] offset:256
	s_nop 1
	v_add_f32_dpp v180, v214, v214 row_ror:8 row_mask:0xf bank_mask:0xf
	v_add_f32_dpp v192, v215, v215 row_ror:8 row_mask:0xf bank_mask:0xf
	v_cndmask_b32_e64 v214, v180, v192, s[90:91]
	v_mov_b32_e32 v215, v214
	s_nop 1
	v_permlane16_swap_b32_e32 v214, v215
	v_add_f32_e32 v214, v214, v215
	v_mov_b32_e32 v215, v214
	s_nop 1
	v_permlane32_swap_b32_e32 v214, v215
	v_add_f32_e32 v214, v214, v215
	s_and_saveexec_b64 s[14:15], s[38:39]
	global_store_dword v211, v214, s[92:93]
	s_or_b64 exec, exec, s[14:15]
	v_mov_b32_dpp v164, v28 row_ror:8 row_mask:0xf bank_mask:0xf
	v_mov_b32_dpp v165, v29 row_ror:8 row_mask:0xf bank_mask:0xf
	v_mov_b32_dpp v166, v30 row_ror:8 row_mask:0xf bank_mask:0xf
	v_mov_b32_dpp v167, v31 row_ror:8 row_mask:0xf bank_mask:0xf
	v_cndmask_b32_e64 v28, v164, v32, s[90:91]
	v_cndmask_b32_e64 v29, v165, v33, s[90:91]
	v_cndmask_b32_e64 v30, v166, v34, s[90:91]
	v_cndmask_b32_e64 v31, v167, v35, s[90:91]
	v_cndmask_b32_e64 v32, v32, v164, s[90:91]
	v_cndmask_b32_e64 v33, v33, v165, s[90:91]
	v_cndmask_b32_e64 v34, v34, v166, s[90:91]
	v_cndmask_b32_e64 v35, v35, v167, s[90:91]
	v_mov_b32_dpp v164, v20 row_ror:8 row_mask:0xf bank_mask:0xf
	v_mov_b32_dpp v165, v21 row_ror:8 row_mask:0xf bank_mask:0xf
	v_mov_b32_dpp v166, v22 row_ror:8 row_mask:0xf bank_mask:0xf
	v_mov_b32_dpp v167, v23 row_ror:8 row_mask:0xf bank_mask:0xf
	v_cndmask_b32_e64 v20, v164, v24, s[90:91]
	v_cndmask_b32_e64 v21, v165, v25, s[90:91]
	v_cndmask_b32_e64 v22, v166, v26, s[90:91]
	v_cndmask_b32_e64 v23, v167, v27, s[90:91]
	v_cndmask_b32_e64 v24, v24, v164, s[90:91]
	v_cndmask_b32_e64 v25, v25, v165, s[90:91]
	v_cndmask_b32_e64 v26, v26, v166, s[90:91]
	v_cndmask_b32_e64 v27, v27, v167, s[90:91]
	s_lshl_b32 s94, s51, 8
	s_add_i32 s94, s94, 160
	s_lshl_b32 s94, s94, 14
	s_add_u32 s86, s48, s94
	s_addc_u32 s87, s49, 0
	s_lshl_b32 s94, s51, 8
	s_add_i32 s94, s94, 160
	s_lshl_b32 s94, s94, 13
	s_add_u32 s88, s12, s94
	s_addc_u32 s89, s13, 0
	s_lshl_b32 s94, s51, 8
	s_add_i32 s94, s94, 160
	s_lshl_b32 s94, s94, 8
	s_add_u32 s92, s22, s94
	s_addc_u32 s93, s23, 0
	s_waitcnt vmcnt(9)
	v_pk_add_f32 v[32:33], v[32:33], v[72:73]
	v_pk_add_f32 v[34:35], v[34:35], v[74:75]
	v_pk_add_f32 v[28:29], v[28:29], v[64:65]
	v_pk_add_f32 v[30:31], v[30:31], v[66:67]
	global_store_dwordx4 v193, v[32:35], s[86:87]
	global_store_dwordx4 v206, v[28:31], s[86:87]
	v_mul_f32_e32 v214, v32, v32
	v_fmac_f32_e32 v214, v33, v33
	v_fmac_f32_e32 v214, v34, v34
	v_fmac_f32_e32 v214, v35, v35
	v_mul_f32_e32 v215, v28, v28
	v_fmac_f32_e32 v215, v29, v29
	v_fmac_f32_e32 v215, v30, v30
	v_fmac_f32_e32 v215, v31, v31
	v_pk_mul_f32 v[164:165], v[32:33], v[148:149]
	v_pk_mul_f32 v[166:167], v[34:35], v[150:151]
	v_cvt_pk_bf16_f32 v168, v164, v165
	v_cvt_pk_bf16_f32 v169, v166, v167
	global_store_dwordx2 v207, v[168:169], s[88:89]
	v_pk_mul_f32 v[164:165], v[28:29], v[156:157]
	v_pk_mul_f32 v[166:167], v[30:31], v[158:159]
	v_cvt_pk_bf16_f32 v170, v164, v165
	v_cvt_pk_bf16_f32 v171, v166, v167
	global_store_dwordx2 v208, v[170:171], s[88:89]
	v_pk_add_f32 v[24:25], v[24:25], v[56:57]
	v_pk_add_f32 v[26:27], v[26:27], v[58:59]
	v_pk_add_f32 v[20:21], v[20:21], v[52:53]
	v_pk_add_f32 v[22:23], v[22:23], v[54:55]
	global_store_dwordx4 v193, v[24:27], s[86:87] offset:512
	global_store_dwordx4 v206, v[20:23], s[86:87] offset:512
	v_fmac_f32_e32 v214, v24, v24
	v_fmac_f32_e32 v214, v25, v25
	v_fmac_f32_e32 v214, v26, v26
	v_fmac_f32_e32 v214, v27, v27
	v_fmac_f32_e32 v215, v20, v20
	v_fmac_f32_e32 v215, v21, v21
	v_fmac_f32_e32 v215, v22, v22
	v_fmac_f32_e32 v215, v23, v23
	v_pk_mul_f32 v[164:165], v[24:25], v[152:153]
	v_pk_mul_f32 v[166:167], v[26:27], v[154:155]
	v_cvt_pk_bf16_f32 v168, v164, v165
	v_cvt_pk_bf16_f32 v169, v166, v167
	global_store_dwordx2 v207, v[168:169], s[88:89] offset:256
	v_pk_mul_f32 v[164:165], v[20:21], v[160:161]
	v_pk_mul_f32 v[166:167], v[22:23], v[162:163]
	v_cvt_pk_bf16_f32 v170, v164, v165
	v_cvt_pk_bf16_f32 v171, v166, v167
	global_store_dwordx2 v208, v[170:171], s[88:89] offset:256
	s_nop 1
	v_add_f32_dpp v180, v214, v214 row_ror:8 row_mask:0xf bank_mask:0xf
	v_add_f32_dpp v192, v215, v215 row_ror:8 row_mask:0xf bank_mask:0xf
	v_cndmask_b32_e64 v214, v180, v192, s[90:91]
	v_mov_b32_e32 v215, v214
	s_nop 1
	v_permlane16_swap_b32_e32 v214, v215
	v_add_f32_e32 v214, v214, v215
	v_mov_b32_e32 v215, v214
	s_nop 1
	v_permlane32_swap_b32_e32 v214, v215
	v_add_f32_e32 v214, v214, v215
	s_and_saveexec_b64 s[14:15], s[38:39]
	global_store_dword v211, v214, s[92:93]
	s_or_b64 exec, exec, s[14:15]
.Lrot_p8x_end:
	s_branch .Lp8epi_end
.Lp8epi_noxg:
	s_bfe_u32 s94, s50, 0x20002
	s_cmp_eq_u32 s94, 1
	s_cbranch_scc1 .Lrot_p8n_1
	s_cmp_eq_u32 s94, 2
	s_cbranch_scc1 .Lrot_p8n_2
	s_cmp_eq_u32 s94, 3
	s_cbranch_scc1 .Lrot_p8n_3
	v_and_b32_e32 v192, 8, v219
	v_cmp_ne_u32_e64 s[90:91], 0, v192
	v_sub_u32_e32 v214, v1, v192
	v_lshlrev_b32_e32 v192, 1, v192
	s_lshl_b32 s94, s50, 8
	v_add3_u32 v215, v240, v192, s94
	v_sub_u32_e32 v180, v240, v192
	v_add3_u32 v180, v180, 16, s94
	v_lshlrev_b32_e32 v193, 14, v214
	v_lshl_add_u32 v206, v180, 2, v193
	v_add_u32_e32 v206, 0x20000, v206
	v_lshl_add_u32 v193, v215, 2, v193
	v_lshlrev_b32_e32 v207, 13, v214
	v_lshl_add_u32 v208, v180, 1, v207
	v_add_u32_e32 v208, 0x10000, v208
	v_lshl_add_u32 v207, v215, 1, v207
	v_lshlrev_b32_e32 v209, 2, v215
	v_lshlrev_b32_e32 v210, 2, v180
	s_lshl_b32 s94, s50, 4
	s_lshl_b32 s95, s34, 2
	s_add_i32 s94, s94, s95
	v_lshlrev_b32_e32 v211, 8, v1
	v_add_u32_e32 v211, s94, v211
	v_xor_b32_e32 v212, 16, v219
	v_lshlrev_b32_e32 v212, 2, v212
	v_xor_b32_e32 v213, 32, v219
	v_lshlrev_b32_e32 v213, 2, v213
	s_lshl_b32 s94, s51, 8
	s_lshl_b32 s94, s94, 14
	s_add_u32 s84, s48, s94
	s_addc_u32 s85, s49, 0
	global_load_dwordx4 v[60:63], v193, s[84:85]
	global_load_dwordx4 v[68:71], v206, s[84:85]
	global_load_dwordx4 v[76:79], v193, s[84:85] offset:512
	global_load_dwordx4 v[80:83], v206, s[84:85] offset:512
	s_lshl_b32 s94, s51, 8
	s_add_i32 s94, s94, 16
	s_lshl_b32 s94, s94, 14
	s_add_u32 s84, s48, s94
	s_addc_u32 s85, s49, 0
	global_load_dwordx4 v[172:175], v193, s[84:85]
	global_load_dwordx4 v[176:179], v206, s[84:85]
	global_load_dwordx4 v[182:185], v193, s[84:85] offset:512
	global_load_dwordx4 v[232:235], v206, s[84:85] offset:512
	v_mov_b32_dpp v164, v140 row_ror:8 row_mask:0xf bank_mask:0xf
	v_mov_b32_dpp v165, v141 row_ror:8 row_mask:0xf bank_mask:0xf
	v_mov_b32_dpp v166, v142 row_ror:8 row_mask:0xf bank_mask:0xf
	v_mov_b32_dpp v167, v143 row_ror:8 row_mask:0xf bank_mask:0xf
	v_cndmask_b32_e64 v140, v164, v144, s[90:91]
	v_cndmask_b32_e64 v141, v165, v145, s[90:91]
	v_cndmask_b32_e64 v142, v166, v146, s[90:91]
	v_cndmask_b32_e64 v143, v167, v147, s[90:91]
	v_cndmask_b32_e64 v144, v144, v164, s[90:91]
	v_cndmask_b32_e64 v145, v145, v165, s[90:91]
	v_cndmask_b32_e64 v146, v146, v166, s[90:91]
	v_cndmask_b32_e64 v147, v147, v167, s[90:91]
	v_mov_b32_dpp v164, v132 row_ror:8 row_mask:0xf bank_mask:0xf
	v_mov_b32_dpp v165, v133 row_ror:8 row_mask:0xf bank_mask:0xf
	v_mov_b32_dpp v166, v134 row_ror:8 row_mask:0xf bank_mask:0xf
	v_mov_b32_dpp v167, v135 row_ror:8 row_mask:0xf bank_mask:0xf
	v_cndmask_b32_e64 v132, v164, v136, s[90:91]
	v_cndmask_b32_e64 v133, v165, v137, s[90:91]
	v_cndmask_b32_e64 v134, v166, v138, s[90:91]
	v_cndmask_b32_e64 v135, v167, v139, s[90:91]
	v_cndmask_b32_e64 v136, v136, v164, s[90:91]
	v_cndmask_b32_e64 v137, v137, v165, s[90:91]
	v_cndmask_b32_e64 v138, v138, v166, s[90:91]
	v_cndmask_b32_e64 v139, v139, v167, s[90:91]
	s_lshl_b32 s94, s51, 8
	s_lshl_b32 s94, s94, 14
	s_add_u32 s86, s48, s94
	s_addc_u32 s87, s49, 0
	s_lshl_b32 s94, s51, 8
	s_lshl_b32 s94, s94, 13
	s_add_u32 s88, s12, s94
	s_addc_u32 s89, s13, 0
	s_lshl_b32 s94, s51, 8
	s_lshl_b32 s94, s94, 8
	s_add_u32 s92, s22, s94
	s_addc_u32 s93, s23, 0
	s_waitcnt vmcnt(4)
	v_pk_add_f32 v[144:145], v[144:145], v[60:61]
	v_pk_add_f32 v[146:147], v[146:147], v[62:63]
	v_pk_add_f32 v[140:141], v[140:141], v[68:69]
	v_pk_add_f32 v[142:143], v[142:143], v[70:71]
	global_store_dwordx4 v193, v[144:147], s[86:87]
	global_store_dwordx4 v206, v[140:143], s[86:87]
	v_pk_add_f32 v[136:137], v[136:137], v[76:77]
	v_pk_add_f32 v[138:139], v[138:139], v[78:79]
	v_pk_add_f32 v[132:133], v[132:133], v[80:81]
	v_pk_add_f32 v[134:135], v[134:135], v[82:83]
	global_store_dwordx4 v193, v[136:139], s[86:87] offset:512
	global_store_dwordx4 v206, v[132:135], s[86:87] offset:512
	s_lshl_b32 s94, s51, 8
	s_add_i32 s94, s94, 32
	s_lshl_b32 s94, s94, 14
	s_add_u32 s84, s48, s94
	s_addc_u32 s85, s49, 0
	global_load_dwordx4 v[144:147], v193, s[84:85]
	global_load_dwordx4 v[140:143], v206, s[84:85]
	global_load_dwordx4 v[136:139], v193, s[84:85] offset:512
	global_load_dwordx4 v[132:135], v206, s[84:85] offset:512
	v_mov_b32_dpp v164, v124 row_ror:8 row_mask:0xf bank_mask:0xf
	v_mov_b32_dpp v165, v125 row_ror:8 row_mask:0xf bank_mask:0xf
	v_mov_b32_dpp v166, v126 row_ror:8 row_mask:0xf bank_mask:0xf
	v_mov_b32_dpp v167, v127 row_ror:8 row_mask:0xf bank_mask:0xf
	v_cndmask_b32_e64 v124, v164, v128, s[90:91]
	v_cndmask_b32_e64 v125, v165, v129, s[90:91]
	v_cndmask_b32_e64 v126, v166, v130, s[90:91]
	v_cndmask_b32_e64 v127, v167, v131, s[90:91]
	v_cndmask_b32_e64 v128, v128, v164, s[90:91]
	v_cndmask_b32_e64 v129, v129, v165, s[90:91]
	v_cndmask_b32_e64 v130, v130, v166, s[90:91]
	v_cndmask_b32_e64 v131, v131, v167, s[90:91]
	v_mov_b32_dpp v164, v116 row_ror:8 row_mask:0xf bank_mask:0xf
	v_mov_b32_dpp v165, v117 row_ror:8 row_mask:0xf bank_mask:0xf
	v_mov_b32_dpp v166, v118 row_ror:8 row_mask:0xf bank_mask:0xf
	v_mov_b32_dpp v167, v119 row_ror:8 row_mask:0xf bank_mask:0xf
	v_cndmask_b32_e64 v116, v164, v120, s[90:91]
	v_cndmask_b32_e64 v117, v165, v121, s[90:91]
	v_cndmask_b32_e64 v118, v166, v122, s[90:91]
	v_cndmask_b32_e64 v119, v167, v123, s[90:91]
	v_cndmask_b32_e64 v120, v120, v164, s[90:91]
	v_cndmask_b32_e64 v121, v121, v165, s[90:91]
	v_cndmask_b32_e64 v122, v122, v166, s[90:91]
	v_cndmask_b32_e64 v123, v123, v167, s[90:91]
	s_lshl_b32 s94, s51, 8
	s_add_i32 s94, s94, 16
	s_lshl_b32 s94, s94, 14
	s_add_u32 s86, s48, s94
	s_addc_u32 s87, s49, 0
	s_lshl_b32 s94, s51, 8
	s_add_i32 s94, s94, 16
	s_lshl_b32 s94, s94, 13
	s_add_u32 s88, s12, s94
	s_addc_u32 s89, s13, 0
	s_lshl_b32 s94, s51, 8
	s_add_i32 s94, s94, 16
	s_lshl_b32 s94, s94, 8
	s_add_u32 s92, s22, s94
	s_addc_u32 s93, s23, 0
	s_waitcnt vmcnt(8)
	v_pk_add_f32 v[128:129], v[128:129], v[172:173]
	v_pk_add_f32 v[130:131], v[130:131], v[174:175]
	v_pk_add_f32 v[124:125], v[124:125], v[176:177]
	v_pk_add_f32 v[126:127], v[126:127], v[178:179]
	global_store_dwordx4 v193, v[128:131], s[86:87]
	global_store_dwordx4 v206, v[124:127], s[86:87]
	v_pk_add_f32 v[120:121], v[120:121], v[182:183]
	v_pk_add_f32 v[122:123], v[122:123], v[184:185]
	v_pk_add_f32 v[116:117], v[116:117], v[232:233]
	v_pk_add_f32 v[118:119], v[118:119], v[234:235]
	global_store_dwordx4 v193, v[120:123], s[86:87] offset:512
	global_store_dwordx4 v206, v[116:119], s[86:87] offset:512
	s_lshl_b32 s94, s51, 8
	s_add_i32 s94, s94, 48
	s_lshl_b32 s94, s94, 14
	s_add_u32 s84, s48, s94
	s_addc_u32 s85, s49, 0
	global_load_dwordx4 v[128:131], v193, s[84:85]
	global_load_dwordx4 v[124:127], v206, s[84:85]
	global_load_dwordx4 v[120:123], v193, s[84:85] offset:512
	global_load_dwordx4 v[116:119], v206, s[84:85] offset:512
	v_mov_b32_dpp v164, v108 row_ror:8 row_mask:0xf bank_mask:0xf
	v_mov_b32_dpp v165, v109 row_ror:8 row_mask:0xf bank_mask:0xf
	v_mov_b32_dpp v166, v110 row_ror:8 row_mask:0xf bank_mask:0xf
	v_mov_b32_dpp v167, v111 row_ror:8 row_mask:0xf bank_mask:0xf
	v_cndmask_b32_e64 v108, v164, v112, s[90:91]
	v_cndmask_b32_e64 v109, v165, v113, s[90:91]
	v_cndmask_b32_e64 v110, v166, v114, s[90:91]
	v_cndmask_b32_e64 v111, v167, v115, s[90:91]
	v_cndmask_b32_e64 v112, v112, v164, s[90:91]
	v_cndmask_b32_e64 v113, v113, v165, s[90:91]
	v_cndmask_b32_e64 v114, v114, v166, s[90:91]
	v_cndmask_b32_e64 v115, v115, v167, s[90:91]
	v_mov_b32_dpp v164, v100 row_ror:8 row_mask:0xf bank_mask:0xf
	v_mov_b32_dpp v165, v101 row_ror:8 row_mask:0xf bank_mask:0xf
	v_mov_b32_dpp v166, v102 row_ror:8 row_mask:0xf bank_mask:0xf
	v_mov_b32_dpp v167, v103 row_ror:8 row_mask:0xf bank_mask:0xf
	v_cndmask_b32_e64 v100, v164, v104, s[90:91]
	v_cndmask_b32_e64 v101, v165, v105, s[90:91]
	v_cndmask_b32_e64 v102, v166, v106, s[90:91]
	v_cndmask_b32_e64 v103, v167, v107, s[90:91]
	v_cndmask_b32_e64 v104, v104, v164, s[90:91]
	v_cndmask_b32_e64 v105, v105, v165, s[90:91]
	v_cndmask_b32_e64 v106, v106, v166, s[90:91]
	v_cndmask_b32_e64 v107, v107, v167, s[90:91]
	s_lshl_b32 s94, s51, 8
	s_add_i32 s94, s94, 32
	s_lshl_b32 s94, s94, 14
	s_add_u32 s86, s48, s94
	s_addc_u32 s87, s49, 0
	s_lshl_b32 s94, s51, 8
	s_add_i32 s94, s94, 32
	s_lshl_b32 s94, s94, 13
	s_add_u32 s88, s12, s94
	s_addc_u32 s89, s13, 0
	s_lshl_b32 s94, s51, 8
	s_add_i32 s94, s94, 32
	s_lshl_b32 s94, s94, 8
	s_add_u32 s92, s22, s94
	s_addc_u32 s93, s23, 0
	s_waitcnt vmcnt(8)
	v_pk_add_f32 v[112:113], v[112:113], v[144:145]
	v_pk_add_f32 v[114:115], v[114:115], v[146:147]
	v_pk_add_f32 v[108:109], v[108:109], v[140:141]
	v_pk_add_f32 v[110:111], v[110:111], v[142:143]
	global_store_dwordx4 v193, v[112:115], s[86:87]
	global_store_dwordx4 v206, v[108:111], s[86:87]
	v_pk_add_f32 v[104:105], v[104:105], v[136:137]
	v_pk_add_f32 v[106:107], v[106:107], v[138:139]
	v_pk_add_f32 v[100:101], v[100:101], v[132:133]
	v_pk_add_f32 v[102:103], v[102:103], v[134:135]
	global_store_dwordx4 v193, v[104:107], s[86:87] offset:512
	global_store_dwordx4 v206, v[100:103], s[86:87] offset:512
	s_lshl_b32 s94, s51, 8
	s_add_i32 s94, s94, 128
	s_lshl_b32 s94, s94, 14
	s_add_u32 s84, s48, s94
	s_addc_u32 s85, s49, 0
	global_load_dwordx4 v[112:115], v193, s[84:85]
	global_load_dwordx4 v[108:111], v206, s[84:85]
	global_load_dwordx4 v[104:107], v193, s[84:85] offset:512
	global_load_dwordx4 v[100:103], v206, s[84:85] offset:512
	v_mov_b32_dpp v164, v92 row_ror:8 row_mask:0xf bank_mask:0xf
	v_mov_b32_dpp v165, v93 row_ror:8 row_mask:0xf bank_mask:0xf
	v_mov_b32_dpp v166, v94 row_ror:8 row_mask:0xf bank_mask:0xf
	v_mov_b32_dpp v167, v95 row_ror:8 row_mask:0xf bank_mask:0xf
	v_cndmask_b32_e64 v92, v164, v96, s[90:91]
	v_cndmask_b32_e64 v93, v165, v97, s[90:91]
	v_cndmask_b32_e64 v94, v166, v98, s[90:91]
	v_cndmask_b32_e64 v95, v167, v99, s[90:91]
	v_cndmask_b32_e64 v96, v96, v164, s[90:91]
	v_cndmask_b32_e64 v97, v97, v165, s[90:91]
	v_cndmask_b32_e64 v98, v98, v166, s[90:91]
	v_cndmask_b32_e64 v99, v99, v167, s[90:91]
	v_mov_b32_dpp v164, v84 row_ror:8 row_mask:0xf bank_mask:0xf
	v_mov_b32_dpp v165, v85 row_ror:8 row_mask:0xf bank_mask:0xf
	v_mov_b32_dpp v166, v86 row_ror:8 row_mask:0xf bank_mask:0xf
	v_mov_b32_dpp v167, v87 row_ror:8 row_mask:0xf bank_mask:0xf
	v_cndmask_b32_e64 v84, v164, v88, s[90:91]
	v_cndmask_b32_e64 v85, v165, v89, s[90:91]
	v_cndmask_b32_e64 v86, v166, v90, s[90:91]
	v_cndmask_b32_e64 v87, v167, v91, s[90:91]
	v_cndmask_b32_e64 v88, v88, v164, s[90:91]
	v_cndmask_b32_e64 v89, v89, v165, s[90:91]
	v_cndmask_b32_e64 v90, v90, v166, s[90:91]
	v_cndmask_b32_e64 v91, v91, v167, s[90:91]
	s_lshl_b32 s94, s51, 8
	s_add_i32 s94, s94, 48
	s_lshl_b32 s94, s94, 14
	s_add_u32 s86, s48, s94
	s_addc_u32 s87, s49, 0
	s_lshl_b32 s94, s51, 8
	s_add_i32 s94, s94, 48
	s_lshl_b32 s94, s94, 13
	s_add_u32 s88, s12, s94
	s_addc_u32 s89, s13, 0
	s_lshl_b32 s94, s51, 8
	s_add_i32 s94, s94, 48
	s_lshl_b32 s94, s94, 8
	s_add_u32 s92, s22, s94
	s_addc_u32 s93, s23, 0
	s_waitcnt vmcnt(8)
	v_pk_add_f32 v[96:97], v[96:97], v[128:129]
	v_pk_add_f32 v[98:99], v[98:99], v[130:131]
	v_pk_add_f32 v[92:93], v[92:93], v[124:125]
	v_pk_add_f32 v[94:95], v[94:95], v[126:127]
	global_store_dwordx4 v193, v[96:99], s[86:87]
	global_store_dwordx4 v206, v[92:95], s[86:87]
	v_pk_add_f32 v[88:89], v[88:89], v[120:121]
	v_pk_add_f32 v[90:91], v[90:91], v[122:123]
	v_pk_add_f32 v[84:85], v[84:85], v[116:117]
	v_pk_add_f32 v[86:87], v[86:87], v[118:119]
	global_store_dwordx4 v193, v[88:91], s[86:87] offset:512
	global_store_dwordx4 v206, v[84:87], s[86:87] offset:512
	s_lshl_b32 s94, s51, 8
	s_add_i32 s94, s94, 144
	s_lshl_b32 s94, s94, 14
	s_add_u32 s84, s48, s94
	s_addc_u32 s85, s49, 0
	global_load_dwordx4 v[96:99], v193, s[84:85]
	global_load_dwordx4 v[92:95], v206, s[84:85]
	global_load_dwordx4 v[88:91], v193, s[84:85] offset:512
	global_load_dwordx4 v[84:87], v206, s[84:85] offset:512
	v_mov_b32_dpp v164, v64 row_ror:8 row_mask:0xf bank_mask:0xf
	v_mov_b32_dpp v165, v65 row_ror:8 row_mask:0xf bank_mask:0xf
	v_mov_b32_dpp v166, v66 row_ror:8 row_mask:0xf bank_mask:0xf
	v_mov_b32_dpp v167, v67 row_ror:8 row_mask:0xf bank_mask:0xf
	v_cndmask_b32_e64 v64, v164, v72, s[90:91]
	v_cndmask_b32_e64 v65, v165, v73, s[90:91]
	v_cndmask_b32_e64 v66, v166, v74, s[90:91]
	v_cndmask_b32_e64 v67, v167, v75, s[90:91]
	v_cndmask_b32_e64 v72, v72, v164, s[90:91]
	v_cndmask_b32_e64 v73, v73, v165, s[90:91]
	v_cndmask_b32_e64 v74, v74, v166, s[90:91]
	v_cndmask_b32_e64 v75, v75, v167, s[90:91]
	v_mov_b32_dpp v164, v52 row_ror:8 row_mask:0xf bank_mask:0xf
	v_mov_b32_dpp v165, v53 row_ror:8 row_mask:0xf bank_mask:0xf
	v_mov_b32_dpp v166, v54 row_ror:8 row_mask:0xf bank_mask:0xf
	v_mov_b32_dpp v167, v55 row_ror:8 row_mask:0xf bank_mask:0xf
	v_cndmask_b32_e64 v52, v164, v56, s[90:91]
	v_cndmask_b32_e64 v53, v165, v57, s[90:91]
	v_cndmask_b32_e64 v54, v166, v58, s[90:91]
	v_cndmask_b32_e64 v55, v167, v59, s[90:91]
	v_cndmask_b32_e64 v56, v56, v164, s[90:91]
	v_cndmask_b32_e64 v57, v57, v165, s[90:91]
	v_cndmask_b32_e64 v58, v58, v166, s[90:91]
	v_cndmask_b32_e64 v59, v59, v167, s[90:91]
	s_lshl_b32 s94, s51, 8
	s_add_i32 s94, s94, 128
	s_lshl_b32 s94, s94, 14
	s_add_u32 s86, s48, s94
	s_addc_u32 s87, s49, 0
	s_lshl_b32 s94, s51, 8
	s_add_i32 s94, s94, 128
	s_lshl_b32 s94, s94, 13
	s_add_u32 s88, s12, s94
	s_addc_u32 s89, s13, 0
	s_lshl_b32 s94, s51, 8
	s_add_i32 s94, s94, 128
	s_lshl_b32 s94, s94, 8
	s_add_u32 s92, s22, s94
	s_addc_u32 s93, s23, 0
	s_waitcnt vmcnt(8)
	v_pk_add_f32 v[72:73], v[72:73], v[112:113]
	v_pk_add_f32 v[74:75], v[74:75], v[114:115]
	v_pk_add_f32 v[64:65], v[64:65], v[108:109]
	v_pk_add_f32 v[66:67], v[66:67], v[110:111]
	global_store_dwordx4 v193, v[72:75], s[86:87]
	global_store_dwordx4 v206, v[64:67], s[86:87]
	v_pk_add_f32 v[56:57], v[56:57], v[104:105]
	v_pk_add_f32 v[58:59], v[58:59], v[106:107]
	v_pk_add_f32 v[52:53], v[52:53], v[100:101]
	v_pk_add_f32 v[54:55], v[54:55], v[102:103]
	global_store_dwordx4 v193, v[56:59], s[86:87] offset:512
	global_store_dwordx4 v206, v[52:55], s[86:87] offset:512
	s_lshl_b32 s94, s51, 8
	s_add_i32 s94, s94, 160
	s_lshl_b32 s94, s94, 14
	s_add_u32 s84, s48, s94
	s_addc_u32 s85, s49, 0
	global_load_dwordx4 v[72:75], v193, s[84:85]
	global_load_dwordx4 v[64:67], v206, s[84:85]
	global_load_dwordx4 v[56:59], v193, s[84:85] offset:512
	global_load_dwordx4 v[52:55], v206, s[84:85] offset:512
	v_mov_b32_dpp v164, v44 row_ror:8 row_mask:0xf bank_mask:0xf
	v_mov_b32_dpp v165, v45 row_ror:8 row_mask:0xf bank_mask:0xf
	v_mov_b32_dpp v166, v46 row_ror:8 row_mask:0xf bank_mask:0xf
	v_mov_b32_dpp v167, v47 row_ror:8 row_mask:0xf bank_mask:0xf
	v_cndmask_b32_e64 v44, v164, v48, s[90:91]
	v_cndmask_b32_e64 v45, v165, v49, s[90:91]
	v_cndmask_b32_e64 v46, v166, v50, s[90:91]
	v_cndmask_b32_e64 v47, v167, v51, s[90:91]
	v_cndmask_b32_e64 v48, v48, v164, s[90:91]
	v_cndmask_b32_e64 v49, v49, v165, s[90:91]
	v_cndmask_b32_e64 v50, v50, v166, s[90:91]
	v_cndmask_b32_e64 v51, v51, v167, s[90:91]
	v_mov_b32_dpp v164, v36 row_ror:8 row_mask:0xf bank_mask:0xf
	v_mov_b32_dpp v165, v37 row_ror:8 row_mask:0xf bank_mask:0xf
	v_mov_b32_dpp v166, v38 row_ror:8 row_mask:0xf bank_mask:0xf
	v_mov_b32_dpp v167, v39 row_ror:8 row_mask:0xf bank_mask:0xf
	v_cndmask_b32_e64 v36, v164, v40, s[90:91]
	v_cndmask_b32_e64 v37, v165, v41, s[90:91]
	v_cndmask_b32_e64 v38, v166, v42, s[90:91]
	v_cndmask_b32_e64 v39, v167, v43, s[90:91]
	v_cndmask_b32_e64 v40, v40, v164, s[90:91]
	v_cndmask_b32_e64 v41, v41, v165, s[90:91]
	v_cndmask_b32_e64 v42, v42, v166, s[90:91]
	v_cndmask_b32_e64 v43, v43, v167, s[90:91]
	s_lshl_b32 s94, s51, 8
	s_add_i32 s94, s94, 144
	s_lshl_b32 s94, s94, 14
	s_add_u32 s86, s48, s94
	s_addc_u32 s87, s49, 0
	s_lshl_b32 s94, s51, 8
	s_add_i32 s94, s94, 144
	s_lshl_b32 s94, s94, 13
	s_add_u32 s88, s12, s94
	s_addc_u32 s89, s13, 0
	s_lshl_b32 s94, s51, 8
	s_add_i32 s94, s94, 144
	s_lshl_b32 s94, s94, 8
	s_add_u32 s92, s22, s94
	s_addc_u32 s93, s23, 0
	s_waitcnt vmcnt(8)
	v_pk_add_f32 v[48:49], v[48:49], v[96:97]
	v_pk_add_f32 v[50:51], v[50:51], v[98:99]
	v_pk_add_f32 v[44:45], v[44:45], v[92:93]
	v_pk_add_f32 v[46:47], v[46:47], v[94:95]
	global_store_dwordx4 v193, v[48:51], s[86:87]
	global_store_dwordx4 v206, v[44:47], s[86:87]
	v_pk_add_f32 v[40:41], v[40:41], v[88:89]
	v_pk_add_f32 v[42:43], v[42:43], v[90:91]
	v_pk_add_f32 v[36:37], v[36:37], v[84:85]
	v_pk_add_f32 v[38:39], v[38:39], v[86:87]
	global_store_dwordx4 v193, v[40:43], s[86:87] offset:512
	global_store_dwordx4 v206, v[36:39], s[86:87] offset:512
	s_lshl_b32 s94, s51, 8
	s_add_i32 s94, s94, 176
	s_lshl_b32 s94, s94, 14
	s_add_u32 s84, s48, s94
	s_addc_u32 s85, s49, 0
	global_load_dwordx4 v[48:51], v193, s[84:85]
	global_load_dwordx4 v[44:47], v206, s[84:85]
	global_load_dwordx4 v[40:43], v193, s[84:85] offset:512
	global_load_dwordx4 v[36:39], v206, s[84:85] offset:512
	v_mov_b32_dpp v164, v28 row_ror:8 row_mask:0xf bank_mask:0xf
	v_mov_b32_dpp v165, v29 row_ror:8 row_mask:0xf bank_mask:0xf
	v_mov_b32_dpp v166, v30 row_ror:8 row_mask:0xf bank_mask:0xf
	v_mov_b32_dpp v167, v31 row_ror:8 row_mask:0xf bank_mask:0xf
	v_cndmask_b32_e64 v28, v164, v32, s[90:91]
	v_cndmask_b32_e64 v29, v165, v33, s[90:91]
	v_cndmask_b32_e64 v30, v166, v34, s[90:91]
	v_cndmask_b32_e64 v31, v167, v35, s[90:91]
	v_cndmask_b32_e64 v32, v32, v164, s[90:91]
	v_cndmask_b32_e64 v33, v33, v165, s[90:91]
	v_cndmask_b32_e64 v34, v34, v166, s[90:91]
	v_cndmask_b32_e64 v35, v35, v167, s[90:91]
	v_mov_b32_dpp v164, v20 row_ror:8 row_mask:0xf bank_mask:0xf
	v_mov_b32_dpp v165, v21 row_ror:8 row_mask:0xf bank_mask:0xf
	v_mov_b32_dpp v166, v22 row_ror:8 row_mask:0xf bank_mask:0xf
	v_mov_b32_dpp v167, v23 row_ror:8 row_mask:0xf bank_mask:0xf
	v_cndmask_b32_e64 v20, v164, v24, s[90:91]
	v_cndmask_b32_e64 v21, v165, v25, s[90:91]
	v_cndmask_b32_e64 v22, v166, v26, s[90:91]
	v_cndmask_b32_e64 v23, v167, v27, s[90:91]
	v_cndmask_b32_e64 v24, v24, v164, s[90:91]
	v_cndmask_b32_e64 v25, v25, v165, s[90:91]
	v_cndmask_b32_e64 v26, v26, v166, s[90:91]
	v_cndmask_b32_e64 v27, v27, v167, s[90:91]
	s_lshl_b32 s94, s51, 8
	s_add_i32 s94, s94, 160
	s_lshl_b32 s94, s94, 14
	s_add_u32 s86, s48, s94
	s_addc_u32 s87, s49, 0
	s_lshl_b32 s94, s51, 8
	s_add_i32 s94, s94, 160
	s_lshl_b32 s94, s94, 13
	s_add_u32 s88, s12, s94
	s_addc_u32 s89, s13, 0
	s_lshl_b32 s94, s51, 8
	s_add_i32 s94, s94, 160
	s_lshl_b32 s94, s94, 8
	s_add_u32 s92, s22, s94
	s_addc_u32 s93, s23, 0
	s_waitcnt vmcnt(8)
	v_pk_add_f32 v[32:33], v[32:33], v[72:73]
	v_pk_add_f32 v[34:35], v[34:35], v[74:75]
	v_pk_add_f32 v[28:29], v[28:29], v[64:65]
	v_pk_add_f32 v[30:31], v[30:31], v[66:67]
	global_store_dwordx4 v193, v[32:35], s[86:87]
	global_store_dwordx4 v206, v[28:31], s[86:87]
	v_pk_add_f32 v[24:25], v[24:25], v[56:57]
	v_pk_add_f32 v[26:27], v[26:27], v[58:59]
	v_pk_add_f32 v[20:21], v[20:21], v[52:53]
	v_pk_add_f32 v[22:23], v[22:23], v[54:55]
	global_store_dwordx4 v193, v[24:27], s[86:87] offset:512
	global_store_dwordx4 v206, v[20:23], s[86:87] offset:512
	v_mov_b32_dpp v164, v12 row_ror:8 row_mask:0xf bank_mask:0xf
	v_mov_b32_dpp v165, v13 row_ror:8 row_mask:0xf bank_mask:0xf
	v_mov_b32_dpp v166, v14 row_ror:8 row_mask:0xf bank_mask:0xf
	v_mov_b32_dpp v167, v15 row_ror:8 row_mask:0xf bank_mask:0xf
	v_cndmask_b32_e64 v12, v164, v16, s[90:91]
	v_cndmask_b32_e64 v13, v165, v17, s[90:91]
	v_cndmask_b32_e64 v14, v166, v18, s[90:91]
	v_cndmask_b32_e64 v15, v167, v19, s[90:91]
	v_cndmask_b32_e64 v16, v16, v164, s[90:91]
	v_cndmask_b32_e64 v17, v17, v165, s[90:91]
	v_cndmask_b32_e64 v18, v18, v166, s[90:91]
	v_cndmask_b32_e64 v19, v19, v167, s[90:91]
	v_mov_b32_dpp v164, v4 row_ror:8 row_mask:0xf bank_mask:0xf
	v_mov_b32_dpp v165, v5 row_ror:8 row_mask:0xf bank_mask:0xf
	v_mov_b32_dpp v166, v6 row_ror:8 row_mask:0xf bank_mask:0xf
	v_mov_b32_dpp v167, v7 row_ror:8 row_mask:0xf bank_mask:0xf
	v_cndmask_b32_e64 v4, v164, v8, s[90:91]
	v_cndmask_b32_e64 v5, v165, v9, s[90:91]
	v_cndmask_b32_e64 v6, v166, v10, s[90:91]
	v_cndmask_b32_e64 v7, v167, v11, s[90:91]
	v_cndmask_b32_e64 v8, v8, v164, s[90:91]
	v_cndmask_b32_e64 v9, v9, v165, s[90:91]
	v_cndmask_b32_e64 v10, v10, v166, s[90:91]
	v_cndmask_b32_e64 v11, v11, v167, s[90:91]
	s_lshl_b32 s94, s51, 8
	s_add_i32 s94, s94, 176
	s_lshl_b32 s94, s94, 14
	s_add_u32 s86, s48, s94
	s_addc_u32 s87, s49, 0
	s_lshl_b32 s94, s51, 8
	s_add_i32 s94, s94, 176
	s_lshl_b32 s94, s94, 13
	s_add_u32 s88, s12, s94
	s_addc_u32 s89, s13, 0
	s_lshl_b32 s94, s51, 8
	s_add_i32 s94, s94, 176
	s_lshl_b32 s94, s94, 8
	s_add_u32 s92, s22, s94
	s_addc_u32 s93, s23, 0
	s_waitcnt vmcnt(4)
	v_pk_add_f32 v[16:17], v[16:17], v[48:49]
	v_pk_add_f32 v[18:19], v[18:19], v[50:51]
	v_pk_add_f32 v[12:13], v[12:13], v[44:45]
	v_pk_add_f32 v[14:15], v[14:15], v[46:47]
	global_store_dwordx4 v193, v[16:19], s[86:87]
	global_store_dwordx4 v206, v[12:15], s[86:87]
	v_pk_add_f32 v[8:9], v[8:9], v[40:41]
	v_pk_add_f32 v[10:11], v[10:11], v[42:43]
	v_pk_add_f32 v[4:5], v[4:5], v[36:37]
	v_pk_add_f32 v[6:7], v[6:7], v[38:39]
	global_store_dwordx4 v193, v[8:11], s[86:87] offset:512
	global_store_dwordx4 v206, v[4:7], s[86:87] offset:512
	s_branch .Lrot_p8n_end
.Lrot_p8n_1:
	v_and_b32_e32 v192, 8, v219
	v_cmp_ne_u32_e64 s[90:91], 0, v192
	v_sub_u32_e32 v214, v1, v192
	v_lshlrev_b32_e32 v192, 1, v192
	s_lshl_b32 s94, s50, 8
	v_add3_u32 v215, v240, v192, s94
	v_sub_u32_e32 v180, v240, v192
	v_add3_u32 v180, v180, 16, s94
	v_lshlrev_b32_e32 v193, 14, v214
	v_lshl_add_u32 v206, v180, 2, v193
	v_add_u32_e32 v206, 0x20000, v206
	v_lshl_add_u32 v193, v215, 2, v193
	v_lshlrev_b32_e32 v207, 13, v214
	v_lshl_add_u32 v208, v180, 1, v207
	v_add_u32_e32 v208, 0x10000, v208
	v_lshl_add_u32 v207, v215, 1, v207
	v_lshlrev_b32_e32 v209, 2, v215
	v_lshlrev_b32_e32 v210, 2, v180
	s_lshl_b32 s94, s50, 4
	s_lshl_b32 s95, s34, 2
	s_add_i32 s94, s94, s95
	v_lshlrev_b32_e32 v211, 8, v1
	v_add_u32_e32 v211, s94, v211
	v_xor_b32_e32 v212, 16, v219
	v_lshlrev_b32_e32 v212, 2, v212
	v_xor_b32_e32 v213, 32, v219
	v_lshlrev_b32_e32 v213, 2, v213
	s_lshl_b32 s94, s51, 8
	s_add_i32 s94, s94, 16
	s_lshl_b32 s94, s94, 14
	s_add_u32 s84, s48, s94
	s_addc_u32 s85, s49, 0
	global_load_dwordx4 v[60:63], v193, s[84:85]
	global_load_dwordx4 v[68:71], v206, s[84:85]
	global_load_dwordx4 v[76:79], v193, s[84:85] offset:512
	global_load_dwordx4 v[80:83], v206, s[84:85] offset:512
	s_lshl_b32 s94, s51, 8
	s_add_i32 s94, s94, 32
	s_lshl_b32 s94, s94, 14
	s_add_u32 s84, s48, s94
	s_addc_u32 s85, s49, 0
	global_load_dwordx4 v[172:175], v193, s[84:85]
	global_load_dwordx4 v[176:179], v206, s[84:85]
	global_load_dwordx4 v[182:185], v193, s[84:85] offset:512
	global_load_dwordx4 v[232:235], v206, s[84:85] offset:512
	v_mov_b32_dpp v164, v124 row_ror:8 row_mask:0xf bank_mask:0xf
	v_mov_b32_dpp v165, v125 row_ror:8 row_mask:0xf bank_mask:0xf
	v_mov_b32_dpp v166, v126 row_ror:8 row_mask:0xf bank_mask:0xf
	v_mov_b32_dpp v167, v127 row_ror:8 row_mask:0xf bank_mask:0xf
	v_cndmask_b32_e64 v124, v164, v128, s[90:91]
	v_cndmask_b32_e64 v125, v165, v129, s[90:91]
	v_cndmask_b32_e64 v126, v166, v130, s[90:91]
	v_cndmask_b32_e64 v127, v167, v131, s[90:91]
	v_cndmask_b32_e64 v128, v128, v164, s[90:91]
	v_cndmask_b32_e64 v129, v129, v165, s[90:91]
	v_cndmask_b32_e64 v130, v130, v166, s[90:91]
	v_cndmask_b32_e64 v131, v131, v167, s[90:91]
	v_mov_b32_dpp v164, v116 row_ror:8 row_mask:0xf bank_mask:0xf
	v_mov_b32_dpp v165, v117 row_ror:8 row_mask:0xf bank_mask:0xf
	v_mov_b32_dpp v166, v118 row_ror:8 row_mask:0xf bank_mask:0xf
	v_mov_b32_dpp v167, v119 row_ror:8 row_mask:0xf bank_mask:0xf
	v_cndmask_b32_e64 v116, v164, v120, s[90:91]
	v_cndmask_b32_e64 v117, v165, v121, s[90:91]
	v_cndmask_b32_e64 v118, v166, v122, s[90:91]
	v_cndmask_b32_e64 v119, v167, v123, s[90:91]
	v_cndmask_b32_e64 v120, v120, v164, s[90:91]
	v_cndmask_b32_e64 v121, v121, v165, s[90:91]
	v_cndmask_b32_e64 v122, v122, v166, s[90:91]
	v_cndmask_b32_e64 v123, v123, v167, s[90:91]
	s_lshl_b32 s94, s51, 8
	s_add_i32 s94, s94, 16
	s_lshl_b32 s94, s94, 14
	s_add_u32 s86, s48, s94
	s_addc_u32 s87, s49, 0
	s_lshl_b32 s94, s51, 8
	s_add_i32 s94, s94, 16
	s_lshl_b32 s94, s94, 13
	s_add_u32 s88, s12, s94
	s_addc_u32 s89, s13, 0
	s_lshl_b32 s94, s51, 8
	s_add_i32 s94, s94, 16
	s_lshl_b32 s94, s94, 8
	s_add_u32 s92, s22, s94
	s_addc_u32 s93, s23, 0
	s_waitcnt vmcnt(4)
	v_pk_add_f32 v[128:129], v[128:129], v[60:61]
	v_pk_add_f32 v[130:131], v[130:131], v[62:63]
	v_pk_add_f32 v[124:125], v[124:125], v[68:69]
	v_pk_add_f32 v[126:127], v[126:127], v[70:71]
	global_store_dwordx4 v193, v[128:131], s[86:87]
	global_store_dwordx4 v206, v[124:127], s[86:87]
	v_pk_add_f32 v[120:121], v[120:121], v[76:77]
	v_pk_add_f32 v[122:123], v[122:123], v[78:79]
	v_pk_add_f32 v[116:117], v[116:117], v[80:81]
	v_pk_add_f32 v[118:119], v[118:119], v[82:83]
	global_store_dwordx4 v193, v[120:123], s[86:87] offset:512
	global_store_dwordx4 v206, v[116:119], s[86:87] offset:512
	s_lshl_b32 s94, s51, 8
	s_add_i32 s94, s94, 48
	s_lshl_b32 s94, s94, 14
	s_add_u32 s84, s48, s94
	s_addc_u32 s85, s49, 0
	global_load_dwordx4 v[128:131], v193, s[84:85]
	global_load_dwordx4 v[124:127], v206, s[84:85]
	global_load_dwordx4 v[120:123], v193, s[84:85] offset:512
	global_load_dwordx4 v[116:119], v206, s[84:85] offset:512
	v_mov_b32_dpp v164, v108 row_ror:8 row_mask:0xf bank_mask:0xf
	v_mov_b32_dpp v165, v109 row_ror:8 row_mask:0xf bank_mask:0xf
	v_mov_b32_dpp v166, v110 row_ror:8 row_mask:0xf bank_mask:0xf
	v_mov_b32_dpp v167, v111 row_ror:8 row_mask:0xf bank_mask:0xf
	v_cndmask_b32_e64 v108, v164, v112, s[90:91]
	v_cndmask_b32_e64 v109, v165, v113, s[90:91]
	v_cndmask_b32_e64 v110, v166, v114, s[90:91]
	v_cndmask_b32_e64 v111, v167, v115, s[90:91]
	v_cndmask_b32_e64 v112, v112, v164, s[90:91]
	v_cndmask_b32_e64 v113, v113, v165, s[90:91]
	v_cndmask_b32_e64 v114, v114, v166, s[90:91]
	v_cndmask_b32_e64 v115, v115, v167, s[90:91]
	v_mov_b32_dpp v164, v100 row_ror:8 row_mask:0xf bank_mask:0xf
	v_mov_b32_dpp v165, v101 row_ror:8 row_mask:0xf bank_mask:0xf
	v_mov_b32_dpp v166, v102 row_ror:8 row_mask:0xf bank_mask:0xf
	v_mov_b32_dpp v167, v103 row_ror:8 row_mask:0xf bank_mask:0xf
	v_cndmask_b32_e64 v100, v164, v104, s[90:91]
	v_cndmask_b32_e64 v101, v165, v105, s[90:91]
	v_cndmask_b32_e64 v102, v166, v106, s[90:91]
	v_cndmask_b32_e64 v103, v167, v107, s[90:91]
	v_cndmask_b32_e64 v104, v104, v164, s[90:91]
	v_cndmask_b32_e64 v105, v105, v165, s[90:91]
	v_cndmask_b32_e64 v106, v106, v166, s[90:91]
	v_cndmask_b32_e64 v107, v107, v167, s[90:91]
	s_lshl_b32 s94, s51, 8
	s_add_i32 s94, s94, 32
	s_lshl_b32 s94, s94, 14
	s_add_u32 s86, s48, s94
	s_addc_u32 s87, s49, 0
	s_lshl_b32 s94, s51, 8
	s_add_i32 s94, s94, 32
	s_lshl_b32 s94, s94, 13
	s_add_u32 s88, s12, s94
	s_addc_u32 s89, s13, 0
	s_lshl_b32 s94, s51, 8
	s_add_i32 s94, s94, 32
	s_lshl_b32 s94, s94, 8
	s_add_u32 s92, s22, s94
	s_addc_u32 s93, s23, 0
	s_waitcnt vmcnt(8)
	v_pk_add_f32 v[112:113], v[112:113], v[172:173]
	v_pk_add_f32 v[114:115], v[114:115], v[174:175]
	v_pk_add_f32 v[108:109], v[108:109], v[176:177]
	v_pk_add_f32 v[110:111], v[110:111], v[178:179]
	global_store_dwordx4 v193, v[112:115], s[86:87]
	global_store_dwordx4 v206, v[108:111], s[86:87]
	v_pk_add_f32 v[104:105], v[104:105], v[182:183]
	v_pk_add_f32 v[106:107], v[106:107], v[184:185]
	v_pk_add_f32 v[100:101], v[100:101], v[232:233]
	v_pk_add_f32 v[102:103], v[102:103], v[234:235]
	global_store_dwordx4 v193, v[104:107], s[86:87] offset:512
	global_store_dwordx4 v206, v[100:103], s[86:87] offset:512
	s_lshl_b32 s94, s51, 8
	s_lshl_b32 s94, s94, 14
	s_add_u32 s84, s48, s94
	s_addc_u32 s85, s49, 0
	global_load_dwordx4 v[112:115], v193, s[84:85]
	global_load_dwordx4 v[108:111], v206, s[84:85]
	global_load_dwordx4 v[104:107], v193, s[84:85] offset:512
	global_load_dwordx4 v[100:103], v206, s[84:85] offset:512
	v_mov_b32_dpp v164, v92 row_ror:8 row_mask:0xf bank_mask:0xf
	v_mov_b32_dpp v165, v93 row_ror:8 row_mask:0xf bank_mask:0xf
	v_mov_b32_dpp v166, v94 row_ror:8 row_mask:0xf bank_mask:0xf
	v_mov_b32_dpp v167, v95 row_ror:8 row_mask:0xf bank_mask:0xf
	v_cndmask_b32_e64 v92, v164, v96, s[90:91]
	v_cndmask_b32_e64 v93, v165, v97, s[90:91]
	v_cndmask_b32_e64 v94, v166, v98, s[90:91]
	v_cndmask_b32_e64 v95, v167, v99, s[90:91]
	v_cndmask_b32_e64 v96, v96, v164, s[90:91]
	v_cndmask_b32_e64 v97, v97, v165, s[90:91]
	v_cndmask_b32_e64 v98, v98, v166, s[90:91]
	v_cndmask_b32_e64 v99, v99, v167, s[90:91]
	v_mov_b32_dpp v164, v84 row_ror:8 row_mask:0xf bank_mask:0xf
	v_mov_b32_dpp v165, v85 row_ror:8 row_mask:0xf bank_mask:0xf
	v_mov_b32_dpp v166, v86 row_ror:8 row_mask:0xf bank_mask:0xf
	v_mov_b32_dpp v167, v87 row_ror:8 row_mask:0xf bank_mask:0xf
	v_cndmask_b32_e64 v84, v164, v88, s[90:91]
	v_cndmask_b32_e64 v85, v165, v89, s[90:91]
	v_cndmask_b32_e64 v86, v166, v90, s[90:91]
	v_cndmask_b32_e64 v87, v167, v91, s[90:91]
	v_cndmask_b32_e64 v88, v88, v164, s[90:91]
	v_cndmask_b32_e64 v89, v89, v165, s[90:91]
	v_cndmask_b32_e64 v90, v90, v166, s[90:91]
	v_cndmask_b32_e64 v91, v91, v167, s[90:91]
	s_lshl_b32 s94, s51, 8
	s_add_i32 s94, s94, 48
	s_lshl_b32 s94, s94, 14
	s_add_u32 s86, s48, s94
	s_addc_u32 s87, s49, 0
	s_lshl_b32 s94, s51, 8
	s_add_i32 s94, s94, 48
	s_lshl_b32 s94, s94, 13
	s_add_u32 s88, s12, s94
	s_addc_u32 s89, s13, 0
	s_lshl_b32 s94, s51, 8
	s_add_i32 s94, s94, 48
	s_lshl_b32 s94, s94, 8
	s_add_u32 s92, s22, s94
	s_addc_u32 s93, s23, 0
	s_waitcnt vmcnt(8)
	v_pk_add_f32 v[96:97], v[96:97], v[128:129]
	v_pk_add_f32 v[98:99], v[98:99], v[130:131]
	v_pk_add_f32 v[92:93], v[92:93], v[124:125]
	v_pk_add_f32 v[94:95], v[94:95], v[126:127]
	global_store_dwordx4 v193, v[96:99], s[86:87]
	global_store_dwordx4 v206, v[92:95], s[86:87]
	v_pk_add_f32 v[88:89], v[88:89], v[120:121]
	v_pk_add_f32 v[90:91], v[90:91], v[122:123]
	v_pk_add_f32 v[84:85], v[84:85], v[116:117]
	v_pk_add_f32 v[86:87], v[86:87], v[118:119]
	global_store_dwordx4 v193, v[88:91], s[86:87] offset:512
	global_store_dwordx4 v206, v[84:87], s[86:87] offset:512
	s_lshl_b32 s94, s51, 8
	s_add_i32 s94, s94, 144
	s_lshl_b32 s94, s94, 14
	s_add_u32 s84, s48, s94
	s_addc_u32 s85, s49, 0
	global_load_dwordx4 v[96:99], v193, s[84:85]
	global_load_dwordx4 v[92:95], v206, s[84:85]
	global_load_dwordx4 v[88:91], v193, s[84:85] offset:512
	global_load_dwordx4 v[84:87], v206, s[84:85] offset:512
	v_mov_b32_dpp v164, v140 row_ror:8 row_mask:0xf bank_mask:0xf
	v_mov_b32_dpp v165, v141 row_ror:8 row_mask:0xf bank_mask:0xf
	v_mov_b32_dpp v166, v142 row_ror:8 row_mask:0xf bank_mask:0xf
	v_mov_b32_dpp v167, v143 row_ror:8 row_mask:0xf bank_mask:0xf
	v_cndmask_b32_e64 v140, v164, v144, s[90:91]
	v_cndmask_b32_e64 v141, v165, v145, s[90:91]
	v_cndmask_b32_e64 v142, v166, v146, s[90:91]
	v_cndmask_b32_e64 v143, v167, v147, s[90:91]
	v_cndmask_b32_e64 v144, v144, v164, s[90:91]
	v_cndmask_b32_e64 v145, v145, v165, s[90:91]
	v_cndmask_b32_e64 v146, v146, v166, s[90:91]
	v_cndmask_b32_e64 v147, v147, v167, s[90:91]
	v_mov_b32_dpp v164, v132 row_ror:8 row_mask:0xf bank_mask:0xf
	v_mov_b32_dpp v165, v133 row_ror:8 row_mask:0xf bank_mask:0xf
	v_mov_b32_dpp v166, v134 row_ror:8 row_mask:0xf bank_mask:0xf
	v_mov_b32_dpp v167, v135 row_ror:8 row_mask:0xf bank_mask:0xf
	v_cndmask_b32_e64 v132, v164, v136, s[90:91]
	v_cndmask_b32_e64 v133, v165, v137, s[90:91]
	v_cndmask_b32_e64 v134, v166, v138, s[90:91]
	v_cndmask_b32_e64 v135, v167, v139, s[90:91]
	v_cndmask_b32_e64 v136, v136, v164, s[90:91]
	v_cndmask_b32_e64 v137, v137, v165, s[90:91]
	v_cndmask_b32_e64 v138, v138, v166, s[90:91]
	v_cndmask_b32_e64 v139, v139, v167, s[90:91]
	s_lshl_b32 s94, s51, 8
	s_lshl_b32 s94, s94, 14
	s_add_u32 s86, s48, s94
	s_addc_u32 s87, s49, 0
	s_lshl_b32 s94, s51, 8
	s_lshl_b32 s94, s94, 13
	s_add_u32 s88, s12, s94
	s_addc_u32 s89, s13, 0
	s_lshl_b32 s94, s51, 8
	s_lshl_b32 s94, s94, 8
	s_add_u32 s92, s22, s94
	s_addc_u32 s93, s23, 0
	s_waitcnt vmcnt(8)
	v_pk_add_f32 v[144:145], v[144:145], v[112:113]
	v_pk_add_f32 v[146:147], v[146:147], v[114:115]
	v_pk_add_f32 v[140:141], v[140:141], v[108:109]
	v_pk_add_f32 v[142:143], v[142:143], v[110:111]
	global_store_dwordx4 v193, v[144:147], s[86:87]
	global_store_dwordx4 v206, v[140:143], s[86:87]
	v_pk_add_f32 v[136:137], v[136:137], v[104:105]
	v_pk_add_f32 v[138:139], v[138:139], v[106:107]
	v_pk_add_f32 v[132:133], v[132:133], v[100:101]
	v_pk_add_f32 v[134:135], v[134:135], v[102:103]
	global_store_dwordx4 v193, v[136:139], s[86:87] offset:512
	global_store_dwordx4 v206, v[132:135], s[86:87] offset:512
	s_lshl_b32 s94, s51, 8
	s_add_i32 s94, s94, 160
	s_lshl_b32 s94, s94, 14
	s_add_u32 s84, s48, s94
	s_addc_u32 s85, s49, 0
	global_load_dwordx4 v[144:147], v193, s[84:85]
	global_load_dwordx4 v[140:143], v206, s[84:85]
	global_load_dwordx4 v[136:139], v193, s[84:85] offset:512
	global_load_dwordx4 v[132:135], v206, s[84:85] offset:512
	v_mov_b32_dpp v164, v44 row_ror:8 row_mask:0xf bank_mask:0xf
	v_mov_b32_dpp v165, v45 row_ror:8 row_mask:0xf bank_mask:0xf
	v_mov_b32_dpp v166, v46 row_ror:8 row_mask:0xf bank_mask:0xf
	v_mov_b32_dpp v167, v47 row_ror:8 row_mask:0xf bank_mask:0xf
	v_cndmask_b32_e64 v44, v164, v48, s[90:91]
	v_cndmask_b32_e64 v45, v165, v49, s[90:91]
	v_cndmask_b32_e64 v46, v166, v50, s[90:91]
	v_cndmask_b32_e64 v47, v167, v51, s[90:91]
	v_cndmask_b32_e64 v48, v48, v164, s[90:91]
	v_cndmask_b32_e64 v49, v49, v165, s[90:91]
	v_cndmask_b32_e64 v50, v50, v166, s[90:91]
	v_cndmask_b32_e64 v51, v51, v167, s[90:91]
	v_mov_b32_dpp v164, v36 row_ror:8 row_mask:0xf bank_mask:0xf
	v_mov_b32_dpp v165, v37 row_ror:8 row_mask:0xf bank_mask:0xf
	v_mov_b32_dpp v166, v38 row_ror:8 row_mask:0xf bank_mask:0xf
	v_mov_b32_dpp v167, v39 row_ror:8 row_mask:0xf bank_mask:0xf
	v_cndmask_b32_e64 v36, v164, v40, s[90:91]
	v_cndmask_b32_e64 v37, v165, v41, s[90:91]
	v_cndmask_b32_e64 v38, v166, v42, s[90:91]
	v_cndmask_b32_e64 v39, v167, v43, s[90:91]
	v_cndmask_b32_e64 v40, v40, v164, s[90:91]
	v_cndmask_b32_e64 v41, v41, v165, s[90:91]
	v_cndmask_b32_e64 v42, v42, v166, s[90:91]
	v_cndmask_b32_e64 v43, v43, v167, s[90:91]
	s_lshl_b32 s94, s51, 8
	s_add_i32 s94, s94, 144
	s_lshl_b32 s94, s94, 14
	s_add_u32 s86, s48, s94
	s_addc_u32 s87, s49, 0
	s_lshl_b32 s94, s51, 8
	s_add_i32 s94, s94, 144
	s_lshl_b32 s94, s94, 13
	s_add_u32 s88, s12, s94
	s_addc_u32 s89, s13, 0
	s_lshl_b32 s94, s51, 8
	s_add_i32 s94, s94, 144
	s_lshl_b32 s94, s94, 8
	s_add_u32 s92, s22, s94
	s_addc_u32 s93, s23, 0
	s_waitcnt vmcnt(8)
	v_pk_add_f32 v[48:49], v[48:49], v[96:97]
	v_pk_add_f32 v[50:51], v[50:51], v[98:99]
	v_pk_add_f32 v[44:45], v[44:45], v[92:93]
	v_pk_add_f32 v[46:47], v[46:47], v[94:95]
	global_store_dwordx4 v193, v[48:51], s[86:87]
	global_store_dwordx4 v206, v[44:47], s[86:87]
	v_pk_add_f32 v[40:41], v[40:41], v[88:89]
	v_pk_add_f32 v[42:43], v[42:43], v[90:91]
	v_pk_add_f32 v[36:37], v[36:37], v[84:85]
	v_pk_add_f32 v[38:39], v[38:39], v[86:87]
	global_store_dwordx4 v193, v[40:43], s[86:87] offset:512
	global_store_dwordx4 v206, v[36:39], s[86:87] offset:512
	s_lshl_b32 s94, s51, 8
	s_add_i32 s94, s94, 176
	s_lshl_b32 s94, s94, 14
	s_add_u32 s84, s48, s94
	s_addc_u32 s85, s49, 0
	global_load_dwordx4 v[48:51], v193, s[84:85]
	global_load_dwordx4 v[44:47], v206, s[84:85]
	global_load_dwordx4 v[40:43], v193, s[84:85] offset:512
	global_load_dwordx4 v[36:39], v206, s[84:85] offset:512
	v_mov_b32_dpp v164, v28 row_ror:8 row_mask:0xf bank_mask:0xf
	v_mov_b32_dpp v165, v29 row_ror:8 row_mask:0xf bank_mask:0xf
	v_mov_b32_dpp v166, v30 row_ror:8 row_mask:0xf bank_mask:0xf
	v_mov_b32_dpp v167, v31 row_ror:8 row_mask:0xf bank_mask:0xf
	v_cndmask_b32_e64 v28, v164, v32, s[90:91]
	v_cndmask_b32_e64 v29, v165, v33, s[90:91]
	v_cndmask_b32_e64 v30, v166, v34, s[90:91]
	v_cndmask_b32_e64 v31, v167, v35, s[90:91]
	v_cndmask_b32_e64 v32, v32, v164, s[90:91]
	v_cndmask_b32_e64 v33, v33, v165, s[90:91]
	v_cndmask_b32_e64 v34, v34, v166, s[90:91]
	v_cndmask_b32_e64 v35, v35, v167, s[90:91]
	v_mov_b32_dpp v164, v20 row_ror:8 row_mask:0xf bank_mask:0xf
	v_mov_b32_dpp v165, v21 row_ror:8 row_mask:0xf bank_mask:0xf
	v_mov_b32_dpp v166, v22 row_ror:8 row_mask:0xf bank_mask:0xf
	v_mov_b32_dpp v167, v23 row_ror:8 row_mask:0xf bank_mask:0xf
	v_cndmask_b32_e64 v20, v164, v24, s[90:91]
	v_cndmask_b32_e64 v21, v165, v25, s[90:91]
	v_cndmask_b32_e64 v22, v166, v26, s[90:91]
	v_cndmask_b32_e64 v23, v167, v27, s[90:91]
	v_cndmask_b32_e64 v24, v24, v164, s[90:91]
	v_cndmask_b32_e64 v25, v25, v165, s[90:91]
	v_cndmask_b32_e64 v26, v26, v166, s[90:91]
	v_cndmask_b32_e64 v27, v27, v167, s[90:91]
	s_lshl_b32 s94, s51, 8
	s_add_i32 s94, s94, 160
	s_lshl_b32 s94, s94, 14
	s_add_u32 s86, s48, s94
	s_addc_u32 s87, s49, 0
	s_lshl_b32 s94, s51, 8
	s_add_i32 s94, s94, 160
	s_lshl_b32 s94, s94, 13
	s_add_u32 s88, s12, s94
	s_addc_u32 s89, s13, 0
	s_lshl_b32 s94, s51, 8
	s_add_i32 s94, s94, 160
	s_lshl_b32 s94, s94, 8
	s_add_u32 s92, s22, s94
	s_addc_u32 s93, s23, 0
	s_waitcnt vmcnt(8)
	v_pk_add_f32 v[32:33], v[32:33], v[144:145]
	v_pk_add_f32 v[34:35], v[34:35], v[146:147]
	v_pk_add_f32 v[28:29], v[28:29], v[140:141]
	v_pk_add_f32 v[30:31], v[30:31], v[142:143]
	global_store_dwordx4 v193, v[32:35], s[86:87]
	global_store_dwordx4 v206, v[28:31], s[86:87]
	v_pk_add_f32 v[24:25], v[24:25], v[136:137]
	v_pk_add_f32 v[26:27], v[26:27], v[138:139]
	v_pk_add_f32 v[20:21], v[20:21], v[132:133]
	v_pk_add_f32 v[22:23], v[22:23], v[134:135]
	global_store_dwordx4 v193, v[24:27], s[86:87] offset:512
	global_store_dwordx4 v206, v[20:23], s[86:87] offset:512
	s_lshl_b32 s94, s51, 8
	s_add_i32 s94, s94, 128
	s_lshl_b32 s94, s94, 14
	s_add_u32 s84, s48, s94
	s_addc_u32 s85, s49, 0
	global_load_dwordx4 v[32:35], v193, s[84:85]
	global_load_dwordx4 v[28:31], v206, s[84:85]
	global_load_dwordx4 v[24:27], v193, s[84:85] offset:512
	global_load_dwordx4 v[20:23], v206, s[84:85] offset:512
	v_mov_b32_dpp v164, v12 row_ror:8 row_mask:0xf bank_mask:0xf
	v_mov_b32_dpp v165, v13 row_ror:8 row_mask:0xf bank_mask:0xf
	v_mov_b32_dpp v166, v14 row_ror:8 row_mask:0xf bank_mask:0xf
	v_mov_b32_dpp v167, v15 row_ror:8 row_mask:0xf bank_mask:0xf
	v_cndmask_b32_e64 v12, v164, v16, s[90:91]
	v_cndmask_b32_e64 v13, v165, v17, s[90:91]
	v_cndmask_b32_e64 v14, v166, v18, s[90:91]
	v_cndmask_b32_e64 v15, v167, v19, s[90:91]
	v_cndmask_b32_e64 v16, v16, v164, s[90:91]
	v_cndmask_b32_e64 v17, v17, v165, s[90:91]
	v_cndmask_b32_e64 v18, v18, v166, s[90:91]
	v_cndmask_b32_e64 v19, v19, v167, s[90:91]
	v_mov_b32_dpp v164, v4 row_ror:8 row_mask:0xf bank_mask:0xf
	v_mov_b32_dpp v165, v5 row_ror:8 row_mask:0xf bank_mask:0xf
	v_mov_b32_dpp v166, v6 row_ror:8 row_mask:0xf bank_mask:0xf
	v_mov_b32_dpp v167, v7 row_ror:8 row_mask:0xf bank_mask:0xf
	v_cndmask_b32_e64 v4, v164, v8, s[90:91]
	v_cndmask_b32_e64 v5, v165, v9, s[90:91]
	v_cndmask_b32_e64 v6, v166, v10, s[90:91]
	v_cndmask_b32_e64 v7, v167, v11, s[90:91]
	v_cndmask_b32_e64 v8, v8, v164, s[90:91]
	v_cndmask_b32_e64 v9, v9, v165, s[90:91]
	v_cndmask_b32_e64 v10, v10, v166, s[90:91]
	v_cndmask_b32_e64 v11, v11, v167, s[90:91]
	s_lshl_b32 s94, s51, 8
	s_add_i32 s94, s94, 176
	s_lshl_b32 s94, s94, 14
	s_add_u32 s86, s48, s94
	s_addc_u32 s87, s49, 0
	s_lshl_b32 s94, s51, 8
	s_add_i32 s94, s94, 176
	s_lshl_b32 s94, s94, 13
	s_add_u32 s88, s12, s94
	s_addc_u32 s89, s13, 0
	s_lshl_b32 s94, s51, 8
	s_add_i32 s94, s94, 176
	s_lshl_b32 s94, s94, 8
	s_add_u32 s92, s22, s94
	s_addc_u32 s93, s23, 0
	s_waitcnt vmcnt(8)
	v_pk_add_f32 v[16:17], v[16:17], v[48:49]
	v_pk_add_f32 v[18:19], v[18:19], v[50:51]
	v_pk_add_f32 v[12:13], v[12:13], v[44:45]
	v_pk_add_f32 v[14:15], v[14:15], v[46:47]
	global_store_dwordx4 v193, v[16:19], s[86:87]
	global_store_dwordx4 v206, v[12:15], s[86:87]
	v_pk_add_f32 v[8:9], v[8:9], v[40:41]
	v_pk_add_f32 v[10:11], v[10:11], v[42:43]
	v_pk_add_f32 v[4:5], v[4:5], v[36:37]
	v_pk_add_f32 v[6:7], v[6:7], v[38:39]
	global_store_dwordx4 v193, v[8:11], s[86:87] offset:512
	global_store_dwordx4 v206, v[4:7], s[86:87] offset:512
	v_mov_b32_dpp v164, v64 row_ror:8 row_mask:0xf bank_mask:0xf
	v_mov_b32_dpp v165, v65 row_ror:8 row_mask:0xf bank_mask:0xf
	v_mov_b32_dpp v166, v66 row_ror:8 row_mask:0xf bank_mask:0xf
	v_mov_b32_dpp v167, v67 row_ror:8 row_mask:0xf bank_mask:0xf
	v_cndmask_b32_e64 v64, v164, v72, s[90:91]
	v_cndmask_b32_e64 v65, v165, v73, s[90:91]
	v_cndmask_b32_e64 v66, v166, v74, s[90:91]
	v_cndmask_b32_e64 v67, v167, v75, s[90:91]
	v_cndmask_b32_e64 v72, v72, v164, s[90:91]
	v_cndmask_b32_e64 v73, v73, v165, s[90:91]
	v_cndmask_b32_e64 v74, v74, v166, s[90:91]
	v_cndmask_b32_e64 v75, v75, v167, s[90:91]
	v_mov_b32_dpp v164, v52 row_ror:8 row_mask:0xf bank_mask:0xf
	v_mov_b32_dpp v165, v53 row_ror:8 row_mask:0xf bank_mask:0xf
	v_mov_b32_dpp v166, v54 row_ror:8 row_mask:0xf bank_mask:0xf
	v_mov_b32_dpp v167, v55 row_ror:8 row_mask:0xf bank_mask:0xf
	v_cndmask_b32_e64 v52, v164, v56, s[90:91]
	v_cndmask_b32_e64 v53, v165, v57, s[90:91]
	v_cndmask_b32_e64 v54, v166, v58, s[90:91]
	v_cndmask_b32_e64 v55, v167, v59, s[90:91]
	v_cndmask_b32_e64 v56, v56, v164, s[90:91]
	v_cndmask_b32_e64 v57, v57, v165, s[90:91]
	v_cndmask_b32_e64 v58, v58, v166, s[90:91]
	v_cndmask_b32_e64 v59, v59, v167, s[90:91]
	s_lshl_b32 s94, s51, 8
	s_add_i32 s94, s94, 128
	s_lshl_b32 s94, s94, 14
	s_add_u32 s86, s48, s94
	s_addc_u32 s87, s49, 0
	s_lshl_b32 s94, s51, 8
	s_add_i32 s94, s94, 128
	s_lshl_b32 s94, s94, 13
	s_add_u32 s88, s12, s94
	s_addc_u32 s89, s13, 0
	s_lshl_b32 s94, s51, 8
	s_add_i32 s94, s94, 128
	s_lshl_b32 s94, s94, 8
	s_add_u32 s92, s22, s94
	s_addc_u32 s93, s23, 0
	s_waitcnt vmcnt(4)
	v_pk_add_f32 v[72:73], v[72:73], v[32:33]
	v_pk_add_f32 v[74:75], v[74:75], v[34:35]
	v_pk_add_f32 v[64:65], v[64:65], v[28:29]
	v_pk_add_f32 v[66:67], v[66:67], v[30:31]
	global_store_dwordx4 v193, v[72:75], s[86:87]
	global_store_dwordx4 v206, v[64:67], s[86:87]
	v_pk_add_f32 v[56:57], v[56:57], v[24:25]
	v_pk_add_f32 v[58:59], v[58:59], v[26:27]
	v_pk_add_f32 v[52:53], v[52:53], v[20:21]
	v_pk_add_f32 v[54:55], v[54:55], v[22:23]
	global_store_dwordx4 v193, v[56:59], s[86:87] offset:512
	global_store_dwordx4 v206, v[52:55], s[86:87] offset:512
	s_branch .Lrot_p8n_end
.Lrot_p8n_2:
	v_and_b32_e32 v192, 8, v219
	v_cmp_ne_u32_e64 s[90:91], 0, v192
	v_sub_u32_e32 v214, v1, v192
	v_lshlrev_b32_e32 v192, 1, v192
	s_lshl_b32 s94, s50, 8
	v_add3_u32 v215, v240, v192, s94
	v_sub_u32_e32 v180, v240, v192
	v_add3_u32 v180, v180, 16, s94
	v_lshlrev_b32_e32 v193, 14, v214
	v_lshl_add_u32 v206, v180, 2, v193
	v_add_u32_e32 v206, 0x20000, v206
	v_lshl_add_u32 v193, v215, 2, v193
	v_lshlrev_b32_e32 v207, 13, v214
	v_lshl_add_u32 v208, v180, 1, v207
	v_add_u32_e32 v208, 0x10000, v208
	v_lshl_add_u32 v207, v215, 1, v207
	v_lshlrev_b32_e32 v209, 2, v215
	v_lshlrev_b32_e32 v210, 2, v180
	s_lshl_b32 s94, s50, 4
	s_lshl_b32 s95, s34, 2
	s_add_i32 s94, s94, s95
	v_lshlrev_b32_e32 v211, 8, v1
	v_add_u32_e32 v211, s94, v211
	v_xor_b32_e32 v212, 16, v219
	v_lshlrev_b32_e32 v212, 2, v212
	v_xor_b32_e32 v213, 32, v219
	v_lshlrev_b32_e32 v213, 2, v213
	s_lshl_b32 s94, s51, 8
	s_add_i32 s94, s94, 32
	s_lshl_b32 s94, s94, 14
	s_add_u32 s84, s48, s94
	s_addc_u32 s85, s49, 0
	global_load_dwordx4 v[60:63], v193, s[84:85]
	global_load_dwordx4 v[68:71], v206, s[84:85]
	global_load_dwordx4 v[76:79], v193, s[84:85] offset:512
	global_load_dwordx4 v[80:83], v206, s[84:85] offset:512
	s_lshl_b32 s94, s51, 8
	s_add_i32 s94, s94, 48
	s_lshl_b32 s94, s94, 14
	s_add_u32 s84, s48, s94
	s_addc_u32 s85, s49, 0
	global_load_dwordx4 v[172:175], v193, s[84:85]
	global_load_dwordx4 v[176:179], v206, s[84:85]
	global_load_dwordx4 v[182:185], v193, s[84:85] offset:512
	global_load_dwordx4 v[232:235], v206, s[84:85] offset:512
	v_mov_b32_dpp v164, v108 row_ror:8 row_mask:0xf bank_mask:0xf
	v_mov_b32_dpp v165, v109 row_ror:8 row_mask:0xf bank_mask:0xf
	v_mov_b32_dpp v166, v110 row_ror:8 row_mask:0xf bank_mask:0xf
	v_mov_b32_dpp v167, v111 row_ror:8 row_mask:0xf bank_mask:0xf
	v_cndmask_b32_e64 v108, v164, v112, s[90:91]
	v_cndmask_b32_e64 v109, v165, v113, s[90:91]
	v_cndmask_b32_e64 v110, v166, v114, s[90:91]
	v_cndmask_b32_e64 v111, v167, v115, s[90:91]
	v_cndmask_b32_e64 v112, v112, v164, s[90:91]
	v_cndmask_b32_e64 v113, v113, v165, s[90:91]
	v_cndmask_b32_e64 v114, v114, v166, s[90:91]
	v_cndmask_b32_e64 v115, v115, v167, s[90:91]
	v_mov_b32_dpp v164, v100 row_ror:8 row_mask:0xf bank_mask:0xf
	v_mov_b32_dpp v165, v101 row_ror:8 row_mask:0xf bank_mask:0xf
	v_mov_b32_dpp v166, v102 row_ror:8 row_mask:0xf bank_mask:0xf
	v_mov_b32_dpp v167, v103 row_ror:8 row_mask:0xf bank_mask:0xf
	v_cndmask_b32_e64 v100, v164, v104, s[90:91]
	v_cndmask_b32_e64 v101, v165, v105, s[90:91]
	v_cndmask_b32_e64 v102, v166, v106, s[90:91]
	v_cndmask_b32_e64 v103, v167, v107, s[90:91]
	v_cndmask_b32_e64 v104, v104, v164, s[90:91]
	v_cndmask_b32_e64 v105, v105, v165, s[90:91]
	v_cndmask_b32_e64 v106, v106, v166, s[90:91]
	v_cndmask_b32_e64 v107, v107, v167, s[90:91]
	s_lshl_b32 s94, s51, 8
	s_add_i32 s94, s94, 32
	s_lshl_b32 s94, s94, 14
	s_add_u32 s86, s48, s94
	s_addc_u32 s87, s49, 0
	s_lshl_b32 s94, s51, 8
	s_add_i32 s94, s94, 32
	s_lshl_b32 s94, s94, 13
	s_add_u32 s88, s12, s94
	s_addc_u32 s89, s13, 0
	s_lshl_b32 s94, s51, 8
	s_add_i32 s94, s94, 32
	s_lshl_b32 s94, s94, 8
	s_add_u32 s92, s22, s94
	s_addc_u32 s93, s23, 0
	s_waitcnt vmcnt(4)
	v_pk_add_f32 v[112:113], v[112:113], v[60:61]
	v_pk_add_f32 v[114:115], v[114:115], v[62:63]
	v_pk_add_f32 v[108:109], v[108:109], v[68:69]
	v_pk_add_f32 v[110:111], v[110:111], v[70:71]
	global_store_dwordx4 v193, v[112:115], s[86:87]
	global_store_dwordx4 v206, v[108:111], s[86:87]
	v_pk_add_f32 v[104:105], v[104:105], v[76:77]
	v_pk_add_f32 v[106:107], v[106:107], v[78:79]
	v_pk_add_f32 v[100:101], v[100:101], v[80:81]
	v_pk_add_f32 v[102:103], v[102:103], v[82:83]
	global_store_dwordx4 v193, v[104:107], s[86:87] offset:512
	global_store_dwordx4 v206, v[100:103], s[86:87] offset:512
	s_lshl_b32 s94, s51, 8
	s_lshl_b32 s94, s94, 14
	s_add_u32 s84, s48, s94
	s_addc_u32 s85, s49, 0
	global_load_dwordx4 v[112:115], v193, s[84:85]
	global_load_dwordx4 v[108:111], v206, s[84:85]
	global_load_dwordx4 v[104:107], v193, s[84:85] offset:512
	global_load_dwordx4 v[100:103], v206, s[84:85] offset:512
	v_mov_b32_dpp v164, v92 row_ror:8 row_mask:0xf bank_mask:0xf
	v_mov_b32_dpp v165, v93 row_ror:8 row_mask:0xf bank_mask:0xf
	v_mov_b32_dpp v166, v94 row_ror:8 row_mask:0xf bank_mask:0xf
	v_mov_b32_dpp v167, v95 row_ror:8 row_mask:0xf bank_mask:0xf
	v_cndmask_b32_e64 v92, v164, v96, s[90:91]
	v_cndmask_b32_e64 v93, v165, v97, s[90:91]
	v_cndmask_b32_e64 v94, v166, v98, s[90:91]
	v_cndmask_b32_e64 v95, v167, v99, s[90:91]
	v_cndmask_b32_e64 v96, v96, v164, s[90:91]
	v_cndmask_b32_e64 v97, v97, v165, s[90:91]
	v_cndmask_b32_e64 v98, v98, v166, s[90:91]
	v_cndmask_b32_e64 v99, v99, v167, s[90:91]
	v_mov_b32_dpp v164, v84 row_ror:8 row_mask:0xf bank_mask:0xf
	v_mov_b32_dpp v165, v85 row_ror:8 row_mask:0xf bank_mask:0xf
	v_mov_b32_dpp v166, v86 row_ror:8 row_mask:0xf bank_mask:0xf
	v_mov_b32_dpp v167, v87 row_ror:8 row_mask:0xf bank_mask:0xf
	v_cndmask_b32_e64 v84, v164, v88, s[90:91]
	v_cndmask_b32_e64 v85, v165, v89, s[90:91]
	v_cndmask_b32_e64 v86, v166, v90, s[90:91]
	v_cndmask_b32_e64 v87, v167, v91, s[90:91]
	v_cndmask_b32_e64 v88, v88, v164, s[90:91]
	v_cndmask_b32_e64 v89, v89, v165, s[90:91]
	v_cndmask_b32_e64 v90, v90, v166, s[90:91]
	v_cndmask_b32_e64 v91, v91, v167, s[90:91]
	s_lshl_b32 s94, s51, 8
	s_add_i32 s94, s94, 48
	s_lshl_b32 s94, s94, 14
	s_add_u32 s86, s48, s94
	s_addc_u32 s87, s49, 0
	s_lshl_b32 s94, s51, 8
	s_add_i32 s94, s94, 48
	s_lshl_b32 s94, s94, 13
	s_add_u32 s88, s12, s94
	s_addc_u32 s89, s13, 0
	s_lshl_b32 s94, s51, 8
	s_add_i32 s94, s94, 48
	s_lshl_b32 s94, s94, 8
	s_add_u32 s92, s22, s94
	s_addc_u32 s93, s23, 0
	s_waitcnt vmcnt(8)
	v_pk_add_f32 v[96:97], v[96:97], v[172:173]
	v_pk_add_f32 v[98:99], v[98:99], v[174:175]
	v_pk_add_f32 v[92:93], v[92:93], v[176:177]
	v_pk_add_f32 v[94:95], v[94:95], v[178:179]
	global_store_dwordx4 v193, v[96:99], s[86:87]
	global_store_dwordx4 v206, v[92:95], s[86:87]
	v_pk_add_f32 v[88:89], v[88:89], v[182:183]
	v_pk_add_f32 v[90:91], v[90:91], v[184:185]
	v_pk_add_f32 v[84:85], v[84:85], v[232:233]
	v_pk_add_f32 v[86:87], v[86:87], v[234:235]
	global_store_dwordx4 v193, v[88:91], s[86:87] offset:512
	global_store_dwordx4 v206, v[84:87], s[86:87] offset:512
	s_lshl_b32 s94, s51, 8
	s_add_i32 s94, s94, 16
	s_lshl_b32 s94, s94, 14
	s_add_u32 s84, s48, s94
	s_addc_u32 s85, s49, 0
	global_load_dwordx4 v[96:99], v193, s[84:85]
	global_load_dwordx4 v[92:95], v206, s[84:85]
	global_load_dwordx4 v[88:91], v193, s[84:85] offset:512
	global_load_dwordx4 v[84:87], v206, s[84:85] offset:512
	v_mov_b32_dpp v164, v140 row_ror:8 row_mask:0xf bank_mask:0xf
	v_mov_b32_dpp v165, v141 row_ror:8 row_mask:0xf bank_mask:0xf
	v_mov_b32_dpp v166, v142 row_ror:8 row_mask:0xf bank_mask:0xf
	v_mov_b32_dpp v167, v143 row_ror:8 row_mask:0xf bank_mask:0xf
	v_cndmask_b32_e64 v140, v164, v144, s[90:91]
	v_cndmask_b32_e64 v141, v165, v145, s[90:91]
	v_cndmask_b32_e64 v142, v166, v146, s[90:91]
	v_cndmask_b32_e64 v143, v167, v147, s[90:91]
	v_cndmask_b32_e64 v144, v144, v164, s[90:91]
	v_cndmask_b32_e64 v145, v145, v165, s[90:91]
	v_cndmask_b32_e64 v146, v146, v166, s[90:91]
	v_cndmask_b32_e64 v147, v147, v167, s[90:91]
	v_mov_b32_dpp v164, v132 row_ror:8 row_mask:0xf bank_mask:0xf
	v_mov_b32_dpp v165, v133 row_ror:8 row_mask:0xf bank_mask:0xf
	v_mov_b32_dpp v166, v134 row_ror:8 row_mask:0xf bank_mask:0xf
	v_mov_b32_dpp v167, v135 row_ror:8 row_mask:0xf bank_mask:0xf
	v_cndmask_b32_e64 v132, v164, v136, s[90:91]
	v_cndmask_b32_e64 v133, v165, v137, s[90:91]
	v_cndmask_b32_e64 v134, v166, v138, s[90:91]
	v_cndmask_b32_e64 v135, v167, v139, s[90:91]
	v_cndmask_b32_e64 v136, v136, v164, s[90:91]
	v_cndmask_b32_e64 v137, v137, v165, s[90:91]
	v_cndmask_b32_e64 v138, v138, v166, s[90:91]
	v_cndmask_b32_e64 v139, v139, v167, s[90:91]
	s_lshl_b32 s94, s51, 8
	s_lshl_b32 s94, s94, 14
	s_add_u32 s86, s48, s94
	s_addc_u32 s87, s49, 0
	s_lshl_b32 s94, s51, 8
	s_lshl_b32 s94, s94, 13
	s_add_u32 s88, s12, s94
	s_addc_u32 s89, s13, 0
	s_lshl_b32 s94, s51, 8
	s_lshl_b32 s94, s94, 8
	s_add_u32 s92, s22, s94
	s_addc_u32 s93, s23, 0
	s_waitcnt vmcnt(8)
	v_pk_add_f32 v[144:145], v[144:145], v[112:113]
	v_pk_add_f32 v[146:147], v[146:147], v[114:115]
	v_pk_add_f32 v[140:141], v[140:141], v[108:109]
	v_pk_add_f32 v[142:143], v[142:143], v[110:111]
	global_store_dwordx4 v193, v[144:147], s[86:87]
	global_store_dwordx4 v206, v[140:143], s[86:87]
	v_pk_add_f32 v[136:137], v[136:137], v[104:105]
	v_pk_add_f32 v[138:139], v[138:139], v[106:107]
	v_pk_add_f32 v[132:133], v[132:133], v[100:101]
	v_pk_add_f32 v[134:135], v[134:135], v[102:103]
	global_store_dwordx4 v193, v[136:139], s[86:87] offset:512
	global_store_dwordx4 v206, v[132:135], s[86:87] offset:512
	s_lshl_b32 s94, s51, 8
	s_add_i32 s94, s94, 160
	s_lshl_b32 s94, s94, 14
	s_add_u32 s84, s48, s94
	s_addc_u32 s85, s49, 0
	global_load_dwordx4 v[144:147], v193, s[84:85]
	global_load_dwordx4 v[140:143], v206, s[84:85]
	global_load_dwordx4 v[136:139], v193, s[84:85] offset:512
	global_load_dwordx4 v[132:135], v206, s[84:85] offset:512
	v_mov_b32_dpp v164, v124 row_ror:8 row_mask:0xf bank_mask:0xf
	v_mov_b32_dpp v165, v125 row_ror:8 row_mask:0xf bank_mask:0xf
	v_mov_b32_dpp v166, v126 row_ror:8 row_mask:0xf bank_mask:0xf
	v_mov_b32_dpp v167, v127 row_ror:8 row_mask:0xf bank_mask:0xf
	v_cndmask_b32_e64 v124, v164, v128, s[90:91]
	v_cndmask_b32_e64 v125, v165, v129, s[90:91]
	v_cndmask_b32_e64 v126, v166, v130, s[90:91]
	v_cndmask_b32_e64 v127, v167, v131, s[90:91]
	v_cndmask_b32_e64 v128, v128, v164, s[90:91]
	v_cndmask_b32_e64 v129, v129, v165, s[90:91]
	v_cndmask_b32_e64 v130, v130, v166, s[90:91]
	v_cndmask_b32_e64 v131, v131, v167, s[90:91]
	v_mov_b32_dpp v164, v116 row_ror:8 row_mask:0xf bank_mask:0xf
	v_mov_b32_dpp v165, v117 row_ror:8 row_mask:0xf bank_mask:0xf
	v_mov_b32_dpp v166, v118 row_ror:8 row_mask:0xf bank_mask:0xf
	v_mov_b32_dpp v167, v119 row_ror:8 row_mask:0xf bank_mask:0xf
	v_cndmask_b32_e64 v116, v164, v120, s[90:91]
	v_cndmask_b32_e64 v117, v165, v121, s[90:91]
	v_cndmask_b32_e64 v118, v166, v122, s[90:91]
	v_cndmask_b32_e64 v119, v167, v123, s[90:91]
	v_cndmask_b32_e64 v120, v120, v164, s[90:91]
	v_cndmask_b32_e64 v121, v121, v165, s[90:91]
	v_cndmask_b32_e64 v122, v122, v166, s[90:91]
	v_cndmask_b32_e64 v123, v123, v167, s[90:91]
	s_lshl_b32 s94, s51, 8
	s_add_i32 s94, s94, 16
	s_lshl_b32 s94, s94, 14
	s_add_u32 s86, s48, s94
	s_addc_u32 s87, s49, 0
	s_lshl_b32 s94, s51, 8
	s_add_i32 s94, s94, 16
	s_lshl_b32 s94, s94, 13
	s_add_u32 s88, s12, s94
	s_addc_u32 s89, s13, 0
	s_lshl_b32 s94, s51, 8
	s_add_i32 s94, s94, 16
	s_lshl_b32 s94, s94, 8
	s_add_u32 s92, s22, s94
	s_addc_u32 s93, s23, 0
	s_waitcnt vmcnt(8)
	v_pk_add_f32 v[128:129], v[128:129], v[96:97]
	v_pk_add_f32 v[130:131], v[130:131], v[98:99]
	v_pk_add_f32 v[124:125], v[124:125], v[92:93]
	v_pk_add_f32 v[126:127], v[126:127], v[94:95]
	global_store_dwordx4 v193, v[128:131], s[86:87]
	global_store_dwordx4 v206, v[124:127], s[86:87]
	v_pk_add_f32 v[120:121], v[120:121], v[88:89]
	v_pk_add_f32 v[122:123], v[122:123], v[90:91]
	v_pk_add_f32 v[116:117], v[116:117], v[84:85]
	v_pk_add_f32 v[118:119], v[118:119], v[86:87]
	global_store_dwordx4 v193, v[120:123], s[86:87] offset:512
	global_store_dwordx4 v206, v[116:119], s[86:87] offset:512
	s_lshl_b32 s94, s51, 8
	s_add_i32 s94, s94, 176
	s_lshl_b32 s94, s94, 14
	s_add_u32 s84, s48, s94
	s_addc_u32 s85, s49, 0
	global_load_dwordx4 v[128:131], v193, s[84:85]
	global_load_dwordx4 v[124:127], v206, s[84:85]
	global_load_dwordx4 v[120:123], v193, s[84:85] offset:512
	global_load_dwordx4 v[116:119], v206, s[84:85] offset:512
	v_mov_b32_dpp v164, v28 row_ror:8 row_mask:0xf bank_mask:0xf
	v_mov_b32_dpp v165, v29 row_ror:8 row_mask:0xf bank_mask:0xf
	v_mov_b32_dpp v166, v30 row_ror:8 row_mask:0xf bank_mask:0xf
	v_mov_b32_dpp v167, v31 row_ror:8 row_mask:0xf bank_mask:0xf
	v_cndmask_b32_e64 v28, v164, v32, s[90:91]
	v_cndmask_b32_e64 v29, v165, v33, s[90:91]
	v_cndmask_b32_e64 v30, v166, v34, s[90:91]
	v_cndmask_b32_e64 v31, v167, v35, s[90:91]
	v_cndmask_b32_e64 v32, v32, v164, s[90:91]
	v_cndmask_b32_e64 v33, v33, v165, s[90:91]
	v_cndmask_b32_e64 v34, v34, v166, s[90:91]
	v_cndmask_b32_e64 v35, v35, v167, s[90:91]
	v_mov_b32_dpp v164, v20 row_ror:8 row_mask:0xf bank_mask:0xf
	v_mov_b32_dpp v165, v21 row_ror:8 row_mask:0xf bank_mask:0xf
	v_mov_b32_dpp v166, v22 row_ror:8 row_mask:0xf bank_mask:0xf
	v_mov_b32_dpp v167, v23 row_ror:8 row_mask:0xf bank_mask:0xf
	v_cndmask_b32_e64 v20, v164, v24, s[90:91]
	v_cndmask_b32_e64 v21, v165, v25, s[90:91]
	v_cndmask_b32_e64 v22, v166, v26, s[90:91]
	v_cndmask_b32_e64 v23, v167, v27, s[90:91]
	v_cndmask_b32_e64 v24, v24, v164, s[90:91]
	v_cndmask_b32_e64 v25, v25, v165, s[90:91]
	v_cndmask_b32_e64 v26, v26, v166, s[90:91]
	v_cndmask_b32_e64 v27, v27, v167, s[90:91]
	s_lshl_b32 s94, s51, 8
	s_add_i32 s94, s94, 160
	s_lshl_b32 s94, s94, 14
	s_add_u32 s86, s48, s94
	s_addc_u32 s87, s49, 0
	s_lshl_b32 s94, s51, 8
	s_add_i32 s94, s94, 160
	s_lshl_b32 s94, s94, 13
	s_add_u32 s88, s12, s94
	s_addc_u32 s89, s13, 0
	s_lshl_b32 s94, s51, 8
	s_add_i32 s94, s94, 160
	s_lshl_b32 s94, s94, 8
	s_add_u32 s92, s22, s94
	s_addc_u32 s93, s23, 0
	s_waitcnt vmcnt(8)
	v_pk_add_f32 v[32:33], v[32:33], v[144:145]
	v_pk_add_f32 v[34:35], v[34:35], v[146:147]
	v_pk_add_f32 v[28:29], v[28:29], v[140:141]
	v_pk_add_f32 v[30:31], v[30:31], v[142:143]
	global_store_dwordx4 v193, v[32:35], s[86:87]
	global_store_dwordx4 v206, v[28:31], s[86:87]
	v_pk_add_f32 v[24:25], v[24:25], v[136:137]
	v_pk_add_f32 v[26:27], v[26:27], v[138:139]
	v_pk_add_f32 v[20:21], v[20:21], v[132:133]
	v_pk_add_f32 v[22:23], v[22:23], v[134:135]
	global_store_dwordx4 v193, v[24:27], s[86:87] offset:512
	global_store_dwordx4 v206, v[20:23], s[86:87] offset:512
	s_lshl_b32 s94, s51, 8
	s_add_i32 s94, s94, 128
	s_lshl_b32 s94, s94, 14
	s_add_u32 s84, s48, s94
	s_addc_u32 s85, s49, 0
	global_load_dwordx4 v[32:35], v193, s[84:85]
	global_load_dwordx4 v[28:31], v206, s[84:85]
	global_load_dwordx4 v[24:27], v193, s[84:85] offset:512
	global_load_dwordx4 v[20:23], v206, s[84:85] offset:512
	v_mov_b32_dpp v164, v12 row_ror:8 row_mask:0xf bank_mask:0xf
	v_mov_b32_dpp v165, v13 row_ror:8 row_mask:0xf bank_mask:0xf
	v_mov_b32_dpp v166, v14 row_ror:8 row_mask:0xf bank_mask:0xf
	v_mov_b32_dpp v167, v15 row_ror:8 row_mask:0xf bank_mask:0xf
	v_cndmask_b32_e64 v12, v164, v16, s[90:91]
	v_cndmask_b32_e64 v13, v165, v17, s[90:91]
	v_cndmask_b32_e64 v14, v166, v18, s[90:91]
	v_cndmask_b32_e64 v15, v167, v19, s[90:91]
	v_cndmask_b32_e64 v16, v16, v164, s[90:91]
	v_cndmask_b32_e64 v17, v17, v165, s[90:91]
	v_cndmask_b32_e64 v18, v18, v166, s[90:91]
	v_cndmask_b32_e64 v19, v19, v167, s[90:91]
	v_mov_b32_dpp v164, v4 row_ror:8 row_mask:0xf bank_mask:0xf
	v_mov_b32_dpp v165, v5 row_ror:8 row_mask:0xf bank_mask:0xf
	v_mov_b32_dpp v166, v6 row_ror:8 row_mask:0xf bank_mask:0xf
	v_mov_b32_dpp v167, v7 row_ror:8 row_mask:0xf bank_mask:0xf
	v_cndmask_b32_e64 v4, v164, v8, s[90:91]
	v_cndmask_b32_e64 v5, v165, v9, s[90:91]
	v_cndmask_b32_e64 v6, v166, v10, s[90:91]
	v_cndmask_b32_e64 v7, v167, v11, s[90:91]
	v_cndmask_b32_e64 v8, v8, v164, s[90:91]
	v_cndmask_b32_e64 v9, v9, v165, s[90:91]
	v_cndmask_b32_e64 v10, v10, v166, s[90:91]
	v_cndmask_b32_e64 v11, v11, v167, s[90:91]
	s_lshl_b32 s94, s51, 8
	s_add_i32 s94, s94, 176
	s_lshl_b32 s94, s94, 14
	s_add_u32 s86, s48, s94
	s_addc_u32 s87, s49, 0
	s_lshl_b32 s94, s51, 8
	s_add_i32 s94, s94, 176
	s_lshl_b32 s94, s94, 13
	s_add_u32 s88, s12, s94
	s_addc_u32 s89, s13, 0
	s_lshl_b32 s94, s51, 8
	s_add_i32 s94, s94, 176
	s_lshl_b32 s94, s94, 8
	s_add_u32 s92, s22, s94
	s_addc_u32 s93, s23, 0
	s_waitcnt vmcnt(8)
	v_pk_add_f32 v[16:17], v[16:17], v[128:129]
	v_pk_add_f32 v[18:19], v[18:19], v[130:131]
	v_pk_add_f32 v[12:13], v[12:13], v[124:125]
	v_pk_add_f32 v[14:15], v[14:15], v[126:127]
	global_store_dwordx4 v193, v[16:19], s[86:87]
	global_store_dwordx4 v206, v[12:15], s[86:87]
	v_pk_add_f32 v[8:9], v[8:9], v[120:121]
	v_pk_add_f32 v[10:11], v[10:11], v[122:123]
	v_pk_add_f32 v[4:5], v[4:5], v[116:117]
	v_pk_add_f32 v[6:7], v[6:7], v[118:119]
	global_store_dwordx4 v193, v[8:11], s[86:87] offset:512
	global_store_dwordx4 v206, v[4:7], s[86:87] offset:512
	s_lshl_b32 s94, s51, 8
	s_add_i32 s94, s94, 144
	s_lshl_b32 s94, s94, 14
	s_add_u32 s84, s48, s94
	s_addc_u32 s85, s49, 0
	global_load_dwordx4 v[16:19], v193, s[84:85]
	global_load_dwordx4 v[12:15], v206, s[84:85]
	global_load_dwordx4 v[8:11], v193, s[84:85] offset:512
	global_load_dwordx4 v[4:7], v206, s[84:85] offset:512
	v_mov_b32_dpp v164, v64 row_ror:8 row_mask:0xf bank_mask:0xf
	v_mov_b32_dpp v165, v65 row_ror:8 row_mask:0xf bank_mask:0xf
	v_mov_b32_dpp v166, v66 row_ror:8 row_mask:0xf bank_mask:0xf
	v_mov_b32_dpp v167, v67 row_ror:8 row_mask:0xf bank_mask:0xf
	v_cndmask_b32_e64 v64, v164, v72, s[90:91]
	v_cndmask_b32_e64 v65, v165, v73, s[90:91]
	v_cndmask_b32_e64 v66, v166, v74, s[90:91]
	v_cndmask_b32_e64 v67, v167, v75, s[90:91]
	v_cndmask_b32_e64 v72, v72, v164, s[90:91]
	v_cndmask_b32_e64 v73, v73, v165, s[90:91]
	v_cndmask_b32_e64 v74, v74, v166, s[90:91]
	v_cndmask_b32_e64 v75, v75, v167, s[90:91]
	v_mov_b32_dpp v164, v52 row_ror:8 row_mask:0xf bank_mask:0xf
	v_mov_b32_dpp v165, v53 row_ror:8 row_mask:0xf bank_mask:0xf
	v_mov_b32_dpp v166, v54 row_ror:8 row_mask:0xf bank_mask:0xf
	v_mov_b32_dpp v167, v55 row_ror:8 row_mask:0xf bank_mask:0xf
	v_cndmask_b32_e64 v52, v164, v56, s[90:91]
	v_cndmask_b32_e64 v53, v165, v57, s[90:91]
	v_cndmask_b32_e64 v54, v166, v58, s[90:91]
	v_cndmask_b32_e64 v55, v167, v59, s[90:91]
	v_cndmask_b32_e64 v56, v56, v164, s[90:91]
	v_cndmask_b32_e64 v57, v57, v165, s[90:91]
	v_cndmask_b32_e64 v58, v58, v166, s[90:91]
	v_cndmask_b32_e64 v59, v59, v167, s[90:91]
	s_lshl_b32 s94, s51, 8
	s_add_i32 s94, s94, 128
	s_lshl_b32 s94, s94, 14
	s_add_u32 s86, s48, s94
	s_addc_u32 s87, s49, 0
	s_lshl_b32 s94, s51, 8
	s_add_i32 s94, s94, 128
	s_lshl_b32 s94, s94, 13
	s_add_u32 s88, s12, s94
	s_addc_u32 s89, s13, 0
	s_lshl_b32 s94, s51, 8
	s_add_i32 s94, s94, 128
	s_lshl_b32 s94, s94, 8
	s_add_u32 s92, s22, s94
	s_addc_u32 s93, s23, 0
	s_waitcnt vmcnt(8)
	v_pk_add_f32 v[72:73], v[72:73], v[32:33]
	v_pk_add_f32 v[74:75], v[74:75], v[34:35]
	v_pk_add_f32 v[64:65], v[64:65], v[28:29]
	v_pk_add_f32 v[66:67], v[66:67], v[30:31]
	global_store_dwordx4 v193, v[72:75], s[86:87]
	global_store_dwordx4 v206, v[64:67], s[86:87]
	v_pk_add_f32 v[56:57], v[56:57], v[24:25]
	v_pk_add_f32 v[58:59], v[58:59], v[26:27]
	v_pk_add_f32 v[52:53], v[52:53], v[20:21]
	v_pk_add_f32 v[54:55], v[54:55], v[22:23]
	global_store_dwordx4 v193, v[56:59], s[86:87] offset:512
	global_store_dwordx4 v206, v[52:55], s[86:87] offset:512
	v_mov_b32_dpp v164, v44 row_ror:8 row_mask:0xf bank_mask:0xf
	v_mov_b32_dpp v165, v45 row_ror:8 row_mask:0xf bank_mask:0xf
	v_mov_b32_dpp v166, v46 row_ror:8 row_mask:0xf bank_mask:0xf
	v_mov_b32_dpp v167, v47 row_ror:8 row_mask:0xf bank_mask:0xf
	v_cndmask_b32_e64 v44, v164, v48, s[90:91]
	v_cndmask_b32_e64 v45, v165, v49, s[90:91]
	v_cndmask_b32_e64 v46, v166, v50, s[90:91]
	v_cndmask_b32_e64 v47, v167, v51, s[90:91]
	v_cndmask_b32_e64 v48, v48, v164, s[90:91]
	v_cndmask_b32_e64 v49, v49, v165, s[90:91]
	v_cndmask_b32_e64 v50, v50, v166, s[90:91]
	v_cndmask_b32_e64 v51, v51, v167, s[90:91]
	v_mov_b32_dpp v164, v36 row_ror:8 row_mask:0xf bank_mask:0xf
	v_mov_b32_dpp v165, v37 row_ror:8 row_mask:0xf bank_mask:0xf
	v_mov_b32_dpp v166, v38 row_ror:8 row_mask:0xf bank_mask:0xf
	v_mov_b32_dpp v167, v39 row_ror:8 row_mask:0xf bank_mask:0xf
	v_cndmask_b32_e64 v36, v164, v40, s[90:91]
	v_cndmask_b32_e64 v37, v165, v41, s[90:91]
	v_cndmask_b32_e64 v38, v166, v42, s[90:91]
	v_cndmask_b32_e64 v39, v167, v43, s[90:91]
	v_cndmask_b32_e64 v40, v40, v164, s[90:91]
	v_cndmask_b32_e64 v41, v41, v165, s[90:91]
	v_cndmask_b32_e64 v42, v42, v166, s[90:91]
	v_cndmask_b32_e64 v43, v43, v167, s[90:91]
	s_lshl_b32 s94, s51, 8
	s_add_i32 s94, s94, 144
	s_lshl_b32 s94, s94, 14
	s_add_u32 s86, s48, s94
	s_addc_u32 s87, s49, 0
	s_lshl_b32 s94, s51, 8
	s_add_i32 s94, s94, 144
	s_lshl_b32 s94, s94, 13
	s_add_u32 s88, s12, s94
	s_addc_u32 s89, s13, 0
	s_lshl_b32 s94, s51, 8
	s_add_i32 s94, s94, 144
	s_lshl_b32 s94, s94, 8
	s_add_u32 s92, s22, s94
	s_addc_u32 s93, s23, 0
	s_waitcnt vmcnt(4)
	v_pk_add_f32 v[48:49], v[48:49], v[16:17]
	v_pk_add_f32 v[50:51], v[50:51], v[18:19]
	v_pk_add_f32 v[44:45], v[44:45], v[12:13]
	v_pk_add_f32 v[46:47], v[46:47], v[14:15]
	global_store_dwordx4 v193, v[48:51], s[86:87]
	global_store_dwordx4 v206, v[44:47], s[86:87]
	v_pk_add_f32 v[40:41], v[40:41], v[8:9]
	v_pk_add_f32 v[42:43], v[42:43], v[10:11]
	v_pk_add_f32 v[36:37], v[36:37], v[4:5]
	v_pk_add_f32 v[38:39], v[38:39], v[6:7]
	global_store_dwordx4 v193, v[40:43], s[86:87] offset:512
	global_store_dwordx4 v206, v[36:39], s[86:87] offset:512
	s_branch .Lrot_p8n_end
.Lrot_p8n_3:
	v_and_b32_e32 v192, 8, v219
	v_cmp_ne_u32_e64 s[90:91], 0, v192
	v_sub_u32_e32 v214, v1, v192
	v_lshlrev_b32_e32 v192, 1, v192
	s_lshl_b32 s94, s50, 8
	v_add3_u32 v215, v240, v192, s94
	v_sub_u32_e32 v180, v240, v192
	v_add3_u32 v180, v180, 16, s94
	v_lshlrev_b32_e32 v193, 14, v214
	v_lshl_add_u32 v206, v180, 2, v193
	v_add_u32_e32 v206, 0x20000, v206
	v_lshl_add_u32 v193, v215, 2, v193
	v_lshlrev_b32_e32 v207, 13, v214
	v_lshl_add_u32 v208, v180, 1, v207
	v_add_u32_e32 v208, 0x10000, v208
	v_lshl_add_u32 v207, v215, 1, v207
	v_lshlrev_b32_e32 v209, 2, v215
	v_lshlrev_b32_e32 v210, 2, v180
	s_lshl_b32 s94, s50, 4
	s_lshl_b32 s95, s34, 2
	s_add_i32 s94, s94, s95
	v_lshlrev_b32_e32 v211, 8, v1
	v_add_u32_e32 v211, s94, v211
	v_xor_b32_e32 v212, 16, v219
	v_lshlrev_b32_e32 v212, 2, v212
	v_xor_b32_e32 v213, 32, v219
	v_lshlrev_b32_e32 v213, 2, v213
	s_lshl_b32 s94, s51, 8
	s_add_i32 s94, s94, 48
	s_lshl_b32 s94, s94, 14
	s_add_u32 s84, s48, s94
	s_addc_u32 s85, s49, 0
	global_load_dwordx4 v[60:63], v193, s[84:85]
	global_load_dwordx4 v[68:71], v206, s[84:85]
	global_load_dwordx4 v[76:79], v193, s[84:85] offset:512
	global_load_dwordx4 v[80:83], v206, s[84:85] offset:512
	s_lshl_b32 s94, s51, 8
	s_lshl_b32 s94, s94, 14
	s_add_u32 s84, s48, s94
	s_addc_u32 s85, s49, 0
	global_load_dwordx4 v[172:175], v193, s[84:85]
	global_load_dwordx4 v[176:179], v206, s[84:85]
	global_load_dwordx4 v[182:185], v193, s[84:85] offset:512
	global_load_dwordx4 v[232:235], v206, s[84:85] offset:512
	v_mov_b32_dpp v164, v92 row_ror:8 row_mask:0xf bank_mask:0xf
	v_mov_b32_dpp v165, v93 row_ror:8 row_mask:0xf bank_mask:0xf
	v_mov_b32_dpp v166, v94 row_ror:8 row_mask:0xf bank_mask:0xf
	v_mov_b32_dpp v167, v95 row_ror:8 row_mask:0xf bank_mask:0xf
	v_cndmask_b32_e64 v92, v164, v96, s[90:91]
	v_cndmask_b32_e64 v93, v165, v97, s[90:91]
	v_cndmask_b32_e64 v94, v166, v98, s[90:91]
	v_cndmask_b32_e64 v95, v167, v99, s[90:91]
	v_cndmask_b32_e64 v96, v96, v164, s[90:91]
	v_cndmask_b32_e64 v97, v97, v165, s[90:91]
	v_cndmask_b32_e64 v98, v98, v166, s[90:91]
	v_cndmask_b32_e64 v99, v99, v167, s[90:91]
	v_mov_b32_dpp v164, v84 row_ror:8 row_mask:0xf bank_mask:0xf
	v_mov_b32_dpp v165, v85 row_ror:8 row_mask:0xf bank_mask:0xf
	v_mov_b32_dpp v166, v86 row_ror:8 row_mask:0xf bank_mask:0xf
	v_mov_b32_dpp v167, v87 row_ror:8 row_mask:0xf bank_mask:0xf
	v_cndmask_b32_e64 v84, v164, v88, s[90:91]
	v_cndmask_b32_e64 v85, v165, v89, s[90:91]
	v_cndmask_b32_e64 v86, v166, v90, s[90:91]
	v_cndmask_b32_e64 v87, v167, v91, s[90:91]
	v_cndmask_b32_e64 v88, v88, v164, s[90:91]
	v_cndmask_b32_e64 v89, v89, v165, s[90:91]
	v_cndmask_b32_e64 v90, v90, v166, s[90:91]
	v_cndmask_b32_e64 v91, v91, v167, s[90:91]
	s_lshl_b32 s94, s51, 8
	s_add_i32 s94, s94, 48
	s_lshl_b32 s94, s94, 14
	s_add_u32 s86, s48, s94
	s_addc_u32 s87, s49, 0
	s_lshl_b32 s94, s51, 8
	s_add_i32 s94, s94, 48
	s_lshl_b32 s94, s94, 13
	s_add_u32 s88, s12, s94
	s_addc_u32 s89, s13, 0
	s_lshl_b32 s94, s51, 8
	s_add_i32 s94, s94, 48
	s_lshl_b32 s94, s94, 8
	s_add_u32 s92, s22, s94
	s_addc_u32 s93, s23, 0
	s_waitcnt vmcnt(4)
	v_pk_add_f32 v[96:97], v[96:97], v[60:61]
	v_pk_add_f32 v[98:99], v[98:99], v[62:63]
	v_pk_add_f32 v[92:93], v[92:93], v[68:69]
	v_pk_add_f32 v[94:95], v[94:95], v[70:71]
	global_store_dwordx4 v193, v[96:99], s[86:87]
	global_store_dwordx4 v206, v[92:95], s[86:87]
	v_pk_add_f32 v[88:89], v[88:89], v[76:77]
	v_pk_add_f32 v[90:91], v[90:91], v[78:79]
	v_pk_add_f32 v[84:85], v[84:85], v[80:81]
	v_pk_add_f32 v[86:87], v[86:87], v[82:83]
	global_store_dwordx4 v193, v[88:91], s[86:87] offset:512
	global_store_dwordx4 v206, v[84:87], s[86:87] offset:512
	s_lshl_b32 s94, s51, 8
	s_add_i32 s94, s94, 16
	s_lshl_b32 s94, s94, 14
	s_add_u32 s84, s48, s94
	s_addc_u32 s85, s49, 0
	global_load_dwordx4 v[96:99], v193, s[84:85]
	global_load_dwordx4 v[92:95], v206, s[84:85]
	global_load_dwordx4 v[88:91], v193, s[84:85] offset:512
	global_load_dwordx4 v[84:87], v206, s[84:85] offset:512
	v_mov_b32_dpp v164, v140 row_ror:8 row_mask:0xf bank_mask:0xf
	v_mov_b32_dpp v165, v141 row_ror:8 row_mask:0xf bank_mask:0xf
	v_mov_b32_dpp v166, v142 row_ror:8 row_mask:0xf bank_mask:0xf
	v_mov_b32_dpp v167, v143 row_ror:8 row_mask:0xf bank_mask:0xf
	v_cndmask_b32_e64 v140, v164, v144, s[90:91]
	v_cndmask_b32_e64 v141, v165, v145, s[90:91]
	v_cndmask_b32_e64 v142, v166, v146, s[90:91]
	v_cndmask_b32_e64 v143, v167, v147, s[90:91]
	v_cndmask_b32_e64 v144, v144, v164, s[90:91]
	v_cndmask_b32_e64 v145, v145, v165, s[90:91]
	v_cndmask_b32_e64 v146, v146, v166, s[90:91]
	v_cndmask_b32_e64 v147, v147, v167, s[90:91]
	v_mov_b32_dpp v164, v132 row_ror:8 row_mask:0xf bank_mask:0xf
	v_mov_b32_dpp v165, v133 row_ror:8 row_mask:0xf bank_mask:0xf
	v_mov_b32_dpp v166, v134 row_ror:8 row_mask:0xf bank_mask:0xf
	v_mov_b32_dpp v167, v135 row_ror:8 row_mask:0xf bank_mask:0xf
	v_cndmask_b32_e64 v132, v164, v136, s[90:91]
	v_cndmask_b32_e64 v133, v165, v137, s[90:91]
	v_cndmask_b32_e64 v134, v166, v138, s[90:91]
	v_cndmask_b32_e64 v135, v167, v139, s[90:91]
	v_cndmask_b32_e64 v136, v136, v164, s[90:91]
	v_cndmask_b32_e64 v137, v137, v165, s[90:91]
	v_cndmask_b32_e64 v138, v138, v166, s[90:91]
	v_cndmask_b32_e64 v139, v139, v167, s[90:91]
	s_lshl_b32 s94, s51, 8
	s_lshl_b32 s94, s94, 14
	s_add_u32 s86, s48, s94
	s_addc_u32 s87, s49, 0
	s_lshl_b32 s94, s51, 8
	s_lshl_b32 s94, s94, 13
	s_add_u32 s88, s12, s94
	s_addc_u32 s89, s13, 0
	s_lshl_b32 s94, s51, 8
	s_lshl_b32 s94, s94, 8
	s_add_u32 s92, s22, s94
	s_addc_u32 s93, s23, 0
	s_waitcnt vmcnt(8)
	v_pk_add_f32 v[144:145], v[144:145], v[172:173]
	v_pk_add_f32 v[146:147], v[146:147], v[174:175]
	v_pk_add_f32 v[140:141], v[140:141], v[176:177]
	v_pk_add_f32 v[142:143], v[142:143], v[178:179]
	global_store_dwordx4 v193, v[144:147], s[86:87]
	global_store_dwordx4 v206, v[140:143], s[86:87]
	v_pk_add_f32 v[136:137], v[136:137], v[182:183]
	v_pk_add_f32 v[138:139], v[138:139], v[184:185]
	v_pk_add_f32 v[132:133], v[132:133], v[232:233]
	v_pk_add_f32 v[134:135], v[134:135], v[234:235]
	global_store_dwordx4 v193, v[136:139], s[86:87] offset:512
	global_store_dwordx4 v206, v[132:135], s[86:87] offset:512
	s_lshl_b32 s94, s51, 8
	s_add_i32 s94, s94, 32
	s_lshl_b32 s94, s94, 14
	s_add_u32 s84, s48, s94
	s_addc_u32 s85, s49, 0
	global_load_dwordx4 v[144:147], v193, s[84:85]
	global_load_dwordx4 v[140:143], v206, s[84:85]
	global_load_dwordx4 v[136:139], v193, s[84:85] offset:512
	global_load_dwordx4 v[132:135], v206, s[84:85] offset:512
	v_mov_b32_dpp v164, v124 row_ror:8 row_mask:0xf bank_mask:0xf
	v_mov_b32_dpp v165, v125 row_ror:8 row_mask:0xf bank_mask:0xf
	v_mov_b32_dpp v166, v126 row_ror:8 row_mask:0xf bank_mask:0xf
	v_mov_b32_dpp v167, v127 row_ror:8 row_mask:0xf bank_mask:0xf
	v_cndmask_b32_e64 v124, v164, v128, s[90:91]
	v_cndmask_b32_e64 v125, v165, v129, s[90:91]
	v_cndmask_b32_e64 v126, v166, v130, s[90:91]
	v_cndmask_b32_e64 v127, v167, v131, s[90:91]
	v_cndmask_b32_e64 v128, v128, v164, s[90:91]
	v_cndmask_b32_e64 v129, v129, v165, s[90:91]
	v_cndmask_b32_e64 v130, v130, v166, s[90:91]
	v_cndmask_b32_e64 v131, v131, v167, s[90:91]
	v_mov_b32_dpp v164, v116 row_ror:8 row_mask:0xf bank_mask:0xf
	v_mov_b32_dpp v165, v117 row_ror:8 row_mask:0xf bank_mask:0xf
	v_mov_b32_dpp v166, v118 row_ror:8 row_mask:0xf bank_mask:0xf
	v_mov_b32_dpp v167, v119 row_ror:8 row_mask:0xf bank_mask:0xf
	v_cndmask_b32_e64 v116, v164, v120, s[90:91]
	v_cndmask_b32_e64 v117, v165, v121, s[90:91]
	v_cndmask_b32_e64 v118, v166, v122, s[90:91]
	v_cndmask_b32_e64 v119, v167, v123, s[90:91]
	v_cndmask_b32_e64 v120, v120, v164, s[90:91]
	v_cndmask_b32_e64 v121, v121, v165, s[90:91]
	v_cndmask_b32_e64 v122, v122, v166, s[90:91]
	v_cndmask_b32_e64 v123, v123, v167, s[90:91]
	s_lshl_b32 s94, s51, 8
	s_add_i32 s94, s94, 16
	s_lshl_b32 s94, s94, 14
	s_add_u32 s86, s48, s94
	s_addc_u32 s87, s49, 0
	s_lshl_b32 s94, s51, 8
	s_add_i32 s94, s94, 16
	s_lshl_b32 s94, s94, 13
	s_add_u32 s88, s12, s94
	s_addc_u32 s89, s13, 0
	s_lshl_b32 s94, s51, 8
	s_add_i32 s94, s94, 16
	s_lshl_b32 s94, s94, 8
	s_add_u32 s92, s22, s94
	s_addc_u32 s93, s23, 0
	s_waitcnt vmcnt(8)
	v_pk_add_f32 v[128:129], v[128:129], v[96:97]
	v_pk_add_f32 v[130:131], v[130:131], v[98:99]
	v_pk_add_f32 v[124:125], v[124:125], v[92:93]
	v_pk_add_f32 v[126:127], v[126:127], v[94:95]
	global_store_dwordx4 v193, v[128:131], s[86:87]
	global_store_dwordx4 v206, v[124:127], s[86:87]
	v_pk_add_f32 v[120:121], v[120:121], v[88:89]
	v_pk_add_f32 v[122:123], v[122:123], v[90:91]
	v_pk_add_f32 v[116:117], v[116:117], v[84:85]
	v_pk_add_f32 v[118:119], v[118:119], v[86:87]
	global_store_dwordx4 v193, v[120:123], s[86:87] offset:512
	global_store_dwordx4 v206, v[116:119], s[86:87] offset:512
	s_lshl_b32 s94, s51, 8
	s_add_i32 s94, s94, 176
	s_lshl_b32 s94, s94, 14
	s_add_u32 s84, s48, s94
	s_addc_u32 s85, s49, 0
	global_load_dwordx4 v[128:131], v193, s[84:85]
	global_load_dwordx4 v[124:127], v206, s[84:85]
	global_load_dwordx4 v[120:123], v193, s[84:85] offset:512
	global_load_dwordx4 v[116:119], v206, s[84:85] offset:512
	v_mov_b32_dpp v164, v108 row_ror:8 row_mask:0xf bank_mask:0xf
	v_mov_b32_dpp v165, v109 row_ror:8 row_mask:0xf bank_mask:0xf
	v_mov_b32_dpp v166, v110 row_ror:8 row_mask:0xf bank_mask:0xf
	v_mov_b32_dpp v167, v111 row_ror:8 row_mask:0xf bank_mask:0xf
	v_cndmask_b32_e64 v108, v164, v112, s[90:91]
	v_cndmask_b32_e64 v109, v165, v113, s[90:91]
	v_cndmask_b32_e64 v110, v166, v114, s[90:91]
	v_cndmask_b32_e64 v111, v167, v115, s[90:91]
	v_cndmask_b32_e64 v112, v112, v164, s[90:91]
	v_cndmask_b32_e64 v113, v113, v165, s[90:91]
	v_cndmask_b32_e64 v114, v114, v166, s[90:91]
	v_cndmask_b32_e64 v115, v115, v167, s[90:91]
	v_mov_b32_dpp v164, v100 row_ror:8 row_mask:0xf bank_mask:0xf
	v_mov_b32_dpp v165, v101 row_ror:8 row_mask:0xf bank_mask:0xf
	v_mov_b32_dpp v166, v102 row_ror:8 row_mask:0xf bank_mask:0xf
	v_mov_b32_dpp v167, v103 row_ror:8 row_mask:0xf bank_mask:0xf
	v_cndmask_b32_e64 v100, v164, v104, s[90:91]
	v_cndmask_b32_e64 v101, v165, v105, s[90:91]
	v_cndmask_b32_e64 v102, v166, v106, s[90:91]
	v_cndmask_b32_e64 v103, v167, v107, s[90:91]
	v_cndmask_b32_e64 v104, v104, v164, s[90:91]
	v_cndmask_b32_e64 v105, v105, v165, s[90:91]
	v_cndmask_b32_e64 v106, v106, v166, s[90:91]
	v_cndmask_b32_e64 v107, v107, v167, s[90:91]
	s_lshl_b32 s94, s51, 8
	s_add_i32 s94, s94, 32
	s_lshl_b32 s94, s94, 14
	s_add_u32 s86, s48, s94
	s_addc_u32 s87, s49, 0
	s_lshl_b32 s94, s51, 8
	s_add_i32 s94, s94, 32
	s_lshl_b32 s94, s94, 13
	s_add_u32 s88, s12, s94
	s_addc_u32 s89, s13, 0
	s_lshl_b32 s94, s51, 8
	s_add_i32 s94, s94, 32
	s_lshl_b32 s94, s94, 8
	s_add_u32 s92, s22, s94
	s_addc_u32 s93, s23, 0
	s_waitcnt vmcnt(8)
	v_pk_add_f32 v[112:113], v[112:113], v[144:145]
	v_pk_add_f32 v[114:115], v[114:115], v[146:147]
	v_pk_add_f32 v[108:109], v[108:109], v[140:141]
	v_pk_add_f32 v[110:111], v[110:111], v[142:143]
	global_store_dwordx4 v193, v[112:115], s[86:87]
	global_store_dwordx4 v206, v[108:111], s[86:87]
	v_pk_add_f32 v[104:105], v[104:105], v[136:137]
	v_pk_add_f32 v[106:107], v[106:107], v[138:139]
	v_pk_add_f32 v[100:101], v[100:101], v[132:133]
	v_pk_add_f32 v[102:103], v[102:103], v[134:135]
	global_store_dwordx4 v193, v[104:107], s[86:87] offset:512
	global_store_dwordx4 v206, v[100:103], s[86:87] offset:512
	s_lshl_b32 s94, s51, 8
	s_add_i32 s94, s94, 128
	s_lshl_b32 s94, s94, 14
	s_add_u32 s84, s48, s94
	s_addc_u32 s85, s49, 0
	global_load_dwordx4 v[112:115], v193, s[84:85]
	global_load_dwordx4 v[108:111], v206, s[84:85]
	global_load_dwordx4 v[104:107], v193, s[84:85] offset:512
	global_load_dwordx4 v[100:103], v206, s[84:85] offset:512
	v_mov_b32_dpp v164, v12 row_ror:8 row_mask:0xf bank_mask:0xf
	v_mov_b32_dpp v165, v13 row_ror:8 row_mask:0xf bank_mask:0xf
	v_mov_b32_dpp v166, v14 row_ror:8 row_mask:0xf bank_mask:0xf
	v_mov_b32_dpp v167, v15 row_ror:8 row_mask:0xf bank_mask:0xf
	v_cndmask_b32_e64 v12, v164, v16, s[90:91]
	v_cndmask_b32_e64 v13, v165, v17, s[90:91]
	v_cndmask_b32_e64 v14, v166, v18, s[90:91]
	v_cndmask_b32_e64 v15, v167, v19, s[90:91]
	v_cndmask_b32_e64 v16, v16, v164, s[90:91]
	v_cndmask_b32_e64 v17, v17, v165, s[90:91]
	v_cndmask_b32_e64 v18, v18, v166, s[90:91]
	v_cndmask_b32_e64 v19, v19, v167, s[90:91]
	v_mov_b32_dpp v164, v4 row_ror:8 row_mask:0xf bank_mask:0xf
	v_mov_b32_dpp v165, v5 row_ror:8 row_mask:0xf bank_mask:0xf
	v_mov_b32_dpp v166, v6 row_ror:8 row_mask:0xf bank_mask:0xf
	v_mov_b32_dpp v167, v7 row_ror:8 row_mask:0xf bank_mask:0xf
	v_cndmask_b32_e64 v4, v164, v8, s[90:91]
	v_cndmask_b32_e64 v5, v165, v9, s[90:91]
	v_cndmask_b32_e64 v6, v166, v10, s[90:91]
	v_cndmask_b32_e64 v7, v167, v11, s[90:91]
	v_cndmask_b32_e64 v8, v8, v164, s[90:91]
	v_cndmask_b32_e64 v9, v9, v165, s[90:91]
	v_cndmask_b32_e64 v10, v10, v166, s[90:91]
	v_cndmask_b32_e64 v11, v11, v167, s[90:91]
	s_lshl_b32 s94, s51, 8
	s_add_i32 s94, s94, 176
	s_lshl_b32 s94, s94, 14
	s_add_u32 s86, s48, s94
	s_addc_u32 s87, s49, 0
	s_lshl_b32 s94, s51, 8
	s_add_i32 s94, s94, 176
	s_lshl_b32 s94, s94, 13
	s_add_u32 s88, s12, s94
	s_addc_u32 s89, s13, 0
	s_lshl_b32 s94, s51, 8
	s_add_i32 s94, s94, 176
	s_lshl_b32 s94, s94, 8
	s_add_u32 s92, s22, s94
	s_addc_u32 s93, s23, 0
	s_waitcnt vmcnt(8)
	v_pk_add_f32 v[16:17], v[16:17], v[128:129]
	v_pk_add_f32 v[18:19], v[18:19], v[130:131]
	v_pk_add_f32 v[12:13], v[12:13], v[124:125]
	v_pk_add_f32 v[14:15], v[14:15], v[126:127]
	global_store_dwordx4 v193, v[16:19], s[86:87]
	global_store_dwordx4 v206, v[12:15], s[86:87]
	v_pk_add_f32 v[8:9], v[8:9], v[120:121]
	v_pk_add_f32 v[10:11], v[10:11], v[122:123]
	v_pk_add_f32 v[4:5], v[4:5], v[116:117]
	v_pk_add_f32 v[6:7], v[6:7], v[118:119]
	global_store_dwordx4 v193, v[8:11], s[86:87] offset:512
	global_store_dwordx4 v206, v[4:7], s[86:87] offset:512
	s_lshl_b32 s94, s51, 8
	s_add_i32 s94, s94, 144
	s_lshl_b32 s94, s94, 14
	s_add_u32 s84, s48, s94
	s_addc_u32 s85, s49, 0
	global_load_dwordx4 v[16:19], v193, s[84:85]
	global_load_dwordx4 v[12:15], v206, s[84:85]
	global_load_dwordx4 v[8:11], v193, s[84:85] offset:512
	global_load_dwordx4 v[4:7], v206, s[84:85] offset:512
	v_mov_b32_dpp v164, v64 row_ror:8 row_mask:0xf bank_mask:0xf
	v_mov_b32_dpp v165, v65 row_ror:8 row_mask:0xf bank_mask:0xf
	v_mov_b32_dpp v166, v66 row_ror:8 row_mask:0xf bank_mask:0xf
	v_mov_b32_dpp v167, v67 row_ror:8 row_mask:0xf bank_mask:0xf
	v_cndmask_b32_e64 v64, v164, v72, s[90:91]
	v_cndmask_b32_e64 v65, v165, v73, s[90:91]
	v_cndmask_b32_e64 v66, v166, v74, s[90:91]
	v_cndmask_b32_e64 v67, v167, v75, s[90:91]
	v_cndmask_b32_e64 v72, v72, v164, s[90:91]
	v_cndmask_b32_e64 v73, v73, v165, s[90:91]
	v_cndmask_b32_e64 v74, v74, v166, s[90:91]
	v_cndmask_b32_e64 v75, v75, v167, s[90:91]
	v_mov_b32_dpp v164, v52 row_ror:8 row_mask:0xf bank_mask:0xf
	v_mov_b32_dpp v165, v53 row_ror:8 row_mask:0xf bank_mask:0xf
	v_mov_b32_dpp v166, v54 row_ror:8 row_mask:0xf bank_mask:0xf
	v_mov_b32_dpp v167, v55 row_ror:8 row_mask:0xf bank_mask:0xf
	v_cndmask_b32_e64 v52, v164, v56, s[90:91]
	v_cndmask_b32_e64 v53, v165, v57, s[90:91]
	v_cndmask_b32_e64 v54, v166, v58, s[90:91]
	v_cndmask_b32_e64 v55, v167, v59, s[90:91]
	v_cndmask_b32_e64 v56, v56, v164, s[90:91]
	v_cndmask_b32_e64 v57, v57, v165, s[90:91]
	v_cndmask_b32_e64 v58, v58, v166, s[90:91]
	v_cndmask_b32_e64 v59, v59, v167, s[90:91]
	s_lshl_b32 s94, s51, 8
	s_add_i32 s94, s94, 128
	s_lshl_b32 s94, s94, 14
	s_add_u32 s86, s48, s94
	s_addc_u32 s87, s49, 0
	s_lshl_b32 s94, s51, 8
	s_add_i32 s94, s94, 128
	s_lshl_b32 s94, s94, 13
	s_add_u32 s88, s12, s94
	s_addc_u32 s89, s13, 0
	s_lshl_b32 s94, s51, 8
	s_add_i32 s94, s94, 128
	s_lshl_b32 s94, s94, 8
	s_add_u32 s92, s22, s94
	s_addc_u32 s93, s23, 0
	s_waitcnt vmcnt(8)
	v_pk_add_f32 v[72:73], v[72:73], v[112:113]
	v_pk_add_f32 v[74:75], v[74:75], v[114:115]
	v_pk_add_f32 v[64:65], v[64:65], v[108:109]
	v_pk_add_f32 v[66:67], v[66:67], v[110:111]
	global_store_dwordx4 v193, v[72:75], s[86:87]
	global_store_dwordx4 v206, v[64:67], s[86:87]
	v_pk_add_f32 v[56:57], v[56:57], v[104:105]
	v_pk_add_f32 v[58:59], v[58:59], v[106:107]
	v_pk_add_f32 v[52:53], v[52:53], v[100:101]
	v_pk_add_f32 v[54:55], v[54:55], v[102:103]
	global_store_dwordx4 v193, v[56:59], s[86:87] offset:512
	global_store_dwordx4 v206, v[52:55], s[86:87] offset:512
	s_lshl_b32 s94, s51, 8
	s_add_i32 s94, s94, 160
	s_lshl_b32 s94, s94, 14
	s_add_u32 s84, s48, s94
	s_addc_u32 s85, s49, 0
	global_load_dwordx4 v[72:75], v193, s[84:85]
	global_load_dwordx4 v[64:67], v206, s[84:85]
	global_load_dwordx4 v[56:59], v193, s[84:85] offset:512
	global_load_dwordx4 v[52:55], v206, s[84:85] offset:512
	v_mov_b32_dpp v164, v44 row_ror:8 row_mask:0xf bank_mask:0xf
	v_mov_b32_dpp v165, v45 row_ror:8 row_mask:0xf bank_mask:0xf
	v_mov_b32_dpp v166, v46 row_ror:8 row_mask:0xf bank_mask:0xf
	v_mov_b32_dpp v167, v47 row_ror:8 row_mask:0xf bank_mask:0xf
	v_cndmask_b32_e64 v44, v164, v48, s[90:91]
	v_cndmask_b32_e64 v45, v165, v49, s[90:91]
	v_cndmask_b32_e64 v46, v166, v50, s[90:91]
	v_cndmask_b32_e64 v47, v167, v51, s[90:91]
	v_cndmask_b32_e64 v48, v48, v164, s[90:91]
	v_cndmask_b32_e64 v49, v49, v165, s[90:91]
	v_cndmask_b32_e64 v50, v50, v166, s[90:91]
	v_cndmask_b32_e64 v51, v51, v167, s[90:91]
	v_mov_b32_dpp v164, v36 row_ror:8 row_mask:0xf bank_mask:0xf
	v_mov_b32_dpp v165, v37 row_ror:8 row_mask:0xf bank_mask:0xf
	v_mov_b32_dpp v166, v38 row_ror:8 row_mask:0xf bank_mask:0xf
	v_mov_b32_dpp v167, v39 row_ror:8 row_mask:0xf bank_mask:0xf
	v_cndmask_b32_e64 v36, v164, v40, s[90:91]
	v_cndmask_b32_e64 v37, v165, v41, s[90:91]
	v_cndmask_b32_e64 v38, v166, v42, s[90:91]
	v_cndmask_b32_e64 v39, v167, v43, s[90:91]
	v_cndmask_b32_e64 v40, v40, v164, s[90:91]
	v_cndmask_b32_e64 v41, v41, v165, s[90:91]
	v_cndmask_b32_e64 v42, v42, v166, s[90:91]
	v_cndmask_b32_e64 v43, v43, v167, s[90:91]
	s_lshl_b32 s94, s51, 8
	s_add_i32 s94, s94, 144
	s_lshl_b32 s94, s94, 14
	s_add_u32 s86, s48, s94
	s_addc_u32 s87, s49, 0
	s_lshl_b32 s94, s51, 8
	s_add_i32 s94, s94, 144
	s_lshl_b32 s94, s94, 13
	s_add_u32 s88, s12, s94
	s_addc_u32 s89, s13, 0
	s_lshl_b32 s94, s51, 8
	s_add_i32 s94, s94, 144
	s_lshl_b32 s94, s94, 8
	s_add_u32 s92, s22, s94
	s_addc_u32 s93, s23, 0
	s_waitcnt vmcnt(8)
	v_pk_add_f32 v[48:49], v[48:49], v[16:17]
	v_pk_add_f32 v[50:51], v[50:51], v[18:19]
	v_pk_add_f32 v[44:45], v[44:45], v[12:13]
	v_pk_add_f32 v[46:47], v[46:47], v[14:15]
	global_store_dwordx4 v193, v[48:51], s[86:87]
	global_store_dwordx4 v206, v[44:47], s[86:87]
	v_pk_add_f32 v[40:41], v[40:41], v[8:9]
	v_pk_add_f32 v[42:43], v[42:43], v[10:11]
	v_pk_add_f32 v[36:37], v[36:37], v[4:5]
	v_pk_add_f32 v[38:39], v[38:39], v[6:7]
	global_store_dwordx4 v193, v[40:43], s[86:87] offset:512
	global_store_dwordx4 v206, v[36:39], s[86:87] offset:512
	v_mov_b32_dpp v164, v28 row_ror:8 row_mask:0xf bank_mask:0xf
	v_mov_b32_dpp v165, v29 row_ror:8 row_mask:0xf bank_mask:0xf
	v_mov_b32_dpp v166, v30 row_ror:8 row_mask:0xf bank_mask:0xf
	v_mov_b32_dpp v167, v31 row_ror:8 row_mask:0xf bank_mask:0xf
	v_cndmask_b32_e64 v28, v164, v32, s[90:91]
	v_cndmask_b32_e64 v29, v165, v33, s[90:91]
	v_cndmask_b32_e64 v30, v166, v34, s[90:91]
	v_cndmask_b32_e64 v31, v167, v35, s[90:91]
	v_cndmask_b32_e64 v32, v32, v164, s[90:91]
	v_cndmask_b32_e64 v33, v33, v165, s[90:91]
	v_cndmask_b32_e64 v34, v34, v166, s[90:91]
	v_cndmask_b32_e64 v35, v35, v167, s[90:91]
	v_mov_b32_dpp v164, v20 row_ror:8 row_mask:0xf bank_mask:0xf
	v_mov_b32_dpp v165, v21 row_ror:8 row_mask:0xf bank_mask:0xf
	v_mov_b32_dpp v166, v22 row_ror:8 row_mask:0xf bank_mask:0xf
	v_mov_b32_dpp v167, v23 row_ror:8 row_mask:0xf bank_mask:0xf
	v_cndmask_b32_e64 v20, v164, v24, s[90:91]
	v_cndmask_b32_e64 v21, v165, v25, s[90:91]
	v_cndmask_b32_e64 v22, v166, v26, s[90:91]
	v_cndmask_b32_e64 v23, v167, v27, s[90:91]
	v_cndmask_b32_e64 v24, v24, v164, s[90:91]
	v_cndmask_b32_e64 v25, v25, v165, s[90:91]
	v_cndmask_b32_e64 v26, v26, v166, s[90:91]
	v_cndmask_b32_e64 v27, v27, v167, s[90:91]
	s_lshl_b32 s94, s51, 8
	s_add_i32 s94, s94, 160
	s_lshl_b32 s94, s94, 14
	s_add_u32 s86, s48, s94
	s_addc_u32 s87, s49, 0
	s_lshl_b32 s94, s51, 8
	s_add_i32 s94, s94, 160
	s_lshl_b32 s94, s94, 13
	s_add_u32 s88, s12, s94
	s_addc_u32 s89, s13, 0
	s_lshl_b32 s94, s51, 8
	s_add_i32 s94, s94, 160
	s_lshl_b32 s94, s94, 8
	s_add_u32 s92, s22, s94
	s_addc_u32 s93, s23, 0
	s_waitcnt vmcnt(4)
	v_pk_add_f32 v[32:33], v[32:33], v[72:73]
	v_pk_add_f32 v[34:35], v[34:35], v[74:75]
	v_pk_add_f32 v[28:29], v[28:29], v[64:65]
	v_pk_add_f32 v[30:31], v[30:31], v[66:67]
	global_store_dwordx4 v193, v[32:35], s[86:87]
	global_store_dwordx4 v206, v[28:31], s[86:87]
	v_pk_add_f32 v[24:25], v[24:25], v[56:57]
	v_pk_add_f32 v[26:27], v[26:27], v[58:59]
	v_pk_add_f32 v[20:21], v[20:21], v[52:53]
	v_pk_add_f32 v[22:23], v[22:23], v[54:55]
	global_store_dwordx4 v193, v[24:27], s[86:87] offset:512
	global_store_dwordx4 v206, v[20:23], s[86:87] offset:512
.Lrot_p8n_end:
.Lp8epi_end:
	v_mov_b32_e32 v232, 0x6c0
	v_mov_b32_e32 v233, 0x750
	v_mov_b32_e32 v234, 0x7e0
	v_mov_b32_e32 v235, 0x870
